# FFT phase: dropped the s_nop pads hipcc adds after packed-f32 ops (dst-sel forwarding rule keyed on a source-select bit; the unpadded form already occurs 63x in the baseline); transpose-norm reads non
# speedup vs baseline: 1.0107x; 1.0080x over previous
.LBB0_197:
	s_lshl_b32 s0, s9, 6
	s_ashr_i32 s1, s0, 31
	v_lshl_add_u64 v[126:127], s[0:1], 1, v[0:1]
	v_lshl_add_u64 v[40:41], v[126:127], 0, v[2:3]
	s_waitcnt vmcnt(0)
	s_barrier
	global_load_dwordx4 v[40:43], v[40:41], off nt
	v_lshl_add_u64 v[44:45], v[126:127], 0, v[4:5]
	global_load_dwordx4 v[44:47], v[44:45], off nt
	v_lshl_add_u64 v[48:49], v[126:127], 0, v[6:7]
	global_load_dwordx4 v[48:51], v[48:49], off nt
	v_lshl_add_u64 v[52:53], v[126:127], 0, v[8:9]
	global_load_dwordx4 v[52:55], v[52:53], off nt
	v_lshl_add_u64 v[56:57], v[126:127], 0, v[10:11]
	global_load_dwordx4 v[56:59], v[56:57], off nt
	v_lshl_add_u64 v[60:61], v[126:127], 0, v[12:13]
	global_load_dwordx4 v[60:63], v[60:61], off nt
	v_lshl_add_u64 v[64:65], v[126:127], 0, v[14:15]
	global_load_dwordx4 v[64:67], v[64:65], off nt
	v_lshl_add_u64 v[68:69], v[126:127], 0, v[16:17]
	global_load_dwordx4 v[68:71], v[68:69], off nt
	v_lshl_add_u64 v[98:99], v[126:127], 0, v[18:19]
	global_load_dwordx4 v[98:101], v[98:99], off nt
	v_lshl_add_u64 v[102:103], v[126:127], 0, v[20:21]
	global_load_dwordx4 v[102:105], v[102:103], off nt
	v_lshl_add_u64 v[106:107], v[126:127], 0, v[22:23]
	global_load_dwordx4 v[106:109], v[106:107], off nt
	v_lshl_add_u64 v[110:111], v[126:127], 0, v[24:25]
	global_load_dwordx4 v[110:113], v[110:111], off nt
	v_lshl_add_u64 v[114:115], v[126:127], 0, v[26:27]
	global_load_dwordx4 v[114:117], v[114:115], off nt
	v_lshl_add_u64 v[118:119], v[126:127], 0, v[28:29]
	global_load_dwordx4 v[118:121], v[118:119], off nt
	v_lshl_add_u64 v[122:123], v[126:127], 0, v[30:31]
	global_load_dwordx4 v[122:125], v[122:123], off nt
	v_lshl_add_u64 v[126:127], v[126:127], 0, v[32:33]
	global_load_dwordx4 v[126:129], v[126:127], off nt
	s_mov_b64 s[38:39], 0
	v_mov_b32_e32 v97, v80
	s_waitcnt vmcnt(15)
	ds_write2_b32 v81, v40, v41 offset1:1
	ds_write2_b32 v81, v42, v43 offset0:2 offset1:3
	s_waitcnt vmcnt(14)
	ds_write2_b32 v82, v44, v45 offset1:1
	ds_write2_b32 v82, v46, v47 offset0:2 offset1:3
	s_waitcnt vmcnt(13)
	ds_write2_b32 v83, v48, v49 offset1:1
	ds_write2_b32 v83, v50, v51 offset0:2 offset1:3
	s_waitcnt vmcnt(12)
	ds_write2_b32 v84, v52, v53 offset1:1
	ds_write2_b32 v84, v54, v55 offset0:2 offset1:3
	s_waitcnt vmcnt(11)
	ds_write2_b32 v85, v56, v57 offset1:1
	ds_write2_b32 v85, v58, v59 offset0:2 offset1:3
	s_waitcnt vmcnt(10)
	ds_write2_b32 v86, v60, v61 offset1:1
	ds_write2_b32 v86, v62, v63 offset0:2 offset1:3
	s_waitcnt vmcnt(9)
	ds_write2_b32 v87, v64, v65 offset1:1
	ds_write2_b32 v87, v66, v67 offset0:2 offset1:3
	s_waitcnt vmcnt(8)
	ds_write2_b32 v88, v68, v69 offset1:1
	ds_write2_b32 v88, v70, v71 offset0:2 offset1:3
	s_waitcnt vmcnt(7)
	ds_write2_b32 v89, v98, v99 offset1:1
	ds_write2_b32 v89, v100, v101 offset0:2 offset1:3
	s_waitcnt vmcnt(6)
	ds_write2_b32 v90, v102, v103 offset1:1
	ds_write2_b32 v90, v104, v105 offset0:2 offset1:3
	s_waitcnt vmcnt(5)
	ds_write2_b32 v91, v106, v107 offset1:1
	ds_write2_b32 v91, v108, v109 offset0:2 offset1:3
	s_waitcnt vmcnt(4)
	ds_write2_b32 v92, v110, v111 offset1:1
	ds_write2_b32 v92, v112, v113 offset0:2 offset1:3
	s_waitcnt vmcnt(3)
	ds_write2_b32 v93, v114, v115 offset1:1
	ds_write2_b32 v93, v116, v117 offset0:2 offset1:3
	s_waitcnt vmcnt(2)
	ds_write2_b32 v94, v118, v119 offset1:1
	ds_write2_b32 v94, v120, v121 offset0:2 offset1:3
	s_waitcnt vmcnt(1)
	ds_write2_b32 v95, v122, v123 offset1:1
	ds_write2_b32 v95, v124, v125 offset0:2 offset1:3
	s_waitcnt vmcnt(0)
	ds_write2_b32 v96, v126, v127 offset1:1
	ds_write2_b32 v96, v128, v129 offset0:2 offset1:3
	s_waitcnt lgkmcnt(0)
	s_barrier
	global_load_dwordx2 v[40:41], v[34:35], off
	global_load_dwordx2 v[42:43], v[34:35], off offset:512
	global_load_dwordx2 v[44:45], v[34:35], off offset:1024
	global_load_dwordx2 v[46:47], v[34:35], off offset:1536
	global_load_dwordx2 v[48:49], v[36:37], off
	global_load_dwordx2 v[50:51], v[36:37], off offset:512
	global_load_dwordx2 v[52:53], v[36:37], off offset:1024
	global_load_dwordx2 v[54:55], v[36:37], off offset:1536
	v_mov_b32_e32 v98, v72
	s_waitcnt vmcnt(0)

.LBB0_206:
	s_or_b64 exec, exec, s[40:41]
	s_waitcnt lgkmcnt(1)
	s_lshl_b64 s[2:3], s[28:29], 16
	v_pk_mul_f32 v[2:3], v[208:209], v[208:209] op_sel:[1,1] op_sel_hi:[0,1] neg_lo:[1,0]
	v_readlane_b32 s6, v254, 43
	v_mov_b32_e32 v54, 1.0
	v_mov_b32_e32 v55, v177
	v_pk_fma_f32 v[2:3], v[208:209], v[208:209], v[2:3] op_sel_hi:[0,1,1]
	v_readlane_b32 s7, v254, 44
	s_add_u32 s40, s6, s2
	s_addc_u32 s41, s7, s3
	v_pk_mul_f32 v[44:45], v[2:3], v[2:3] op_sel:[1,1] op_sel_hi:[1,0] neg_lo:[0,1]
	v_pk_mul_f32 v[6:7], v[208:209], v[176:177] op_sel:[1,1] op_sel_hi:[0,1] neg_lo:[1,0]
	s_add_i32 s3, 0, 0x11000
	v_pk_fma_f32 v[44:45], v[2:3], v[2:3], v[44:45] op_sel_hi:[1,0,1]
	v_pk_fma_f32 v[70:71], v[208:209], v[54:55], v[6:7] op_sel_hi:[1,0,1]
	v_pk_mul_f32 v[0:1], v[176:177], v[2:3] op_sel:[1,1] op_sel_hi:[1,0] neg_lo:[0,1]
	v_mov_b32_e32 v5, s3
	v_pk_fma_f32 v[72:73], v[54:55], v[2:3], v[0:1] op_sel_hi:[0,1,1]
	v_pk_mul_f32 v[0:1], v[70:71], v[2:3] op_sel:[1,1] op_sel_hi:[1,0] neg_lo:[0,1]
	s_waitcnt lgkmcnt(0)
	s_barrier
	ds_read_b128 v[62:65], v5
	v_pk_fma_f32 v[60:61], v[2:3], v[70:71], v[0:1] op_sel_hi:[1,0,1]
	v_pk_mul_f32 v[0:1], v[176:177], v[44:45] op_sel:[1,1] op_sel_hi:[1,0] neg_lo:[0,1]
	v_pk_fma_f32 v[58:59], v[54:55], v[44:45], v[0:1] op_sel_hi:[0,1,1]
	v_pk_mul_f32 v[0:1], v[70:71], v[44:45] op_sel:[1,1] op_sel_hi:[1,0] neg_lo:[0,1]
	v_readlane_b32 s2, v254, 61
	v_pk_fma_f32 v[52:53], v[70:71], v[44:45], v[0:1] op_sel_hi:[0,1,1]
	v_pk_mul_f32 v[0:1], v[72:73], v[44:45] op_sel:[1,1] op_sel_hi:[1,0] neg_lo:[0,1]
	v_mov_b32_e32 v5, s2
	v_pk_mul_f32 v[50:51], v[44:45], v[44:45] op_sel:[1,1] op_sel_hi:[1,0] neg_lo:[0,1]
	v_pk_fma_f32 v[48:49], v[44:45], v[72:73], v[0:1] op_sel_hi:[1,0,1]
	v_pk_mul_f32 v[0:1], v[60:61], v[44:45] op_sel:[1,1] op_sel_hi:[1,0] neg_lo:[0,1]
	ds_read_b128 v[66:69], v5
	v_pk_fma_f32 v[42:43], v[44:45], v[60:61], v[0:1] op_sel_hi:[1,0,1]
	v_pk_fma_f32 v[0:1], v[44:45], v[44:45], v[50:51] op_sel_hi:[1,0,1]
	s_waitcnt lgkmcnt(1)
	v_add_f32_e32 v5, 0, v62
	v_add_f32_e32 v5, v5, v63
	v_pk_mul_f32 v[2:3], v[176:177], v[0:1] op_sel:[1,1] op_sel_hi:[1,0] neg_lo:[0,1]
	v_add_f32_e32 v5, v5, v64
	v_mov_b32_e32 v12, v206
	v_add_f32_e32 v5, v5, v65
	s_waitcnt lgkmcnt(0)
	v_add_f32_e32 v5, v5, v66
	v_lshlrev_b32_sdwa v64, v228, v12 dst_sel:DWORD dst_unused:UNUSED_PAD src0_sel:DWORD src1_sel:BYTE_0
	v_lshrrev_b32_e32 v12, 1, v206
	v_add_f32_e32 v5, v5, v67
	v_and_b32_e32 v12, 0x78, v12
	v_pk_fma_f32 v[44:45], v[54:55], v[0:1], v[2:3] op_sel_hi:[0,1,1]
	v_pk_mul_f32 v[46:47], v[70:71], v[0:1] op_sel:[1,1] op_sel_hi:[1,0] neg_lo:[0,1]
	v_pk_mul_f32 v[2:3], v[72:73], v[0:1] op_sel:[1,1] op_sel_hi:[1,0] neg_lo:[0,1]
	v_pk_mul_f32 v[50:51], v[60:61], v[0:1] op_sel:[1,1] op_sel_hi:[1,0] neg_lo:[0,1]
	v_pk_mul_f32 v[74:75], v[58:59], v[0:1] op_sel:[1,1] op_sel_hi:[1,0] neg_lo:[0,1]
	v_pk_mul_f32 v[76:77], v[52:53], v[0:1] op_sel:[1,1] op_sel_hi:[1,0] neg_lo:[0,1]
	v_pk_mul_f32 v[78:79], v[48:49], v[0:1] op_sel:[1,1] op_sel_hi:[1,0] neg_lo:[0,1]
	v_pk_mul_f32 v[80:81], v[42:43], v[0:1] op_sel:[1,1] op_sel_hi:[1,0] neg_lo:[0,1]
	v_add_f32_e32 v5, v5, v68
	v_add3_u32 v12, v207, v64, v12
	v_pk_fma_f32 v[2:3], v[72:73], v[0:1], v[2:3] op_sel_hi:[0,1,1]
	v_add_f32_e32 v5, v5, v69
	v_pk_fma_f32 v[62:63], v[70:71], v[0:1], v[46:47] op_sel_hi:[0,1,1]
	v_pk_fma_f32 v[56:57], v[60:61], v[0:1], v[50:51] op_sel_hi:[0,1,1]
	v_pk_fma_f32 v[50:51], v[0:1], v[58:59], v[74:75] op_sel_hi:[1,0,1]
	v_pk_fma_f32 v[46:47], v[0:1], v[52:53], v[76:77] op_sel_hi:[1,0,1]
	v_pk_fma_f32 v[6:7], v[0:1], v[48:49], v[78:79] op_sel_hi:[1,0,1]
	v_pk_fma_f32 v[0:1], v[0:1], v[42:43], v[80:81] op_sel_hi:[1,0,1]
	ds_read_b64 v[64:65], v12
	ds_read_b64 v[66:67], v12 offset:2176
	ds_read_b64 v[68:69], v12 offset:4352
	ds_read_b64 v[74:75], v12 offset:6528
	ds_read_b64 v[76:77], v12 offset:8704
	ds_read_b64 v[78:79], v12 offset:10880
	ds_read_b64 v[80:81], v12 offset:13056
	ds_read_b64 v[82:83], v12 offset:15232
	ds_read_b64 v[84:85], v12 offset:17408
	ds_read_b64 v[86:87], v12 offset:19584
	ds_read_b64 v[88:89], v12 offset:21760
	ds_read_b64 v[90:91], v12 offset:23936
	ds_read_b64 v[92:93], v12 offset:26112
	ds_read_b64 v[94:95], v12 offset:28288
	ds_read_b64 v[96:97], v12 offset:30464
	ds_read_b64 v[98:99], v12 offset:32640
	s_waitcnt lgkmcnt(7)
	v_pk_add_f32 v[100:101], v[64:65], v[84:85]
	v_pk_add_f32 v[64:65], v[64:65], v[84:85] neg_lo:[0,1] neg_hi:[0,1]
	s_waitcnt lgkmcnt(3)
	v_pk_add_f32 v[84:85], v[76:77], v[92:93]
	v_pk_add_f32 v[76:77], v[76:77], v[92:93] neg_lo:[0,1] neg_hi:[0,1]
	v_pk_add_f32 v[102:103], v[64:65], v[76:77] op_sel:[0,1] op_sel_hi:[1,0] neg_hi:[0,1]
	v_pk_add_f32 v[64:65], v[64:65], v[76:77] op_sel:[0,1] op_sel_hi:[1,0] neg_lo:[0,1]
	v_pk_add_f32 v[92:93], v[66:67], v[86:87]
	v_pk_add_f32 v[66:67], v[66:67], v[86:87] neg_lo:[0,1] neg_hi:[0,1]
	s_waitcnt lgkmcnt(2)
	v_pk_add_f32 v[86:87], v[78:79], v[94:95]
	v_pk_add_f32 v[78:79], v[78:79], v[94:95] neg_lo:[0,1] neg_hi:[0,1]
	v_pk_add_f32 v[76:77], v[100:101], v[84:85]
	v_xor_b32_e32 v95, 0x80000000, v78
	v_mov_b32_e32 v94, v79
	v_pk_add_f32 v[78:79], v[92:93], v[86:87]
	v_pk_add_f32 v[86:87], v[92:93], v[86:87] neg_lo:[0,1] neg_hi:[0,1]
	v_pk_add_f32 v[92:93], v[68:69], v[88:89]
	v_pk_add_f32 v[68:69], v[68:69], v[88:89] neg_lo:[0,1] neg_hi:[0,1]
	s_waitcnt lgkmcnt(1)
	v_pk_add_f32 v[88:89], v[80:81], v[96:97]
	v_pk_add_f32 v[80:81], v[80:81], v[96:97] neg_lo:[0,1] neg_hi:[0,1]
	v_pk_add_f32 v[84:85], v[100:101], v[84:85] neg_lo:[0,1] neg_hi:[0,1]
	v_pk_add_f32 v[100:101], v[66:67], v[94:95]
	v_pk_add_f32 v[66:67], v[66:67], v[94:95] neg_lo:[0,1] neg_hi:[0,1]
	v_xor_b32_e32 v95, 0x80000000, v80
	v_mov_b32_e32 v94, v81
	v_pk_add_f32 v[80:81], v[92:93], v[88:89]
	v_pk_add_f32 v[88:89], v[92:93], v[88:89] neg_lo:[0,1] neg_hi:[0,1]
	v_pk_add_f32 v[92:93], v[74:75], v[90:91]
	v_pk_add_f32 v[74:75], v[74:75], v[90:91] neg_lo:[0,1] neg_hi:[0,1]
	s_waitcnt lgkmcnt(0)
	v_pk_add_f32 v[90:91], v[82:83], v[98:99]
	v_pk_add_f32 v[82:83], v[82:83], v[98:99] neg_lo:[0,1] neg_hi:[0,1]
	v_pk_add_f32 v[96:97], v[68:69], v[94:95]
	v_pk_add_f32 v[68:69], v[68:69], v[94:95] neg_lo:[0,1] neg_hi:[0,1]
	v_pk_add_f32 v[98:99], v[74:75], v[82:83] op_sel:[0,1] op_sel_hi:[1,0] neg_hi:[0,1]
	v_pk_add_f32 v[74:75], v[74:75], v[82:83] op_sel:[0,1] op_sel_hi:[1,0] neg_lo:[0,1]
	v_pk_mul_f32 v[94:95], v[86:87], s[12:13] op_sel:[1,0] op_sel_hi:[0,0] neg_lo:[1,0]
	v_pk_add_f32 v[82:83], v[92:93], v[90:91]
	v_pk_fma_f32 v[86:87], v[86:87], s[12:13], v[94:95] op_sel_hi:[1,0,1] neg_lo:[0,0,1] neg_hi:[0,0,1]
	v_pk_mul_f32 v[94:95], v[66:67], s[36:37] op_sel:[1,0] op_sel_hi:[0,0] neg_lo:[1,0]
	v_pk_add_f32 v[90:91], v[92:93], v[90:91] neg_lo:[0,1] neg_hi:[0,1]
	v_pk_fma_f32 v[66:67], v[66:67], s[22:23], v[94:95] op_sel_hi:[1,0,1] neg_lo:[0,0,1] neg_hi:[0,0,1]
	v_pk_mul_f32 v[94:95], v[96:97], s[12:13] op_sel:[1,0] op_sel_hi:[0,0] neg_lo:[1,0]
	v_pk_fma_f32 v[94:95], v[96:97], s[12:13], v[94:95] op_sel_hi:[1,0,1] neg_lo:[0,0,1] neg_hi:[0,0,1]
	v_pk_fma_f32 v[88:89], v[88:89], 0, v[88:89] op_sel:[0,0,1] op_sel_hi:[1,0,0] neg_hi:[0,0,1]
	v_pk_mul_f32 v[96:97], v[68:69], s[12:13] op_sel:[1,0] op_sel_hi:[0,0] neg_lo:[1,0]
	v_pk_fma_f32 v[68:69], v[68:69], s[18:19], v[96:97] op_sel_hi:[1,0,1] neg_lo:[0,0,1] neg_hi:[0,0,1]
	v_pk_mul_f32 v[96:97], v[98:99], s[36:37] op_sel:[1,0] op_sel_hi:[0,0] neg_lo:[1,0]
	v_pk_mul_f32 v[92:93], v[100:101], s[22:23] op_sel:[1,0] op_sel_hi:[0,0] neg_lo:[1,0]
	v_pk_fma_f32 v[96:97], v[98:99], s[22:23], v[96:97] op_sel_hi:[1,0,1] neg_lo:[0,0,1] neg_hi:[0,0,1]
	v_pk_mul_f32 v[98:99], v[90:91], s[12:13] op_sel:[1,0] op_sel_hi:[0,0] neg_lo:[1,0]
	v_pk_fma_f32 v[92:93], v[100:101], s[36:37], v[92:93] op_sel_hi:[1,0,1] neg_lo:[0,0,1] neg_hi:[0,0,1]
	v_pk_fma_f32 v[90:91], v[90:91], s[18:19], v[98:99] op_sel_hi:[1,0,1] neg_lo:[0,0,1] neg_hi:[0,0,1]
	v_xor_b32_e32 v98, 0x80000000, v75
	v_mov_b32_e32 v99, v74
	v_pk_mul_f32 v[74:75], v[74:75], s[36:37] op_sel_hi:[1,0]
	v_pk_fma_f32 v[74:75], v[98:99], s[22:23], v[74:75] op_sel_hi:[1,0,1] neg_lo:[0,0,1] neg_hi:[0,0,1]
	v_pk_add_f32 v[98:99], v[76:77], v[80:81]
	v_pk_add_f32 v[76:77], v[76:77], v[80:81] neg_lo:[0,1] neg_hi:[0,1]
	v_pk_add_f32 v[80:81], v[78:79], v[82:83]
	v_pk_add_f32 v[78:79], v[78:79], v[82:83] neg_lo:[0,1] neg_hi:[0,1]
	v_xor_b32_e32 v83, 0x80000000, v78
	v_mov_b32_e32 v82, v79
	v_pk_add_f32 v[78:79], v[98:99], v[80:81]
	v_pk_add_f32 v[80:81], v[98:99], v[80:81] neg_lo:[0,1] neg_hi:[0,1]
	v_pk_add_f32 v[98:99], v[92:93], v[96:97]
	v_pk_add_f32 v[92:93], v[92:93], v[96:97] neg_lo:[0,1] neg_hi:[0,1]
	v_pk_add_f32 v[100:101], v[76:77], v[82:83]
	v_pk_add_f32 v[76:77], v[76:77], v[82:83] neg_lo:[0,1] neg_hi:[0,1]
	v_pk_add_f32 v[82:83], v[102:103], v[94:95]
	v_pk_add_f32 v[94:95], v[102:103], v[94:95] neg_lo:[0,1] neg_hi:[0,1]
	v_pk_add_f32 v[102:103], v[94:95], v[92:93] op_sel:[0,1] op_sel_hi:[1,0] neg_hi:[0,1]
	v_pk_add_f32 v[94:95], v[94:95], v[92:93] op_sel:[0,1] op_sel_hi:[1,0] neg_lo:[0,1]
	v_pk_add_f32 v[96:97], v[84:85], v[88:89]
	v_pk_add_f32 v[84:85], v[84:85], v[88:89] neg_lo:[0,1] neg_hi:[0,1]
	v_pk_add_f32 v[88:89], v[86:87], v[90:91]
	v_pk_add_f32 v[86:87], v[86:87], v[90:91] neg_lo:[0,1] neg_hi:[0,1]
	v_pk_add_f32 v[92:93], v[82:83], v[98:99]
	v_pk_add_f32 v[82:83], v[82:83], v[98:99] neg_lo:[0,1] neg_hi:[0,1]
	v_pk_add_f32 v[98:99], v[84:85], v[86:87] op_sel:[0,1] op_sel_hi:[1,0] neg_hi:[0,1]
	v_pk_add_f32 v[84:85], v[84:85], v[86:87] op_sel:[0,1] op_sel_hi:[1,0] neg_lo:[0,1]
	v_pk_add_f32 v[90:91], v[64:65], v[68:69]
	v_pk_add_f32 v[64:65], v[64:65], v[68:69] neg_lo:[0,1] neg_hi:[0,1]
	v_pk_add_f32 v[68:69], v[66:67], v[74:75]
	v_pk_add_f32 v[66:67], v[66:67], v[74:75] neg_lo:[0,1] neg_hi:[0,1]
	v_pk_add_f32 v[86:87], v[96:97], v[88:89]
	v_pk_add_f32 v[88:89], v[96:97], v[88:89] neg_lo:[0,1] neg_hi:[0,1]
	v_pk_add_f32 v[96:97], v[64:65], v[66:67] op_sel:[0,1] op_sel_hi:[1,0] neg_hi:[0,1]
	v_pk_add_f32 v[64:65], v[64:65], v[66:67] op_sel:[0,1] op_sel_hi:[1,0] neg_lo:[0,1]
	v_xor_b32_e32 v74, 0x80000000, v55
	v_mov_b32_e32 v75, v54
	v_pk_mul_f32 v[74:75], v[74:75], v[78:79] op_sel:[0,1]
	v_pk_add_f32 v[66:67], v[90:91], v[68:69]
	v_pk_fma_f32 v[54:55], v[54:55], v[78:79], v[74:75] op_sel_hi:[1,0,1]
	ds_write_b64 v12, v[54:55]
	v_pk_mul_f32 v[54:55], v[70:71], v[92:93] op_sel:[1,1] op_sel_hi:[0,1] neg_lo:[1,0]
	v_pk_add_f32 v[68:69], v[90:91], v[68:69] neg_lo:[0,1] neg_hi:[0,1]
	v_pk_fma_f32 v[54:55], v[70:71], v[92:93], v[54:55] op_sel_hi:[1,0,1]
	ds_write_b64 v12, v[54:55] offset:2176
	v_pk_mul_f32 v[54:55], v[72:73], v[86:87] op_sel:[1,1] op_sel_hi:[0,1] neg_lo:[1,0]
	v_pk_fma_f32 v[54:55], v[72:73], v[86:87], v[54:55] op_sel_hi:[1,0,1]
	ds_write_b64 v12, v[54:55] offset:4352
	v_pk_mul_f32 v[54:55], v[60:61], v[66:67] op_sel:[1,1] op_sel_hi:[0,1] neg_lo:[1,0]
	v_pk_fma_f32 v[54:55], v[60:61], v[66:67], v[54:55] op_sel_hi:[1,0,1]
	ds_write_b64 v12, v[54:55] offset:6528
	v_pk_mul_f32 v[54:55], v[58:59], v[100:101] op_sel:[1,1] op_sel_hi:[0,1] neg_lo:[1,0]
	v_pk_fma_f32 v[54:55], v[58:59], v[100:101], v[54:55] op_sel_hi:[1,0,1]
	ds_write_b64 v12, v[54:55] offset:8704
	v_pk_mul_f32 v[54:55], v[52:53], v[102:103] op_sel:[1,1] op_sel_hi:[0,1] neg_lo:[1,0]
	v_pk_fma_f32 v[52:53], v[52:53], v[102:103], v[54:55] op_sel_hi:[1,0,1]
	ds_write_b64 v12, v[52:53] offset:10880
	v_pk_mul_f32 v[52:53], v[48:49], v[98:99] op_sel:[1,1] op_sel_hi:[0,1] neg_lo:[1,0]
	v_pk_fma_f32 v[48:49], v[48:49], v[98:99], v[52:53] op_sel_hi:[1,0,1]
	ds_write_b64 v12, v[48:49] offset:13056
	v_pk_mul_f32 v[48:49], v[42:43], v[96:97] op_sel:[1,1] op_sel_hi:[0,1] neg_lo:[1,0]
	v_pk_fma_f32 v[42:43], v[42:43], v[96:97], v[48:49] op_sel_hi:[1,0,1]
	ds_write_b64 v12, v[42:43] offset:15232
	v_pk_mul_f32 v[42:43], v[44:45], v[80:81] op_sel:[1,1] op_sel_hi:[0,1] neg_lo:[1,0]
	v_pk_fma_f32 v[42:43], v[44:45], v[80:81], v[42:43] op_sel_hi:[1,0,1]
	ds_write_b64 v12, v[42:43] offset:17408
	v_pk_mul_f32 v[42:43], v[62:63], v[82:83] op_sel:[1,1] op_sel_hi:[0,1] neg_lo:[1,0]
	v_pk_fma_f32 v[42:43], v[62:63], v[82:83], v[42:43] op_sel_hi:[1,0,1]
	ds_write_b64 v12, v[42:43] offset:19584
	v_pk_mul_f32 v[42:43], v[2:3], v[88:89] op_sel:[1,1] op_sel_hi:[0,1] neg_lo:[1,0]
	v_pk_fma_f32 v[2:3], v[2:3], v[88:89], v[42:43] op_sel_hi:[1,0,1]
	ds_write_b64 v12, v[2:3] offset:21760
	v_pk_mul_f32 v[2:3], v[56:57], v[68:69] op_sel:[1,1] op_sel_hi:[0,1] neg_lo:[1,0]
	v_pk_fma_f32 v[2:3], v[56:57], v[68:69], v[2:3] op_sel_hi:[1,0,1]
	ds_write_b64 v12, v[2:3] offset:23936
	v_pk_mul_f32 v[2:3], v[50:51], v[76:77] op_sel:[1,1] op_sel_hi:[0,1] neg_lo:[1,0]
	v_pk_fma_f32 v[2:3], v[50:51], v[76:77], v[2:3] op_sel_hi:[1,0,1]
	ds_write_b64 v12, v[2:3] offset:26112
	v_pk_mul_f32 v[2:3], v[46:47], v[94:95] op_sel:[1,1] op_sel_hi:[0,1] neg_lo:[1,0]
	v_pk_fma_f32 v[2:3], v[46:47], v[94:95], v[2:3] op_sel_hi:[1,0,1]
	ds_write_b64 v12, v[2:3] offset:28288
	v_pk_mul_f32 v[2:3], v[6:7], v[84:85] op_sel:[1,1] op_sel_hi:[0,1] neg_lo:[1,0]
	v_pk_fma_f32 v[2:3], v[6:7], v[84:85], v[2:3] op_sel_hi:[1,0,1]
	ds_write_b64 v12, v[2:3] offset:30464
	v_pk_mul_f32 v[2:3], v[0:1], v[64:65] op_sel:[1,1] op_sel_hi:[0,1] neg_lo:[1,0]
	v_pk_fma_f32 v[0:1], v[0:1], v[64:65], v[2:3] op_sel_hi:[1,0,1]
	ds_write_b64 v12, v[0:1] offset:32640
	v_mov_b32_e32 v78, 1.0
	v_pk_mul_f32 v[2:3], v[210:211], v[210:211] op_sel:[1,1] op_sel_hi:[0,1] neg_lo:[1,0]
	v_mov_b32_e32 v79, v177
	v_pk_fma_f32 v[2:3], v[210:211], v[210:211], v[2:3] op_sel_hi:[0,1,1]
	v_pk_mul_f32 v[44:45], v[2:3], v[2:3] op_sel:[1,1] op_sel_hi:[1,0] neg_lo:[0,1]
	v_pk_mul_f32 v[6:7], v[210:211], v[176:177] op_sel:[1,1] op_sel_hi:[0,1] neg_lo:[1,0]
	v_pk_fma_f32 v[44:45], v[2:3], v[2:3], v[44:45] op_sel_hi:[1,0,1]
	v_pk_fma_f32 v[80:81], v[210:211], v[78:79], v[6:7] op_sel_hi:[1,0,1]
	v_pk_mul_f32 v[0:1], v[176:177], v[2:3] op_sel:[1,1] op_sel_hi:[1,0] neg_lo:[0,1]
	v_pk_fma_f32 v[82:83], v[78:79], v[2:3], v[0:1] op_sel_hi:[0,1,1]
	v_pk_mul_f32 v[0:1], v[80:81], v[2:3] op_sel:[1,1] op_sel_hi:[1,0] neg_lo:[0,1]
	v_pk_mul_f32 v[48:49], v[44:45], v[44:45] op_sel:[1,1] op_sel_hi:[1,0] neg_lo:[0,1]
	v_pk_fma_f32 v[84:85], v[2:3], v[80:81], v[0:1] op_sel_hi:[1,0,1]
	v_pk_mul_f32 v[0:1], v[176:177], v[44:45] op_sel:[1,1] op_sel_hi:[1,0] neg_lo:[0,1]
	v_pk_fma_f32 v[86:87], v[78:79], v[44:45], v[0:1] op_sel_hi:[0,1,1]
	v_pk_mul_f32 v[0:1], v[80:81], v[44:45] op_sel:[1,1] op_sel_hi:[1,0] neg_lo:[0,1]
	s_waitcnt lgkmcnt(0)
	v_pk_fma_f32 v[88:89], v[80:81], v[44:45], v[0:1] op_sel_hi:[0,1,1]
	v_pk_mul_f32 v[0:1], v[82:83], v[44:45] op_sel:[1,1] op_sel_hi:[1,0] neg_lo:[0,1]
	s_barrier
	v_pk_fma_f32 v[90:91], v[44:45], v[82:83], v[0:1] op_sel_hi:[1,0,1]
	v_pk_mul_f32 v[0:1], v[84:85], v[44:45] op_sel:[1,1] op_sel_hi:[1,0] neg_lo:[0,1]
	v_pk_fma_f32 v[92:93], v[44:45], v[84:85], v[0:1] op_sel_hi:[1,0,1]
	v_pk_fma_f32 v[0:1], v[44:45], v[44:45], v[48:49] op_sel_hi:[1,0,1]
	v_add_f32_e32 v5, 0x3727c5ac, v5
	v_pk_mul_f32 v[2:3], v[176:177], v[0:1] op_sel:[1,1] op_sel_hi:[1,0] neg_lo:[0,1]
	v_pk_fma_f32 v[94:95], v[78:79], v[0:1], v[2:3] op_sel_hi:[0,1,1]
	v_pk_mul_f32 v[2:3], v[80:81], v[0:1] op_sel:[1,1] op_sel_hi:[1,0] neg_lo:[0,1]
	v_pk_fma_f32 v[96:97], v[80:81], v[0:1], v[2:3] op_sel_hi:[0,1,1]
	v_pk_mul_f32 v[2:3], v[82:83], v[0:1] op_sel:[1,1] op_sel_hi:[1,0] neg_lo:[0,1]
	v_cmp_gt_f32_e32 vcc, s23, v5
	v_pk_fma_f32 v[98:99], v[82:83], v[0:1], v[2:3] op_sel_hi:[0,1,1]
	v_pk_mul_f32 v[2:3], v[84:85], v[0:1] op_sel:[1,1] op_sel_hi:[1,0] neg_lo:[0,1]
	s_mov_b32 s2, 0x39000000
	v_pk_fma_f32 v[44:45], v[84:85], v[0:1], v[2:3] op_sel_hi:[0,1,1]
	v_pk_mul_f32 v[2:3], v[86:87], v[0:1] op_sel:[1,1] op_sel_hi:[1,0] neg_lo:[0,1]
	s_add_u32 s6, s40, 0x2000
	v_pk_fma_f32 v[42:43], v[0:1], v[86:87], v[2:3] op_sel_hi:[1,0,1]
	v_pk_mul_f32 v[2:3], v[88:89], v[0:1] op_sel:[1,1] op_sel_hi:[1,0] neg_lo:[0,1]
	s_addc_u32 s7, s41, 0
	v_pk_fma_f32 v[6:7], v[0:1], v[88:89], v[2:3] op_sel_hi:[1,0,1]
	v_pk_mul_f32 v[2:3], v[90:91], v[0:1] op_sel:[1,1] op_sel_hi:[1,0] neg_lo:[0,1]
	v_pk_mul_f32 v[46:47], v[92:93], v[0:1] op_sel:[1,1] op_sel_hi:[1,0] neg_lo:[0,1]
	v_pk_fma_f32 v[2:3], v[0:1], v[90:91], v[2:3] op_sel_hi:[1,0,1]
	v_pk_fma_f32 v[0:1], v[0:1], v[92:93], v[46:47] op_sel_hi:[1,0,1]
	v_bfe_u32 v46, v206, 4, 4
	v_and_b32_e32 v12, 15, v206
	v_mul_u32_u24_e32 v46, 0x880, v46
	v_lshlrev_b32_e32 v12, 3, v12
	v_add3_u32 v12, v207, v46, v12
	ds_read2_b64 v[46:49], v12 offset1:17
	ds_read2_b64 v[50:53], v12 offset0:34 offset1:51
	ds_read2_b64 v[54:57], v12 offset0:68 offset1:85
	ds_read2_b64 v[58:61], v12 offset0:136 offset1:153
	ds_read2_b64 v[62:65], v12 offset0:102 offset1:119
	ds_read2_b64 v[66:69], v12 offset0:204 offset1:221
	ds_read2_b64 v[70:73], v12 offset0:170 offset1:187
	ds_read2_b64 v[74:77], v12 offset0:238 offset1:255
	s_waitcnt lgkmcnt(4)
	v_pk_add_f32 v[100:101], v[46:47], v[58:59]
	v_pk_add_f32 v[46:47], v[46:47], v[58:59] neg_lo:[0,1] neg_hi:[0,1]
	s_waitcnt lgkmcnt(2)
	v_pk_add_f32 v[58:59], v[54:55], v[66:67]
	v_pk_add_f32 v[54:55], v[54:55], v[66:67] neg_lo:[0,1] neg_hi:[0,1]
	v_pk_add_f32 v[102:103], v[46:47], v[54:55] op_sel:[0,1] op_sel_hi:[1,0] neg_hi:[0,1]
	v_pk_add_f32 v[46:47], v[46:47], v[54:55] op_sel:[0,1] op_sel_hi:[1,0] neg_lo:[0,1]
	v_pk_add_f32 v[66:67], v[48:49], v[60:61]
	v_pk_add_f32 v[48:49], v[48:49], v[60:61] neg_lo:[0,1] neg_hi:[0,1]
	v_pk_add_f32 v[60:61], v[56:57], v[68:69]
	v_pk_add_f32 v[56:57], v[56:57], v[68:69] neg_lo:[0,1] neg_hi:[0,1]
	v_pk_add_f32 v[54:55], v[100:101], v[58:59]
	v_pk_add_f32 v[58:59], v[100:101], v[58:59] neg_lo:[0,1] neg_hi:[0,1]
	v_pk_add_f32 v[100:101], v[48:49], v[56:57] op_sel:[0,1] op_sel_hi:[1,0] neg_hi:[0,1]
	v_pk_add_f32 v[48:49], v[48:49], v[56:57] op_sel:[0,1] op_sel_hi:[1,0] neg_lo:[0,1]
	s_waitcnt lgkmcnt(0)
	v_pk_add_f32 v[68:69], v[62:63], v[74:75]
	v_pk_add_f32 v[62:63], v[62:63], v[74:75] neg_lo:[0,1] neg_hi:[0,1]
	v_pk_add_f32 v[56:57], v[66:67], v[60:61]
	v_pk_add_f32 v[60:61], v[66:67], v[60:61] neg_lo:[0,1] neg_hi:[0,1]
	v_pk_add_f32 v[66:67], v[50:51], v[70:71]
	v_pk_add_f32 v[50:51], v[50:51], v[70:71] neg_lo:[0,1] neg_hi:[0,1]
	v_pk_add_f32 v[74:75], v[50:51], v[62:63] op_sel:[0,1] op_sel_hi:[1,0] neg_hi:[0,1]
	v_pk_add_f32 v[50:51], v[50:51], v[62:63] op_sel:[0,1] op_sel_hi:[1,0] neg_lo:[0,1]
	v_pk_add_f32 v[70:71], v[64:65], v[76:77]
	v_pk_add_f32 v[64:65], v[64:65], v[76:77] neg_lo:[0,1] neg_hi:[0,1]
	v_pk_add_f32 v[62:63], v[66:67], v[68:69]
	v_pk_add_f32 v[66:67], v[66:67], v[68:69] neg_lo:[0,1] neg_hi:[0,1]
	v_pk_add_f32 v[68:69], v[52:53], v[72:73]
	v_pk_add_f32 v[52:53], v[52:53], v[72:73] neg_lo:[0,1] neg_hi:[0,1]
	v_pk_add_f32 v[76:77], v[52:53], v[64:65] op_sel:[0,1] op_sel_hi:[1,0] neg_hi:[0,1]
	v_pk_add_f32 v[52:53], v[52:53], v[64:65] op_sel:[0,1] op_sel_hi:[1,0] neg_lo:[0,1]
	v_pk_mul_f32 v[72:73], v[60:61], s[12:13] op_sel:[1,0] op_sel_hi:[0,0] neg_lo:[1,0]
	v_pk_add_f32 v[64:65], v[68:69], v[70:71]
	v_pk_fma_f32 v[60:61], v[60:61], s[12:13], v[72:73] op_sel_hi:[1,0,1] neg_lo:[0,0,1] neg_hi:[0,0,1]
	v_pk_mul_f32 v[72:73], v[48:49], s[36:37] op_sel:[1,0] op_sel_hi:[0,0] neg_lo:[1,0]
	v_pk_add_f32 v[68:69], v[68:69], v[70:71] neg_lo:[0,1] neg_hi:[0,1]
	v_pk_fma_f32 v[48:49], v[48:49], s[22:23], v[72:73] op_sel_hi:[1,0,1] neg_lo:[0,0,1] neg_hi:[0,0,1]
	v_pk_mul_f32 v[72:73], v[74:75], s[12:13] op_sel:[1,0] op_sel_hi:[0,0] neg_lo:[1,0]
	v_pk_fma_f32 v[72:73], v[74:75], s[12:13], v[72:73] op_sel_hi:[1,0,1] neg_lo:[0,0,1] neg_hi:[0,0,1]
	v_pk_fma_f32 v[66:67], v[66:67], 0, v[66:67] op_sel:[0,0,1] op_sel_hi:[1,0,0] neg_hi:[0,0,1]
	v_pk_mul_f32 v[74:75], v[50:51], s[12:13] op_sel:[1,0] op_sel_hi:[0,0] neg_lo:[1,0]
	v_pk_fma_f32 v[50:51], v[50:51], s[18:19], v[74:75] op_sel_hi:[1,0,1] neg_lo:[0,0,1] neg_hi:[0,0,1]
	v_pk_mul_f32 v[74:75], v[76:77], s[36:37] op_sel:[1,0] op_sel_hi:[0,0] neg_lo:[1,0]
	v_pk_mul_f32 v[70:71], v[100:101], s[22:23] op_sel:[1,0] op_sel_hi:[0,0] neg_lo:[1,0]
	v_pk_fma_f32 v[74:75], v[76:77], s[22:23], v[74:75] op_sel_hi:[1,0,1] neg_lo:[0,0,1] neg_hi:[0,0,1]
	v_pk_mul_f32 v[76:77], v[68:69], s[12:13] op_sel:[1,0] op_sel_hi:[0,0] neg_lo:[1,0]
	v_pk_fma_f32 v[70:71], v[100:101], s[36:37], v[70:71] op_sel_hi:[1,0,1] neg_lo:[0,0,1] neg_hi:[0,0,1]
	v_pk_fma_f32 v[68:69], v[68:69], s[18:19], v[76:77] op_sel_hi:[1,0,1] neg_lo:[0,0,1] neg_hi:[0,0,1]
	v_xor_b32_e32 v76, 0x80000000, v53
	v_mov_b32_e32 v77, v52
	v_pk_mul_f32 v[52:53], v[52:53], s[36:37] op_sel_hi:[1,0]
	v_pk_fma_f32 v[52:53], v[76:77], s[22:23], v[52:53] op_sel_hi:[1,0,1] neg_lo:[0,0,1] neg_hi:[0,0,1]
	v_pk_add_f32 v[76:77], v[54:55], v[62:63]
	v_pk_add_f32 v[54:55], v[54:55], v[62:63] neg_lo:[0,1] neg_hi:[0,1]
	v_pk_add_f32 v[62:63], v[56:57], v[64:65]
	v_pk_add_f32 v[56:57], v[56:57], v[64:65] neg_lo:[0,1] neg_hi:[0,1]
	v_xor_b32_e32 v65, 0x80000000, v56
	v_mov_b32_e32 v64, v57
	v_pk_add_f32 v[56:57], v[76:77], v[62:63]
	v_pk_add_f32 v[62:63], v[76:77], v[62:63] neg_lo:[0,1] neg_hi:[0,1]
	v_pk_add_f32 v[76:77], v[70:71], v[74:75]
	v_pk_add_f32 v[70:71], v[70:71], v[74:75] neg_lo:[0,1] neg_hi:[0,1]
	v_pk_add_f32 v[100:101], v[54:55], v[64:65]
	v_pk_add_f32 v[54:55], v[54:55], v[64:65] neg_lo:[0,1] neg_hi:[0,1]
	v_pk_add_f32 v[64:65], v[102:103], v[72:73]
	v_pk_add_f32 v[72:73], v[102:103], v[72:73] neg_lo:[0,1] neg_hi:[0,1]
	v_pk_add_f32 v[102:103], v[72:73], v[70:71] op_sel:[0,1] op_sel_hi:[1,0] neg_hi:[0,1]
	v_pk_add_f32 v[72:73], v[72:73], v[70:71] op_sel:[0,1] op_sel_hi:[1,0] neg_lo:[0,1]
	v_pk_add_f32 v[74:75], v[58:59], v[66:67]
	v_pk_add_f32 v[58:59], v[58:59], v[66:67] neg_lo:[0,1] neg_hi:[0,1]
	v_pk_add_f32 v[66:67], v[60:61], v[68:69]
	v_pk_add_f32 v[60:61], v[60:61], v[68:69] neg_lo:[0,1] neg_hi:[0,1]
	v_pk_add_f32 v[70:71], v[64:65], v[76:77]
	v_pk_add_f32 v[64:65], v[64:65], v[76:77] neg_lo:[0,1] neg_hi:[0,1]
	v_pk_add_f32 v[76:77], v[58:59], v[60:61] op_sel:[0,1] op_sel_hi:[1,0] neg_hi:[0,1]
	v_pk_add_f32 v[58:59], v[58:59], v[60:61] op_sel:[0,1] op_sel_hi:[1,0] neg_lo:[0,1]
	v_pk_add_f32 v[68:69], v[46:47], v[50:51]
	v_pk_add_f32 v[46:47], v[46:47], v[50:51] neg_lo:[0,1] neg_hi:[0,1]
	v_pk_add_f32 v[50:51], v[48:49], v[52:53]
	v_pk_add_f32 v[48:49], v[48:49], v[52:53] neg_lo:[0,1] neg_hi:[0,1]
	v_pk_add_f32 v[60:61], v[74:75], v[66:67]
	v_pk_add_f32 v[66:67], v[74:75], v[66:67] neg_lo:[0,1] neg_hi:[0,1]
	v_pk_add_f32 v[74:75], v[46:47], v[48:49] op_sel:[0,1] op_sel_hi:[1,0] neg_hi:[0,1]
	v_pk_add_f32 v[46:47], v[46:47], v[48:49] op_sel:[0,1] op_sel_hi:[1,0] neg_lo:[0,1]
	v_xor_b32_e32 v52, 0x80000000, v79
	v_mov_b32_e32 v53, v78
	v_pk_mul_f32 v[52:53], v[52:53], v[56:57] op_sel:[0,1]
	v_pk_add_f32 v[48:49], v[68:69], v[50:51]
	v_pk_fma_f32 v[52:53], v[78:79], v[56:57], v[52:53] op_sel_hi:[1,0,1]
	v_pk_mul_f32 v[56:57], v[80:81], v[70:71] op_sel:[1,1] op_sel_hi:[0,1] neg_lo:[1,0]
	v_pk_add_f32 v[50:51], v[68:69], v[50:51] neg_lo:[0,1] neg_hi:[0,1]
	v_pk_fma_f32 v[56:57], v[80:81], v[70:71], v[56:57] op_sel_hi:[1,0,1]
	ds_write2_b64 v12, v[52:53], v[56:57] offset1:17
	v_pk_mul_f32 v[52:53], v[82:83], v[60:61] op_sel:[1,1] op_sel_hi:[0,1] neg_lo:[1,0]
	v_pk_mul_f32 v[56:57], v[84:85], v[48:49] op_sel:[1,1] op_sel_hi:[0,1] neg_lo:[1,0]
	v_pk_fma_f32 v[52:53], v[82:83], v[60:61], v[52:53] op_sel_hi:[1,0,1]
	v_pk_fma_f32 v[48:49], v[84:85], v[48:49], v[56:57] op_sel_hi:[1,0,1]
	ds_write2_b64 v12, v[52:53], v[48:49] offset0:34 offset1:51
	v_pk_mul_f32 v[48:49], v[86:87], v[100:101] op_sel:[1,1] op_sel_hi:[0,1] neg_lo:[1,0]
	v_pk_mul_f32 v[52:53], v[88:89], v[102:103] op_sel:[1,1] op_sel_hi:[0,1] neg_lo:[1,0]
	v_pk_fma_f32 v[48:49], v[86:87], v[100:101], v[48:49] op_sel_hi:[1,0,1]
	v_pk_fma_f32 v[52:53], v[88:89], v[102:103], v[52:53] op_sel_hi:[1,0,1]
	ds_write2_b64 v12, v[48:49], v[52:53] offset0:68 offset1:85
	v_pk_mul_f32 v[48:49], v[90:91], v[76:77] op_sel:[1,1] op_sel_hi:[0,1] neg_lo:[1,0]
	v_pk_mul_f32 v[52:53], v[92:93], v[74:75] op_sel:[1,1] op_sel_hi:[0,1] neg_lo:[1,0]
	v_pk_fma_f32 v[48:49], v[90:91], v[76:77], v[48:49] op_sel_hi:[1,0,1]
	v_pk_fma_f32 v[52:53], v[92:93], v[74:75], v[52:53] op_sel_hi:[1,0,1]
	ds_write2_b64 v12, v[48:49], v[52:53] offset0:102 offset1:119
	v_pk_mul_f32 v[48:49], v[94:95], v[62:63] op_sel:[1,1] op_sel_hi:[0,1] neg_lo:[1,0]
	v_pk_mul_f32 v[52:53], v[96:97], v[64:65] op_sel:[1,1] op_sel_hi:[0,1] neg_lo:[1,0]
	v_pk_fma_f32 v[48:49], v[94:95], v[62:63], v[48:49] op_sel_hi:[1,0,1]
	v_pk_fma_f32 v[52:53], v[96:97], v[64:65], v[52:53] op_sel_hi:[1,0,1]
	ds_write2_b64 v12, v[48:49], v[52:53] offset0:136 offset1:153
	v_pk_mul_f32 v[48:49], v[98:99], v[66:67] op_sel:[1,1] op_sel_hi:[0,1] neg_lo:[1,0]
	v_pk_mul_f32 v[52:53], v[44:45], v[50:51] op_sel:[1,1] op_sel_hi:[0,1] neg_lo:[1,0]
	v_pk_fma_f32 v[48:49], v[98:99], v[66:67], v[48:49] op_sel_hi:[1,0,1]
	v_pk_fma_f32 v[44:45], v[44:45], v[50:51], v[52:53] op_sel_hi:[1,0,1]
	ds_write2_b64 v12, v[48:49], v[44:45] offset0:170 offset1:187
	v_pk_mul_f32 v[44:45], v[42:43], v[54:55] op_sel:[1,1] op_sel_hi:[0,1] neg_lo:[1,0]
	v_pk_fma_f32 v[42:43], v[42:43], v[54:55], v[44:45] op_sel_hi:[1,0,1]
	v_pk_mul_f32 v[44:45], v[6:7], v[72:73] op_sel:[1,1] op_sel_hi:[0,1] neg_lo:[1,0]
	v_pk_fma_f32 v[6:7], v[6:7], v[72:73], v[44:45] op_sel_hi:[1,0,1]
	ds_write2_b64 v12, v[42:43], v[6:7] offset0:204 offset1:221
	v_pk_mul_f32 v[6:7], v[2:3], v[58:59] op_sel:[1,1] op_sel_hi:[0,1] neg_lo:[1,0]
	v_pk_fma_f32 v[2:3], v[2:3], v[58:59], v[6:7] op_sel_hi:[1,0,1]
	v_pk_mul_f32 v[6:7], v[0:1], v[46:47] op_sel:[1,1] op_sel_hi:[0,1] neg_lo:[1,0]
	v_pk_fma_f32 v[0:1], v[0:1], v[46:47], v[6:7] op_sel_hi:[1,0,1]
	ds_write2_b64 v12, v[2:3], v[0:1] offset0:238 offset1:255
	s_waitcnt lgkmcnt(0)
	s_barrier
	v_mul_f32_e32 v12, 0x4b800000, v5
	v_and_b32_e32 v0, 0xff, v206
	v_mad_u32_u24 v6, v0, s19, v207
	ds_read2_b64 v[0:3], v6 offset1:1
	ds_read2_b64 v[42:45], v6 offset0:2 offset1:3
	ds_read2_b64 v[46:49], v6 offset0:8 offset1:9
	ds_read2_b64 v[50:53], v6 offset0:4 offset1:5
	ds_read2_b64 v[54:57], v6 offset0:6 offset1:7
	ds_read2_b64 v[58:61], v6 offset0:12 offset1:13
	ds_read2_b64 v[62:65], v6 offset0:10 offset1:11
	ds_read2_b64 v[66:69], v6 offset0:14 offset1:15
	s_waitcnt lgkmcnt(5)
	v_pk_add_f32 v[6:7], v[0:1], v[46:47]
	v_pk_add_f32 v[0:1], v[0:1], v[46:47] neg_lo:[0,1] neg_hi:[0,1]
	s_waitcnt lgkmcnt(2)
	v_pk_add_f32 v[46:47], v[50:51], v[58:59]
	v_pk_add_f32 v[50:51], v[50:51], v[58:59] neg_lo:[0,1] neg_hi:[0,1]
	v_cndmask_b32_e32 v5, v5, v12, vcc
	v_xor_b32_e32 v59, 0x80000000, v50
	v_mov_b32_e32 v58, v51
	v_pk_add_f32 v[50:51], v[6:7], v[46:47]
	v_pk_add_f32 v[6:7], v[6:7], v[46:47] neg_lo:[0,1] neg_hi:[0,1]
	v_pk_add_f32 v[46:47], v[2:3], v[48:49]
	v_pk_add_f32 v[2:3], v[2:3], v[48:49] neg_lo:[0,1] neg_hi:[0,1]
	v_pk_add_f32 v[48:49], v[52:53], v[60:61]
	v_pk_add_f32 v[52:53], v[52:53], v[60:61] neg_lo:[0,1] neg_hi:[0,1]
	v_pk_add_f32 v[70:71], v[0:1], v[58:59]
	v_pk_add_f32 v[0:1], v[0:1], v[58:59] neg_lo:[0,1] neg_hi:[0,1]
	v_pk_add_f32 v[60:61], v[2:3], v[52:53] op_sel:[0,1] op_sel_hi:[1,0] neg_hi:[0,1]
	v_pk_add_f32 v[2:3], v[2:3], v[52:53] op_sel:[0,1] op_sel_hi:[1,0] neg_lo:[0,1]
	s_waitcnt lgkmcnt(0)
	v_pk_add_f32 v[58:59], v[54:55], v[66:67]
	v_pk_add_f32 v[54:55], v[54:55], v[66:67] neg_lo:[0,1] neg_hi:[0,1]
	v_pk_add_f32 v[52:53], v[46:47], v[48:49]
	v_pk_add_f32 v[46:47], v[46:47], v[48:49] neg_lo:[0,1] neg_hi:[0,1]
	v_pk_add_f32 v[48:49], v[42:43], v[62:63]
	v_pk_add_f32 v[42:43], v[42:43], v[62:63] neg_lo:[0,1] neg_hi:[0,1]
	v_xor_b32_e32 v63, 0x80000000, v54
	v_mov_b32_e32 v62, v55
	v_pk_add_f32 v[54:55], v[48:49], v[58:59]
	v_pk_add_f32 v[66:67], v[42:43], v[62:63]
	v_pk_add_f32 v[48:49], v[48:49], v[58:59] neg_lo:[0,1] neg_hi:[0,1]
	v_pk_add_f32 v[42:43], v[42:43], v[62:63] neg_lo:[0,1] neg_hi:[0,1]
	v_pk_add_f32 v[58:59], v[44:45], v[64:65]
	v_pk_add_f32 v[62:63], v[56:57], v[68:69]
	v_pk_add_f32 v[56:57], v[56:57], v[68:69] neg_lo:[0,1] neg_hi:[0,1]
	v_pk_add_f32 v[44:45], v[44:45], v[64:65] neg_lo:[0,1] neg_hi:[0,1]
	v_xor_b32_e32 v65, 0x80000000, v56
	v_mov_b32_e32 v64, v57
	v_pk_add_f32 v[56:57], v[58:59], v[62:63]
	v_pk_add_f32 v[58:59], v[58:59], v[62:63] neg_lo:[0,1] neg_hi:[0,1]
	v_pk_mul_f32 v[62:63], v[60:61], s[22:23] op_sel:[1,0] op_sel_hi:[0,0] neg_lo:[1,0]
	v_pk_add_f32 v[68:69], v[44:45], v[64:65]
	v_pk_fma_f32 v[60:61], v[60:61], s[36:37], v[62:63] op_sel_hi:[1,0,1] neg_lo:[0,0,1] neg_hi:[0,0,1]
	v_pk_mul_f32 v[62:63], v[46:47], s[12:13] op_sel:[1,0] op_sel_hi:[0,0] neg_lo:[1,0]
	v_pk_add_f32 v[44:45], v[44:45], v[64:65] neg_lo:[0,1] neg_hi:[0,1]
	v_pk_fma_f32 v[46:47], v[46:47], s[12:13], v[62:63] op_sel_hi:[1,0,1] neg_lo:[0,0,1] neg_hi:[0,0,1]
	v_pk_mul_f32 v[62:63], v[2:3], s[36:37] op_sel:[1,0] op_sel_hi:[0,0] neg_lo:[1,0]
	v_pk_fma_f32 v[2:3], v[2:3], s[22:23], v[62:63] op_sel_hi:[1,0,1] neg_lo:[0,0,1] neg_hi:[0,0,1]
	v_pk_mul_f32 v[62:63], v[66:67], s[12:13] op_sel:[1,0] op_sel_hi:[0,0] neg_lo:[1,0]
	v_pk_fma_f32 v[48:49], v[48:49], 0, v[48:49] op_sel:[0,0,1] op_sel_hi:[1,0,0] neg_hi:[0,0,1]
	v_pk_fma_f32 v[62:63], v[66:67], s[12:13], v[62:63] op_sel_hi:[1,0,1] neg_lo:[0,0,1] neg_hi:[0,0,1]
	v_pk_mul_f32 v[64:65], v[42:43], s[12:13] op_sel:[1,0] op_sel_hi:[0,0] neg_lo:[1,0]
	v_pk_fma_f32 v[42:43], v[42:43], s[18:19], v[64:65] op_sel_hi:[1,0,1] neg_lo:[0,0,1] neg_hi:[0,0,1]
	v_pk_mul_f32 v[66:67], v[58:59], s[12:13] op_sel:[1,0] op_sel_hi:[0,0] neg_lo:[1,0]
	v_pk_mul_f32 v[64:65], v[68:69], s[36:37] op_sel:[1,0] op_sel_hi:[0,0] neg_lo:[1,0]
	v_pk_fma_f32 v[58:59], v[58:59], s[18:19], v[66:67] op_sel_hi:[1,0,1] neg_lo:[0,0,1] neg_hi:[0,0,1]
	v_xor_b32_e32 v66, 0x80000000, v45
	v_mov_b32_e32 v67, v44
	v_pk_mul_f32 v[44:45], v[44:45], s[36:37] op_sel_hi:[1,0]
	v_pk_fma_f32 v[64:65], v[68:69], s[22:23], v[64:65] op_sel_hi:[1,0,1] neg_lo:[0,0,1] neg_hi:[0,0,1]
	v_pk_fma_f32 v[44:45], v[66:67], s[22:23], v[44:45] op_sel_hi:[1,0,1] neg_lo:[0,0,1] neg_hi:[0,0,1]
	v_pk_add_f32 v[66:67], v[50:51], v[54:55]
	v_pk_add_f32 v[50:51], v[50:51], v[54:55] neg_lo:[0,1] neg_hi:[0,1]
	v_pk_add_f32 v[54:55], v[52:53], v[56:57]
	v_pk_add_f32 v[52:53], v[52:53], v[56:57] neg_lo:[0,1] neg_hi:[0,1]
	v_rsq_f32_e32 v5, v5
	v_xor_b32_e32 v57, 0x80000000, v52
	v_mov_b32_e32 v56, v53
	v_pk_add_f32 v[52:53], v[66:67], v[54:55]
	v_pk_add_f32 v[54:55], v[66:67], v[54:55] neg_lo:[0,1] neg_hi:[0,1]
	v_pk_add_f32 v[66:67], v[60:61], v[64:65]
	v_pk_add_f32 v[60:61], v[60:61], v[64:65] neg_lo:[0,1] neg_hi:[0,1]
	v_pk_add_f32 v[68:69], v[50:51], v[56:57]
	v_pk_add_f32 v[50:51], v[50:51], v[56:57] neg_lo:[0,1] neg_hi:[0,1]
	v_pk_add_f32 v[56:57], v[70:71], v[62:63]
	v_pk_add_f32 v[62:63], v[70:71], v[62:63] neg_lo:[0,1] neg_hi:[0,1]
	v_pk_add_f32 v[70:71], v[62:63], v[60:61] op_sel:[0,1] op_sel_hi:[1,0] neg_hi:[0,1]
	v_pk_add_f32 v[62:63], v[62:63], v[60:61] op_sel:[0,1] op_sel_hi:[1,0] neg_lo:[0,1]
	v_pk_add_f32 v[64:65], v[6:7], v[48:49]
	v_pk_add_f32 v[6:7], v[6:7], v[48:49] neg_lo:[0,1] neg_hi:[0,1]
	v_pk_add_f32 v[48:49], v[46:47], v[58:59]
	v_pk_add_f32 v[46:47], v[46:47], v[58:59] neg_lo:[0,1] neg_hi:[0,1]
	v_mul_f32_e32 v12, 0x45800000, v5
	v_pk_add_f32 v[60:61], v[56:57], v[66:67]
	v_pk_add_f32 v[56:57], v[56:57], v[66:67] neg_lo:[0,1] neg_hi:[0,1]
	v_pk_add_f32 v[66:67], v[6:7], v[46:47] op_sel:[0,1] op_sel_hi:[1,0] neg_hi:[0,1]
	v_pk_add_f32 v[6:7], v[6:7], v[46:47] op_sel:[0,1] op_sel_hi:[1,0] neg_lo:[0,1]
	v_pk_add_f32 v[58:59], v[0:1], v[42:43]
	v_pk_add_f32 v[0:1], v[0:1], v[42:43] neg_lo:[0,1] neg_hi:[0,1]
	v_pk_add_f32 v[42:43], v[2:3], v[44:45]
	v_pk_add_f32 v[2:3], v[2:3], v[44:45] neg_lo:[0,1] neg_hi:[0,1]
	v_cndmask_b32_e32 v5, v5, v12, vcc
	v_pk_mul_f32 v[4:5], v[4:5], s[2:3] op_sel_hi:[1,0]
	v_pk_add_f32 v[46:47], v[64:65], v[48:49]
	v_pk_add_f32 v[48:49], v[64:65], v[48:49] neg_lo:[0,1] neg_hi:[0,1]
	v_pk_add_f32 v[64:65], v[0:1], v[2:3] op_sel:[0,1] op_sel_hi:[1,0] neg_hi:[0,1]
	v_pk_add_f32 v[0:1], v[0:1], v[2:3] op_sel:[0,1] op_sel_hi:[1,0] neg_lo:[0,1]
	v_pk_fma_f32 v[44:45], v[4:5], v[52:53], v[4:5] op_sel:[1,0,0] op_sel_hi:[0,1,1]
	v_pk_mul_f32 v[52:53], v[4:5], v[52:53]
	v_pk_add_f32 v[2:3], v[58:59], v[42:43]
	v_pk_add_f32 v[42:43], v[58:59], v[42:43] neg_lo:[0,1] neg_hi:[0,1]
	v_mov_b32_e32 v45, v53
	v_pk_fma_f32 v[52:53], v[4:5], v[68:69], v[4:5] op_sel:[1,0,0] op_sel_hi:[0,1,1]
	v_pk_mul_f32 v[58:59], v[4:5], v[68:69]
	v_pk_mul_f32 v[68:69], v[4:5], v[70:71]
	v_mov_b32_e32 v53, v59
	v_pk_fma_f32 v[58:59], v[4:5], v[54:55], v[4:5] op_sel:[1,0,0] op_sel_hi:[0,1,1]
	v_pk_mul_f32 v[54:55], v[4:5], v[54:55]
	v_mov_b32_e32 v59, v55
	v_pk_fma_f32 v[54:55], v[4:5], v[50:51], v[4:5] op_sel:[1,0,0] op_sel_hi:[0,1,1]
	v_pk_mul_f32 v[50:51], v[4:5], v[50:51]
	s_barrier
	v_mov_b32_e32 v55, v51
	v_pk_fma_f32 v[50:51], v[4:5], v[60:61], v[4:5] op_sel:[1,0,0] op_sel_hi:[0,1,1]
	v_pk_mul_f32 v[60:61], v[4:5], v[60:61]
	v_mov_b32_e32 v51, v61
	v_pk_fma_f32 v[60:61], v[4:5], v[70:71], v[4:5] op_sel:[1,0,0] op_sel_hi:[0,1,1]
	v_mov_b32_e32 v61, v69
	v_pk_fma_f32 v[68:69], v[4:5], v[56:57], v[4:5] op_sel:[1,0,0] op_sel_hi:[0,1,1]
	v_pk_mul_f32 v[56:57], v[4:5], v[56:57]
	v_mov_b32_e32 v69, v57
	v_pk_fma_f32 v[56:57], v[4:5], v[62:63], v[4:5] op_sel:[1,0,0] op_sel_hi:[0,1,1]
	v_pk_mul_f32 v[62:63], v[4:5], v[62:63]
	v_mov_b32_e32 v57, v63
	v_pk_fma_f32 v[62:63], v[4:5], v[46:47], v[4:5] op_sel:[1,0,0] op_sel_hi:[0,1,1]
	v_pk_mul_f32 v[46:47], v[4:5], v[46:47]
	v_mov_b32_e32 v63, v47
	v_pk_fma_f32 v[46:47], v[4:5], v[66:67], v[4:5] op_sel:[1,0,0] op_sel_hi:[0,1,1]
	v_pk_mul_f32 v[66:67], v[4:5], v[66:67]
	v_mov_b32_e32 v47, v67
	v_pk_fma_f32 v[66:67], v[4:5], v[48:49], v[4:5] op_sel:[1,0,0] op_sel_hi:[0,1,1]
	v_pk_mul_f32 v[48:49], v[4:5], v[48:49]
	v_mov_b32_e32 v67, v49
	v_pk_fma_f32 v[48:49], v[4:5], v[6:7], v[4:5] op_sel:[1,0,0] op_sel_hi:[0,1,1]
	v_pk_mul_f32 v[6:7], v[4:5], v[6:7]
	v_mov_b32_e32 v49, v7
	v_pk_fma_f32 v[6:7], v[4:5], v[2:3], v[4:5] op_sel:[1,0,0] op_sel_hi:[0,1,1]
	v_pk_mul_f32 v[2:3], v[4:5], v[2:3]
	v_mov_b32_e32 v7, v3
	v_pk_fma_f32 v[2:3], v[4:5], v[64:65], v[4:5] op_sel:[1,0,0] op_sel_hi:[0,1,1]
	v_pk_mul_f32 v[64:65], v[4:5], v[64:65]
	v_mov_b32_e32 v3, v65
	v_pk_fma_f32 v[64:65], v[4:5], v[42:43], v[4:5] op_sel:[1,0,0] op_sel_hi:[0,1,1]
	v_pk_mul_f32 v[42:43], v[4:5], v[42:43]
	v_mov_b32_e32 v65, v43
	v_pk_fma_f32 v[42:43], v[4:5], v[0:1], v[4:5] op_sel:[1,0,0] op_sel_hi:[0,1,1]
	v_pk_mul_f32 v[0:1], v[4:5], v[0:1]
	v_mov_b32_e32 v43, v1
	v_and_b32_e32 v0, 0x1ff, v212
	v_lshl_add_u32 v0, v0, 3, 0
	v_add_u32_e32 v0, 0x11040, v0
	ds_write2st64_b64 v0, v[44:45], v[52:53] offset1:8
	ds_write2st64_b64 v0, v[58:59], v[54:55] offset0:16 offset1:24
	ds_write2st64_b64 v0, v[50:51], v[60:61] offset0:32 offset1:40
	ds_write2st64_b64 v0, v[68:69], v[56:57] offset0:48 offset1:56
	ds_write2st64_b64 v0, v[62:63], v[46:47] offset0:64 offset1:72
	ds_write2st64_b64 v0, v[66:67], v[48:49] offset0:80 offset1:88
	ds_write2st64_b64 v0, v[6:7], v[2:3] offset0:96 offset1:104
	ds_write2st64_b64 v0, v[64:65], v[42:43] offset0:112 offset1:120
	v_add_f32_e32 v47, v20, v20
	v_and_b32_e32 v0, 0x1ff, v212
	v_lshlrev_b32_e32 v1, 3, v0
	v_add_u32_e32 v2, -1, v1
	v_cmp_ne_u32_e32 vcc, 0, v0
	v_add_u32_e32 v1, 8, v1
	s_waitcnt vmcnt(0)
	v_mul_f32_e32 v47, v47, v25
	v_cndmask_b32_e32 v176, 0, v2, vcc
	v_cmp_ne_u32_e32 vcc, s37, v0
	v_lshlrev_b64 v[42:43], 1, v[176:177]
	v_lshlrev_b32_e32 v0, 4, v0
	v_cndmask_b32_e32 v12, v229, v1, vcc
	v_lshl_add_u64 v[44:45], s[40:41], 0, v[42:43]
	v_lshlrev_b32_e32 v12, 1, v12
	global_load_dwordx4 v[4:7], v0, s[40:41]
	s_nop 0
	global_load_dwordx4 v[0:3], v0, s[6:7]
	v_lshl_add_u64 v[42:43], s[6:7], 0, v[42:43]
	global_load_ushort v143, v[44:45], off
	global_load_ushort v142, v12, s[40:41]
	global_load_ushort v141, v[42:43], off
	global_load_ushort v140, v12, s[6:7]
	s_nop 0
	global_load_dword v12, v177, s[44:45]
	v_mov_b32_e32 v43, v212
	v_add_f32_e32 v176, v20, v25
	v_and_b32_e32 v42, 0x1ff, v212
	v_bfe_u32 v44, v212, 1, 8
	v_cmp_eq_u32_e32 vcc, 0, v42
	v_sub_f32_e32 v48, v20, v25
	v_mul_f32_e32 v25, v25, v25
	v_lshl_add_u32 v46, v42, 3, v44
	v_mov_b32_e32 v44, v213
	v_mov_b32_e32 v45, v214
	v_cndmask_b32_e32 v47, 0, v47, vcc
	v_fmac_f32_e32 v25, v20, v20
	v_cndmask_b32_e32 v20, v48, v176, vcc
	v_add_f32_e32 v25, v25, v47
	v_lshl_add_u32 v50, v46, 3, 0
	v_pk_mul_f32 v[46:47], v[44:45], v[20:21] op_sel_hi:[1,0]
	v_pk_mul_f32 v[48:49], v[214:215], s[8:9] op_sel_hi:[0,1]
	v_pk_fma_f32 v[44:45], v[212:213], s[30:31], v[48:49] op_sel:[1,0,0]
	v_add_f32_e32 v20, v21, v19
	v_sub_f32_e32 v48, v21, v19
	v_mul_f32_e32 v19, v19, v19
	v_fmac_f32_e32 v19, v21, v21
	v_mov_b32_e32 v21, v177
	v_add_u32_e32 v51, 0x8800, v50
	ds_write2_b64 v50, v[176:177], v[20:21] offset1:1
	v_pk_mul_f32 v[20:21], v[48:49], v[44:45] op_sel_hi:[0,1]
	ds_write2_b64 v51, v[46:47], v[20:21] offset1:1
	v_pk_mul_f32 v[20:21], v[44:45], s[8:9] op_sel:[1,0]
	v_add_f32_e32 v176, v22, v18
	v_pk_fma_f32 v[20:21], v[44:45], s[30:31], v[20:21] op_sel_hi:[0,1,1]
	v_sub_f32_e32 v44, v22, v18
	v_mul_f32_e32 v18, v18, v18
	v_add_f32_e32 v19, v19, v25
	v_fmac_f32_e32 v18, v22, v22
	v_add_f32_e32 v25, v18, v19
	v_pk_mul_f32 v[18:19], v[44:45], v[20:21] op_sel_hi:[0,1]
	v_pk_mul_f32 v[44:45], v[20:21], s[8:9] op_sel:[1,0]
	v_add_f32_e32 v22, v23, v17
	v_pk_fma_f32 v[20:21], v[20:21], s[30:31], v[44:45] op_sel_hi:[0,1,1]
	v_sub_f32_e32 v44, v23, v17
	v_mul_f32_e32 v17, v17, v17
	v_fmac_f32_e32 v17, v23, v23
	v_mov_b32_e32 v23, v177
	v_add_u32_e32 v46, 0x8810, v50
	ds_write2_b64 v50, v[176:177], v[22:23] offset0:2 offset1:3
	v_pk_mul_f32 v[22:23], v[44:45], v[20:21] op_sel_hi:[0,1]
	ds_write2_b64 v46, v[18:19], v[22:23] offset1:1
	v_pk_mul_f32 v[18:19], v[20:21], s[8:9] op_sel:[1,0]
	v_add_f32_e32 v176, v8, v16
	v_pk_fma_f32 v[18:19], v[20:21], s[30:31], v[18:19] op_sel_hi:[0,1,1]
	v_sub_f32_e32 v20, v8, v16
	v_mul_f32_e32 v16, v16, v16
	v_add_f32_e32 v17, v17, v25
	v_fmac_f32_e32 v16, v8, v8
	v_add_f32_e32 v8, v16, v17
	v_pk_mul_f32 v[16:17], v[20:21], v[18:19] op_sel_hi:[0,1]
	v_mul_f32_e32 v20, v15, v15
	v_fmac_f32_e32 v20, v9, v9
	v_add_f32_e32 v8, v20, v8
	v_mul_f32_e32 v20, v14, v14
	v_fmac_f32_e32 v20, v10, v10
	v_add_f32_e32 v8, v20, v8
	v_mul_f32_e32 v20, v13, v13
	v_fmac_f32_e32 v20, v11, v11
	v_add_f32_e32 v23, v20, v8
	ds_bpermute_b32 v25, v27, v23
	v_pk_mul_f32 v[20:21], v[18:19], s[8:9] op_sel:[1,0]
	v_add_f32_e32 v8, v9, v15
	v_pk_fma_f32 v[18:19], v[18:19], s[30:31], v[20:21] op_sel_hi:[0,1,1]
	v_sub_f32_e32 v20, v9, v15
	s_waitcnt lgkmcnt(0)
	v_add_f32_e32 v15, v23, v25
	ds_bpermute_b32 v21, v29, v15
	v_mov_b32_e32 v9, v177
	v_add_u32_e32 v22, 0x8820, v50
	ds_write2_b64 v50, v[176:177], v[8:9] offset0:4 offset1:5
	v_add_f32_e32 v176, v10, v14
	s_waitcnt lgkmcnt(1)
	v_pk_mul_f32 v[8:9], v[20:21], v[18:19] op_sel_hi:[0,1]
	v_add_f32_e32 v15, v15, v21
	ds_write2_b64 v22, v[16:17], v[8:9] offset1:1
	ds_bpermute_b32 v16, v35, v15
	v_pk_mul_f32 v[8:9], v[18:19], s[8:9] op_sel:[1,0]
	v_sub_f32_e32 v10, v10, v14
	v_pk_fma_f32 v[8:9], v[18:19], s[30:31], v[8:9] op_sel_hi:[0,1,1]
	v_add_u32_e32 v20, 0x8830, v50
	s_waitcnt lgkmcnt(0)
	v_add_f32_e32 v18, v15, v16
	ds_bpermute_b32 v19, v37, v18
	v_pk_mul_f32 v[16:17], v[8:9], s[8:9] op_sel:[1,0]
	v_pk_mul_f32 v[14:15], v[10:11], v[8:9] op_sel_hi:[0,1]
	v_pk_fma_f32 v[16:17], v[8:9], s[30:31], v[16:17] op_sel_hi:[0,1,1]
	v_add_f32_e32 v8, v11, v13
	s_waitcnt lgkmcnt(0)
	v_add_f32_e32 v18, v18, v19
	ds_bpermute_b32 v19, v39, v18
	v_mov_b32_e32 v9, v177
	ds_write2_b64 v50, v[176:177], v[8:9] offset0:6 offset1:7
	v_sub_f32_e32 v10, v11, v13
	v_pk_mul_f32 v[10:11], v[10:11], v[16:17] op_sel_hi:[0,1]
	s_waitcnt lgkmcnt(1)
	v_add_f32_e32 v8, v18, v19
	ds_bpermute_b32 v9, v40, v8
	ds_write2_b64 v20, v[14:15], v[10:11] offset1:1
	v_and_b32_e32 v10, 63, v212
	v_cmp_eq_u32_e32 vcc, 0, v10
	s_and_saveexec_b64 s[28:29], vcc
	v_readlane_b32 s64, v255, 6
	v_readlane_b32 s65, v255, 7
	v_readlane_b32 s66, v255, 8
	v_readlane_b32 s67, v255, 9
	s_cbranch_execz .LBB0_208
	v_lshrrev_b32_e32 v10, 4, v42
	v_add_u32_e32 v10, 0, v10
	v_add_u32_e32 v10, 0x11000, v10
	s_waitcnt lgkmcnt(1)
	v_add_f32_e32 v8, v8, v9
	ds_write_b32 v10, v8
.LBB0_208:
	s_or_b64 exec, exec, s[28:29]
	s_waitcnt lgkmcnt(1)
	v_mov_b32_e32 v46, 1.0
	v_mov_b32_e32 v47, v177
	v_pk_mul_f32 v[10:11], v[208:209], v[208:209] op_sel:[1,1] op_sel_hi:[0,1] neg_lo:[1,0]
	v_mov_b32_e32 v13, s3
	v_pk_fma_f32 v[10:11], v[208:209], v[208:209], v[10:11] op_sel_hi:[0,1,1]
	v_pk_mul_f32 v[14:15], v[208:209], v[176:177] op_sel:[1,1] op_sel_hi:[0,1] neg_lo:[1,0]
	v_pk_mul_f32 v[18:19], v[10:11], v[10:11] op_sel:[1,1] op_sel_hi:[1,0] neg_lo:[0,1]
	v_pk_fma_f32 v[56:57], v[208:209], v[46:47], v[14:15] op_sel_hi:[1,0,1]
	v_pk_mul_f32 v[8:9], v[176:177], v[10:11] op_sel:[1,1] op_sel_hi:[1,0] neg_lo:[0,1]
	v_pk_fma_f32 v[58:59], v[46:47], v[10:11], v[8:9] op_sel_hi:[0,1,1]
	v_pk_mul_f32 v[8:9], v[56:57], v[10:11] op_sel:[1,1] op_sel_hi:[1,0] neg_lo:[0,1]
	s_waitcnt lgkmcnt(0)
	s_barrier
	ds_read_b128 v[14:17], v13
	v_pk_fma_f32 v[20:21], v[10:11], v[10:11], v[18:19] op_sel_hi:[1,0,1]
	v_readlane_b32 s2, v254, 61
	s_nop 1
	v_mov_b32_e32 v13, s2
	v_pk_fma_f32 v[60:61], v[10:11], v[56:57], v[8:9] op_sel_hi:[1,0,1]
	v_pk_mul_f32 v[8:9], v[176:177], v[20:21] op_sel:[1,1] op_sel_hi:[1,0] neg_lo:[0,1]
	ds_read_b128 v[52:55], v13
	v_pk_fma_f32 v[50:51], v[46:47], v[20:21], v[8:9] op_sel_hi:[0,1,1]
	v_pk_mul_f32 v[8:9], v[56:57], v[20:21] op_sel:[1,1] op_sel_hi:[1,0] neg_lo:[0,1]
	s_waitcnt lgkmcnt(1)
	v_add_f32_e32 v13, 0, v14
	v_pk_fma_f32 v[44:45], v[56:57], v[20:21], v[8:9] op_sel_hi:[0,1,1]
	v_pk_mul_f32 v[8:9], v[58:59], v[20:21] op_sel:[1,1] op_sel_hi:[1,0] neg_lo:[0,1]
	v_add_f32_e32 v13, v13, v15
	v_pk_mul_f32 v[42:43], v[20:21], v[20:21] op_sel:[1,1] op_sel_hi:[1,0] neg_lo:[0,1]
	v_pk_fma_f32 v[22:23], v[20:21], v[58:59], v[8:9] op_sel_hi:[1,0,1]
	v_pk_mul_f32 v[8:9], v[60:61], v[20:21] op_sel:[1,1] op_sel_hi:[1,0] neg_lo:[0,1]
	v_add_f32_e32 v13, v13, v16
	v_mov_b32_e32 v25, v206
	v_pk_fma_f32 v[18:19], v[20:21], v[60:61], v[8:9] op_sel_hi:[1,0,1]
	v_pk_fma_f32 v[8:9], v[20:21], v[20:21], v[42:43] op_sel_hi:[1,0,1]
	v_add_f32_e32 v13, v13, v17
	s_waitcnt lgkmcnt(0)
	v_add_f32_e32 v13, v13, v52
	v_lshlrev_b32_sdwa v27, v228, v25 dst_sel:DWORD dst_unused:UNUSED_PAD src0_sel:DWORD src1_sel:BYTE_0
	v_lshrrev_b32_e32 v25, 1, v206
	v_pk_mul_f32 v[10:11], v[176:177], v[8:9] op_sel:[1,1] op_sel_hi:[1,0] neg_lo:[0,1]
	v_add_f32_e32 v13, v13, v53
	v_and_b32_e32 v25, 0x78, v25
	v_pk_fma_f32 v[20:21], v[46:47], v[8:9], v[10:11] op_sel_hi:[0,1,1]
	v_pk_mul_f32 v[48:49], v[56:57], v[8:9] op_sel:[1,1] op_sel_hi:[1,0] neg_lo:[0,1]
	v_pk_mul_f32 v[10:11], v[58:59], v[8:9] op_sel:[1,1] op_sel_hi:[1,0] neg_lo:[0,1]
	v_pk_mul_f32 v[62:63], v[60:61], v[8:9] op_sel:[1,1] op_sel_hi:[1,0] neg_lo:[0,1]
	v_pk_mul_f32 v[64:65], v[50:51], v[8:9] op_sel:[1,1] op_sel_hi:[1,0] neg_lo:[0,1]
	v_pk_mul_f32 v[66:67], v[44:45], v[8:9] op_sel:[1,1] op_sel_hi:[1,0] neg_lo:[0,1]
	v_pk_mul_f32 v[68:69], v[22:23], v[8:9] op_sel:[1,1] op_sel_hi:[1,0] neg_lo:[0,1]
	v_pk_mul_f32 v[70:71], v[18:19], v[8:9] op_sel:[1,1] op_sel_hi:[1,0] neg_lo:[0,1]
	v_add_f32_e32 v13, v13, v54
	v_add3_u32 v25, v207, v27, v25
	v_pk_fma_f32 v[10:11], v[58:59], v[8:9], v[10:11] op_sel_hi:[0,1,1]
	v_add_f32_e32 v13, v13, v55
	v_pk_fma_f32 v[52:53], v[56:57], v[8:9], v[48:49] op_sel_hi:[0,1,1]
	v_pk_fma_f32 v[48:49], v[60:61], v[8:9], v[62:63] op_sel_hi:[0,1,1]
	v_pk_fma_f32 v[42:43], v[8:9], v[50:51], v[64:65] op_sel_hi:[1,0,1]
	v_pk_fma_f32 v[16:17], v[8:9], v[44:45], v[66:67] op_sel_hi:[1,0,1]
	v_pk_fma_f32 v[14:15], v[8:9], v[22:23], v[68:69] op_sel_hi:[1,0,1]
	v_pk_fma_f32 v[8:9], v[8:9], v[18:19], v[70:71] op_sel_hi:[1,0,1]
	ds_read_b64 v[54:55], v25
	ds_read_b64 v[62:63], v25 offset:2176
	ds_read_b64 v[64:65], v25 offset:4352
	ds_read_b64 v[66:67], v25 offset:6528
	ds_read_b64 v[68:69], v25 offset:8704
	ds_read_b64 v[70:71], v25 offset:10880
	ds_read_b64 v[72:73], v25 offset:13056
	ds_read_b64 v[74:75], v25 offset:15232
	ds_read_b64 v[76:77], v25 offset:17408
	ds_read_b64 v[78:79], v25 offset:19584
	ds_read_b64 v[80:81], v25 offset:21760
	ds_read_b64 v[82:83], v25 offset:23936
	ds_read_b64 v[84:85], v25 offset:26112
	ds_read_b64 v[86:87], v25 offset:28288
	ds_read_b64 v[88:89], v25 offset:30464
	ds_read_b64 v[90:91], v25 offset:32640
	s_waitcnt lgkmcnt(7)
	v_pk_add_f32 v[92:93], v[54:55], v[76:77]
	v_pk_add_f32 v[54:55], v[54:55], v[76:77] neg_lo:[0,1] neg_hi:[0,1]
	s_waitcnt lgkmcnt(3)
	v_pk_add_f32 v[76:77], v[68:69], v[84:85]
	v_pk_add_f32 v[68:69], v[68:69], v[84:85] neg_lo:[0,1] neg_hi:[0,1]
	s_lshl_b64 s[42:43], s[42:43], 16
	v_pk_add_f32 v[94:95], v[54:55], v[68:69] op_sel:[0,1] op_sel_hi:[1,0] neg_hi:[0,1]
	v_pk_add_f32 v[54:55], v[54:55], v[68:69] op_sel:[0,1] op_sel_hi:[1,0] neg_lo:[0,1]
	v_pk_add_f32 v[84:85], v[62:63], v[78:79]
	v_pk_add_f32 v[62:63], v[62:63], v[78:79] neg_lo:[0,1] neg_hi:[0,1]
	s_waitcnt lgkmcnt(2)
	v_pk_add_f32 v[78:79], v[70:71], v[86:87]
	v_pk_add_f32 v[70:71], v[70:71], v[86:87] neg_lo:[0,1] neg_hi:[0,1]
	v_pk_add_f32 v[68:69], v[92:93], v[76:77]
	v_xor_b32_e32 v87, 0x80000000, v70
	v_mov_b32_e32 v86, v71
	v_pk_add_f32 v[70:71], v[84:85], v[78:79]
	v_pk_add_f32 v[78:79], v[84:85], v[78:79] neg_lo:[0,1] neg_hi:[0,1]
	v_pk_add_f32 v[84:85], v[64:65], v[80:81]
	v_pk_add_f32 v[64:65], v[64:65], v[80:81] neg_lo:[0,1] neg_hi:[0,1]
	s_waitcnt lgkmcnt(1)
	v_pk_add_f32 v[80:81], v[72:73], v[88:89]
	v_pk_add_f32 v[72:73], v[72:73], v[88:89] neg_lo:[0,1] neg_hi:[0,1]
	v_pk_add_f32 v[76:77], v[92:93], v[76:77] neg_lo:[0,1] neg_hi:[0,1]
	v_pk_add_f32 v[92:93], v[62:63], v[86:87]
	v_pk_add_f32 v[62:63], v[62:63], v[86:87] neg_lo:[0,1] neg_hi:[0,1]
	v_xor_b32_e32 v87, 0x80000000, v72
	v_mov_b32_e32 v86, v73
	v_pk_add_f32 v[72:73], v[84:85], v[80:81]
	v_pk_add_f32 v[80:81], v[84:85], v[80:81] neg_lo:[0,1] neg_hi:[0,1]
	v_pk_add_f32 v[84:85], v[66:67], v[82:83]
	v_pk_add_f32 v[66:67], v[66:67], v[82:83] neg_lo:[0,1] neg_hi:[0,1]
	s_waitcnt lgkmcnt(0)
	v_pk_add_f32 v[82:83], v[74:75], v[90:91]
	v_pk_add_f32 v[74:75], v[74:75], v[90:91] neg_lo:[0,1] neg_hi:[0,1]
	v_pk_add_f32 v[88:89], v[64:65], v[86:87]
	v_pk_add_f32 v[64:65], v[64:65], v[86:87] neg_lo:[0,1] neg_hi:[0,1]
	v_pk_add_f32 v[90:91], v[66:67], v[74:75] op_sel:[0,1] op_sel_hi:[1,0] neg_hi:[0,1]
	v_pk_add_f32 v[66:67], v[66:67], v[74:75] op_sel:[0,1] op_sel_hi:[1,0] neg_lo:[0,1]
	v_pk_mul_f32 v[86:87], v[78:79], s[12:13] op_sel:[1,0] op_sel_hi:[0,0] neg_lo:[1,0]
	v_pk_add_f32 v[74:75], v[84:85], v[82:83]
	v_pk_fma_f32 v[78:79], v[78:79], s[12:13], v[86:87] op_sel_hi:[1,0,1] neg_lo:[0,0,1] neg_hi:[0,0,1]
	v_pk_mul_f32 v[86:87], v[62:63], s[36:37] op_sel:[1,0] op_sel_hi:[0,0] neg_lo:[1,0]
	v_pk_add_f32 v[82:83], v[84:85], v[82:83] neg_lo:[0,1] neg_hi:[0,1]
	v_pk_fma_f32 v[62:63], v[62:63], s[22:23], v[86:87] op_sel_hi:[1,0,1] neg_lo:[0,0,1] neg_hi:[0,0,1]
	v_pk_mul_f32 v[86:87], v[88:89], s[12:13] op_sel:[1,0] op_sel_hi:[0,0] neg_lo:[1,0]
	v_pk_fma_f32 v[86:87], v[88:89], s[12:13], v[86:87] op_sel_hi:[1,0,1] neg_lo:[0,0,1] neg_hi:[0,0,1]
	v_pk_fma_f32 v[80:81], v[80:81], 0, v[80:81] op_sel:[0,0,1] op_sel_hi:[1,0,0] neg_hi:[0,0,1]
	v_pk_mul_f32 v[88:89], v[64:65], s[12:13] op_sel:[1,0] op_sel_hi:[0,0] neg_lo:[1,0]
	v_pk_fma_f32 v[64:65], v[64:65], s[18:19], v[88:89] op_sel_hi:[1,0,1] neg_lo:[0,0,1] neg_hi:[0,0,1]
	v_pk_mul_f32 v[88:89], v[90:91], s[36:37] op_sel:[1,0] op_sel_hi:[0,0] neg_lo:[1,0]
	v_pk_mul_f32 v[84:85], v[92:93], s[22:23] op_sel:[1,0] op_sel_hi:[0,0] neg_lo:[1,0]
	v_pk_fma_f32 v[88:89], v[90:91], s[22:23], v[88:89] op_sel_hi:[1,0,1] neg_lo:[0,0,1] neg_hi:[0,0,1]
	v_pk_mul_f32 v[90:91], v[82:83], s[12:13] op_sel:[1,0] op_sel_hi:[0,0] neg_lo:[1,0]
	v_pk_fma_f32 v[84:85], v[92:93], s[36:37], v[84:85] op_sel_hi:[1,0,1] neg_lo:[0,0,1] neg_hi:[0,0,1]
	v_pk_fma_f32 v[82:83], v[82:83], s[18:19], v[90:91] op_sel_hi:[1,0,1] neg_lo:[0,0,1] neg_hi:[0,0,1]
	v_xor_b32_e32 v90, 0x80000000, v67
	v_mov_b32_e32 v91, v66
	v_pk_mul_f32 v[66:67], v[66:67], s[36:37] op_sel_hi:[1,0]
	v_pk_fma_f32 v[66:67], v[90:91], s[22:23], v[66:67] op_sel_hi:[1,0,1] neg_lo:[0,0,1] neg_hi:[0,0,1]
	v_pk_add_f32 v[90:91], v[68:69], v[72:73]
	v_pk_add_f32 v[68:69], v[68:69], v[72:73] neg_lo:[0,1] neg_hi:[0,1]
	v_pk_add_f32 v[72:73], v[70:71], v[74:75]
	v_pk_add_f32 v[70:71], v[70:71], v[74:75] neg_lo:[0,1] neg_hi:[0,1]
	v_xor_b32_e32 v75, 0x80000000, v70
	v_mov_b32_e32 v74, v71
	v_pk_add_f32 v[70:71], v[90:91], v[72:73]
	v_pk_add_f32 v[72:73], v[90:91], v[72:73] neg_lo:[0,1] neg_hi:[0,1]
	v_pk_add_f32 v[90:91], v[84:85], v[88:89]
	v_pk_add_f32 v[84:85], v[84:85], v[88:89] neg_lo:[0,1] neg_hi:[0,1]
	v_pk_add_f32 v[92:93], v[68:69], v[74:75]
	v_pk_add_f32 v[68:69], v[68:69], v[74:75] neg_lo:[0,1] neg_hi:[0,1]
	v_pk_add_f32 v[74:75], v[94:95], v[86:87]
	v_pk_add_f32 v[86:87], v[94:95], v[86:87] neg_lo:[0,1] neg_hi:[0,1]
	v_pk_add_f32 v[94:95], v[86:87], v[84:85] op_sel:[0,1] op_sel_hi:[1,0] neg_hi:[0,1]
	v_pk_add_f32 v[86:87], v[86:87], v[84:85] op_sel:[0,1] op_sel_hi:[1,0] neg_lo:[0,1]
	v_pk_add_f32 v[88:89], v[76:77], v[80:81]
	v_pk_add_f32 v[76:77], v[76:77], v[80:81] neg_lo:[0,1] neg_hi:[0,1]
	v_pk_add_f32 v[80:81], v[78:79], v[82:83]
	v_pk_add_f32 v[78:79], v[78:79], v[82:83] neg_lo:[0,1] neg_hi:[0,1]
	v_pk_add_f32 v[84:85], v[74:75], v[90:91]
	v_pk_add_f32 v[74:75], v[74:75], v[90:91] neg_lo:[0,1] neg_hi:[0,1]
	v_pk_add_f32 v[90:91], v[76:77], v[78:79] op_sel:[0,1] op_sel_hi:[1,0] neg_hi:[0,1]
	v_pk_add_f32 v[76:77], v[76:77], v[78:79] op_sel:[0,1] op_sel_hi:[1,0] neg_lo:[0,1]
	v_pk_add_f32 v[82:83], v[54:55], v[64:65]
	v_pk_add_f32 v[54:55], v[54:55], v[64:65] neg_lo:[0,1] neg_hi:[0,1]
	v_pk_add_f32 v[64:65], v[62:63], v[66:67]
	v_pk_add_f32 v[62:63], v[62:63], v[66:67] neg_lo:[0,1] neg_hi:[0,1]
	v_pk_add_f32 v[78:79], v[88:89], v[80:81]
	v_pk_add_f32 v[80:81], v[88:89], v[80:81] neg_lo:[0,1] neg_hi:[0,1]
	v_pk_add_f32 v[88:89], v[54:55], v[62:63] op_sel:[0,1] op_sel_hi:[1,0] neg_hi:[0,1]
	v_pk_add_f32 v[54:55], v[54:55], v[62:63] op_sel:[0,1] op_sel_hi:[1,0] neg_lo:[0,1]
	v_xor_b32_e32 v66, 0x80000000, v47
	v_mov_b32_e32 v67, v46
	v_pk_mul_f32 v[66:67], v[66:67], v[70:71] op_sel:[0,1]
	v_pk_add_f32 v[62:63], v[82:83], v[64:65]
	v_pk_fma_f32 v[46:47], v[46:47], v[70:71], v[66:67] op_sel_hi:[1,0,1]
	ds_write_b64 v25, v[46:47]
	v_pk_mul_f32 v[46:47], v[56:57], v[84:85] op_sel:[1,1] op_sel_hi:[0,1] neg_lo:[1,0]
	v_pk_add_f32 v[64:65], v[82:83], v[64:65] neg_lo:[0,1] neg_hi:[0,1]
	v_pk_fma_f32 v[46:47], v[56:57], v[84:85], v[46:47] op_sel_hi:[1,0,1]
	ds_write_b64 v25, v[46:47] offset:2176
	v_pk_mul_f32 v[46:47], v[58:59], v[78:79] op_sel:[1,1] op_sel_hi:[0,1] neg_lo:[1,0]
	v_pk_fma_f32 v[46:47], v[58:59], v[78:79], v[46:47] op_sel_hi:[1,0,1]
	ds_write_b64 v25, v[46:47] offset:4352
	v_pk_mul_f32 v[46:47], v[60:61], v[62:63] op_sel:[1,1] op_sel_hi:[0,1] neg_lo:[1,0]
	v_pk_fma_f32 v[46:47], v[60:61], v[62:63], v[46:47] op_sel_hi:[1,0,1]
	ds_write_b64 v25, v[46:47] offset:6528
	v_pk_mul_f32 v[46:47], v[50:51], v[92:93] op_sel:[1,1] op_sel_hi:[0,1] neg_lo:[1,0]
	v_pk_fma_f32 v[46:47], v[50:51], v[92:93], v[46:47] op_sel_hi:[1,0,1]
	ds_write_b64 v25, v[46:47] offset:8704
	v_pk_mul_f32 v[46:47], v[44:45], v[94:95] op_sel:[1,1] op_sel_hi:[0,1] neg_lo:[1,0]
	v_pk_fma_f32 v[44:45], v[44:45], v[94:95], v[46:47] op_sel_hi:[1,0,1]
	ds_write_b64 v25, v[44:45] offset:10880
	v_pk_mul_f32 v[44:45], v[22:23], v[90:91] op_sel:[1,1] op_sel_hi:[0,1] neg_lo:[1,0]
	v_pk_fma_f32 v[22:23], v[22:23], v[90:91], v[44:45] op_sel_hi:[1,0,1]
	ds_write_b64 v25, v[22:23] offset:13056
	v_pk_mul_f32 v[22:23], v[18:19], v[88:89] op_sel:[1,1] op_sel_hi:[0,1] neg_lo:[1,0]
	v_pk_fma_f32 v[18:19], v[18:19], v[88:89], v[22:23] op_sel_hi:[1,0,1]
	ds_write_b64 v25, v[18:19] offset:15232
	v_pk_mul_f32 v[18:19], v[20:21], v[72:73] op_sel:[1,1] op_sel_hi:[0,1] neg_lo:[1,0]
	v_pk_fma_f32 v[18:19], v[20:21], v[72:73], v[18:19] op_sel_hi:[1,0,1]
	ds_write_b64 v25, v[18:19] offset:17408
	v_pk_mul_f32 v[18:19], v[52:53], v[74:75] op_sel:[1,1] op_sel_hi:[0,1] neg_lo:[1,0]
	v_pk_fma_f32 v[18:19], v[52:53], v[74:75], v[18:19] op_sel_hi:[1,0,1]
	ds_write_b64 v25, v[18:19] offset:19584
	v_pk_mul_f32 v[18:19], v[10:11], v[80:81] op_sel:[1,1] op_sel_hi:[0,1] neg_lo:[1,0]
	v_pk_fma_f32 v[10:11], v[10:11], v[80:81], v[18:19] op_sel_hi:[1,0,1]
	ds_write_b64 v25, v[10:11] offset:21760
	v_pk_mul_f32 v[10:11], v[48:49], v[64:65] op_sel:[1,1] op_sel_hi:[0,1] neg_lo:[1,0]
	v_pk_fma_f32 v[10:11], v[48:49], v[64:65], v[10:11] op_sel_hi:[1,0,1]
	ds_write_b64 v25, v[10:11] offset:23936
	v_pk_mul_f32 v[10:11], v[42:43], v[68:69] op_sel:[1,1] op_sel_hi:[0,1] neg_lo:[1,0]
	v_pk_fma_f32 v[10:11], v[42:43], v[68:69], v[10:11] op_sel_hi:[1,0,1]
	ds_write_b64 v25, v[10:11] offset:26112
	v_pk_mul_f32 v[10:11], v[16:17], v[86:87] op_sel:[1,1] op_sel_hi:[0,1] neg_lo:[1,0]
	v_pk_fma_f32 v[10:11], v[16:17], v[86:87], v[10:11] op_sel_hi:[1,0,1]
	ds_write_b64 v25, v[10:11] offset:28288
	v_pk_mul_f32 v[10:11], v[14:15], v[76:77] op_sel:[1,1] op_sel_hi:[0,1] neg_lo:[1,0]
	v_pk_fma_f32 v[10:11], v[14:15], v[76:77], v[10:11] op_sel_hi:[1,0,1]
	ds_write_b64 v25, v[10:11] offset:30464
	v_pk_mul_f32 v[10:11], v[8:9], v[54:55] op_sel:[1,1] op_sel_hi:[0,1] neg_lo:[1,0]
	v_pk_fma_f32 v[8:9], v[8:9], v[54:55], v[10:11] op_sel_hi:[1,0,1]
	ds_write_b64 v25, v[8:9] offset:32640
	v_mov_b32_e32 v70, 1.0
	v_pk_mul_f32 v[10:11], v[210:211], v[210:211] op_sel:[1,1] op_sel_hi:[0,1] neg_lo:[1,0]
	v_mov_b32_e32 v71, v177
	v_pk_fma_f32 v[10:11], v[210:211], v[210:211], v[10:11] op_sel_hi:[0,1,1]
	v_pk_mul_f32 v[18:19], v[10:11], v[10:11] op_sel:[1,1] op_sel_hi:[1,0] neg_lo:[0,1]
	v_pk_mul_f32 v[14:15], v[210:211], v[176:177] op_sel:[1,1] op_sel_hi:[0,1] neg_lo:[1,0]
	v_pk_fma_f32 v[18:19], v[10:11], v[10:11], v[18:19] op_sel_hi:[1,0,1]
	v_pk_fma_f32 v[72:73], v[210:211], v[70:71], v[14:15] op_sel_hi:[1,0,1]
	v_pk_mul_f32 v[8:9], v[176:177], v[10:11] op_sel:[1,1] op_sel_hi:[1,0] neg_lo:[0,1]
	v_pk_fma_f32 v[74:75], v[70:71], v[10:11], v[8:9] op_sel_hi:[0,1,1]
	v_pk_mul_f32 v[8:9], v[72:73], v[10:11] op_sel:[1,1] op_sel_hi:[1,0] neg_lo:[0,1]
	v_pk_mul_f32 v[22:23], v[18:19], v[18:19] op_sel:[1,1] op_sel_hi:[1,0] neg_lo:[0,1]
	v_pk_fma_f32 v[76:77], v[10:11], v[72:73], v[8:9] op_sel_hi:[1,0,1]
	v_pk_mul_f32 v[8:9], v[176:177], v[18:19] op_sel:[1,1] op_sel_hi:[1,0] neg_lo:[0,1]
	v_pk_fma_f32 v[78:79], v[70:71], v[18:19], v[8:9] op_sel_hi:[0,1,1]
	v_pk_mul_f32 v[8:9], v[72:73], v[18:19] op_sel:[1,1] op_sel_hi:[1,0] neg_lo:[0,1]
	s_waitcnt lgkmcnt(0)
	v_pk_fma_f32 v[80:81], v[72:73], v[18:19], v[8:9] op_sel_hi:[0,1,1]
	v_pk_mul_f32 v[8:9], v[74:75], v[18:19] op_sel:[1,1] op_sel_hi:[1,0] neg_lo:[0,1]
	s_barrier
	v_pk_fma_f32 v[82:83], v[18:19], v[74:75], v[8:9] op_sel_hi:[1,0,1]
	v_pk_mul_f32 v[8:9], v[76:77], v[18:19] op_sel:[1,1] op_sel_hi:[1,0] neg_lo:[0,1]
	v_pk_fma_f32 v[84:85], v[18:19], v[76:77], v[8:9] op_sel_hi:[1,0,1]
	v_pk_fma_f32 v[8:9], v[18:19], v[18:19], v[22:23] op_sel_hi:[1,0,1]
	v_add_f32_e32 v13, 0x3727c5ac, v13
	v_pk_mul_f32 v[10:11], v[176:177], v[8:9] op_sel:[1,1] op_sel_hi:[1,0] neg_lo:[0,1]
	v_pk_fma_f32 v[86:87], v[70:71], v[8:9], v[10:11] op_sel_hi:[0,1,1]
	v_pk_mul_f32 v[10:11], v[72:73], v[8:9] op_sel:[1,1] op_sel_hi:[1,0] neg_lo:[0,1]
	v_cmp_gt_f32_e32 vcc, s23, v13
	v_pk_fma_f32 v[88:89], v[72:73], v[8:9], v[10:11] op_sel_hi:[0,1,1]
	v_pk_mul_f32 v[10:11], v[74:75], v[8:9] op_sel:[1,1] op_sel_hi:[1,0] neg_lo:[0,1]
	s_lshl_b64 s[0:1], s[0:1], 16
	v_pk_fma_f32 v[90:91], v[74:75], v[8:9], v[10:11] op_sel_hi:[0,1,1]
	v_pk_mul_f32 v[10:11], v[76:77], v[8:9] op_sel:[1,1] op_sel_hi:[1,0] neg_lo:[0,1]
	s_mov_b32 s2, 0x39000000
	v_pk_fma_f32 v[18:19], v[76:77], v[8:9], v[10:11] op_sel_hi:[0,1,1]
	v_pk_mul_f32 v[10:11], v[78:79], v[8:9] op_sel:[1,1] op_sel_hi:[1,0] neg_lo:[0,1]
	s_add_u32 s28, s64, s0
	v_pk_fma_f32 v[16:17], v[8:9], v[78:79], v[10:11] op_sel_hi:[1,0,1]
	v_pk_mul_f32 v[10:11], v[80:81], v[8:9] op_sel:[1,1] op_sel_hi:[1,0] neg_lo:[0,1]
	s_addc_u32 s29, s65, s1
	v_pk_fma_f32 v[14:15], v[8:9], v[80:81], v[10:11] op_sel_hi:[1,0,1]
	v_pk_mul_f32 v[10:11], v[82:83], v[8:9] op_sel:[1,1] op_sel_hi:[1,0] neg_lo:[0,1]
	v_pk_mul_f32 v[20:21], v[84:85], v[8:9] op_sel:[1,1] op_sel_hi:[1,0] neg_lo:[0,1]
	v_pk_fma_f32 v[10:11], v[8:9], v[82:83], v[10:11] op_sel_hi:[1,0,1]
	v_pk_fma_f32 v[8:9], v[8:9], v[84:85], v[20:21] op_sel_hi:[1,0,1]
	s_add_u32 s39, s64, s42
	v_bfe_u32 v21, v206, 4, 4
	v_and_b32_e32 v20, 15, v206
	v_mul_u32_u24_e32 v21, 0x880, v21
	v_lshlrev_b32_e32 v20, 3, v20
	v_add3_u32 v25, v207, v21, v20
	ds_read2_b64 v[20:23], v25 offset1:17
	ds_read2_b64 v[42:45], v25 offset0:34 offset1:51
	ds_read2_b64 v[46:49], v25 offset0:68 offset1:85
	ds_read2_b64 v[50:53], v25 offset0:136 offset1:153
	ds_read2_b64 v[54:57], v25 offset0:102 offset1:119
	ds_read2_b64 v[58:61], v25 offset0:204 offset1:221
	ds_read2_b64 v[62:65], v25 offset0:170 offset1:187
	ds_read2_b64 v[66:69], v25 offset0:238 offset1:255
	s_waitcnt lgkmcnt(4)
	v_pk_add_f32 v[92:93], v[20:21], v[50:51]
	v_pk_add_f32 v[20:21], v[20:21], v[50:51] neg_lo:[0,1] neg_hi:[0,1]
	s_waitcnt lgkmcnt(2)
	v_pk_add_f32 v[50:51], v[46:47], v[58:59]
	v_pk_add_f32 v[46:47], v[46:47], v[58:59] neg_lo:[0,1] neg_hi:[0,1]
	v_mov_b32_e32 v40, v32
	v_pk_add_f32 v[94:95], v[20:21], v[46:47] op_sel:[0,1] op_sel_hi:[1,0] neg_hi:[0,1]
	v_pk_add_f32 v[20:21], v[20:21], v[46:47] op_sel:[0,1] op_sel_hi:[1,0] neg_lo:[0,1]
	v_pk_add_f32 v[58:59], v[22:23], v[52:53]
	v_pk_add_f32 v[22:23], v[22:23], v[52:53] neg_lo:[0,1] neg_hi:[0,1]
	v_pk_add_f32 v[52:53], v[48:49], v[60:61]
	v_pk_add_f32 v[48:49], v[48:49], v[60:61] neg_lo:[0,1] neg_hi:[0,1]
	v_pk_add_f32 v[46:47], v[92:93], v[50:51]
	v_pk_add_f32 v[50:51], v[92:93], v[50:51] neg_lo:[0,1] neg_hi:[0,1]
	v_pk_add_f32 v[92:93], v[22:23], v[48:49] op_sel:[0,1] op_sel_hi:[1,0] neg_hi:[0,1]
	v_pk_add_f32 v[22:23], v[22:23], v[48:49] op_sel:[0,1] op_sel_hi:[1,0] neg_lo:[0,1]
	s_waitcnt lgkmcnt(0)
	v_pk_add_f32 v[60:61], v[54:55], v[66:67]
	v_pk_add_f32 v[54:55], v[54:55], v[66:67] neg_lo:[0,1] neg_hi:[0,1]
	v_pk_add_f32 v[48:49], v[58:59], v[52:53]
	v_pk_add_f32 v[52:53], v[58:59], v[52:53] neg_lo:[0,1] neg_hi:[0,1]
	v_pk_add_f32 v[58:59], v[42:43], v[62:63]
	v_pk_add_f32 v[42:43], v[42:43], v[62:63] neg_lo:[0,1] neg_hi:[0,1]
	v_pk_add_f32 v[66:67], v[42:43], v[54:55] op_sel:[0,1] op_sel_hi:[1,0] neg_hi:[0,1]
	v_pk_add_f32 v[42:43], v[42:43], v[54:55] op_sel:[0,1] op_sel_hi:[1,0] neg_lo:[0,1]
	v_pk_add_f32 v[62:63], v[56:57], v[68:69]
	v_pk_add_f32 v[56:57], v[56:57], v[68:69] neg_lo:[0,1] neg_hi:[0,1]
	v_pk_add_f32 v[54:55], v[58:59], v[60:61]
	v_pk_add_f32 v[58:59], v[58:59], v[60:61] neg_lo:[0,1] neg_hi:[0,1]
	v_pk_add_f32 v[60:61], v[44:45], v[64:65]
	v_pk_add_f32 v[44:45], v[44:45], v[64:65] neg_lo:[0,1] neg_hi:[0,1]
	v_pk_add_f32 v[68:69], v[44:45], v[56:57] op_sel:[0,1] op_sel_hi:[1,0] neg_hi:[0,1]
	v_pk_add_f32 v[44:45], v[44:45], v[56:57] op_sel:[0,1] op_sel_hi:[1,0] neg_lo:[0,1]
	v_pk_mul_f32 v[64:65], v[52:53], s[12:13] op_sel:[1,0] op_sel_hi:[0,0] neg_lo:[1,0]
	v_pk_add_f32 v[56:57], v[60:61], v[62:63]
	v_pk_fma_f32 v[52:53], v[52:53], s[12:13], v[64:65] op_sel_hi:[1,0,1] neg_lo:[0,0,1] neg_hi:[0,0,1]
	v_pk_mul_f32 v[64:65], v[22:23], s[36:37] op_sel:[1,0] op_sel_hi:[0,0] neg_lo:[1,0]
	v_pk_add_f32 v[60:61], v[60:61], v[62:63] neg_lo:[0,1] neg_hi:[0,1]
	v_pk_fma_f32 v[22:23], v[22:23], s[22:23], v[64:65] op_sel_hi:[1,0,1] neg_lo:[0,0,1] neg_hi:[0,0,1]
	v_pk_mul_f32 v[64:65], v[66:67], s[12:13] op_sel:[1,0] op_sel_hi:[0,0] neg_lo:[1,0]
	v_pk_fma_f32 v[64:65], v[66:67], s[12:13], v[64:65] op_sel_hi:[1,0,1] neg_lo:[0,0,1] neg_hi:[0,0,1]
	v_pk_fma_f32 v[58:59], v[58:59], 0, v[58:59] op_sel:[0,0,1] op_sel_hi:[1,0,0] neg_hi:[0,0,1]
	v_pk_mul_f32 v[66:67], v[42:43], s[12:13] op_sel:[1,0] op_sel_hi:[0,0] neg_lo:[1,0]
	v_pk_fma_f32 v[42:43], v[42:43], s[18:19], v[66:67] op_sel_hi:[1,0,1] neg_lo:[0,0,1] neg_hi:[0,0,1]
	v_pk_mul_f32 v[66:67], v[68:69], s[36:37] op_sel:[1,0] op_sel_hi:[0,0] neg_lo:[1,0]
	v_pk_mul_f32 v[62:63], v[92:93], s[22:23] op_sel:[1,0] op_sel_hi:[0,0] neg_lo:[1,0]
	v_pk_fma_f32 v[66:67], v[68:69], s[22:23], v[66:67] op_sel_hi:[1,0,1] neg_lo:[0,0,1] neg_hi:[0,0,1]
	v_pk_mul_f32 v[68:69], v[60:61], s[12:13] op_sel:[1,0] op_sel_hi:[0,0] neg_lo:[1,0]
	v_pk_fma_f32 v[62:63], v[92:93], s[36:37], v[62:63] op_sel_hi:[1,0,1] neg_lo:[0,0,1] neg_hi:[0,0,1]
	v_pk_fma_f32 v[60:61], v[60:61], s[18:19], v[68:69] op_sel_hi:[1,0,1] neg_lo:[0,0,1] neg_hi:[0,0,1]
	v_xor_b32_e32 v68, 0x80000000, v45
	v_mov_b32_e32 v69, v44
	v_pk_mul_f32 v[44:45], v[44:45], s[36:37] op_sel_hi:[1,0]
	v_mov_b32_e32 v98, v41
	v_pk_fma_f32 v[44:45], v[68:69], s[22:23], v[44:45] op_sel_hi:[1,0,1] neg_lo:[0,0,1] neg_hi:[0,0,1]
	v_pk_add_f32 v[68:69], v[46:47], v[54:55]
	v_pk_add_f32 v[46:47], v[46:47], v[54:55] neg_lo:[0,1] neg_hi:[0,1]
	v_pk_add_f32 v[54:55], v[48:49], v[56:57]
	v_pk_add_f32 v[48:49], v[48:49], v[56:57] neg_lo:[0,1] neg_hi:[0,1]
	v_mov_b32_e32 v99, v32
	v_xor_b32_e32 v57, 0x80000000, v48
	v_mov_b32_e32 v56, v49
	v_pk_add_f32 v[48:49], v[68:69], v[54:55]
	v_pk_add_f32 v[54:55], v[68:69], v[54:55] neg_lo:[0,1] neg_hi:[0,1]
	v_pk_add_f32 v[68:69], v[62:63], v[66:67]
	v_pk_add_f32 v[62:63], v[62:63], v[66:67] neg_lo:[0,1] neg_hi:[0,1]
	v_pk_add_f32 v[92:93], v[46:47], v[56:57]
	v_pk_add_f32 v[46:47], v[46:47], v[56:57] neg_lo:[0,1] neg_hi:[0,1]
	v_pk_add_f32 v[56:57], v[94:95], v[64:65]
	v_pk_add_f32 v[64:65], v[94:95], v[64:65] neg_lo:[0,1] neg_hi:[0,1]
	v_pk_add_f32 v[94:95], v[64:65], v[62:63] op_sel:[0,1] op_sel_hi:[1,0] neg_hi:[0,1]
	v_pk_add_f32 v[64:65], v[64:65], v[62:63] op_sel:[0,1] op_sel_hi:[1,0] neg_lo:[0,1]
	v_pk_add_f32 v[66:67], v[50:51], v[58:59]
	v_pk_add_f32 v[50:51], v[50:51], v[58:59] neg_lo:[0,1] neg_hi:[0,1]
	v_pk_add_f32 v[58:59], v[52:53], v[60:61]
	v_pk_add_f32 v[52:53], v[52:53], v[60:61] neg_lo:[0,1] neg_hi:[0,1]
	v_pk_add_f32 v[62:63], v[56:57], v[68:69]
	v_pk_add_f32 v[56:57], v[56:57], v[68:69] neg_lo:[0,1] neg_hi:[0,1]
	v_pk_add_f32 v[68:69], v[50:51], v[52:53] op_sel:[0,1] op_sel_hi:[1,0] neg_hi:[0,1]
	v_pk_add_f32 v[50:51], v[50:51], v[52:53] op_sel:[0,1] op_sel_hi:[1,0] neg_lo:[0,1]
	v_pk_add_f32 v[60:61], v[20:21], v[42:43]
	v_pk_add_f32 v[20:21], v[20:21], v[42:43] neg_lo:[0,1] neg_hi:[0,1]
	v_pk_add_f32 v[42:43], v[22:23], v[44:45]
	v_pk_add_f32 v[22:23], v[22:23], v[44:45] neg_lo:[0,1] neg_hi:[0,1]
	v_pk_add_f32 v[52:53], v[66:67], v[58:59]
	v_pk_add_f32 v[58:59], v[66:67], v[58:59] neg_lo:[0,1] neg_hi:[0,1]
	v_pk_add_f32 v[66:67], v[20:21], v[22:23] op_sel:[0,1] op_sel_hi:[1,0] neg_hi:[0,1]
	v_pk_add_f32 v[20:21], v[20:21], v[22:23] op_sel:[0,1] op_sel_hi:[1,0] neg_lo:[0,1]
	v_xor_b32_e32 v44, 0x80000000, v71
	v_mov_b32_e32 v45, v70
	v_pk_mul_f32 v[44:45], v[44:45], v[48:49] op_sel:[0,1]
	v_pk_add_f32 v[22:23], v[60:61], v[42:43]
	v_pk_fma_f32 v[44:45], v[70:71], v[48:49], v[44:45] op_sel_hi:[1,0,1]
	v_pk_mul_f32 v[48:49], v[72:73], v[62:63] op_sel:[1,1] op_sel_hi:[0,1] neg_lo:[1,0]
	v_pk_add_f32 v[42:43], v[60:61], v[42:43] neg_lo:[0,1] neg_hi:[0,1]
	v_pk_fma_f32 v[48:49], v[72:73], v[62:63], v[48:49] op_sel_hi:[1,0,1]
	ds_write2_b64 v25, v[44:45], v[48:49] offset1:17
	v_pk_mul_f32 v[44:45], v[74:75], v[52:53] op_sel:[1,1] op_sel_hi:[0,1] neg_lo:[1,0]
	v_pk_mul_f32 v[48:49], v[76:77], v[22:23] op_sel:[1,1] op_sel_hi:[0,1] neg_lo:[1,0]
	v_pk_fma_f32 v[44:45], v[74:75], v[52:53], v[44:45] op_sel_hi:[1,0,1]
	v_pk_fma_f32 v[22:23], v[76:77], v[22:23], v[48:49] op_sel_hi:[1,0,1]
	ds_write2_b64 v25, v[44:45], v[22:23] offset0:34 offset1:51
	v_pk_mul_f32 v[22:23], v[78:79], v[92:93] op_sel:[1,1] op_sel_hi:[0,1] neg_lo:[1,0]
	v_pk_mul_f32 v[44:45], v[80:81], v[94:95] op_sel:[1,1] op_sel_hi:[0,1] neg_lo:[1,0]
	v_pk_fma_f32 v[22:23], v[78:79], v[92:93], v[22:23] op_sel_hi:[1,0,1]
	v_pk_fma_f32 v[44:45], v[80:81], v[94:95], v[44:45] op_sel_hi:[1,0,1]
	ds_write2_b64 v25, v[22:23], v[44:45] offset0:68 offset1:85
	v_pk_mul_f32 v[22:23], v[82:83], v[68:69] op_sel:[1,1] op_sel_hi:[0,1] neg_lo:[1,0]
	v_pk_mul_f32 v[44:45], v[84:85], v[66:67] op_sel:[1,1] op_sel_hi:[0,1] neg_lo:[1,0]
	v_pk_fma_f32 v[22:23], v[82:83], v[68:69], v[22:23] op_sel_hi:[1,0,1]
	v_pk_fma_f32 v[44:45], v[84:85], v[66:67], v[44:45] op_sel_hi:[1,0,1]
	ds_write2_b64 v25, v[22:23], v[44:45] offset0:102 offset1:119
	v_pk_mul_f32 v[22:23], v[86:87], v[54:55] op_sel:[1,1] op_sel_hi:[0,1] neg_lo:[1,0]
	v_pk_mul_f32 v[44:45], v[88:89], v[56:57] op_sel:[1,1] op_sel_hi:[0,1] neg_lo:[1,0]
	v_pk_fma_f32 v[22:23], v[86:87], v[54:55], v[22:23] op_sel_hi:[1,0,1]
	v_pk_fma_f32 v[44:45], v[88:89], v[56:57], v[44:45] op_sel_hi:[1,0,1]
	ds_write2_b64 v25, v[22:23], v[44:45] offset0:136 offset1:153
	v_pk_mul_f32 v[22:23], v[90:91], v[58:59] op_sel:[1,1] op_sel_hi:[0,1] neg_lo:[1,0]
	v_pk_mul_f32 v[44:45], v[18:19], v[42:43] op_sel:[1,1] op_sel_hi:[0,1] neg_lo:[1,0]
	v_pk_fma_f32 v[22:23], v[90:91], v[58:59], v[22:23] op_sel_hi:[1,0,1]
	v_pk_fma_f32 v[18:19], v[18:19], v[42:43], v[44:45] op_sel_hi:[1,0,1]
	ds_write2_b64 v25, v[22:23], v[18:19] offset0:170 offset1:187
	v_pk_mul_f32 v[18:19], v[16:17], v[46:47] op_sel:[1,1] op_sel_hi:[0,1] neg_lo:[1,0]
	v_mov_b32_e32 v29, v28
	v_pk_fma_f32 v[16:17], v[16:17], v[46:47], v[18:19] op_sel_hi:[1,0,1]
	v_pk_mul_f32 v[18:19], v[14:15], v[64:65] op_sel:[1,1] op_sel_hi:[0,1] neg_lo:[1,0]
	v_mov_b32_e32 v27, v26
	v_pk_fma_f32 v[14:15], v[14:15], v[64:65], v[18:19] op_sel_hi:[1,0,1]
	ds_write2_b64 v25, v[16:17], v[14:15] offset0:204 offset1:221
	v_pk_mul_f32 v[14:15], v[10:11], v[50:51] op_sel:[1,1] op_sel_hi:[0,1] neg_lo:[1,0]
	v_mov_b32_e32 v39, v38
	v_pk_fma_f32 v[10:11], v[10:11], v[50:51], v[14:15] op_sel_hi:[1,0,1]
	v_pk_mul_f32 v[14:15], v[8:9], v[20:21] op_sel:[1,1] op_sel_hi:[0,1] neg_lo:[1,0]
	v_mov_b32_e32 v37, v36
	v_pk_fma_f32 v[8:9], v[8:9], v[20:21], v[14:15] op_sel_hi:[1,0,1]
	ds_write2_b64 v25, v[10:11], v[8:9] offset0:238 offset1:255
	s_waitcnt lgkmcnt(0)
	s_barrier
	v_mov_b32_e32 v25, v24
	v_and_b32_e32 v8, 0xff, v206
	v_mad_u32_u24 v22, v8, s19, v207
	ds_read2_b64 v[8:11], v22 offset1:1
	ds_read2_b64 v[14:17], v22 offset0:2 offset1:3
	ds_read2_b64 v[18:21], v22 offset0:8 offset1:9
	ds_read2_b64 v[42:45], v22 offset0:4 offset1:5
	ds_read2_b64 v[46:49], v22 offset0:6 offset1:7
	ds_read2_b64 v[50:53], v22 offset0:12 offset1:13
	ds_read2_b64 v[54:57], v22 offset0:10 offset1:11
	ds_read2_b64 v[58:61], v22 offset0:14 offset1:15
	s_waitcnt lgkmcnt(5)
	v_pk_add_f32 v[22:23], v[8:9], v[18:19]
	v_pk_add_f32 v[8:9], v[8:9], v[18:19] neg_lo:[0,1] neg_hi:[0,1]
	s_waitcnt lgkmcnt(2)
	v_pk_add_f32 v[18:19], v[42:43], v[50:51]
	v_pk_add_f32 v[42:43], v[42:43], v[50:51] neg_lo:[0,1] neg_hi:[0,1]
	v_mov_b32_e32 v35, v34
	v_xor_b32_e32 v51, 0x80000000, v42
	v_mov_b32_e32 v50, v43
	v_pk_add_f32 v[42:43], v[22:23], v[18:19]
	v_pk_add_f32 v[18:19], v[22:23], v[18:19] neg_lo:[0,1] neg_hi:[0,1]
	v_pk_add_f32 v[22:23], v[10:11], v[20:21]
	v_pk_add_f32 v[10:11], v[10:11], v[20:21] neg_lo:[0,1] neg_hi:[0,1]
	v_pk_add_f32 v[20:21], v[44:45], v[52:53]
	v_pk_add_f32 v[44:45], v[44:45], v[52:53] neg_lo:[0,1] neg_hi:[0,1]
	v_pk_add_f32 v[62:63], v[8:9], v[50:51]
	v_pk_add_f32 v[8:9], v[8:9], v[50:51] neg_lo:[0,1] neg_hi:[0,1]
	v_pk_add_f32 v[52:53], v[10:11], v[44:45] op_sel:[0,1] op_sel_hi:[1,0] neg_hi:[0,1]
	v_pk_add_f32 v[10:11], v[10:11], v[44:45] op_sel:[0,1] op_sel_hi:[1,0] neg_lo:[0,1]
	s_waitcnt lgkmcnt(0)
	v_pk_add_f32 v[50:51], v[46:47], v[58:59]
	v_pk_add_f32 v[46:47], v[46:47], v[58:59] neg_lo:[0,1] neg_hi:[0,1]
	v_pk_add_f32 v[44:45], v[22:23], v[20:21]
	v_pk_add_f32 v[20:21], v[22:23], v[20:21] neg_lo:[0,1] neg_hi:[0,1]
	v_pk_add_f32 v[22:23], v[14:15], v[54:55]
	v_pk_add_f32 v[14:15], v[14:15], v[54:55] neg_lo:[0,1] neg_hi:[0,1]
	v_xor_b32_e32 v55, 0x80000000, v46
	v_mov_b32_e32 v54, v47
	v_pk_add_f32 v[46:47], v[22:23], v[50:51]
	v_pk_add_f32 v[58:59], v[14:15], v[54:55]
	v_pk_add_f32 v[22:23], v[22:23], v[50:51] neg_lo:[0,1] neg_hi:[0,1]
	v_pk_add_f32 v[14:15], v[14:15], v[54:55] neg_lo:[0,1] neg_hi:[0,1]
	v_pk_add_f32 v[50:51], v[16:17], v[56:57]
	v_pk_add_f32 v[54:55], v[48:49], v[60:61]
	v_pk_add_f32 v[48:49], v[48:49], v[60:61] neg_lo:[0,1] neg_hi:[0,1]
	v_pk_add_f32 v[16:17], v[16:17], v[56:57] neg_lo:[0,1] neg_hi:[0,1]
	v_xor_b32_e32 v57, 0x80000000, v48
	v_mov_b32_e32 v56, v49
	v_pk_add_f32 v[48:49], v[50:51], v[54:55]
	v_pk_add_f32 v[50:51], v[50:51], v[54:55] neg_lo:[0,1] neg_hi:[0,1]
	v_pk_mul_f32 v[54:55], v[52:53], s[22:23] op_sel:[1,0] op_sel_hi:[0,0] neg_lo:[1,0]
	v_pk_add_f32 v[60:61], v[16:17], v[56:57]
	v_pk_fma_f32 v[52:53], v[52:53], s[36:37], v[54:55] op_sel_hi:[1,0,1] neg_lo:[0,0,1] neg_hi:[0,0,1]
	v_pk_mul_f32 v[54:55], v[20:21], s[12:13] op_sel:[1,0] op_sel_hi:[0,0] neg_lo:[1,0]
	v_pk_add_f32 v[16:17], v[16:17], v[56:57] neg_lo:[0,1] neg_hi:[0,1]
	v_pk_fma_f32 v[20:21], v[20:21], s[12:13], v[54:55] op_sel_hi:[1,0,1] neg_lo:[0,0,1] neg_hi:[0,0,1]
	v_pk_mul_f32 v[54:55], v[10:11], s[36:37] op_sel:[1,0] op_sel_hi:[0,0] neg_lo:[1,0]
	v_pk_fma_f32 v[10:11], v[10:11], s[22:23], v[54:55] op_sel_hi:[1,0,1] neg_lo:[0,0,1] neg_hi:[0,0,1]
	v_pk_mul_f32 v[54:55], v[58:59], s[12:13] op_sel:[1,0] op_sel_hi:[0,0] neg_lo:[1,0]
	v_pk_fma_f32 v[22:23], v[22:23], 0, v[22:23] op_sel:[0,0,1] op_sel_hi:[1,0,0] neg_hi:[0,0,1]
	v_pk_fma_f32 v[54:55], v[58:59], s[12:13], v[54:55] op_sel_hi:[1,0,1] neg_lo:[0,0,1] neg_hi:[0,0,1]
	v_pk_mul_f32 v[56:57], v[14:15], s[12:13] op_sel:[1,0] op_sel_hi:[0,0] neg_lo:[1,0]
	v_pk_fma_f32 v[14:15], v[14:15], s[18:19], v[56:57] op_sel_hi:[1,0,1] neg_lo:[0,0,1] neg_hi:[0,0,1]
	v_pk_mul_f32 v[58:59], v[50:51], s[12:13] op_sel:[1,0] op_sel_hi:[0,0] neg_lo:[1,0]
	v_pk_mul_f32 v[56:57], v[60:61], s[36:37] op_sel:[1,0] op_sel_hi:[0,0] neg_lo:[1,0]
	v_pk_fma_f32 v[50:51], v[50:51], s[18:19], v[58:59] op_sel_hi:[1,0,1] neg_lo:[0,0,1] neg_hi:[0,0,1]
	v_xor_b32_e32 v58, 0x80000000, v17
	v_mov_b32_e32 v59, v16
	v_pk_mul_f32 v[16:17], v[16:17], s[36:37] op_sel_hi:[1,0]
	v_pk_fma_f32 v[56:57], v[60:61], s[22:23], v[56:57] op_sel_hi:[1,0,1] neg_lo:[0,0,1] neg_hi:[0,0,1]
	v_pk_fma_f32 v[16:17], v[58:59], s[22:23], v[16:17] op_sel_hi:[1,0,1] neg_lo:[0,0,1] neg_hi:[0,0,1]
	v_pk_add_f32 v[58:59], v[42:43], v[46:47]
	v_pk_add_f32 v[42:43], v[42:43], v[46:47] neg_lo:[0,1] neg_hi:[0,1]
	v_pk_add_f32 v[46:47], v[44:45], v[48:49]
	v_pk_add_f32 v[44:45], v[44:45], v[48:49] neg_lo:[0,1] neg_hi:[0,1]
	v_mov_b32_e32 v100, v31
	v_xor_b32_e32 v49, 0x80000000, v44
	v_mov_b32_e32 v48, v45
	v_pk_add_f32 v[44:45], v[58:59], v[46:47]
	v_pk_add_f32 v[46:47], v[58:59], v[46:47] neg_lo:[0,1] neg_hi:[0,1]
	v_pk_add_f32 v[58:59], v[52:53], v[56:57]
	v_pk_add_f32 v[52:53], v[52:53], v[56:57] neg_lo:[0,1] neg_hi:[0,1]
	v_pk_add_f32 v[60:61], v[42:43], v[48:49]
	v_pk_add_f32 v[42:43], v[42:43], v[48:49] neg_lo:[0,1] neg_hi:[0,1]
	v_pk_add_f32 v[48:49], v[62:63], v[54:55]
	v_pk_add_f32 v[54:55], v[62:63], v[54:55] neg_lo:[0,1] neg_hi:[0,1]
	v_pk_add_f32 v[62:63], v[54:55], v[52:53] op_sel:[0,1] op_sel_hi:[1,0] neg_hi:[0,1]
	v_pk_add_f32 v[54:55], v[54:55], v[52:53] op_sel:[0,1] op_sel_hi:[1,0] neg_lo:[0,1]
	v_pk_add_f32 v[56:57], v[18:19], v[22:23]
	v_pk_add_f32 v[18:19], v[18:19], v[22:23] neg_lo:[0,1] neg_hi:[0,1]
	v_pk_add_f32 v[22:23], v[20:21], v[50:51]
	v_pk_add_f32 v[20:21], v[20:21], v[50:51] neg_lo:[0,1] neg_hi:[0,1]
	v_pk_add_f32 v[52:53], v[48:49], v[58:59]
	v_xor_b32_e32 v51, 0x80000000, v20
	v_mul_f32_e32 v20, 0x4b800000, v13
	v_cndmask_b32_e32 v13, v13, v20, vcc
	v_rsq_f32_e32 v13, v13
	v_mov_b32_e32 v50, v21
	v_pk_add_f32 v[64:65], v[18:19], v[50:51]
	v_pk_add_f32 v[66:67], v[18:19], v[50:51] neg_lo:[0,1] neg_hi:[0,1]
	v_pk_add_f32 v[18:19], v[8:9], v[14:15]
	v_pk_add_f32 v[8:9], v[8:9], v[14:15] neg_lo:[0,1] neg_hi:[0,1]
	v_pk_add_f32 v[14:15], v[10:11], v[16:17]
	v_pk_add_f32 v[10:11], v[10:11], v[16:17] neg_lo:[0,1] neg_hi:[0,1]
	v_pk_add_f32 v[48:49], v[48:49], v[58:59] neg_lo:[0,1] neg_hi:[0,1]
	v_pk_add_f32 v[68:69], v[8:9], v[10:11] op_sel:[0,1] op_sel_hi:[1,0] neg_hi:[0,1]
	v_pk_add_f32 v[8:9], v[8:9], v[10:11] op_sel:[0,1] op_sel_hi:[1,0] neg_lo:[0,1]
	v_mul_f32_e32 v16, 0x45800000, v13
	v_cndmask_b32_e32 v13, v13, v16, vcc
	v_pk_add_f32 v[58:59], v[56:57], v[22:23]
	v_pk_add_f32 v[56:57], v[56:57], v[22:23] neg_lo:[0,1] neg_hi:[0,1]
	v_pk_add_f32 v[10:11], v[18:19], v[14:15]
	v_pk_add_f32 v[14:15], v[18:19], v[14:15] neg_lo:[0,1] neg_hi:[0,1]
	s_waitcnt vmcnt(0)
	v_pk_mul_f32 v[12:13], v[12:13], s[2:3] op_sel_hi:[1,0]
	v_mov_b32_e32 v101, v31
	v_pk_fma_f32 v[16:17], v[12:13], v[44:45], v[12:13] op_sel:[1,0,0] op_sel_hi:[0,1,1]
	v_pk_mul_f32 v[70:71], v[12:13], v[44:45]
	v_pk_fma_f32 v[18:19], v[12:13], v[60:61], v[12:13] op_sel:[1,0,0] op_sel_hi:[0,1,1]
	v_pk_mul_f32 v[72:73], v[12:13], v[60:61]
	v_pk_fma_f32 v[20:21], v[12:13], v[46:47], v[12:13] op_sel:[1,0,0] op_sel_hi:[0,1,1]
	v_pk_mul_f32 v[74:75], v[12:13], v[46:47]
	v_pk_fma_f32 v[22:23], v[12:13], v[42:43], v[12:13] op_sel:[1,0,0] op_sel_hi:[0,1,1]
	v_pk_mul_f32 v[76:77], v[12:13], v[42:43]
	v_pk_fma_f32 v[42:43], v[12:13], v[52:53], v[12:13] op_sel:[1,0,0] op_sel_hi:[0,1,1]
	v_pk_mul_f32 v[78:79], v[12:13], v[52:53]
	v_pk_fma_f32 v[44:45], v[12:13], v[62:63], v[12:13] op_sel:[1,0,0] op_sel_hi:[0,1,1]
	v_pk_mul_f32 v[80:81], v[12:13], v[62:63]
	v_pk_fma_f32 v[46:47], v[12:13], v[48:49], v[12:13] op_sel:[1,0,0] op_sel_hi:[0,1,1]
	v_pk_mul_f32 v[82:83], v[12:13], v[48:49]
	v_pk_fma_f32 v[48:49], v[12:13], v[54:55], v[12:13] op_sel:[1,0,0] op_sel_hi:[0,1,1]
	v_pk_mul_f32 v[84:85], v[12:13], v[54:55]
	v_pk_fma_f32 v[50:51], v[12:13], v[58:59], v[12:13] op_sel:[1,0,0] op_sel_hi:[0,1,1]
	v_pk_mul_f32 v[86:87], v[12:13], v[58:59]
	v_pk_fma_f32 v[52:53], v[12:13], v[64:65], v[12:13] op_sel:[1,0,0] op_sel_hi:[0,1,1]
	v_pk_mul_f32 v[88:89], v[12:13], v[64:65]
	v_pk_fma_f32 v[54:55], v[12:13], v[56:57], v[12:13] op_sel:[1,0,0] op_sel_hi:[0,1,1]
	v_pk_mul_f32 v[90:91], v[12:13], v[56:57]
	v_pk_fma_f32 v[56:57], v[12:13], v[66:67], v[12:13] op_sel:[1,0,0] op_sel_hi:[0,1,1]
	v_pk_mul_f32 v[92:93], v[12:13], v[66:67]
	v_pk_fma_f32 v[58:59], v[12:13], v[10:11], v[12:13] op_sel:[1,0,0] op_sel_hi:[0,1,1]
	v_pk_mul_f32 v[10:11], v[12:13], v[10:11]
	v_pk_fma_f32 v[60:61], v[12:13], v[68:69], v[12:13] op_sel:[1,0,0] op_sel_hi:[0,1,1]
	v_pk_mul_f32 v[94:95], v[12:13], v[68:69]
	v_pk_fma_f32 v[62:63], v[12:13], v[14:15], v[12:13] op_sel:[1,0,0] op_sel_hi:[0,1,1]
	v_pk_mul_f32 v[14:15], v[12:13], v[14:15]
	v_pk_fma_f32 v[64:65], v[12:13], v[8:9], v[12:13] op_sel:[1,0,0] op_sel_hi:[0,1,1]
	v_pk_mul_f32 v[8:9], v[12:13], v[8:9]
	v_mov_b32_e32 v17, v71
	v_mov_b32_e32 v19, v73
	v_mov_b32_e32 v21, v75
	v_mov_b32_e32 v23, v77
	v_mov_b32_e32 v43, v79
	v_mov_b32_e32 v45, v81
	v_mov_b32_e32 v47, v83
	v_mov_b32_e32 v49, v85
	v_mov_b32_e32 v51, v87
	v_mov_b32_e32 v53, v89
	v_mov_b32_e32 v55, v91
	v_mov_b32_e32 v57, v93
	v_mov_b32_e32 v59, v11
	v_mov_b32_e32 v61, v95
	v_mov_b32_e32 v63, v15
	v_mov_b32_e32 v65, v9
	v_xor_b32_e32 v66, 0x80000000, v71
	v_mov_b32_e32 v67, v16
	v_xor_b32_e32 v68, 0x80000000, v73
	v_mov_b32_e32 v69, v18
	v_xor_b32_e32 v70, 0x80000000, v75
	v_mov_b32_e32 v71, v20
	v_xor_b32_e32 v72, 0x80000000, v77
	v_mov_b32_e32 v73, v22
	v_xor_b32_e32 v74, 0x80000000, v79
	v_mov_b32_e32 v75, v42
	v_xor_b32_e32 v76, 0x80000000, v81
	v_mov_b32_e32 v77, v44
	v_xor_b32_e32 v78, 0x80000000, v83
	v_mov_b32_e32 v79, v46
	v_xor_b32_e32 v80, 0x80000000, v85
	v_mov_b32_e32 v81, v48
	v_xor_b32_e32 v82, 0x80000000, v87
	v_mov_b32_e32 v83, v50
	v_xor_b32_e32 v84, 0x80000000, v89
	v_mov_b32_e32 v85, v52
	v_xor_b32_e32 v86, 0x80000000, v91
	v_mov_b32_e32 v87, v54
	v_xor_b32_e32 v88, 0x80000000, v93
	v_mov_b32_e32 v89, v56
	v_xor_b32_e32 v90, 0x80000000, v11
	v_mov_b32_e32 v91, v58
	v_xor_b32_e32 v92, 0x80000000, v95
	v_mov_b32_e32 v93, v60
	v_xor_b32_e32 v94, 0x80000000, v15
	v_mov_b32_e32 v95, v62
	v_xor_b32_e32 v96, 0x80000000, v9
	v_mov_b32_e32 v97, v64
	v_mov_b32_e32 v102, v30
	v_mov_b32_e32 v103, v30
	s_addc_u32 s46, s65, s43
	s_mov_b64 s[42:43], 0
	s_movk_i32 s47, 0x2000
	s_barrier
.LBB0_209:
	s_waitcnt vmcnt(5)
	v_lshlrev_b32_e32 v10, 16, v143
	v_and_b32_e32 v121, 0x1ff, v212
	v_cmp_eq_u32_e32 vcc, 0, v121
	v_and_b32_e32 v12, 0xffff0000, v4
	v_lshlrev_b32_e32 v13, 16, v4
	v_cndmask_b32_e64 v10, v10, 0, vcc
	v_pk_mul_f32 v[14:15], v[32:33], v[12:13]
	v_mov_b32_e32 v105, v13
	v_fma_f32 v4, v41, v10, v15
	v_add_f32_e32 v4, v14, v4
	v_add_f32_e32 v14, v219, v4
	v_and_b32_e32 v4, 0xffff0000, v5
	v_lshlrev_b32_e32 v5, 16, v5
	v_mov_b32_e32 v104, v5
	v_pk_mul_f32 v[104:105], v[40:41], v[104:105]
	v_pk_mul_f32 v[106:107], v[32:33], v[4:5]
	v_fma_f32 v10, v33, v12, v105
	v_add_f32_e32 v10, v104, v10
	v_add_f32_e32 v104, v219, v10
	v_fma_f32 v10, v41, v12, v107
	v_lshlrev_b32_e32 v107, 16, v6
	v_mov_b32_e32 v108, v107
	v_mov_b32_e32 v109, v5
	v_add_f32_e32 v10, v106, v10
	v_and_b32_e32 v106, 0xffff0000, v6
	v_pk_mul_f32 v[108:109], v[40:41], v[108:109]
	v_pk_mul_f32 v[110:111], v[32:33], v[106:107]
	v_fma_f32 v5, v33, v4, v109
	v_add_f32_e32 v5, v108, v5
	v_fma_f32 v4, v41, v4, v111
	v_add_f32_e32 v108, v219, v5
	v_add_f32_e32 v4, v110, v4
	v_lshlrev_b32_e32 v5, 16, v7
	v_add_f32_e32 v110, v219, v4
	v_and_b32_e32 v4, 0xffff0000, v7
	v_mov_b32_e32 v6, v5
	v_mov_b32_e32 v7, v107
	v_pk_mul_f32 v[6:7], v[40:41], v[6:7]
	s_waitcnt vmcnt(4)
	v_lshlrev_b32_e32 v11, 16, v142
	v_fma_f32 v7, v33, v106, v7
	v_add_f32_e32 v6, v6, v7
	v_add_f32_e32 v112, v219, v6
	v_pk_mul_f32 v[6:7], v[32:33], v[4:5]
	v_cmp_eq_u32_e64 s[0:1], s37, v121
	v_fma_f32 v7, v41, v106, v7
	v_add_f32_e32 v12, v219, v10
	v_cndmask_b32_e64 v11, v11, 0, s[0:1]
	v_add_f32_e32 v6, v6, v7
	v_mov_b32_e32 v10, v5
	v_add_f32_e32 v106, v219, v6
	v_pk_mul_f32 v[6:7], v[98:99], v[10:11]
	s_waitcnt vmcnt(2)
	v_lshlrev_b32_e32 v5, 16, v140
	v_fma_f32 v4, v33, v4, v6
	v_add_f32_e32 v4, v4, v7
	v_add_f32_e32 v10, v219, v4
	v_lshlrev_b32_e32 v4, 16, v141
	v_and_b32_e32 v6, 0xffff0000, v0
	v_lshlrev_b32_e32 v7, 16, v0
	v_cndmask_b32_e64 v4, v4, 0, vcc
	v_pk_mul_f32 v[114:115], v[32:33], v[6:7]
	v_mov_b32_e32 v117, v7
	v_fma_f32 v0, v41, v4, v115
	v_add_f32_e32 v0, v114, v0
	v_add_f32_e32 v114, v219, v0
	v_and_b32_e32 v0, 0xffff0000, v1
	v_lshlrev_b32_e32 v1, 16, v1
	v_mov_b32_e32 v116, v1
	v_pk_mul_f32 v[116:117], v[40:41], v[116:117]
	v_lshlrev_b32_e32 v7, 16, v2
	v_fma_f32 v4, v33, v6, v117
	v_mov_b32_e32 v118, v7
	v_mov_b32_e32 v119, v1
	v_add_f32_e32 v4, v116, v4
	v_pk_mul_f32 v[116:117], v[32:33], v[0:1]
	v_pk_mul_f32 v[118:119], v[40:41], v[118:119]
	v_add_f32_e32 v105, v219, v4
	v_fma_f32 v4, v41, v6, v117
	v_and_b32_e32 v6, 0xffff0000, v2
	v_fma_f32 v1, v33, v0, v119
	v_add_f32_e32 v1, v118, v1
	v_pk_mul_f32 v[118:119], v[32:33], v[6:7]
	v_add_f32_e32 v109, v219, v1
	v_fma_f32 v0, v41, v0, v119
	v_add_f32_e32 v0, v118, v0
	v_lshlrev_b32_e32 v1, 16, v3
	v_add_f32_e32 v118, v219, v0
	v_and_b32_e32 v0, 0xffff0000, v3
	v_mov_b32_e32 v2, v1
	v_mov_b32_e32 v3, v7
	v_pk_mul_f32 v[2:3], v[40:41], v[2:3]
	v_add_f32_e32 v4, v116, v4
	v_fma_f32 v3, v33, v6, v3
	v_add_f32_e32 v2, v2, v3
	v_add_f32_e32 v113, v219, v2
	v_pk_mul_f32 v[2:3], v[32:33], v[0:1]
	v_cndmask_b32_e64 v5, v5, 0, s[0:1]
	v_fma_f32 v3, v41, v6, v3
	v_add_f32_e32 v116, v219, v4
	v_add_f32_e32 v2, v2, v3
	v_mov_b32_e32 v4, v1
	v_add_f32_e32 v120, v219, v2
	v_pk_mul_f32 v[2:3], v[98:99], v[4:5]
	v_lshlrev_b32_e32 v122, 3, v121
	v_fma_f32 v0, v33, v0, v2
	v_add_f32_e32 v0, v0, v3
	v_add_f32_e32 v11, v219, v0
	v_add_u32_e32 v0, -1, v122
	v_cndmask_b32_e64 v176, v0, 0, vcc
	v_add_u32_e32 v0, 8, v122
	s_add_u32 s44, s28, s42
	v_cndmask_b32_e64 v13, v0, v229, s[0:1]
	v_lshlrev_b32_e32 v0, 4, v121
	v_mov_b32_e32 v1, v177
	s_addc_u32 s45, s29, s43
	v_bfe_u32 v8, v212, 1, 8
	v_lshl_add_u64 v[0:1], s[44:45], 0, v[0:1]
	v_add_u32_e32 v126, v122, v8
	v_mov_b32_e32 v9, v214
	v_mov_b32_e32 v8, v213
	v_add_co_u32_e32 v2, vcc, s5, v0
	v_lshl_add_u32 v117, v126, 3, 0
	s_nop 0
	v_addc_co_u32_e32 v3, vcc, 0, v1, vcc
	v_xor_b32_e32 v126, 0x80000000, v9
	v_mov_b32_e32 v127, v8
	s_mov_b32 s9, s30
	v_add_co_u32_e32 v4, vcc, s27, v0
	v_pk_mul_f32 v[126:127], v[126:127], v[114:115] op_sel_hi:[1,0]
	v_pk_mul_f32 v[128:129], v[214:215], s[8:9] op_sel_hi:[0,1]
	v_addc_co_u32_e32 v5, vcc, 0, v1, vcc
	v_pk_fma_f32 v[126:127], v[8:9], v[14:15], v[126:127] op_sel_hi:[1,0,1]
	v_pk_fma_f32 v[8:9], v[212:213], s[30:31], v[128:129] op_sel:[1,0,0]
	v_mov_b32_e32 v15, v114
	global_load_dwordx4 v[0:3], v[2:3], off
	s_nop 0
	global_load_dwordx4 v[4:7], v[4:5], off
	ds_write2_b64 v117, v[14:15], v[104:105] offset1:1
	v_pk_mul_f32 v[14:15], v[104:105], v[8:9] op_sel:[1,1] op_sel_hi:[1,0] neg_lo:[0,1]
	v_lshl_add_u64 v[122:123], v[176:177], 1, s[44:45]
	v_lshlrev_b32_e32 v176, 1, v13
	v_add_u32_e32 v13, 0x8800, v117
	v_pk_fma_f32 v[14:15], v[8:9], v[104:105], v[14:15] op_sel_hi:[1,0,1]
	ds_write2_b64 v13, v[126:127], v[14:15] offset1:1
	v_pk_mul_f32 v[14:15], v[8:9], s[8:9] op_sel:[1,0]
	v_add_u32_e32 v107, 0x8810, v117
	v_pk_fma_f32 v[8:9], v[8:9], s[30:31], v[14:15] op_sel_hi:[0,1,1]
	v_pk_mul_f32 v[14:15], v[116:117], v[8:9] op_sel:[0,1] op_sel_hi:[0,0] neg_lo:[0,1]
	v_pk_mul_f32 v[104:105], v[8:9], s[8:9] op_sel:[1,0]
	v_pk_fma_f32 v[14:15], v[12:13], v[8:9], v[14:15] op_sel_hi:[0,1,1]
	v_pk_fma_f32 v[8:9], v[8:9], s[30:31], v[104:105] op_sel_hi:[0,1,1]
	v_mov_b32_e32 v13, v116
	ds_write2_b64 v117, v[12:13], v[108:109] offset0:2 offset1:3
	v_pk_mul_f32 v[12:13], v[108:109], v[8:9] op_sel:[1,1] op_sel_hi:[1,0] neg_lo:[0,1]
	v_pk_fma_f32 v[12:13], v[108:109], v[8:9], v[12:13] op_sel_hi:[0,1,1]
	ds_write2_b64 v107, v[14:15], v[12:13] offset1:1
	v_pk_mul_f32 v[12:13], v[8:9], s[8:9] op_sel:[1,0]
	v_add_u32_e32 v107, 0x8820, v117
	v_pk_fma_f32 v[8:9], v[8:9], s[30:31], v[12:13] op_sel_hi:[0,1,1]
	v_pk_mul_f32 v[12:13], v[118:119], v[8:9] op_sel:[0,1] op_sel_hi:[0,0] neg_lo:[0,1]
	v_pk_mul_f32 v[14:15], v[8:9], s[8:9] op_sel:[1,0]
	v_pk_fma_f32 v[12:13], v[110:111], v[8:9], v[12:13] op_sel_hi:[0,1,1]
	v_pk_fma_f32 v[8:9], v[8:9], s[30:31], v[14:15] op_sel_hi:[0,1,1]
	v_pk_mul_f32 v[14:15], v[112:113], v[8:9] op_sel:[1,1] op_sel_hi:[1,0] neg_lo:[0,1]
	v_pk_fma_f32 v[14:15], v[112:113], v[8:9], v[14:15] op_sel_hi:[0,1,1]
	ds_write2_b64 v107, v[12:13], v[14:15] offset1:1
	v_pk_mul_f32 v[12:13], v[8:9], s[8:9] op_sel:[1,0]
	v_add_u32_e32 v108, 0x8830, v117
	v_pk_fma_f32 v[8:9], v[8:9], s[30:31], v[12:13] op_sel_hi:[0,1,1]
	v_pk_mul_f32 v[12:13], v[120:121], v[8:9] op_sel:[0,1] op_sel_hi:[0,0] neg_lo:[0,1]
	v_pk_mul_f32 v[14:15], v[8:9], s[8:9] op_sel:[1,0]
	v_pk_fma_f32 v[12:13], v[106:107], v[8:9], v[12:13] op_sel_hi:[0,1,1]
	v_pk_fma_f32 v[8:9], v[8:9], s[30:31], v[14:15] op_sel_hi:[0,1,1]
	v_pk_mul_f32 v[14:15], v[10:11], v[8:9] op_sel:[1,1] op_sel_hi:[1,0] neg_lo:[0,1]
	v_pk_fma_f32 v[8:9], v[10:11], v[8:9], v[14:15] op_sel_hi:[0,1,1]
	ds_write2_b64 v108, v[12:13], v[8:9] offset1:1
	v_add_co_u32_e32 v8, vcc, s27, v122
	v_mov_b32_e32 v107, v120
	s_nop 0
	v_addc_co_u32_e32 v9, vcc, 0, v123, vcc
	ds_write2_b64 v117, v[106:107], v[10:11] offset0:6 offset1:7
	v_add_co_u32_e32 v10, vcc, s5, v122
	v_lshl_add_u64 v[124:125], s[44:45], 0, v[176:177]
	s_nop 0
	v_addc_co_u32_e32 v11, vcc, 0, v123, vcc
	v_add_co_u32_e32 v12, vcc, s27, v124
	v_mov_b32_e32 v111, v118
	s_nop 0
	v_addc_co_u32_e32 v13, vcc, 0, v125, vcc
	ds_write2_b64 v117, v[110:111], v[112:113] offset0:4 offset1:5
	v_add_co_u32_e32 v14, vcc, s5, v124
	v_mov_b32_e32 v110, 1.0
	s_nop 0
	v_addc_co_u32_e32 v15, vcc, 0, v125, vcc
	global_load_ushort v162, v[8:9], off
	global_load_ushort v163, v[10:11], off
	global_load_ushort v160, v[12:13], off
	global_load_ushort v161, v[14:15], off
	v_mov_b32_e32 v111, v177
	v_pk_mul_f32 v[10:11], v[208:209], v[208:209] op_sel:[1,1] op_sel_hi:[0,1] neg_lo:[1,0]
	s_waitcnt lgkmcnt(0)
	v_pk_fma_f32 v[10:11], v[208:209], v[208:209], v[10:11] op_sel_hi:[0,1,1]
	v_pk_mul_f32 v[104:105], v[10:11], v[10:11] op_sel:[1,1] op_sel_hi:[1,0] neg_lo:[0,1]
	v_pk_mul_f32 v[12:13], v[208:209], v[176:177] op_sel:[1,1] op_sel_hi:[0,1] neg_lo:[1,0]
	v_pk_fma_f32 v[104:105], v[10:11], v[10:11], v[104:105] op_sel_hi:[1,0,1]
	v_pk_fma_f32 v[114:115], v[208:209], v[110:111], v[12:13] op_sel_hi:[1,0,1]
	v_pk_mul_f32 v[8:9], v[176:177], v[10:11] op_sel:[1,1] op_sel_hi:[1,0] neg_lo:[0,1]
	v_pk_fma_f32 v[116:117], v[110:111], v[10:11], v[8:9] op_sel_hi:[0,1,1]
	v_pk_mul_f32 v[8:9], v[114:115], v[10:11] op_sel:[1,1] op_sel_hi:[1,0] neg_lo:[0,1]
	v_pk_mul_f32 v[108:109], v[104:105], v[104:105] op_sel:[1,1] op_sel_hi:[1,0] neg_lo:[0,1]
	v_pk_fma_f32 v[118:119], v[10:11], v[114:115], v[8:9] op_sel_hi:[1,0,1]
	v_pk_mul_f32 v[8:9], v[176:177], v[104:105] op_sel:[1,1] op_sel_hi:[1,0] neg_lo:[0,1]
	v_pk_fma_f32 v[120:121], v[110:111], v[104:105], v[8:9] op_sel_hi:[0,1,1]
	v_pk_mul_f32 v[8:9], v[114:115], v[104:105] op_sel:[1,1] op_sel_hi:[1,0] neg_lo:[0,1]
	s_barrier
	v_pk_fma_f32 v[122:123], v[114:115], v[104:105], v[8:9] op_sel_hi:[0,1,1]
	v_pk_mul_f32 v[8:9], v[116:117], v[104:105] op_sel:[1,1] op_sel_hi:[1,0] neg_lo:[0,1]
	v_pk_fma_f32 v[124:125], v[104:105], v[116:117], v[8:9] op_sel_hi:[1,0,1]
	v_pk_mul_f32 v[8:9], v[118:119], v[104:105] op_sel:[1,1] op_sel_hi:[1,0] neg_lo:[0,1]
	v_pk_fma_f32 v[126:127], v[104:105], v[118:119], v[8:9] op_sel_hi:[1,0,1]
	v_pk_fma_f32 v[8:9], v[104:105], v[104:105], v[108:109] op_sel_hi:[1,0,1]
	v_pk_mul_f32 v[10:11], v[176:177], v[8:9] op_sel:[1,1] op_sel_hi:[1,0] neg_lo:[0,1]
	v_pk_fma_f32 v[112:113], v[110:111], v[8:9], v[10:11] op_sel_hi:[0,1,1]
	v_pk_mul_f32 v[10:11], v[114:115], v[8:9] op_sel:[1,1] op_sel_hi:[1,0] neg_lo:[0,1]
	v_pk_fma_f32 v[108:109], v[114:115], v[8:9], v[10:11] op_sel_hi:[0,1,1]
	v_pk_mul_f32 v[10:11], v[116:117], v[8:9] op_sel:[1,1] op_sel_hi:[1,0] neg_lo:[0,1]
	v_pk_fma_f32 v[106:107], v[116:117], v[8:9], v[10:11] op_sel_hi:[0,1,1]
	v_pk_mul_f32 v[10:11], v[118:119], v[8:9] op_sel:[1,1] op_sel_hi:[1,0] neg_lo:[0,1]
	v_pk_fma_f32 v[104:105], v[118:119], v[8:9], v[10:11] op_sel_hi:[0,1,1]
	v_pk_mul_f32 v[10:11], v[120:121], v[8:9] op_sel:[1,1] op_sel_hi:[1,0] neg_lo:[0,1]
	v_pk_fma_f32 v[14:15], v[8:9], v[120:121], v[10:11] op_sel_hi:[1,0,1]
	v_pk_mul_f32 v[10:11], v[122:123], v[8:9] op_sel:[1,1] op_sel_hi:[1,0] neg_lo:[0,1]
	v_pk_fma_f32 v[12:13], v[8:9], v[122:123], v[10:11] op_sel_hi:[1,0,1]
	v_pk_mul_f32 v[10:11], v[124:125], v[8:9] op_sel:[1,1] op_sel_hi:[1,0] neg_lo:[0,1]
	v_pk_mul_f32 v[128:129], v[126:127], v[8:9] op_sel:[1,1] op_sel_hi:[1,0] neg_lo:[0,1]
	v_pk_fma_f32 v[10:11], v[8:9], v[124:125], v[10:11] op_sel_hi:[1,0,1]
	v_pk_fma_f32 v[8:9], v[8:9], v[126:127], v[128:129] op_sel_hi:[1,0,1]
	v_mov_b32_e32 v128, v206
	s_nop 0
	v_lshlrev_b32_sdwa v129, v228, v128 dst_sel:DWORD dst_unused:UNUSED_PAD src0_sel:DWORD src1_sel:BYTE_0
	v_lshrrev_b32_e32 v128, 1, v206
	v_and_b32_e32 v128, 0x78, v128
	v_add3_u32 v168, v207, v129, v128
	ds_read_b64 v[128:129], v168
	ds_read_b64 v[130:131], v168 offset:2176
	ds_read_b64 v[132:133], v168 offset:4352
	ds_read_b64 v[134:135], v168 offset:6528
	ds_read_b64 v[136:137], v168 offset:8704
	ds_read_b64 v[138:139], v168 offset:10880
	ds_read_b64 v[140:141], v168 offset:13056
	ds_read_b64 v[142:143], v168 offset:15232
	ds_read_b64 v[144:145], v168 offset:17408
	ds_read_b64 v[146:147], v168 offset:19584
	ds_read_b64 v[148:149], v168 offset:21760
	ds_read_b64 v[150:151], v168 offset:23936
	ds_read_b64 v[152:153], v168 offset:26112
	ds_read_b64 v[154:155], v168 offset:28288
	ds_read_b64 v[156:157], v168 offset:30464
	ds_read_b64 v[158:159], v168 offset:32640
	s_waitcnt lgkmcnt(7)
	v_pk_add_f32 v[164:165], v[128:129], v[144:145]
	v_pk_add_f32 v[128:129], v[128:129], v[144:145] neg_lo:[0,1] neg_hi:[0,1]
	s_waitcnt lgkmcnt(3)
	v_pk_add_f32 v[144:145], v[136:137], v[152:153]
	v_pk_add_f32 v[136:137], v[136:137], v[152:153] neg_lo:[0,1] neg_hi:[0,1]
	v_pk_add_f32 v[166:167], v[128:129], v[136:137] op_sel:[0,1] op_sel_hi:[1,0] neg_hi:[0,1]
	v_pk_add_f32 v[128:129], v[128:129], v[136:137] op_sel:[0,1] op_sel_hi:[1,0] neg_lo:[0,1]
	v_pk_add_f32 v[152:153], v[130:131], v[146:147]
	v_pk_add_f32 v[130:131], v[130:131], v[146:147] neg_lo:[0,1] neg_hi:[0,1]
	s_waitcnt lgkmcnt(2)
	v_pk_add_f32 v[146:147], v[138:139], v[154:155]
	v_pk_add_f32 v[138:139], v[138:139], v[154:155] neg_lo:[0,1] neg_hi:[0,1]
	v_pk_add_f32 v[136:137], v[164:165], v[144:145]
	v_xor_b32_e32 v155, 0x80000000, v138
	v_mov_b32_e32 v154, v139
	v_pk_add_f32 v[138:139], v[152:153], v[146:147]
	v_pk_add_f32 v[146:147], v[152:153], v[146:147] neg_lo:[0,1] neg_hi:[0,1]
	v_pk_add_f32 v[152:153], v[132:133], v[148:149]
	v_pk_add_f32 v[132:133], v[132:133], v[148:149] neg_lo:[0,1] neg_hi:[0,1]
	s_waitcnt lgkmcnt(1)
	v_pk_add_f32 v[148:149], v[140:141], v[156:157]
	v_pk_add_f32 v[140:141], v[140:141], v[156:157] neg_lo:[0,1] neg_hi:[0,1]
	v_pk_add_f32 v[144:145], v[164:165], v[144:145] neg_lo:[0,1] neg_hi:[0,1]
	v_pk_add_f32 v[164:165], v[130:131], v[154:155]
	v_pk_add_f32 v[130:131], v[130:131], v[154:155] neg_lo:[0,1] neg_hi:[0,1]
	v_xor_b32_e32 v155, 0x80000000, v140
	v_mov_b32_e32 v154, v141
	v_pk_add_f32 v[140:141], v[152:153], v[148:149]
	v_pk_add_f32 v[148:149], v[152:153], v[148:149] neg_lo:[0,1] neg_hi:[0,1]
	v_pk_add_f32 v[152:153], v[134:135], v[150:151]
	v_pk_add_f32 v[134:135], v[134:135], v[150:151] neg_lo:[0,1] neg_hi:[0,1]
	s_waitcnt lgkmcnt(0)
	v_pk_add_f32 v[150:151], v[142:143], v[158:159]
	v_pk_add_f32 v[142:143], v[142:143], v[158:159] neg_lo:[0,1] neg_hi:[0,1]
	v_pk_add_f32 v[156:157], v[132:133], v[154:155]
	v_pk_add_f32 v[132:133], v[132:133], v[154:155] neg_lo:[0,1] neg_hi:[0,1]
	v_pk_add_f32 v[158:159], v[134:135], v[142:143] op_sel:[0,1] op_sel_hi:[1,0] neg_hi:[0,1]
	v_pk_add_f32 v[134:135], v[134:135], v[142:143] op_sel:[0,1] op_sel_hi:[1,0] neg_lo:[0,1]
	v_pk_mul_f32 v[154:155], v[146:147], s[12:13] op_sel:[1,0] op_sel_hi:[0,0] neg_lo:[1,0]
	v_pk_add_f32 v[142:143], v[152:153], v[150:151]
	v_pk_fma_f32 v[146:147], v[146:147], s[12:13], v[154:155] op_sel_hi:[1,0,1] neg_lo:[0,0,1] neg_hi:[0,0,1]
	v_pk_mul_f32 v[154:155], v[130:131], s[36:37] op_sel:[1,0] op_sel_hi:[0,0] neg_lo:[1,0]
	v_pk_add_f32 v[150:151], v[152:153], v[150:151] neg_lo:[0,1] neg_hi:[0,1]
	v_pk_fma_f32 v[130:131], v[130:131], s[22:23], v[154:155] op_sel_hi:[1,0,1] neg_lo:[0,0,1] neg_hi:[0,0,1]
	v_pk_mul_f32 v[154:155], v[156:157], s[12:13] op_sel:[1,0] op_sel_hi:[0,0] neg_lo:[1,0]
	v_pk_fma_f32 v[154:155], v[156:157], s[12:13], v[154:155] op_sel_hi:[1,0,1] neg_lo:[0,0,1] neg_hi:[0,0,1]
	v_pk_fma_f32 v[148:149], v[148:149], 0, v[148:149] op_sel:[0,0,1] op_sel_hi:[1,0,0] neg_hi:[0,0,1]
	v_pk_mul_f32 v[156:157], v[132:133], s[12:13] op_sel:[1,0] op_sel_hi:[0,0] neg_lo:[1,0]
	v_pk_fma_f32 v[132:133], v[132:133], s[18:19], v[156:157] op_sel_hi:[1,0,1] neg_lo:[0,0,1] neg_hi:[0,0,1]
	v_pk_mul_f32 v[156:157], v[158:159], s[36:37] op_sel:[1,0] op_sel_hi:[0,0] neg_lo:[1,0]
	v_pk_mul_f32 v[152:153], v[164:165], s[22:23] op_sel:[1,0] op_sel_hi:[0,0] neg_lo:[1,0]
	v_pk_fma_f32 v[156:157], v[158:159], s[22:23], v[156:157] op_sel_hi:[1,0,1] neg_lo:[0,0,1] neg_hi:[0,0,1]
	v_pk_mul_f32 v[158:159], v[150:151], s[12:13] op_sel:[1,0] op_sel_hi:[0,0] neg_lo:[1,0]
	v_pk_fma_f32 v[152:153], v[164:165], s[36:37], v[152:153] op_sel_hi:[1,0,1] neg_lo:[0,0,1] neg_hi:[0,0,1]
	v_pk_fma_f32 v[150:151], v[150:151], s[18:19], v[158:159] op_sel_hi:[1,0,1] neg_lo:[0,0,1] neg_hi:[0,0,1]
	v_xor_b32_e32 v158, 0x80000000, v135
	v_mov_b32_e32 v159, v134
	v_pk_mul_f32 v[134:135], v[134:135], s[36:37] op_sel_hi:[1,0]
	v_pk_fma_f32 v[134:135], v[158:159], s[22:23], v[134:135] op_sel_hi:[1,0,1] neg_lo:[0,0,1] neg_hi:[0,0,1]
	v_pk_add_f32 v[158:159], v[136:137], v[140:141]
	v_pk_add_f32 v[136:137], v[136:137], v[140:141] neg_lo:[0,1] neg_hi:[0,1]
	v_pk_add_f32 v[140:141], v[138:139], v[142:143]
	v_pk_add_f32 v[138:139], v[138:139], v[142:143] neg_lo:[0,1] neg_hi:[0,1]
	v_xor_b32_e32 v143, 0x80000000, v138
	v_mov_b32_e32 v142, v139
	v_pk_add_f32 v[138:139], v[158:159], v[140:141]
	v_pk_add_f32 v[140:141], v[158:159], v[140:141] neg_lo:[0,1] neg_hi:[0,1]
	v_pk_add_f32 v[158:159], v[152:153], v[156:157]
	v_pk_add_f32 v[152:153], v[152:153], v[156:157] neg_lo:[0,1] neg_hi:[0,1]
	v_pk_add_f32 v[164:165], v[136:137], v[142:143]
	v_pk_add_f32 v[136:137], v[136:137], v[142:143] neg_lo:[0,1] neg_hi:[0,1]
	v_pk_add_f32 v[142:143], v[166:167], v[154:155]
	v_pk_add_f32 v[154:155], v[166:167], v[154:155] neg_lo:[0,1] neg_hi:[0,1]
	v_pk_add_f32 v[166:167], v[154:155], v[152:153] op_sel:[0,1] op_sel_hi:[1,0] neg_hi:[0,1]
	v_pk_add_f32 v[154:155], v[154:155], v[152:153] op_sel:[0,1] op_sel_hi:[1,0] neg_lo:[0,1]
	v_pk_add_f32 v[156:157], v[144:145], v[148:149]
	v_pk_add_f32 v[144:145], v[144:145], v[148:149] neg_lo:[0,1] neg_hi:[0,1]
	v_pk_add_f32 v[148:149], v[146:147], v[150:151]
	v_pk_add_f32 v[146:147], v[146:147], v[150:151] neg_lo:[0,1] neg_hi:[0,1]
	v_pk_add_f32 v[152:153], v[142:143], v[158:159]
	v_pk_add_f32 v[142:143], v[142:143], v[158:159] neg_lo:[0,1] neg_hi:[0,1]
	v_pk_add_f32 v[158:159], v[144:145], v[146:147] op_sel:[0,1] op_sel_hi:[1,0] neg_hi:[0,1]
	v_pk_add_f32 v[144:145], v[144:145], v[146:147] op_sel:[0,1] op_sel_hi:[1,0] neg_lo:[0,1]
	v_pk_add_f32 v[150:151], v[128:129], v[132:133]
	v_pk_add_f32 v[128:129], v[128:129], v[132:133] neg_lo:[0,1] neg_hi:[0,1]
	v_pk_add_f32 v[132:133], v[130:131], v[134:135]
	v_pk_add_f32 v[130:131], v[130:131], v[134:135] neg_lo:[0,1] neg_hi:[0,1]
	v_pk_add_f32 v[146:147], v[156:157], v[148:149]
	v_pk_add_f32 v[148:149], v[156:157], v[148:149] neg_lo:[0,1] neg_hi:[0,1]
	v_pk_add_f32 v[156:157], v[128:129], v[130:131] op_sel:[0,1] op_sel_hi:[1,0] neg_hi:[0,1]
	v_pk_add_f32 v[128:129], v[128:129], v[130:131] op_sel:[0,1] op_sel_hi:[1,0] neg_lo:[0,1]
	v_xor_b32_e32 v134, 0x80000000, v111
	v_mov_b32_e32 v135, v110
	v_pk_mul_f32 v[134:135], v[134:135], v[138:139] op_sel:[0,1]
	v_pk_add_f32 v[130:131], v[150:151], v[132:133]
	v_pk_fma_f32 v[110:111], v[110:111], v[138:139], v[134:135] op_sel_hi:[1,0,1]
	ds_write_b64 v168, v[110:111]
	v_pk_mul_f32 v[110:111], v[114:115], v[152:153] op_sel:[1,1] op_sel_hi:[0,1] neg_lo:[1,0]
	v_pk_add_f32 v[132:133], v[150:151], v[132:133] neg_lo:[0,1] neg_hi:[0,1]
	v_pk_fma_f32 v[110:111], v[114:115], v[152:153], v[110:111] op_sel_hi:[1,0,1]
	ds_write_b64 v168, v[110:111] offset:2176
	v_pk_mul_f32 v[110:111], v[116:117], v[146:147] op_sel:[1,1] op_sel_hi:[0,1] neg_lo:[1,0]
	v_pk_fma_f32 v[110:111], v[116:117], v[146:147], v[110:111] op_sel_hi:[1,0,1]
	ds_write_b64 v168, v[110:111] offset:4352
	v_pk_mul_f32 v[110:111], v[118:119], v[130:131] op_sel:[1,1] op_sel_hi:[0,1] neg_lo:[1,0]
	v_pk_fma_f32 v[110:111], v[118:119], v[130:131], v[110:111] op_sel_hi:[1,0,1]
	ds_write_b64 v168, v[110:111] offset:6528
	v_pk_mul_f32 v[110:111], v[120:121], v[164:165] op_sel:[1,1] op_sel_hi:[0,1] neg_lo:[1,0]
	v_pk_fma_f32 v[110:111], v[120:121], v[164:165], v[110:111] op_sel_hi:[1,0,1]
	ds_write_b64 v168, v[110:111] offset:8704
	v_pk_mul_f32 v[110:111], v[122:123], v[166:167] op_sel:[1,1] op_sel_hi:[0,1] neg_lo:[1,0]
	v_pk_fma_f32 v[110:111], v[122:123], v[166:167], v[110:111] op_sel_hi:[1,0,1]
	ds_write_b64 v168, v[110:111] offset:10880
	v_pk_mul_f32 v[110:111], v[124:125], v[158:159] op_sel:[1,1] op_sel_hi:[0,1] neg_lo:[1,0]
	v_pk_fma_f32 v[110:111], v[124:125], v[158:159], v[110:111] op_sel_hi:[1,0,1]
	ds_write_b64 v168, v[110:111] offset:13056
	v_pk_mul_f32 v[110:111], v[126:127], v[156:157] op_sel:[1,1] op_sel_hi:[0,1] neg_lo:[1,0]
	v_pk_fma_f32 v[110:111], v[126:127], v[156:157], v[110:111] op_sel_hi:[1,0,1]
	ds_write_b64 v168, v[110:111] offset:15232
	v_pk_mul_f32 v[110:111], v[112:113], v[140:141] op_sel:[1,1] op_sel_hi:[0,1] neg_lo:[1,0]
	v_pk_fma_f32 v[110:111], v[112:113], v[140:141], v[110:111] op_sel_hi:[1,0,1]
	ds_write_b64 v168, v[110:111] offset:17408
	v_pk_mul_f32 v[110:111], v[108:109], v[142:143] op_sel:[1,1] op_sel_hi:[0,1] neg_lo:[1,0]
	v_pk_fma_f32 v[108:109], v[108:109], v[142:143], v[110:111] op_sel_hi:[1,0,1]
	ds_write_b64 v168, v[108:109] offset:19584
	v_pk_mul_f32 v[108:109], v[106:107], v[148:149] op_sel:[1,1] op_sel_hi:[0,1] neg_lo:[1,0]
	v_pk_fma_f32 v[106:107], v[106:107], v[148:149], v[108:109] op_sel_hi:[1,0,1]
	ds_write_b64 v168, v[106:107] offset:21760
	v_pk_mul_f32 v[106:107], v[104:105], v[132:133] op_sel:[1,1] op_sel_hi:[0,1] neg_lo:[1,0]
	v_pk_fma_f32 v[104:105], v[104:105], v[132:133], v[106:107] op_sel_hi:[1,0,1]
	ds_write_b64 v168, v[104:105] offset:23936
	v_pk_mul_f32 v[104:105], v[14:15], v[136:137] op_sel:[1,1] op_sel_hi:[0,1] neg_lo:[1,0]
	v_pk_fma_f32 v[14:15], v[14:15], v[136:137], v[104:105] op_sel_hi:[1,0,1]
	ds_write_b64 v168, v[14:15] offset:26112
	v_pk_mul_f32 v[14:15], v[12:13], v[154:155] op_sel:[1,1] op_sel_hi:[0,1] neg_lo:[1,0]
	v_pk_fma_f32 v[12:13], v[12:13], v[154:155], v[14:15] op_sel_hi:[1,0,1]
	ds_write_b64 v168, v[12:13] offset:28288
	v_pk_mul_f32 v[12:13], v[10:11], v[144:145] op_sel:[1,1] op_sel_hi:[0,1] neg_lo:[1,0]
	v_pk_fma_f32 v[10:11], v[10:11], v[144:145], v[12:13] op_sel_hi:[1,0,1]
	ds_write_b64 v168, v[10:11] offset:30464
	v_pk_mul_f32 v[10:11], v[8:9], v[128:129] op_sel:[1,1] op_sel_hi:[0,1] neg_lo:[1,0]
	v_pk_fma_f32 v[8:9], v[8:9], v[128:129], v[10:11] op_sel_hi:[1,0,1]
	ds_write_b64 v168, v[8:9] offset:32640
	v_mov_b32_e32 v116, 1.0
	v_pk_mul_f32 v[10:11], v[210:211], v[210:211] op_sel:[1,1] op_sel_hi:[0,1] neg_lo:[1,0]
	v_mov_b32_e32 v117, v177
	v_pk_fma_f32 v[10:11], v[210:211], v[210:211], v[10:11] op_sel_hi:[0,1,1]
	v_pk_mul_f32 v[104:105], v[10:11], v[10:11] op_sel:[1,1] op_sel_hi:[1,0] neg_lo:[0,1]
	v_pk_mul_f32 v[12:13], v[210:211], v[176:177] op_sel:[1,1] op_sel_hi:[0,1] neg_lo:[1,0]
	v_pk_fma_f32 v[104:105], v[10:11], v[10:11], v[104:105] op_sel_hi:[1,0,1]
	v_pk_fma_f32 v[126:127], v[210:211], v[116:117], v[12:13] op_sel_hi:[1,0,1]
	v_pk_mul_f32 v[8:9], v[176:177], v[10:11] op_sel:[1,1] op_sel_hi:[1,0] neg_lo:[0,1]
	v_pk_fma_f32 v[124:125], v[116:117], v[10:11], v[8:9] op_sel_hi:[0,1,1]
	v_pk_mul_f32 v[8:9], v[126:127], v[10:11] op_sel:[1,1] op_sel_hi:[1,0] neg_lo:[0,1]
	v_pk_mul_f32 v[108:109], v[104:105], v[104:105] op_sel:[1,1] op_sel_hi:[1,0] neg_lo:[0,1]
	v_pk_fma_f32 v[122:123], v[10:11], v[126:127], v[8:9] op_sel_hi:[1,0,1]
	v_pk_mul_f32 v[8:9], v[176:177], v[104:105] op_sel:[1,1] op_sel_hi:[1,0] neg_lo:[0,1]
	v_pk_fma_f32 v[120:121], v[116:117], v[104:105], v[8:9] op_sel_hi:[0,1,1]
	v_pk_mul_f32 v[8:9], v[126:127], v[104:105] op_sel:[1,1] op_sel_hi:[1,0] neg_lo:[0,1]
	s_waitcnt lgkmcnt(0)
	v_pk_fma_f32 v[118:119], v[126:127], v[104:105], v[8:9] op_sel_hi:[0,1,1]
	v_pk_mul_f32 v[8:9], v[124:125], v[104:105] op_sel:[1,1] op_sel_hi:[1,0] neg_lo:[0,1]
	s_barrier
	v_pk_fma_f32 v[114:115], v[104:105], v[124:125], v[8:9] op_sel_hi:[1,0,1]
	v_pk_mul_f32 v[8:9], v[122:123], v[104:105] op_sel:[1,1] op_sel_hi:[1,0] neg_lo:[0,1]
	v_pk_fma_f32 v[112:113], v[104:105], v[122:123], v[8:9] op_sel_hi:[1,0,1]
	v_pk_fma_f32 v[8:9], v[104:105], v[104:105], v[108:109] op_sel_hi:[1,0,1]
	v_pk_mul_f32 v[10:11], v[176:177], v[8:9] op_sel:[1,1] op_sel_hi:[1,0] neg_lo:[0,1]
	v_pk_fma_f32 v[110:111], v[116:117], v[8:9], v[10:11] op_sel_hi:[0,1,1]
	v_pk_mul_f32 v[10:11], v[126:127], v[8:9] op_sel:[1,1] op_sel_hi:[1,0] neg_lo:[0,1]
	v_pk_fma_f32 v[108:109], v[126:127], v[8:9], v[10:11] op_sel_hi:[0,1,1]
	v_pk_mul_f32 v[10:11], v[124:125], v[8:9] op_sel:[1,1] op_sel_hi:[1,0] neg_lo:[0,1]
	v_pk_fma_f32 v[106:107], v[124:125], v[8:9], v[10:11] op_sel_hi:[0,1,1]
	v_pk_mul_f32 v[10:11], v[122:123], v[8:9] op_sel:[1,1] op_sel_hi:[1,0] neg_lo:[0,1]
	v_pk_fma_f32 v[104:105], v[122:123], v[8:9], v[10:11] op_sel_hi:[0,1,1]
	v_pk_mul_f32 v[10:11], v[120:121], v[8:9] op_sel:[1,1] op_sel_hi:[1,0] neg_lo:[0,1]
	v_pk_fma_f32 v[14:15], v[8:9], v[120:121], v[10:11] op_sel_hi:[1,0,1]
	v_pk_mul_f32 v[10:11], v[118:119], v[8:9] op_sel:[1,1] op_sel_hi:[1,0] neg_lo:[0,1]
	v_pk_fma_f32 v[12:13], v[8:9], v[118:119], v[10:11] op_sel_hi:[1,0,1]
	v_pk_mul_f32 v[10:11], v[114:115], v[8:9] op_sel:[1,1] op_sel_hi:[1,0] neg_lo:[0,1]
	v_pk_mul_f32 v[128:129], v[112:113], v[8:9] op_sel:[1,1] op_sel_hi:[1,0] neg_lo:[0,1]
	v_pk_fma_f32 v[10:11], v[8:9], v[114:115], v[10:11] op_sel_hi:[1,0,1]
	v_pk_fma_f32 v[8:9], v[8:9], v[112:113], v[128:129] op_sel_hi:[1,0,1]
	s_nop 0
	v_bfe_u32 v129, v206, 4, 4
	v_and_b32_e32 v128, 15, v206
	v_mul_u32_u24_e32 v129, 0x880, v129
	v_lshlrev_b32_e32 v128, 3, v128
	v_add3_u32 v176, v207, v129, v128
	ds_read2_b64 v[128:131], v176 offset1:17
	ds_read2_b64 v[132:135], v176 offset0:34 offset1:51
	ds_read2_b64 v[136:139], v176 offset0:68 offset1:85
	ds_read2_b64 v[140:143], v176 offset0:136 offset1:153
	ds_read2_b64 v[144:147], v176 offset0:102 offset1:119
	ds_read2_b64 v[148:151], v176 offset0:204 offset1:221
	ds_read2_b64 v[152:155], v176 offset0:170 offset1:187
	ds_read2_b64 v[156:159], v176 offset0:238 offset1:255
	s_waitcnt lgkmcnt(4)
	v_pk_add_f32 v[164:165], v[128:129], v[140:141]
	v_pk_add_f32 v[128:129], v[128:129], v[140:141] neg_lo:[0,1] neg_hi:[0,1]
	s_waitcnt lgkmcnt(2)
	v_pk_add_f32 v[140:141], v[136:137], v[148:149]
	v_pk_add_f32 v[136:137], v[136:137], v[148:149] neg_lo:[0,1] neg_hi:[0,1]
	v_pk_add_f32 v[166:167], v[128:129], v[136:137] op_sel:[0,1] op_sel_hi:[1,0] neg_hi:[0,1]
	v_pk_add_f32 v[128:129], v[128:129], v[136:137] op_sel:[0,1] op_sel_hi:[1,0] neg_lo:[0,1]
	v_pk_add_f32 v[148:149], v[130:131], v[142:143]
	v_pk_add_f32 v[130:131], v[130:131], v[142:143] neg_lo:[0,1] neg_hi:[0,1]
	v_pk_add_f32 v[142:143], v[138:139], v[150:151]
	v_pk_add_f32 v[138:139], v[138:139], v[150:151] neg_lo:[0,1] neg_hi:[0,1]
	v_pk_add_f32 v[136:137], v[164:165], v[140:141]
	v_pk_add_f32 v[140:141], v[164:165], v[140:141] neg_lo:[0,1] neg_hi:[0,1]
	v_pk_add_f32 v[164:165], v[130:131], v[138:139] op_sel:[0,1] op_sel_hi:[1,0] neg_hi:[0,1]
	v_pk_add_f32 v[130:131], v[130:131], v[138:139] op_sel:[0,1] op_sel_hi:[1,0] neg_lo:[0,1]
	s_waitcnt lgkmcnt(0)
	v_pk_add_f32 v[150:151], v[144:145], v[156:157]
	v_pk_add_f32 v[144:145], v[144:145], v[156:157] neg_lo:[0,1] neg_hi:[0,1]
	v_pk_add_f32 v[138:139], v[148:149], v[142:143]
	v_pk_add_f32 v[142:143], v[148:149], v[142:143] neg_lo:[0,1] neg_hi:[0,1]
	v_pk_add_f32 v[148:149], v[132:133], v[152:153]
	v_pk_add_f32 v[132:133], v[132:133], v[152:153] neg_lo:[0,1] neg_hi:[0,1]
	v_pk_add_f32 v[156:157], v[132:133], v[144:145] op_sel:[0,1] op_sel_hi:[1,0] neg_hi:[0,1]
	v_pk_add_f32 v[132:133], v[132:133], v[144:145] op_sel:[0,1] op_sel_hi:[1,0] neg_lo:[0,1]
	v_pk_add_f32 v[152:153], v[146:147], v[158:159]
	v_pk_add_f32 v[146:147], v[146:147], v[158:159] neg_lo:[0,1] neg_hi:[0,1]
	v_pk_add_f32 v[144:145], v[148:149], v[150:151]
	v_pk_add_f32 v[148:149], v[148:149], v[150:151] neg_lo:[0,1] neg_hi:[0,1]
	v_pk_add_f32 v[150:151], v[134:135], v[154:155]
	v_pk_add_f32 v[134:135], v[134:135], v[154:155] neg_lo:[0,1] neg_hi:[0,1]
	v_pk_add_f32 v[158:159], v[134:135], v[146:147] op_sel:[0,1] op_sel_hi:[1,0] neg_hi:[0,1]
	v_pk_add_f32 v[134:135], v[134:135], v[146:147] op_sel:[0,1] op_sel_hi:[1,0] neg_lo:[0,1]
	v_pk_mul_f32 v[154:155], v[142:143], s[12:13] op_sel:[1,0] op_sel_hi:[0,0] neg_lo:[1,0]
	v_pk_add_f32 v[146:147], v[150:151], v[152:153]
	v_pk_fma_f32 v[142:143], v[142:143], s[12:13], v[154:155] op_sel_hi:[1,0,1] neg_lo:[0,0,1] neg_hi:[0,0,1]
	v_pk_mul_f32 v[154:155], v[130:131], s[36:37] op_sel:[1,0] op_sel_hi:[0,0] neg_lo:[1,0]
	v_pk_add_f32 v[150:151], v[150:151], v[152:153] neg_lo:[0,1] neg_hi:[0,1]
	v_pk_fma_f32 v[130:131], v[130:131], s[22:23], v[154:155] op_sel_hi:[1,0,1] neg_lo:[0,0,1] neg_hi:[0,0,1]
	v_pk_mul_f32 v[154:155], v[156:157], s[12:13] op_sel:[1,0] op_sel_hi:[0,0] neg_lo:[1,0]
	v_pk_fma_f32 v[154:155], v[156:157], s[12:13], v[154:155] op_sel_hi:[1,0,1] neg_lo:[0,0,1] neg_hi:[0,0,1]
	v_pk_fma_f32 v[148:149], v[148:149], 0, v[148:149] op_sel:[0,0,1] op_sel_hi:[1,0,0] neg_hi:[0,0,1]
	v_pk_mul_f32 v[156:157], v[132:133], s[12:13] op_sel:[1,0] op_sel_hi:[0,0] neg_lo:[1,0]
	v_pk_fma_f32 v[132:133], v[132:133], s[18:19], v[156:157] op_sel_hi:[1,0,1] neg_lo:[0,0,1] neg_hi:[0,0,1]
	v_pk_mul_f32 v[156:157], v[158:159], s[36:37] op_sel:[1,0] op_sel_hi:[0,0] neg_lo:[1,0]
	v_pk_mul_f32 v[152:153], v[164:165], s[22:23] op_sel:[1,0] op_sel_hi:[0,0] neg_lo:[1,0]
	v_pk_fma_f32 v[156:157], v[158:159], s[22:23], v[156:157] op_sel_hi:[1,0,1] neg_lo:[0,0,1] neg_hi:[0,0,1]
	v_pk_mul_f32 v[158:159], v[150:151], s[12:13] op_sel:[1,0] op_sel_hi:[0,0] neg_lo:[1,0]
	v_pk_fma_f32 v[152:153], v[164:165], s[36:37], v[152:153] op_sel_hi:[1,0,1] neg_lo:[0,0,1] neg_hi:[0,0,1]
	v_pk_fma_f32 v[150:151], v[150:151], s[18:19], v[158:159] op_sel_hi:[1,0,1] neg_lo:[0,0,1] neg_hi:[0,0,1]
	v_xor_b32_e32 v158, 0x80000000, v135
	v_mov_b32_e32 v159, v134
	v_pk_mul_f32 v[134:135], v[134:135], s[36:37] op_sel_hi:[1,0]
	v_pk_fma_f32 v[134:135], v[158:159], s[22:23], v[134:135] op_sel_hi:[1,0,1] neg_lo:[0,0,1] neg_hi:[0,0,1]
	v_pk_add_f32 v[158:159], v[136:137], v[144:145]
	v_pk_add_f32 v[136:137], v[136:137], v[144:145] neg_lo:[0,1] neg_hi:[0,1]
	v_pk_add_f32 v[144:145], v[138:139], v[146:147]
	v_pk_add_f32 v[138:139], v[138:139], v[146:147] neg_lo:[0,1] neg_hi:[0,1]
	v_xor_b32_e32 v147, 0x80000000, v138
	v_mov_b32_e32 v146, v139
	v_pk_add_f32 v[138:139], v[158:159], v[144:145]
	v_pk_add_f32 v[164:165], v[136:137], v[146:147]
	v_pk_add_f32 v[144:145], v[158:159], v[144:145] neg_lo:[0,1] neg_hi:[0,1]
	v_pk_add_f32 v[146:147], v[136:137], v[146:147] neg_lo:[0,1] neg_hi:[0,1]
	v_pk_add_f32 v[136:137], v[166:167], v[154:155]
	v_pk_add_f32 v[158:159], v[152:153], v[156:157]
	v_pk_add_f32 v[152:153], v[152:153], v[156:157] neg_lo:[0,1] neg_hi:[0,1]
	v_pk_add_f32 v[154:155], v[166:167], v[154:155] neg_lo:[0,1] neg_hi:[0,1]
	v_xor_b32_e32 v157, 0x80000000, v152
	v_mov_b32_e32 v156, v153
	v_pk_add_f32 v[152:153], v[136:137], v[158:159]
	v_pk_add_f32 v[168:169], v[136:137], v[158:159] neg_lo:[0,1] neg_hi:[0,1]
	v_pk_add_f32 v[136:137], v[140:141], v[148:149]
	v_pk_add_f32 v[140:141], v[140:141], v[148:149] neg_lo:[0,1] neg_hi:[0,1]
	v_pk_add_f32 v[148:149], v[142:143], v[150:151]
	v_pk_add_f32 v[166:167], v[154:155], v[156:157]
	v_pk_add_f32 v[170:171], v[154:155], v[156:157] neg_lo:[0,1] neg_hi:[0,1]
	v_pk_add_f32 v[142:143], v[142:143], v[150:151] neg_lo:[0,1] neg_hi:[0,1]
	v_pk_add_f32 v[154:155], v[136:137], v[148:149]
	v_pk_add_f32 v[148:149], v[136:137], v[148:149] neg_lo:[0,1] neg_hi:[0,1]
	v_pk_add_f32 v[136:137], v[128:129], v[132:133]
	v_pk_add_f32 v[128:129], v[128:129], v[132:133] neg_lo:[0,1] neg_hi:[0,1]
	v_pk_add_f32 v[132:133], v[130:131], v[134:135]
	v_pk_add_f32 v[130:131], v[130:131], v[134:135] neg_lo:[0,1] neg_hi:[0,1]
	v_xor_b32_e32 v151, 0x80000000, v142
	v_mov_b32_e32 v150, v143
	v_xor_b32_e32 v135, 0x80000000, v130
	v_mov_b32_e32 v134, v131
	v_xor_b32_e32 v142, 0x80000000, v117
	v_mov_b32_e32 v143, v116
	v_pk_add_f32 v[172:173], v[140:141], v[150:151]
	v_pk_add_f32 v[174:175], v[140:141], v[150:151] neg_lo:[0,1] neg_hi:[0,1]
	v_pk_add_f32 v[130:131], v[136:137], v[132:133]
	v_pk_add_f32 v[150:151], v[128:129], v[134:135]
	v_pk_add_f32 v[198:199], v[136:137], v[132:133] neg_lo:[0,1] neg_hi:[0,1]
	v_pk_add_f32 v[200:201], v[128:129], v[134:135] neg_lo:[0,1] neg_hi:[0,1]
	v_pk_mul_f32 v[128:129], v[142:143], v[138:139] op_sel:[0,1]
	v_pk_mul_f32 v[132:133], v[126:127], v[152:153] op_sel:[1,1] op_sel_hi:[0,1] neg_lo:[1,0]
	v_pk_fma_f32 v[128:129], v[116:117], v[138:139], v[128:129] op_sel_hi:[1,0,1]
	v_pk_fma_f32 v[132:133], v[126:127], v[152:153], v[132:133] op_sel_hi:[1,0,1]
	ds_write2_b64 v176, v[128:129], v[132:133] offset1:17
	v_pk_mul_f32 v[128:129], v[124:125], v[154:155] op_sel:[1,1] op_sel_hi:[0,1] neg_lo:[1,0]
	v_pk_mul_f32 v[132:133], v[122:123], v[130:131] op_sel:[1,1] op_sel_hi:[0,1] neg_lo:[1,0]
	v_pk_fma_f32 v[128:129], v[124:125], v[154:155], v[128:129] op_sel_hi:[1,0,1]
	v_pk_fma_f32 v[130:131], v[122:123], v[130:131], v[132:133] op_sel_hi:[1,0,1]
	ds_write2_b64 v176, v[128:129], v[130:131] offset0:34 offset1:51
	v_pk_mul_f32 v[128:129], v[120:121], v[164:165] op_sel:[1,1] op_sel_hi:[0,1] neg_lo:[1,0]
	v_pk_mul_f32 v[130:131], v[118:119], v[166:167] op_sel:[1,1] op_sel_hi:[0,1] neg_lo:[1,0]
	v_pk_fma_f32 v[128:129], v[120:121], v[164:165], v[128:129] op_sel_hi:[1,0,1]
	v_pk_fma_f32 v[130:131], v[118:119], v[166:167], v[130:131] op_sel_hi:[1,0,1]
	ds_write2_b64 v176, v[128:129], v[130:131] offset0:68 offset1:85
	v_pk_mul_f32 v[128:129], v[114:115], v[172:173] op_sel:[1,1] op_sel_hi:[0,1] neg_lo:[1,0]
	v_pk_mul_f32 v[130:131], v[112:113], v[150:151] op_sel:[1,1] op_sel_hi:[0,1] neg_lo:[1,0]
	v_pk_fma_f32 v[128:129], v[114:115], v[172:173], v[128:129] op_sel_hi:[1,0,1]
	v_pk_fma_f32 v[130:131], v[112:113], v[150:151], v[130:131] op_sel_hi:[1,0,1]
	ds_write2_b64 v176, v[128:129], v[130:131] offset0:102 offset1:119
	v_pk_mul_f32 v[128:129], v[110:111], v[144:145] op_sel:[1,1] op_sel_hi:[0,1] neg_lo:[1,0]
	v_pk_mul_f32 v[130:131], v[108:109], v[168:169] op_sel:[1,1] op_sel_hi:[0,1] neg_lo:[1,0]
	v_pk_fma_f32 v[128:129], v[110:111], v[144:145], v[128:129] op_sel_hi:[1,0,1]
	v_pk_fma_f32 v[130:131], v[108:109], v[168:169], v[130:131] op_sel_hi:[1,0,1]
	ds_write2_b64 v176, v[128:129], v[130:131] offset0:136 offset1:153
	v_pk_mul_f32 v[128:129], v[106:107], v[148:149] op_sel:[1,1] op_sel_hi:[0,1] neg_lo:[1,0]
	v_pk_fma_f32 v[128:129], v[106:107], v[148:149], v[128:129] op_sel_hi:[1,0,1]
	v_pk_mul_f32 v[130:131], v[104:105], v[198:199] op_sel:[1,1] op_sel_hi:[0,1] neg_lo:[1,0]
	v_pk_fma_f32 v[130:131], v[104:105], v[198:199], v[130:131] op_sel_hi:[1,0,1]
	ds_write2_b64 v176, v[128:129], v[130:131] offset0:170 offset1:187
	v_pk_mul_f32 v[128:129], v[14:15], v[146:147] op_sel:[1,1] op_sel_hi:[0,1] neg_lo:[1,0]
	v_pk_fma_f32 v[128:129], v[14:15], v[146:147], v[128:129] op_sel_hi:[1,0,1]
	v_pk_mul_f32 v[144:145], v[12:13], v[170:171] op_sel:[1,1] op_sel_hi:[0,1] neg_lo:[1,0]
	v_pk_fma_f32 v[144:145], v[12:13], v[170:171], v[144:145] op_sel_hi:[1,0,1]
	ds_write2_b64 v176, v[128:129], v[144:145] offset0:204 offset1:221
	v_pk_mul_f32 v[144:145], v[10:11], v[174:175] op_sel:[1,1] op_sel_hi:[0,1] neg_lo:[1,0]
	v_pk_fma_f32 v[164:165], v[10:11], v[174:175], v[144:145] op_sel_hi:[1,0,1]
	v_pk_mul_f32 v[166:167], v[8:9], v[200:201] op_sel:[1,1] op_sel_hi:[0,1] neg_lo:[1,0]
	v_pk_fma_f32 v[166:167], v[8:9], v[200:201], v[166:167] op_sel_hi:[1,0,1]
	ds_write2_b64 v176, v[164:165], v[166:167] offset0:238 offset1:255
	s_waitcnt lgkmcnt(0)
	s_barrier
	s_nop 0
	v_and_b32_e32 v129, 0xff, v206
	v_mad_u32_u24 v129, v129, s19, v207
	ds_read2_b64 v[164:167], v129 offset1:1
	ds_read2_b64 v[168:171], v129 offset0:2 offset1:3
	ds_read2_b64 v[172:175], v129 offset0:8 offset1:9
	ds_read2_b64 v[198:201], v129 offset0:4 offset1:5
	ds_read2_b64 v[202:205], v129 offset0:6 offset1:7
	ds_read2_b64 v[232:235], v129 offset0:12 offset1:13
	ds_read2_b64 v[236:239], v129 offset0:10 offset1:11
	ds_read2_b64 v[240:243], v129 offset0:14 offset1:15
	s_waitcnt lgkmcnt(5)
	v_pk_add_f32 v[244:245], v[164:165], v[172:173]
	v_pk_add_f32 v[164:165], v[164:165], v[172:173] neg_lo:[0,1] neg_hi:[0,1]
	s_waitcnt lgkmcnt(2)
	v_pk_add_f32 v[172:173], v[198:199], v[232:233]
	v_pk_add_f32 v[198:199], v[198:199], v[232:233] neg_lo:[0,1] neg_hi:[0,1]
	v_pk_add_f32 v[246:247], v[164:165], v[198:199] op_sel:[0,1] op_sel_hi:[1,0] neg_hi:[0,1]
	v_pk_add_f32 v[164:165], v[164:165], v[198:199] op_sel:[0,1] op_sel_hi:[1,0] neg_lo:[0,1]
	v_pk_add_f32 v[232:233], v[166:167], v[174:175]
	v_pk_add_f32 v[166:167], v[166:167], v[174:175] neg_lo:[0,1] neg_hi:[0,1]
	v_pk_add_f32 v[174:175], v[200:201], v[234:235]
	v_pk_add_f32 v[200:201], v[200:201], v[234:235] neg_lo:[0,1] neg_hi:[0,1]
	v_pk_add_f32 v[198:199], v[244:245], v[172:173]
	v_pk_add_f32 v[172:173], v[244:245], v[172:173] neg_lo:[0,1] neg_hi:[0,1]
	v_pk_add_f32 v[244:245], v[166:167], v[200:201] op_sel:[0,1] op_sel_hi:[1,0] neg_hi:[0,1]
	v_pk_add_f32 v[166:167], v[166:167], v[200:201] op_sel:[0,1] op_sel_hi:[1,0] neg_lo:[0,1]
	s_waitcnt lgkmcnt(0)
	v_pk_add_f32 v[234:235], v[202:203], v[240:241]
	v_pk_add_f32 v[202:203], v[202:203], v[240:241] neg_lo:[0,1] neg_hi:[0,1]
	v_pk_add_f32 v[200:201], v[232:233], v[174:175]
	v_pk_add_f32 v[174:175], v[232:233], v[174:175] neg_lo:[0,1] neg_hi:[0,1]
	v_pk_add_f32 v[232:233], v[168:169], v[236:237]
	v_pk_add_f32 v[168:169], v[168:169], v[236:237] neg_lo:[0,1] neg_hi:[0,1]
	v_pk_add_f32 v[240:241], v[168:169], v[202:203] op_sel:[0,1] op_sel_hi:[1,0] neg_hi:[0,1]
	v_pk_add_f32 v[168:169], v[168:169], v[202:203] op_sel:[0,1] op_sel_hi:[1,0] neg_lo:[0,1]
	v_pk_add_f32 v[236:237], v[204:205], v[242:243]
	v_pk_add_f32 v[204:205], v[204:205], v[242:243] neg_lo:[0,1] neg_hi:[0,1]
	v_pk_add_f32 v[202:203], v[232:233], v[234:235]
	v_pk_add_f32 v[232:233], v[232:233], v[234:235] neg_lo:[0,1] neg_hi:[0,1]
	v_pk_add_f32 v[234:235], v[170:171], v[238:239]
	v_pk_add_f32 v[170:171], v[170:171], v[238:239] neg_lo:[0,1] neg_hi:[0,1]
	v_pk_add_f32 v[242:243], v[170:171], v[204:205] op_sel:[0,1] op_sel_hi:[1,0] neg_hi:[0,1]
	v_pk_add_f32 v[170:171], v[170:171], v[204:205] op_sel:[0,1] op_sel_hi:[1,0] neg_lo:[0,1]
	v_pk_mul_f32 v[238:239], v[174:175], s[12:13] op_sel:[1,0] op_sel_hi:[0,0] neg_lo:[1,0]
	v_pk_add_f32 v[204:205], v[234:235], v[236:237]
	v_pk_fma_f32 v[174:175], v[174:175], s[12:13], v[238:239] op_sel_hi:[1,0,1] neg_lo:[0,0,1] neg_hi:[0,0,1]
	v_pk_mul_f32 v[238:239], v[166:167], s[36:37] op_sel:[1,0] op_sel_hi:[0,0] neg_lo:[1,0]
	v_pk_add_f32 v[234:235], v[234:235], v[236:237] neg_lo:[0,1] neg_hi:[0,1]
	v_pk_fma_f32 v[166:167], v[166:167], s[22:23], v[238:239] op_sel_hi:[1,0,1] neg_lo:[0,0,1] neg_hi:[0,0,1]
	v_pk_mul_f32 v[238:239], v[240:241], s[12:13] op_sel:[1,0] op_sel_hi:[0,0] neg_lo:[1,0]
	v_pk_fma_f32 v[238:239], v[240:241], s[12:13], v[238:239] op_sel_hi:[1,0,1] neg_lo:[0,0,1] neg_hi:[0,0,1]
	v_pk_fma_f32 v[232:233], v[232:233], 0, v[232:233] op_sel:[0,0,1] op_sel_hi:[1,0,0] neg_hi:[0,0,1]
	v_pk_mul_f32 v[240:241], v[168:169], s[12:13] op_sel:[1,0] op_sel_hi:[0,0] neg_lo:[1,0]
	v_pk_fma_f32 v[168:169], v[168:169], s[18:19], v[240:241] op_sel_hi:[1,0,1] neg_lo:[0,0,1] neg_hi:[0,0,1]
	v_pk_mul_f32 v[240:241], v[242:243], s[36:37] op_sel:[1,0] op_sel_hi:[0,0] neg_lo:[1,0]
	v_pk_mul_f32 v[236:237], v[244:245], s[22:23] op_sel:[1,0] op_sel_hi:[0,0] neg_lo:[1,0]
	v_pk_fma_f32 v[240:241], v[242:243], s[22:23], v[240:241] op_sel_hi:[1,0,1] neg_lo:[0,0,1] neg_hi:[0,0,1]
	v_pk_mul_f32 v[242:243], v[234:235], s[12:13] op_sel:[1,0] op_sel_hi:[0,0] neg_lo:[1,0]
	v_pk_fma_f32 v[236:237], v[244:245], s[36:37], v[236:237] op_sel_hi:[1,0,1] neg_lo:[0,0,1] neg_hi:[0,0,1]
	v_pk_fma_f32 v[234:235], v[234:235], s[18:19], v[242:243] op_sel_hi:[1,0,1] neg_lo:[0,0,1] neg_hi:[0,0,1]
	v_xor_b32_e32 v242, 0x80000000, v171
	v_mov_b32_e32 v243, v170
	v_pk_mul_f32 v[170:171], v[170:171], s[36:37] op_sel_hi:[1,0]
	v_pk_fma_f32 v[170:171], v[242:243], s[22:23], v[170:171] op_sel_hi:[1,0,1] neg_lo:[0,0,1] neg_hi:[0,0,1]
	v_pk_add_f32 v[242:243], v[198:199], v[202:203]
	v_pk_add_f32 v[198:199], v[198:199], v[202:203] neg_lo:[0,1] neg_hi:[0,1]
	v_pk_add_f32 v[202:203], v[200:201], v[204:205]
	v_pk_add_f32 v[200:201], v[200:201], v[204:205] neg_lo:[0,1] neg_hi:[0,1]
	v_xor_b32_e32 v205, 0x80000000, v200
	v_mov_b32_e32 v204, v201
	v_pk_add_f32 v[200:201], v[242:243], v[202:203]
	v_pk_add_f32 v[202:203], v[242:243], v[202:203] neg_lo:[0,1] neg_hi:[0,1]
	v_pk_add_f32 v[242:243], v[236:237], v[240:241]
	v_pk_add_f32 v[236:237], v[236:237], v[240:241] neg_lo:[0,1] neg_hi:[0,1]
	v_pk_add_f32 v[244:245], v[198:199], v[204:205]
	v_pk_add_f32 v[198:199], v[198:199], v[204:205] neg_lo:[0,1] neg_hi:[0,1]
	v_pk_add_f32 v[204:205], v[246:247], v[238:239]
	v_pk_add_f32 v[238:239], v[246:247], v[238:239] neg_lo:[0,1] neg_hi:[0,1]
	v_pk_add_f32 v[246:247], v[238:239], v[236:237] op_sel:[0,1] op_sel_hi:[1,0] neg_hi:[0,1]
	v_pk_add_f32 v[238:239], v[238:239], v[236:237] op_sel:[0,1] op_sel_hi:[1,0] neg_lo:[0,1]
	v_pk_add_f32 v[240:241], v[172:173], v[232:233]
	v_pk_add_f32 v[172:173], v[172:173], v[232:233] neg_lo:[0,1] neg_hi:[0,1]
	v_pk_add_f32 v[232:233], v[174:175], v[234:235]
	v_pk_add_f32 v[174:175], v[174:175], v[234:235] neg_lo:[0,1] neg_hi:[0,1]
	v_pk_add_f32 v[236:237], v[204:205], v[242:243]
	v_pk_add_f32 v[204:205], v[204:205], v[242:243] neg_lo:[0,1] neg_hi:[0,1]
	v_pk_add_f32 v[242:243], v[172:173], v[174:175] op_sel:[0,1] op_sel_hi:[1,0] neg_hi:[0,1]
	v_pk_add_f32 v[172:173], v[172:173], v[174:175] op_sel:[0,1] op_sel_hi:[1,0] neg_lo:[0,1]
	v_pk_add_f32 v[234:235], v[164:165], v[168:169]
	v_pk_add_f32 v[164:165], v[164:165], v[168:169] neg_lo:[0,1] neg_hi:[0,1]
	v_pk_add_f32 v[168:169], v[166:167], v[170:171]
	v_pk_add_f32 v[166:167], v[166:167], v[170:171] neg_lo:[0,1] neg_hi:[0,1]
	v_pk_add_f32 v[174:175], v[240:241], v[232:233]
	v_pk_add_f32 v[232:233], v[240:241], v[232:233] neg_lo:[0,1] neg_hi:[0,1]
	v_pk_add_f32 v[240:241], v[164:165], v[166:167] op_sel:[0,1] op_sel_hi:[1,0] neg_hi:[0,1]
	v_pk_add_f32 v[164:165], v[164:165], v[166:167] op_sel:[0,1] op_sel_hi:[1,0] neg_lo:[0,1]
	v_pk_mul_f32 v[170:171], v[66:67], v[200:201] op_sel:[0,1]
	v_pk_add_f32 v[166:167], v[234:235], v[168:169]
	v_pk_fma_f32 v[170:171], v[16:17], v[200:201], v[170:171] op_sel_hi:[1,0,1]
	v_pk_mul_f32 v[200:201], v[68:69], v[244:245] op_sel:[0,1]
	v_pk_add_f32 v[168:169], v[234:235], v[168:169] neg_lo:[0,1] neg_hi:[0,1]
	v_pk_fma_f32 v[200:201], v[18:19], v[244:245], v[200:201] op_sel_hi:[1,0,1]
	v_pk_mul_f32 v[244:245], v[78:79], v[204:205] op_sel:[0,1]
	v_pk_mul_f32 v[234:235], v[70:71], v[202:203] op_sel:[0,1]
	v_pk_fma_f32 v[204:205], v[46:47], v[204:205], v[244:245] op_sel_hi:[1,0,1]
	v_pk_mul_f32 v[244:245], v[80:81], v[238:239] op_sel:[0,1]
	v_pk_fma_f32 v[202:203], v[20:21], v[202:203], v[234:235] op_sel_hi:[1,0,1]
	v_pk_fma_f32 v[238:239], v[48:49], v[238:239], v[244:245] op_sel_hi:[1,0,1]
	v_pk_mul_f32 v[244:245], v[82:83], v[174:175] op_sel:[0,1]
	v_pk_mul_f32 v[234:235], v[72:73], v[198:199] op_sel:[0,1]
	v_pk_fma_f32 v[174:175], v[50:51], v[174:175], v[244:245] op_sel_hi:[1,0,1]
	v_pk_mul_f32 v[244:245], v[84:85], v[242:243] op_sel:[0,1]
	v_pk_fma_f32 v[198:199], v[22:23], v[198:199], v[234:235] op_sel_hi:[1,0,1]
	v_pk_fma_f32 v[242:243], v[52:53], v[242:243], v[244:245] op_sel_hi:[1,0,1]
	v_pk_mul_f32 v[244:245], v[86:87], v[232:233] op_sel:[0,1]
	v_pk_mul_f32 v[234:235], v[74:75], v[236:237] op_sel:[0,1]
	v_pk_fma_f32 v[232:233], v[54:55], v[232:233], v[244:245] op_sel_hi:[1,0,1]
	v_pk_mul_f32 v[244:245], v[88:89], v[172:173] op_sel:[0,1]
	v_pk_fma_f32 v[234:235], v[42:43], v[236:237], v[234:235] op_sel_hi:[1,0,1]
	v_pk_fma_f32 v[172:173], v[56:57], v[172:173], v[244:245] op_sel_hi:[1,0,1]
	v_pk_mul_f32 v[244:245], v[90:91], v[166:167] op_sel:[0,1]
	v_pk_mul_f32 v[236:237], v[76:77], v[246:247] op_sel:[0,1]
	v_pk_fma_f32 v[166:167], v[58:59], v[166:167], v[244:245] op_sel_hi:[1,0,1]
	v_pk_mul_f32 v[244:245], v[92:93], v[240:241] op_sel:[0,1]
	v_pk_fma_f32 v[236:237], v[44:45], v[246:247], v[236:237] op_sel_hi:[1,0,1]
	v_pk_fma_f32 v[240:241], v[60:61], v[240:241], v[244:245] op_sel_hi:[1,0,1]
	v_pk_mul_f32 v[244:245], v[94:95], v[168:169] op_sel:[0,1]
	v_pk_fma_f32 v[168:169], v[62:63], v[168:169], v[244:245] op_sel_hi:[1,0,1]
	v_pk_mul_f32 v[244:245], v[96:97], v[164:165] op_sel:[0,1]
	v_pk_fma_f32 v[164:165], v[64:65], v[164:165], v[244:245] op_sel_hi:[1,0,1]
	v_pk_add_f32 v[244:245], v[170:171], v[202:203]
	v_pk_add_f32 v[170:171], v[170:171], v[202:203] neg_lo:[0,1] neg_hi:[0,1]
	v_pk_add_f32 v[202:203], v[200:201], v[198:199]
	v_pk_add_f32 v[198:199], v[200:201], v[198:199] neg_lo:[0,1] neg_hi:[0,1]
	v_pk_add_f32 v[246:247], v[170:171], v[198:199] op_sel:[0,1] op_sel_hi:[1,0] neg_lo:[0,1]
	v_pk_add_f32 v[170:171], v[170:171], v[198:199] op_sel:[0,1] op_sel_hi:[1,0] neg_hi:[0,1]
	v_pk_add_f32 v[200:201], v[234:235], v[204:205]
	v_pk_add_f32 v[204:205], v[234:235], v[204:205] neg_lo:[0,1] neg_hi:[0,1]
	v_pk_add_f32 v[234:235], v[236:237], v[238:239]
	v_pk_add_f32 v[236:237], v[236:237], v[238:239] neg_lo:[0,1] neg_hi:[0,1]
	v_pk_add_f32 v[198:199], v[244:245], v[202:203]
	v_xor_b32_e32 v238, 0x80000000, v237
	v_mov_b32_e32 v239, v236
	v_pk_add_f32 v[236:237], v[200:201], v[234:235]
	v_pk_add_f32 v[200:201], v[200:201], v[234:235] neg_lo:[0,1] neg_hi:[0,1]
	v_pk_add_f32 v[234:235], v[174:175], v[232:233]
	v_pk_add_f32 v[174:175], v[174:175], v[232:233] neg_lo:[0,1] neg_hi:[0,1]
	v_pk_add_f32 v[232:233], v[242:243], v[172:173]
	v_pk_add_f32 v[172:173], v[242:243], v[172:173] neg_lo:[0,1] neg_hi:[0,1]
	v_pk_add_f32 v[202:203], v[244:245], v[202:203] neg_lo:[0,1] neg_hi:[0,1]
	v_pk_add_f32 v[244:245], v[204:205], v[238:239]
	v_pk_add_f32 v[204:205], v[204:205], v[238:239] neg_lo:[0,1] neg_hi:[0,1]
	v_xor_b32_e32 v238, 0x80000000, v173
	v_mov_b32_e32 v239, v172
	v_pk_add_f32 v[172:173], v[234:235], v[232:233]
	v_pk_add_f32 v[232:233], v[234:235], v[232:233] neg_lo:[0,1] neg_hi:[0,1]
	v_pk_add_f32 v[234:235], v[166:167], v[168:169]
	v_pk_add_f32 v[166:167], v[166:167], v[168:169] neg_lo:[0,1] neg_hi:[0,1]
	v_pk_add_f32 v[168:169], v[240:241], v[164:165]
	v_pk_add_f32 v[164:165], v[240:241], v[164:165] neg_lo:[0,1] neg_hi:[0,1]
	v_pk_add_f32 v[242:243], v[174:175], v[238:239]
	v_pk_add_f32 v[174:175], v[174:175], v[238:239] neg_lo:[0,1] neg_hi:[0,1]
	v_pk_add_f32 v[240:241], v[166:167], v[164:165] op_sel:[0,1] op_sel_hi:[1,0] neg_lo:[0,1]
	v_pk_add_f32 v[166:167], v[166:167], v[164:165] op_sel:[0,1] op_sel_hi:[1,0] neg_hi:[0,1]
	v_pk_mul_f32 v[238:239], v[200:201], s[12:13] op_sel:[1,0] op_sel_hi:[0,0] neg_lo:[1,0]
	v_pk_add_f32 v[164:165], v[234:235], v[168:169]
	v_pk_fma_f32 v[200:201], v[200:201], s[12:13], v[238:239] op_sel_hi:[1,0,1]
	v_pk_mul_f32 v[238:239], v[204:205], s[36:37] op_sel:[1,0] op_sel_hi:[0,0] neg_lo:[1,0]
	v_pk_add_f32 v[168:169], v[234:235], v[168:169] neg_lo:[0,1] neg_hi:[0,1]
	v_pk_fma_f32 v[204:205], v[204:205], s[22:23], v[238:239] op_sel_hi:[1,0,1]
	v_pk_mul_f32 v[238:239], v[242:243], s[12:13] op_sel:[1,0] op_sel_hi:[0,0] neg_lo:[1,0]
	v_pk_fma_f32 v[238:239], v[242:243], s[12:13], v[238:239] op_sel_hi:[1,0,1]
	v_pk_fma_f32 v[232:233], v[232:233], 0, v[232:233] op_sel:[0,0,1] op_sel_hi:[1,0,0] neg_lo:[0,0,1]
	v_xor_b32_e32 v242, 0x80000000, v175
	v_mov_b32_e32 v243, v174
	v_pk_mul_f32 v[174:175], v[174:175], s[12:13] op_sel_hi:[1,0]
	v_pk_fma_f32 v[174:175], v[242:243], s[12:13], v[174:175] op_sel_hi:[1,0,1] neg_lo:[0,0,1] neg_hi:[0,0,1]
	v_pk_mul_f32 v[242:243], v[240:241], s[36:37] op_sel:[1,0] op_sel_hi:[0,0] neg_lo:[1,0]
	v_pk_mul_f32 v[234:235], v[244:245], s[22:23] op_sel:[1,0] op_sel_hi:[0,0] neg_lo:[1,0]
	v_pk_fma_f32 v[240:241], v[240:241], s[22:23], v[242:243] op_sel_hi:[1,0,1]
	v_xor_b32_e32 v242, 0x80000000, v169
	v_mov_b32_e32 v243, v168
	v_pk_mul_f32 v[168:169], v[168:169], s[12:13] op_sel_hi:[1,0]
	v_pk_fma_f32 v[234:235], v[244:245], s[36:37], v[234:235] op_sel_hi:[1,0,1]
	v_pk_fma_f32 v[168:169], v[242:243], s[12:13], v[168:169] op_sel_hi:[1,0,1] neg_lo:[0,0,1] neg_hi:[0,0,1]
	v_pk_mul_f32 v[242:243], v[166:167], s[22:23] op_sel:[1,0] op_sel_hi:[0,0] neg_lo:[1,0]
	v_pk_fma_f32 v[166:167], v[166:167], s[26:27], v[242:243] op_sel_hi:[1,0,1] neg_lo:[0,0,1] neg_hi:[0,0,1]
	v_pk_add_f32 v[242:243], v[198:199], v[172:173]
	v_pk_add_f32 v[172:173], v[198:199], v[172:173] neg_lo:[0,1] neg_hi:[0,1]
	v_pk_add_f32 v[198:199], v[236:237], v[164:165]
	v_pk_add_f32 v[164:165], v[236:237], v[164:165] neg_lo:[0,1] neg_hi:[0,1]
	v_xor_b32_e32 v236, 0x80000000, v165
	v_mov_b32_e32 v237, v164
	v_pk_add_f32 v[164:165], v[242:243], v[198:199]
	v_pk_add_f32 v[198:199], v[242:243], v[198:199] neg_lo:[0,1] neg_hi:[0,1]
	v_pk_add_f32 v[242:243], v[234:235], v[240:241]
	v_pk_add_f32 v[234:235], v[234:235], v[240:241] neg_lo:[0,1] neg_hi:[0,1]
	v_pk_add_f32 v[244:245], v[172:173], v[236:237]
	v_pk_add_f32 v[172:173], v[172:173], v[236:237] neg_lo:[0,1] neg_hi:[0,1]
	v_pk_add_f32 v[236:237], v[246:247], v[238:239]
	v_pk_add_f32 v[238:239], v[246:247], v[238:239] neg_lo:[0,1] neg_hi:[0,1]
	v_pk_add_f32 v[246:247], v[238:239], v[234:235] op_sel:[0,1] op_sel_hi:[1,0] neg_lo:[0,1]
	v_pk_add_f32 v[238:239], v[238:239], v[234:235] op_sel:[0,1] op_sel_hi:[1,0] neg_hi:[0,1]
	v_pk_add_f32 v[240:241], v[202:203], v[232:233]
	v_pk_add_f32 v[202:203], v[202:203], v[232:233] neg_lo:[0,1] neg_hi:[0,1]
	v_pk_add_f32 v[232:233], v[200:201], v[168:169]
	v_pk_add_f32 v[168:169], v[200:201], v[168:169] neg_lo:[0,1] neg_hi:[0,1]
	v_pk_add_f32 v[234:235], v[236:237], v[242:243]
	v_pk_add_f32 v[236:237], v[236:237], v[242:243] neg_lo:[0,1] neg_hi:[0,1]
	v_pk_add_f32 v[242:243], v[202:203], v[168:169] op_sel:[0,1] op_sel_hi:[1,0] neg_lo:[0,1]
	v_pk_add_f32 v[200:201], v[202:203], v[168:169] op_sel:[0,1] op_sel_hi:[1,0] neg_hi:[0,1]
	v_pk_add_f32 v[202:203], v[170:171], v[174:175]
	v_pk_add_f32 v[170:171], v[170:171], v[174:175] neg_lo:[0,1] neg_hi:[0,1]
	v_pk_add_f32 v[174:175], v[204:205], v[166:167]
	v_pk_add_f32 v[166:167], v[204:205], v[166:167] neg_lo:[0,1] neg_hi:[0,1]
	v_pk_add_f32 v[168:169], v[240:241], v[232:233]
	v_xor_b32_e32 v204, 0x80000000, v167
	v_mov_b32_e32 v205, v166
	v_pk_add_f32 v[166:167], v[202:203], v[174:175]
	v_pk_add_f32 v[174:175], v[202:203], v[174:175] neg_lo:[0,1] neg_hi:[0,1]
	v_mov_b32_e32 v202, v116
	v_mov_b32_e32 v203, v142
	v_pk_mul_f32 v[142:143], v[202:203], v[164:165] op_sel_hi:[1,0]
	v_pk_add_f32 v[232:233], v[240:241], v[232:233] neg_lo:[0,1] neg_hi:[0,1]
	v_pk_fma_f32 v[116:117], v[116:117], v[164:165], v[142:143] op_sel:[1,1,0] op_sel_hi:[0,1,1]
	v_pk_mul_f32 v[142:143], v[126:127], v[234:235] op_sel_hi:[1,0] neg_hi:[1,0]
	v_pk_add_f32 v[240:241], v[170:171], v[204:205]
	v_pk_fma_f32 v[126:127], v[126:127], v[234:235], v[142:143] op_sel:[1,1,0] op_sel_hi:[0,1,1]
	ds_write2_b64 v129, v[116:117], v[126:127] offset1:1
	v_pk_mul_f32 v[116:117], v[124:125], v[168:169] op_sel_hi:[1,0] neg_hi:[1,0]
	v_pk_add_f32 v[170:171], v[170:171], v[204:205] neg_lo:[0,1] neg_hi:[0,1]
	v_pk_fma_f32 v[116:117], v[124:125], v[168:169], v[116:117] op_sel:[1,1,0] op_sel_hi:[0,1,1]
	v_pk_mul_f32 v[124:125], v[122:123], v[166:167] op_sel_hi:[1,0] neg_hi:[1,0]
	v_pk_fma_f32 v[122:123], v[122:123], v[166:167], v[124:125] op_sel:[1,1,0] op_sel_hi:[0,1,1]
	ds_write2_b64 v129, v[116:117], v[122:123] offset0:2 offset1:3
	v_pk_mul_f32 v[116:117], v[120:121], v[244:245] op_sel_hi:[1,0] neg_hi:[1,0]
	v_pk_fma_f32 v[116:117], v[120:121], v[244:245], v[116:117] op_sel:[1,1,0] op_sel_hi:[0,1,1]
	v_pk_mul_f32 v[120:121], v[118:119], v[246:247] op_sel_hi:[1,0] neg_hi:[1,0]
	v_pk_fma_f32 v[118:119], v[118:119], v[246:247], v[120:121] op_sel:[1,1,0] op_sel_hi:[0,1,1]
	ds_write2_b64 v129, v[116:117], v[118:119] offset0:4 offset1:5
	v_pk_mul_f32 v[116:117], v[114:115], v[242:243] op_sel_hi:[1,0] neg_hi:[1,0]
	v_pk_fma_f32 v[114:115], v[114:115], v[242:243], v[116:117] op_sel:[1,1,0] op_sel_hi:[0,1,1]
	v_pk_mul_f32 v[116:117], v[112:113], v[240:241] op_sel_hi:[1,0] neg_hi:[1,0]
	v_pk_fma_f32 v[112:113], v[112:113], v[240:241], v[116:117] op_sel:[1,1,0] op_sel_hi:[0,1,1]
	ds_write2_b64 v129, v[114:115], v[112:113] offset0:6 offset1:7
	v_pk_mul_f32 v[112:113], v[110:111], v[198:199] op_sel_hi:[1,0] neg_hi:[1,0]
	v_pk_fma_f32 v[110:111], v[110:111], v[198:199], v[112:113] op_sel:[1,1,0] op_sel_hi:[0,1,1]
	v_pk_mul_f32 v[112:113], v[108:109], v[236:237] op_sel_hi:[1,0] neg_hi:[1,0]
	v_pk_fma_f32 v[108:109], v[108:109], v[236:237], v[112:113] op_sel:[1,1,0] op_sel_hi:[0,1,1]
	ds_write2_b64 v129, v[110:111], v[108:109] offset0:8 offset1:9
	v_pk_mul_f32 v[108:109], v[106:107], v[232:233] op_sel_hi:[1,0] neg_hi:[1,0]
	v_pk_fma_f32 v[106:107], v[106:107], v[232:233], v[108:109] op_sel:[1,1,0] op_sel_hi:[0,1,1]
	v_pk_mul_f32 v[108:109], v[104:105], v[174:175] op_sel_hi:[1,0] neg_hi:[1,0]
	v_pk_fma_f32 v[104:105], v[104:105], v[174:175], v[108:109] op_sel:[1,1,0] op_sel_hi:[0,1,1]
	ds_write2_b64 v129, v[106:107], v[104:105] offset0:10 offset1:11
	v_pk_mul_f32 v[104:105], v[14:15], v[172:173] op_sel_hi:[1,0] neg_hi:[1,0]
	v_pk_fma_f32 v[14:15], v[14:15], v[172:173], v[104:105] op_sel:[1,1,0] op_sel_hi:[0,1,1]
	v_pk_mul_f32 v[104:105], v[12:13], v[238:239] op_sel_hi:[1,0] neg_hi:[1,0]
	v_pk_fma_f32 v[12:13], v[12:13], v[238:239], v[104:105] op_sel:[1,1,0] op_sel_hi:[0,1,1]
	ds_write2_b64 v129, v[14:15], v[12:13] offset0:12 offset1:13
	v_pk_mul_f32 v[12:13], v[10:11], v[200:201] op_sel_hi:[1,0] neg_hi:[1,0]
	v_pk_fma_f32 v[10:11], v[10:11], v[200:201], v[12:13] op_sel:[1,1,0] op_sel_hi:[0,1,1]
	v_pk_mul_f32 v[12:13], v[8:9], v[170:171] op_sel_hi:[1,0] neg_hi:[1,0]
	v_pk_fma_f32 v[8:9], v[8:9], v[170:171], v[12:13] op_sel:[1,1,0] op_sel_hi:[0,1,1]
	ds_write2_b64 v129, v[10:11], v[8:9] offset0:14 offset1:15
	v_mov_b32_e32 v8, v217
	v_mov_b32_e32 v9, v218
	v_mov_b32_e32 v138, v215
	v_xor_b32_e32 v12, 0x80000000, v9
	v_mov_b32_e32 v13, v8
	v_pk_mul_f32 v[10:11], v[12:13], v[218:219] op_sel_hi:[1,0]
	v_mov_b32_e32 v139, v216
	v_pk_fma_f32 v[10:11], v[216:217], v[8:9], v[10:11] op_sel:[1,0,0]
	v_pk_mul_f32 v[104:105], v[10:11], v[10:11] op_sel:[1,1] op_sel_hi:[1,0] neg_lo:[0,1]
	v_pk_mul_f32 v[12:13], v[12:13], v[216:217] op_sel_hi:[1,0]
	v_pk_fma_f32 v[104:105], v[10:11], v[10:11], v[104:105] op_sel_hi:[1,0,1]
	v_pk_fma_f32 v[140:141], v[8:9], v[214:215], v[12:13] op_sel:[0,1,0]
	v_pk_mul_f32 v[8:9], v[216:217], v[10:11] op_sel:[0,1] op_sel_hi:[0,0] neg_lo:[0,1]
	v_pk_fma_f32 v[142:143], v[214:215], v[10:11], v[8:9] op_sel:[1,0,0]
	v_pk_mul_f32 v[8:9], v[140:141], v[10:11] op_sel:[1,1] op_sel_hi:[1,0] neg_lo:[0,1]
	v_pk_mul_f32 v[108:109], v[104:105], v[104:105] op_sel:[1,1] op_sel_hi:[1,0] neg_lo:[0,1]
	v_pk_fma_f32 v[144:145], v[10:11], v[140:141], v[8:9] op_sel_hi:[1,0,1]
	v_pk_mul_f32 v[8:9], v[216:217], v[104:105] op_sel:[0,1] op_sel_hi:[0,0] neg_lo:[0,1]
	v_pk_fma_f32 v[146:147], v[214:215], v[104:105], v[8:9] op_sel:[1,0,0]
	v_pk_mul_f32 v[8:9], v[140:141], v[104:105] op_sel:[1,1] op_sel_hi:[1,0] neg_lo:[0,1]
	s_waitcnt lgkmcnt(0)
	v_pk_fma_f32 v[148:149], v[140:141], v[104:105], v[8:9] op_sel_hi:[0,1,1]
	v_pk_mul_f32 v[8:9], v[142:143], v[104:105] op_sel:[1,1] op_sel_hi:[1,0] neg_lo:[0,1]
	s_barrier
	v_pk_fma_f32 v[150:151], v[104:105], v[142:143], v[8:9] op_sel_hi:[1,0,1]
	v_pk_mul_f32 v[8:9], v[144:145], v[104:105] op_sel:[1,1] op_sel_hi:[1,0] neg_lo:[0,1]
	v_pk_fma_f32 v[152:153], v[104:105], v[144:145], v[8:9] op_sel_hi:[1,0,1]
	v_pk_fma_f32 v[8:9], v[104:105], v[104:105], v[108:109] op_sel_hi:[1,0,1]
	v_pk_mul_f32 v[10:11], v[216:217], v[8:9] op_sel:[0,1] op_sel_hi:[0,0] neg_lo:[0,1]
	v_pk_fma_f32 v[154:155], v[214:215], v[8:9], v[10:11] op_sel:[1,0,0]
	v_pk_mul_f32 v[10:11], v[140:141], v[8:9] op_sel:[1,1] op_sel_hi:[1,0] neg_lo:[0,1]
	v_pk_fma_f32 v[156:157], v[140:141], v[8:9], v[10:11] op_sel_hi:[0,1,1]
	v_pk_mul_f32 v[10:11], v[142:143], v[8:9] op_sel:[1,1] op_sel_hi:[1,0] neg_lo:[0,1]
	v_pk_fma_f32 v[158:159], v[142:143], v[8:9], v[10:11] op_sel_hi:[0,1,1]
	v_pk_mul_f32 v[10:11], v[144:145], v[8:9] op_sel:[1,1] op_sel_hi:[1,0] neg_lo:[0,1]
	v_pk_fma_f32 v[104:105], v[144:145], v[8:9], v[10:11] op_sel_hi:[0,1,1]
	v_pk_mul_f32 v[10:11], v[146:147], v[8:9] op_sel:[1,1] op_sel_hi:[1,0] neg_lo:[0,1]
	v_pk_fma_f32 v[14:15], v[8:9], v[146:147], v[10:11] op_sel_hi:[1,0,1]
	v_pk_mul_f32 v[10:11], v[148:149], v[8:9] op_sel:[1,1] op_sel_hi:[1,0] neg_lo:[0,1]
	v_pk_fma_f32 v[12:13], v[8:9], v[148:149], v[10:11] op_sel_hi:[1,0,1]
	v_pk_mul_f32 v[10:11], v[150:151], v[8:9] op_sel:[1,1] op_sel_hi:[1,0] neg_lo:[0,1]
	v_pk_mul_f32 v[106:107], v[152:153], v[8:9] op_sel:[1,1] op_sel_hi:[1,0] neg_lo:[0,1]
	v_pk_fma_f32 v[10:11], v[8:9], v[150:151], v[10:11] op_sel_hi:[1,0,1]
	v_pk_fma_f32 v[8:9], v[8:9], v[152:153], v[106:107] op_sel_hi:[1,0,1]
	s_nop 0
	v_bfe_u32 v107, v206, 4, 4
	v_and_b32_e32 v106, 15, v206
	v_mul_u32_u24_e32 v107, 0x880, v107
	v_lshlrev_b32_e32 v106, 3, v106
	v_add3_u32 v168, v207, v107, v106
	ds_read2_b64 v[106:109], v168 offset1:17
	ds_read2_b64 v[110:113], v168 offset0:34 offset1:51
	ds_read2_b64 v[114:117], v168 offset0:68 offset1:85
	ds_read2_b64 v[118:121], v168 offset0:136 offset1:153
	ds_read2_b64 v[122:125], v168 offset0:102 offset1:119
	ds_read2_b64 v[126:129], v168 offset0:204 offset1:221
	ds_read2_b64 v[130:133], v168 offset0:170 offset1:187
	ds_read2_b64 v[134:137], v168 offset0:238 offset1:255
	s_waitcnt lgkmcnt(4)
	v_pk_add_f32 v[164:165], v[106:107], v[118:119]
	v_pk_add_f32 v[106:107], v[106:107], v[118:119] neg_lo:[0,1] neg_hi:[0,1]
	s_waitcnt lgkmcnt(2)
	v_pk_add_f32 v[118:119], v[114:115], v[126:127]
	v_pk_add_f32 v[114:115], v[114:115], v[126:127] neg_lo:[0,1] neg_hi:[0,1]
	v_pk_add_f32 v[166:167], v[106:107], v[114:115] op_sel:[0,1] op_sel_hi:[1,0] neg_lo:[0,1]
	v_pk_add_f32 v[106:107], v[106:107], v[114:115] op_sel:[0,1] op_sel_hi:[1,0] neg_hi:[0,1]
	v_pk_add_f32 v[126:127], v[108:109], v[120:121]
	v_pk_add_f32 v[108:109], v[108:109], v[120:121] neg_lo:[0,1] neg_hi:[0,1]
	v_pk_add_f32 v[120:121], v[116:117], v[128:129]
	v_pk_add_f32 v[116:117], v[116:117], v[128:129] neg_lo:[0,1] neg_hi:[0,1]
	v_pk_add_f32 v[114:115], v[164:165], v[118:119]
	v_pk_add_f32 v[118:119], v[164:165], v[118:119] neg_lo:[0,1] neg_hi:[0,1]
	v_pk_add_f32 v[164:165], v[108:109], v[116:117] op_sel:[0,1] op_sel_hi:[1,0] neg_lo:[0,1]
	v_pk_add_f32 v[108:109], v[108:109], v[116:117] op_sel:[0,1] op_sel_hi:[1,0] neg_hi:[0,1]
	s_waitcnt lgkmcnt(0)
	v_pk_add_f32 v[128:129], v[122:123], v[134:135]
	v_pk_add_f32 v[122:123], v[122:123], v[134:135] neg_lo:[0,1] neg_hi:[0,1]
	v_pk_add_f32 v[116:117], v[126:127], v[120:121]
	v_pk_add_f32 v[120:121], v[126:127], v[120:121] neg_lo:[0,1] neg_hi:[0,1]
	v_pk_add_f32 v[126:127], v[110:111], v[130:131]
	v_pk_add_f32 v[110:111], v[110:111], v[130:131] neg_lo:[0,1] neg_hi:[0,1]
	v_pk_add_f32 v[134:135], v[110:111], v[122:123] op_sel:[0,1] op_sel_hi:[1,0] neg_lo:[0,1]
	v_pk_add_f32 v[110:111], v[110:111], v[122:123] op_sel:[0,1] op_sel_hi:[1,0] neg_hi:[0,1]
	v_pk_add_f32 v[130:131], v[124:125], v[136:137]
	v_pk_add_f32 v[124:125], v[124:125], v[136:137] neg_lo:[0,1] neg_hi:[0,1]
	v_pk_add_f32 v[122:123], v[126:127], v[128:129]
	v_pk_add_f32 v[126:127], v[126:127], v[128:129] neg_lo:[0,1] neg_hi:[0,1]
	v_pk_add_f32 v[128:129], v[112:113], v[132:133]
	v_pk_add_f32 v[112:113], v[112:113], v[132:133] neg_lo:[0,1] neg_hi:[0,1]
	v_pk_add_f32 v[136:137], v[112:113], v[124:125] op_sel:[0,1] op_sel_hi:[1,0] neg_lo:[0,1]
	v_pk_add_f32 v[112:113], v[112:113], v[124:125] op_sel:[0,1] op_sel_hi:[1,0] neg_hi:[0,1]
	v_pk_mul_f32 v[132:133], v[120:121], s[12:13] op_sel:[1,0] op_sel_hi:[0,0] neg_lo:[1,0]
	v_pk_add_f32 v[124:125], v[128:129], v[130:131]
	v_pk_fma_f32 v[120:121], v[120:121], s[12:13], v[132:133] op_sel_hi:[1,0,1]
	v_pk_mul_f32 v[132:133], v[108:109], s[36:37] op_sel:[1,0] op_sel_hi:[0,0] neg_lo:[1,0]
	v_pk_add_f32 v[128:129], v[128:129], v[130:131] neg_lo:[0,1] neg_hi:[0,1]
	v_pk_fma_f32 v[108:109], v[108:109], s[22:23], v[132:133] op_sel_hi:[1,0,1]
	v_pk_mul_f32 v[132:133], v[134:135], s[12:13] op_sel:[1,0] op_sel_hi:[0,0] neg_lo:[1,0]
	v_pk_fma_f32 v[132:133], v[134:135], s[12:13], v[132:133] op_sel_hi:[1,0,1]
	v_pk_fma_f32 v[126:127], v[126:127], 0, v[126:127] op_sel:[0,0,1] op_sel_hi:[1,0,0] neg_lo:[0,0,1]
	v_xor_b32_e32 v134, 0x80000000, v111
	v_mov_b32_e32 v135, v110
	v_pk_mul_f32 v[110:111], v[110:111], s[12:13] op_sel_hi:[1,0]
	v_pk_fma_f32 v[110:111], v[134:135], s[12:13], v[110:111] op_sel_hi:[1,0,1] neg_lo:[0,0,1] neg_hi:[0,0,1]
	v_pk_mul_f32 v[134:135], v[136:137], s[36:37] op_sel:[1,0] op_sel_hi:[0,0] neg_lo:[1,0]
	v_pk_mul_f32 v[130:131], v[164:165], s[22:23] op_sel:[1,0] op_sel_hi:[0,0] neg_lo:[1,0]
	v_pk_fma_f32 v[134:135], v[136:137], s[22:23], v[134:135] op_sel_hi:[1,0,1]
	v_xor_b32_e32 v136, 0x80000000, v129
	v_mov_b32_e32 v137, v128
	v_pk_mul_f32 v[128:129], v[128:129], s[12:13] op_sel_hi:[1,0]
	v_pk_fma_f32 v[130:131], v[164:165], s[36:37], v[130:131] op_sel_hi:[1,0,1]
	v_pk_fma_f32 v[128:129], v[136:137], s[12:13], v[128:129] op_sel_hi:[1,0,1] neg_lo:[0,0,1] neg_hi:[0,0,1]
	v_pk_mul_f32 v[136:137], v[112:113], s[22:23] op_sel:[1,0] op_sel_hi:[0,0] neg_lo:[1,0]
	v_pk_fma_f32 v[112:113], v[112:113], s[26:27], v[136:137] op_sel_hi:[1,0,1] neg_lo:[0,0,1] neg_hi:[0,0,1]
	v_pk_add_f32 v[136:137], v[114:115], v[122:123]
	v_pk_add_f32 v[114:115], v[114:115], v[122:123] neg_lo:[0,1] neg_hi:[0,1]
	v_pk_add_f32 v[122:123], v[116:117], v[124:125]
	v_pk_add_f32 v[116:117], v[116:117], v[124:125] neg_lo:[0,1] neg_hi:[0,1]
	v_xor_b32_e32 v124, 0x80000000, v117
	v_mov_b32_e32 v125, v116
	v_pk_add_f32 v[116:117], v[136:137], v[122:123]
	v_pk_add_f32 v[122:123], v[136:137], v[122:123] neg_lo:[0,1] neg_hi:[0,1]
	v_pk_add_f32 v[136:137], v[130:131], v[134:135]
	v_pk_add_f32 v[130:131], v[130:131], v[134:135] neg_lo:[0,1] neg_hi:[0,1]
	v_pk_add_f32 v[164:165], v[114:115], v[124:125]
	v_pk_add_f32 v[114:115], v[114:115], v[124:125] neg_lo:[0,1] neg_hi:[0,1]
	v_pk_add_f32 v[124:125], v[166:167], v[132:133]
	v_pk_add_f32 v[132:133], v[166:167], v[132:133] neg_lo:[0,1] neg_hi:[0,1]
	v_pk_add_f32 v[166:167], v[132:133], v[130:131] op_sel:[0,1] op_sel_hi:[1,0] neg_lo:[0,1]
	v_pk_add_f32 v[132:133], v[132:133], v[130:131] op_sel:[0,1] op_sel_hi:[1,0] neg_hi:[0,1]
	v_pk_add_f32 v[134:135], v[118:119], v[126:127]
	v_pk_add_f32 v[118:119], v[118:119], v[126:127] neg_lo:[0,1] neg_hi:[0,1]
	v_pk_add_f32 v[126:127], v[120:121], v[128:129]
	v_pk_add_f32 v[120:121], v[120:121], v[128:129] neg_lo:[0,1] neg_hi:[0,1]
	v_pk_add_f32 v[130:131], v[124:125], v[136:137]
	v_pk_add_f32 v[124:125], v[124:125], v[136:137] neg_lo:[0,1] neg_hi:[0,1]
	v_pk_add_f32 v[136:137], v[118:119], v[120:121] op_sel:[0,1] op_sel_hi:[1,0] neg_lo:[0,1]
	v_pk_add_f32 v[118:119], v[118:119], v[120:121] op_sel:[0,1] op_sel_hi:[1,0] neg_hi:[0,1]
	v_pk_add_f32 v[128:129], v[106:107], v[110:111]
	v_pk_add_f32 v[106:107], v[106:107], v[110:111] neg_lo:[0,1] neg_hi:[0,1]
	v_pk_add_f32 v[110:111], v[108:109], v[112:113]
	v_pk_add_f32 v[108:109], v[108:109], v[112:113] neg_lo:[0,1] neg_hi:[0,1]
	v_pk_add_f32 v[120:121], v[134:135], v[126:127]
	v_pk_add_f32 v[126:127], v[134:135], v[126:127] neg_lo:[0,1] neg_hi:[0,1]
	v_pk_add_f32 v[134:135], v[106:107], v[108:109] op_sel:[0,1] op_sel_hi:[1,0] neg_lo:[0,1]
	v_pk_add_f32 v[106:107], v[106:107], v[108:109] op_sel:[0,1] op_sel_hi:[1,0] neg_hi:[0,1]
	v_xor_b32_e32 v112, 0x80000000, v139
	v_mov_b32_e32 v113, v138
	v_pk_mul_f32 v[112:113], v[112:113], v[116:117] op_sel:[0,1]
	v_pk_add_f32 v[108:109], v[128:129], v[110:111]
	v_pk_fma_f32 v[112:113], v[138:139], v[116:117], v[112:113] op_sel_hi:[1,0,1]
	v_pk_mul_f32 v[116:117], v[140:141], v[130:131] op_sel:[1,1] op_sel_hi:[0,1] neg_lo:[1,0]
	v_pk_add_f32 v[110:111], v[128:129], v[110:111] neg_lo:[0,1] neg_hi:[0,1]
	v_pk_fma_f32 v[116:117], v[140:141], v[130:131], v[116:117] op_sel_hi:[1,0,1]
	ds_write2_b64 v168, v[112:113], v[116:117] offset1:17
	v_pk_mul_f32 v[112:113], v[142:143], v[120:121] op_sel:[1,1] op_sel_hi:[0,1] neg_lo:[1,0]
	v_pk_mul_f32 v[116:117], v[144:145], v[108:109] op_sel:[1,1] op_sel_hi:[0,1] neg_lo:[1,0]
	v_pk_fma_f32 v[112:113], v[142:143], v[120:121], v[112:113] op_sel_hi:[1,0,1]
	v_pk_fma_f32 v[108:109], v[144:145], v[108:109], v[116:117] op_sel_hi:[1,0,1]
	ds_write2_b64 v168, v[112:113], v[108:109] offset0:34 offset1:51
	v_pk_mul_f32 v[108:109], v[146:147], v[164:165] op_sel:[1,1] op_sel_hi:[0,1] neg_lo:[1,0]
	v_pk_mul_f32 v[112:113], v[148:149], v[166:167] op_sel:[1,1] op_sel_hi:[0,1] neg_lo:[1,0]
	v_pk_fma_f32 v[108:109], v[146:147], v[164:165], v[108:109] op_sel_hi:[1,0,1]
	v_pk_fma_f32 v[112:113], v[148:149], v[166:167], v[112:113] op_sel_hi:[1,0,1]
	ds_write2_b64 v168, v[108:109], v[112:113] offset0:68 offset1:85
	v_pk_mul_f32 v[108:109], v[150:151], v[136:137] op_sel:[1,1] op_sel_hi:[0,1] neg_lo:[1,0]
	v_pk_mul_f32 v[112:113], v[152:153], v[134:135] op_sel:[1,1] op_sel_hi:[0,1] neg_lo:[1,0]
	v_pk_fma_f32 v[108:109], v[150:151], v[136:137], v[108:109] op_sel_hi:[1,0,1]
	v_pk_fma_f32 v[112:113], v[152:153], v[134:135], v[112:113] op_sel_hi:[1,0,1]
	ds_write2_b64 v168, v[108:109], v[112:113] offset0:102 offset1:119
	v_pk_mul_f32 v[108:109], v[154:155], v[122:123] op_sel:[1,1] op_sel_hi:[0,1] neg_lo:[1,0]
	v_pk_mul_f32 v[112:113], v[156:157], v[124:125] op_sel:[1,1] op_sel_hi:[0,1] neg_lo:[1,0]
	v_pk_fma_f32 v[108:109], v[154:155], v[122:123], v[108:109] op_sel_hi:[1,0,1]
	v_pk_fma_f32 v[112:113], v[156:157], v[124:125], v[112:113] op_sel_hi:[1,0,1]
	ds_write2_b64 v168, v[108:109], v[112:113] offset0:136 offset1:153
	v_pk_mul_f32 v[108:109], v[158:159], v[126:127] op_sel:[1,1] op_sel_hi:[0,1] neg_lo:[1,0]
	v_pk_mul_f32 v[112:113], v[104:105], v[110:111] op_sel:[1,1] op_sel_hi:[0,1] neg_lo:[1,0]
	v_pk_fma_f32 v[108:109], v[158:159], v[126:127], v[108:109] op_sel_hi:[1,0,1]
	v_pk_fma_f32 v[104:105], v[104:105], v[110:111], v[112:113] op_sel_hi:[1,0,1]
	ds_write2_b64 v168, v[108:109], v[104:105] offset0:170 offset1:187
	v_pk_mul_f32 v[104:105], v[14:15], v[114:115] op_sel:[1,1] op_sel_hi:[0,1] neg_lo:[1,0]
	v_pk_fma_f32 v[14:15], v[14:15], v[114:115], v[104:105] op_sel_hi:[1,0,1]
	v_pk_mul_f32 v[104:105], v[12:13], v[132:133] op_sel:[1,1] op_sel_hi:[0,1] neg_lo:[1,0]
	v_pk_fma_f32 v[12:13], v[12:13], v[132:133], v[104:105] op_sel_hi:[1,0,1]
	ds_write2_b64 v168, v[14:15], v[12:13] offset0:204 offset1:221
	v_pk_mul_f32 v[12:13], v[10:11], v[118:119] op_sel:[1,1] op_sel_hi:[0,1] neg_lo:[1,0]
	v_pk_fma_f32 v[10:11], v[10:11], v[118:119], v[12:13] op_sel_hi:[1,0,1]
	v_pk_mul_f32 v[12:13], v[8:9], v[106:107] op_sel:[1,1] op_sel_hi:[0,1] neg_lo:[1,0]
	v_pk_fma_f32 v[8:9], v[8:9], v[106:107], v[12:13] op_sel_hi:[1,0,1]
	ds_write2_b64 v168, v[10:11], v[8:9] offset0:238 offset1:255
	v_mov_b32_e32 v8, v206
	s_waitcnt lgkmcnt(0)
	s_barrier
	s_nop 0
	v_lshlrev_b32_sdwa v9, v228, v8 dst_sel:DWORD dst_unused:UNUSED_PAD src0_sel:DWORD src1_sel:BYTE_0
	v_lshrrev_b32_e32 v8, 1, v206
	v_and_b32_e32 v8, 0x78, v8
	v_add3_u32 v132, v207, v9, v8
	ds_read_b64 v[8:9], v132
	ds_read_b64 v[10:11], v132 offset:2176
	ds_read_b64 v[12:13], v132 offset:4352
	ds_read_b64 v[14:15], v132 offset:6528
	ds_read_b64 v[104:105], v132 offset:8704
	ds_read_b64 v[106:107], v132 offset:10880
	ds_read_b64 v[108:109], v132 offset:13056
	ds_read_b64 v[110:111], v132 offset:15232
	ds_read_b64 v[112:113], v132 offset:17408
	ds_read_b64 v[114:115], v132 offset:19584
	ds_read_b64 v[116:117], v132 offset:21760
	ds_read_b64 v[118:119], v132 offset:23936
	ds_read_b64 v[120:121], v132 offset:26112
	ds_read_b64 v[122:123], v132 offset:28288
	ds_read_b64 v[124:125], v132 offset:30464
	ds_read_b64 v[126:127], v132 offset:32640
	s_waitcnt lgkmcnt(7)
	v_pk_add_f32 v[128:129], v[8:9], v[112:113]
	v_pk_add_f32 v[8:9], v[8:9], v[112:113] neg_lo:[0,1] neg_hi:[0,1]
	s_waitcnt lgkmcnt(3)
	v_pk_add_f32 v[112:113], v[104:105], v[120:121]
	v_pk_add_f32 v[104:105], v[104:105], v[120:121] neg_lo:[0,1] neg_hi:[0,1]
	v_pk_add_f32 v[130:131], v[8:9], v[104:105] op_sel:[0,1] op_sel_hi:[1,0] neg_lo:[0,1]
	v_pk_add_f32 v[8:9], v[8:9], v[104:105] op_sel:[0,1] op_sel_hi:[1,0] neg_hi:[0,1]
	v_pk_add_f32 v[120:121], v[10:11], v[114:115]
	v_pk_add_f32 v[10:11], v[10:11], v[114:115] neg_lo:[0,1] neg_hi:[0,1]
	s_waitcnt lgkmcnt(2)
	v_pk_add_f32 v[114:115], v[106:107], v[122:123]
	v_pk_add_f32 v[106:107], v[106:107], v[122:123] neg_lo:[0,1] neg_hi:[0,1]
	v_pk_add_f32 v[104:105], v[128:129], v[112:113]
	v_xor_b32_e32 v122, 0x80000000, v107
	v_mov_b32_e32 v123, v106
	v_pk_add_f32 v[106:107], v[120:121], v[114:115]
	v_pk_add_f32 v[114:115], v[120:121], v[114:115] neg_lo:[0,1] neg_hi:[0,1]
	v_pk_add_f32 v[120:121], v[12:13], v[116:117]
	v_pk_add_f32 v[12:13], v[12:13], v[116:117] neg_lo:[0,1] neg_hi:[0,1]
	s_waitcnt lgkmcnt(1)
	v_pk_add_f32 v[116:117], v[108:109], v[124:125]
	v_pk_add_f32 v[108:109], v[108:109], v[124:125] neg_lo:[0,1] neg_hi:[0,1]
	v_pk_add_f32 v[112:113], v[128:129], v[112:113] neg_lo:[0,1] neg_hi:[0,1]
	v_pk_add_f32 v[128:129], v[10:11], v[122:123]
	v_pk_add_f32 v[10:11], v[10:11], v[122:123] neg_lo:[0,1] neg_hi:[0,1]
	v_xor_b32_e32 v122, 0x80000000, v109
	v_mov_b32_e32 v123, v108
	v_pk_add_f32 v[108:109], v[120:121], v[116:117]
	v_pk_add_f32 v[116:117], v[120:121], v[116:117] neg_lo:[0,1] neg_hi:[0,1]
	v_pk_add_f32 v[120:121], v[14:15], v[118:119]
	v_pk_add_f32 v[14:15], v[14:15], v[118:119] neg_lo:[0,1] neg_hi:[0,1]
	s_waitcnt lgkmcnt(0)
	v_pk_add_f32 v[118:119], v[110:111], v[126:127]
	v_pk_add_f32 v[110:111], v[110:111], v[126:127] neg_lo:[0,1] neg_hi:[0,1]
	v_pk_add_f32 v[124:125], v[12:13], v[122:123]
	v_pk_add_f32 v[12:13], v[12:13], v[122:123] neg_lo:[0,1] neg_hi:[0,1]
	v_pk_add_f32 v[126:127], v[14:15], v[110:111] op_sel:[0,1] op_sel_hi:[1,0] neg_lo:[0,1]
	v_pk_add_f32 v[14:15], v[14:15], v[110:111] op_sel:[0,1] op_sel_hi:[1,0] neg_hi:[0,1]
	v_pk_mul_f32 v[122:123], v[114:115], s[12:13] op_sel:[1,0] op_sel_hi:[0,0] neg_lo:[1,0]
	v_pk_add_f32 v[110:111], v[120:121], v[118:119]
	v_pk_fma_f32 v[114:115], v[114:115], s[12:13], v[122:123] op_sel_hi:[1,0,1]
	v_pk_mul_f32 v[122:123], v[10:11], s[36:37] op_sel:[1,0] op_sel_hi:[0,0] neg_lo:[1,0]
	v_pk_add_f32 v[118:119], v[120:121], v[118:119] neg_lo:[0,1] neg_hi:[0,1]
	v_pk_fma_f32 v[10:11], v[10:11], s[22:23], v[122:123] op_sel_hi:[1,0,1]
	v_pk_mul_f32 v[122:123], v[124:125], s[12:13] op_sel:[1,0] op_sel_hi:[0,0] neg_lo:[1,0]
	v_pk_fma_f32 v[122:123], v[124:125], s[12:13], v[122:123] op_sel_hi:[1,0,1]
	v_pk_fma_f32 v[116:117], v[116:117], 0, v[116:117] op_sel:[0,0,1] op_sel_hi:[1,0,0] neg_lo:[0,0,1]
	v_xor_b32_e32 v124, 0x80000000, v13
	v_mov_b32_e32 v125, v12
	v_pk_mul_f32 v[12:13], v[12:13], s[12:13] op_sel_hi:[1,0]
	v_pk_fma_f32 v[12:13], v[124:125], s[12:13], v[12:13] op_sel_hi:[1,0,1] neg_lo:[0,0,1] neg_hi:[0,0,1]
	v_pk_mul_f32 v[124:125], v[126:127], s[36:37] op_sel:[1,0] op_sel_hi:[0,0] neg_lo:[1,0]
	v_pk_mul_f32 v[120:121], v[128:129], s[22:23] op_sel:[1,0] op_sel_hi:[0,0] neg_lo:[1,0]
	v_pk_fma_f32 v[124:125], v[126:127], s[22:23], v[124:125] op_sel_hi:[1,0,1]
	v_xor_b32_e32 v126, 0x80000000, v119
	v_mov_b32_e32 v127, v118
	v_pk_mul_f32 v[118:119], v[118:119], s[12:13] op_sel_hi:[1,0]
	v_pk_fma_f32 v[120:121], v[128:129], s[36:37], v[120:121] op_sel_hi:[1,0,1]
	v_pk_fma_f32 v[118:119], v[126:127], s[12:13], v[118:119] op_sel_hi:[1,0,1] neg_lo:[0,0,1] neg_hi:[0,0,1]
	v_pk_mul_f32 v[126:127], v[14:15], s[22:23] op_sel:[1,0] op_sel_hi:[0,0] neg_lo:[1,0]
	v_pk_fma_f32 v[14:15], v[14:15], s[26:27], v[126:127] op_sel_hi:[1,0,1] neg_lo:[0,0,1] neg_hi:[0,0,1]
	v_pk_add_f32 v[126:127], v[104:105], v[108:109]
	v_pk_add_f32 v[104:105], v[104:105], v[108:109] neg_lo:[0,1] neg_hi:[0,1]
	v_pk_add_f32 v[108:109], v[106:107], v[110:111]
	v_pk_add_f32 v[106:107], v[106:107], v[110:111] neg_lo:[0,1] neg_hi:[0,1]
	v_xor_b32_e32 v110, 0x80000000, v107
	v_mov_b32_e32 v111, v106
	v_pk_add_f32 v[106:107], v[126:127], v[108:109]
	v_pk_add_f32 v[108:109], v[126:127], v[108:109] neg_lo:[0,1] neg_hi:[0,1]
	v_pk_add_f32 v[126:127], v[120:121], v[124:125]
	v_pk_add_f32 v[120:121], v[120:121], v[124:125] neg_lo:[0,1] neg_hi:[0,1]
	v_pk_add_f32 v[128:129], v[104:105], v[110:111]
	v_pk_add_f32 v[104:105], v[104:105], v[110:111] neg_lo:[0,1] neg_hi:[0,1]
	v_pk_add_f32 v[110:111], v[130:131], v[122:123]
	v_pk_add_f32 v[122:123], v[130:131], v[122:123] neg_lo:[0,1] neg_hi:[0,1]
	v_pk_add_f32 v[130:131], v[122:123], v[120:121] op_sel:[0,1] op_sel_hi:[1,0] neg_lo:[0,1]
	v_pk_add_f32 v[122:123], v[122:123], v[120:121] op_sel:[0,1] op_sel_hi:[1,0] neg_hi:[0,1]
	v_pk_add_f32 v[124:125], v[112:113], v[116:117]
	v_pk_add_f32 v[112:113], v[112:113], v[116:117] neg_lo:[0,1] neg_hi:[0,1]
	v_pk_add_f32 v[116:117], v[114:115], v[118:119]
	v_pk_add_f32 v[114:115], v[114:115], v[118:119] neg_lo:[0,1] neg_hi:[0,1]
	v_pk_add_f32 v[120:121], v[110:111], v[126:127]
	v_pk_add_f32 v[110:111], v[110:111], v[126:127] neg_lo:[0,1] neg_hi:[0,1]
	v_pk_add_f32 v[126:127], v[112:113], v[114:115] op_sel:[0,1] op_sel_hi:[1,0] neg_lo:[0,1]
	v_pk_add_f32 v[112:113], v[112:113], v[114:115] op_sel:[0,1] op_sel_hi:[1,0] neg_hi:[0,1]
	v_pk_add_f32 v[118:119], v[8:9], v[12:13]
	v_pk_add_f32 v[8:9], v[8:9], v[12:13] neg_lo:[0,1] neg_hi:[0,1]
	v_pk_add_f32 v[12:13], v[10:11], v[14:15]
	v_pk_add_f32 v[10:11], v[10:11], v[14:15] neg_lo:[0,1] neg_hi:[0,1]
	v_pk_add_f32 v[114:115], v[124:125], v[116:117]
	v_pk_add_f32 v[116:117], v[124:125], v[116:117] neg_lo:[0,1] neg_hi:[0,1]
	v_pk_add_f32 v[124:125], v[8:9], v[10:11] op_sel:[0,1] op_sel_hi:[1,0] neg_lo:[0,1]
	v_pk_add_f32 v[8:9], v[8:9], v[10:11] op_sel:[0,1] op_sel_hi:[1,0] neg_hi:[0,1]
	v_pk_add_f32 v[10:11], v[118:119], v[12:13]
	v_pk_add_f32 v[12:13], v[118:119], v[12:13] neg_lo:[0,1] neg_hi:[0,1]
	ds_write_b64 v132, v[106:107]
	ds_write_b64 v132, v[128:129] offset:8704
	ds_write_b64 v132, v[108:109] offset:17408
	ds_write_b64 v132, v[104:105] offset:26112
	ds_write_b64 v132, v[120:121] offset:2176
	ds_write_b64 v132, v[130:131] offset:10880
	ds_write_b64 v132, v[110:111] offset:19584
	ds_write_b64 v132, v[122:123] offset:28288
	ds_write_b64 v132, v[114:115] offset:4352
	ds_write_b64 v132, v[126:127] offset:13056
	ds_write_b64 v132, v[116:117] offset:21760
	ds_write_b64 v132, v[112:113] offset:30464
	ds_write_b64 v132, v[10:11] offset:6528
	ds_write_b64 v132, v[124:125] offset:15232
	ds_write_b64 v132, v[12:13] offset:23936
	ds_write_b64 v132, v[8:9] offset:32640
	s_waitcnt lgkmcnt(0)
	s_barrier
	s_waitcnt vmcnt(4)
	v_lshlrev_b32_e32 v9, 16, v4
	v_and_b32_e32 v104, 0x1ff, v212
	v_lshlrev_b32_e32 v105, 3, v104
	v_bfe_u32 v8, v212, 1, 8
	v_add_u32_e32 v106, v105, v8
	v_lshlrev_b32_e32 v8, 16, v0
	v_and_b32_e32 v11, 0xffff0000, v4
	v_and_b32_e32 v10, 0xffff0000, v0
	s_waitcnt vmcnt(2)
	v_lshlrev_b32_e32 v0, 16, v163
	v_lshlrev_b32_e32 v4, 16, v162
	v_cmp_eq_u32_e32 vcc, 0, v104
	v_pk_mul_f32 v[14:15], v[38:39], v[10:11]
	v_cmp_eq_u32_e64 s[0:1], s37, v104
	v_cndmask_b32_e64 v13, v4, 0, vcc
	v_cndmask_b32_e64 v12, v0, 0, vcc
	v_pk_mul_f32 v[12:13], v[24:25], v[12:13]
	v_and_b32_e32 v4, 0xffff0000, v1
	v_pk_fma_f32 v[12:13], v[38:39], v[8:9], v[12:13]
	v_pk_fma_f32 v[8:9], v[24:25], v[8:9], v[14:15]
	v_pk_fma_f32 v[12:13], v[26:27], v[10:11], v[12:13]
	v_lshl_add_u32 v136, v106, 3, 0
	v_pk_add_f32 v[122:123], v[28:29], v[12:13]
	v_lshlrev_b32_e32 v13, 16, v5
	v_lshlrev_b32_e32 v12, 16, v1
	v_pk_mul_f32 v[0:1], v[38:39], v[12:13]
	v_pk_fma_f32 v[8:9], v[26:27], v[12:13], v[8:9]
	v_and_b32_e32 v5, 0xffff0000, v5
	v_pk_fma_f32 v[0:1], v[24:25], v[10:11], v[0:1]
	v_pk_add_f32 v[124:125], v[28:29], v[8:9]
	v_pk_fma_f32 v[0:1], v[26:27], v[4:5], v[0:1]
	v_pk_mul_f32 v[8:9], v[38:39], v[4:5]
	v_pk_add_f32 v[126:127], v[28:29], v[0:1]
	v_lshlrev_b32_e32 v1, 16, v6
	v_lshlrev_b32_e32 v0, 16, v2
	v_pk_fma_f32 v[8:9], v[24:25], v[12:13], v[8:9]
	v_pk_mul_f32 v[10:11], v[38:39], v[0:1]
	v_pk_fma_f32 v[8:9], v[26:27], v[0:1], v[8:9]
	v_pk_fma_f32 v[4:5], v[24:25], v[4:5], v[10:11]
	v_pk_add_f32 v[128:129], v[28:29], v[8:9]
	v_and_b32_e32 v9, 0xffff0000, v6
	v_and_b32_e32 v8, 0xffff0000, v2
	v_pk_fma_f32 v[4:5], v[26:27], v[8:9], v[4:5]
	v_lshlrev_b32_e32 v11, 16, v7
	v_pk_add_f32 v[130:131], v[28:29], v[4:5]
	v_pk_mul_f32 v[4:5], v[38:39], v[8:9]
	v_lshlrev_b32_e32 v10, 16, v3
	v_pk_fma_f32 v[0:1], v[24:25], v[0:1], v[4:5]
	s_waitcnt vmcnt(0)
	v_lshlrev_b32_e32 v6, 16, v161
	v_pk_fma_f32 v[0:1], v[26:27], v[10:11], v[0:1]
	v_cndmask_b32_e64 v6, v6, 0, s[0:1]
	v_pk_add_f32 v[4:5], v[28:29], v[0:1]
	v_and_b32_e32 v0, 0xffff0000, v3
	v_pk_mul_f32 v[2:3], v[38:39], v[10:11]
	v_and_b32_e32 v1, 0xffff0000, v7
	v_pk_fma_f32 v[2:3], v[24:25], v[8:9], v[2:3]
	v_lshlrev_b32_e32 v7, 16, v160
	v_pk_fma_f32 v[2:3], v[26:27], v[0:1], v[2:3]
	v_pk_mul_f32 v[0:1], v[38:39], v[0:1]
	v_cndmask_b32_e64 v7, v7, 0, s[0:1]
	v_pk_fma_f32 v[0:1], v[24:25], v[10:11], v[0:1]
	v_mov_b32_e32 v121, v214
	v_pk_fma_f32 v[0:1], v[26:27], v[6:7], v[0:1]
	v_add_u32_e32 v6, -1, v105
	v_cndmask_b32_e64 v176, v6, 0, vcc
	v_add_u32_e32 v6, 8, v105
	v_cndmask_b32_e64 v105, v6, v229, s[0:1]
	s_add_u32 s0, s39, s42
	v_lshlrev_b32_e32 v6, 4, v104
	v_mov_b32_e32 v7, v177
	s_addc_u32 s1, s46, s43
	v_lshl_add_u64 v[6:7], s[0:1], 0, v[6:7]
	v_add_co_u32_e32 v8, vcc, s5, v6
	v_mov_b32_e32 v120, v213
	s_nop 0
	v_addc_co_u32_e32 v9, vcc, 0, v7, vcc
	v_add_co_u32_e32 v6, vcc, s27, v6
	v_add_u32_e32 v137, 0x8800, v136
	s_nop 0
	v_addc_co_u32_e32 v7, vcc, 0, v7, vcc
	global_load_dwordx4 v[12:15], v[8:9], off
	s_nop 0
	global_load_dwordx4 v[8:11], v[6:7], off
	ds_read2_b64 v[108:111], v137 offset1:1
	v_lshl_add_u64 v[6:7], v[176:177], 1, s[0:1]
	v_lshlrev_b32_e32 v176, 1, v105
	ds_read2_b64 v[104:107], v136 offset1:1
	v_xor_b32_e32 v135, 0x80000000, v121
	v_mov_b32_e32 v134, v120
	v_add_u32_e32 v138, 0x8810, v136
	ds_read2_b64 v[112:115], v138 offset1:1
	s_waitcnt lgkmcnt(2)
	v_pk_mul_f32 v[116:117], v[134:135], v[108:109] op_sel_hi:[1,0]
	v_lshl_add_u64 v[132:133], s[0:1], 0, v[176:177]
	v_pk_fma_f32 v[108:109], v[120:121], v[108:109], v[116:117] op_sel:[1,1,0] op_sel_hi:[0,1,1]
	ds_read2_b64 v[116:119], v136 offset0:2 offset1:3
	s_waitcnt lgkmcnt(2)
	v_pk_add_f32 v[104:105], v[104:105], v[108:109]
	v_mov_b32_e32 v108, v135
	v_pk_mul_f32 v[104:105], v[122:123], v[104:105]
	v_mov_b32_e32 v109, v120
	v_pk_mul_f32 v[108:109], v[108:109], v[104:105] op_sel:[0,1]
	v_pk_mul_f32 v[122:123], v[214:215], s[8:9] op_sel_hi:[0,1]
	v_pk_fma_f32 v[108:109], v[120:121], v[104:105], v[108:109] op_sel_hi:[1,0,1]
	v_pk_fma_f32 v[120:121], v[212:213], s[30:31], v[122:123] op_sel:[1,0,0]
	v_pk_mul_f32 v[134:135], v[120:121], v[110:111] op_sel_hi:[1,0] neg_hi:[1,0]
	v_mov_b32_e32 v110, v111
	v_pk_fma_f32 v[110:111], v[120:121], v[110:111], v[134:135] op_sel:[1,1,0] op_sel_hi:[0,1,1]
	v_pk_add_f32 v[106:107], v[106:107], v[110:111]
	v_add_u32_e32 v122, 0x8820, v136
	v_pk_mul_f32 v[106:107], v[124:125], v[106:107]
	ds_write2_b64 v136, v[104:105], v[106:107] offset1:1
	v_pk_mul_f32 v[104:105], v[120:121], v[106:107] op_sel:[1,1] op_sel_hi:[0,1] neg_lo:[1,0]
	v_pk_add_f32 v[2:3], v[28:29], v[2:3]
	v_pk_fma_f32 v[104:105], v[120:121], v[106:107], v[104:105] op_sel_hi:[1,0,1]
	ds_write2_b64 v137, v[108:109], v[104:105] offset1:1
	v_pk_mul_f32 v[104:105], v[120:121], s[8:9] op_sel:[1,0]
	v_pk_add_f32 v[0:1], v[28:29], v[0:1]
	v_pk_fma_f32 v[104:105], v[120:121], s[30:31], v[104:105] op_sel_hi:[0,1,1]
	s_waitcnt lgkmcnt(3)
	v_pk_mul_f32 v[108:109], v[104:105], v[112:113] op_sel_hi:[1,0] neg_hi:[1,0]
	v_pk_fma_f32 v[108:109], v[104:105], v[112:113], v[108:109] op_sel:[1,1,0] op_sel_hi:[0,1,1]
	s_waitcnt lgkmcnt(2)
	v_pk_add_f32 v[108:109], v[116:117], v[108:109]
	v_pk_mul_f32 v[108:109], v[126:127], v[108:109]
	v_pk_mul_f32 v[110:111], v[104:105], s[8:9] op_sel:[1,0]
	v_pk_mul_f32 v[106:107], v[104:105], v[108:109] op_sel:[1,1] op_sel_hi:[0,1] neg_lo:[1,0]
	v_pk_fma_f32 v[110:111], v[104:105], s[30:31], v[110:111] op_sel_hi:[0,1,1]
	v_pk_fma_f32 v[106:107], v[104:105], v[108:109], v[106:107] op_sel_hi:[1,0,1]
	v_pk_mul_f32 v[112:113], v[110:111], v[114:115] op_sel_hi:[1,0] neg_hi:[1,0]
	v_pk_fma_f32 v[112:113], v[110:111], v[114:115], v[112:113] op_sel:[1,1,0] op_sel_hi:[0,1,1]
	v_pk_add_f32 v[112:113], v[118:119], v[112:113]
	v_pk_mul_f32 v[112:113], v[128:129], v[112:113]
	v_pk_mul_f32 v[104:105], v[110:111], v[112:113] op_sel:[1,1] op_sel_hi:[0,1] neg_lo:[1,0]
	ds_write2_b64 v136, v[108:109], v[112:113] offset0:2 offset1:3
	v_pk_fma_f32 v[104:105], v[110:111], v[112:113], v[104:105] op_sel_hi:[1,0,1]
	ds_write2_b64 v138, v[106:107], v[104:105] offset1:1
	ds_read2_b64 v[104:107], v122 offset1:1
	v_pk_mul_f32 v[108:109], v[110:111], s[8:9] op_sel:[1,0]
	v_pk_fma_f32 v[116:117], v[110:111], s[30:31], v[108:109] op_sel_hi:[0,1,1]
	ds_read2_b64 v[108:111], v136 offset0:4 offset1:5
	s_waitcnt lgkmcnt(1)
	v_pk_mul_f32 v[112:113], v[116:117], v[104:105] op_sel_hi:[1,0] neg_hi:[1,0]
	v_pk_fma_f32 v[104:105], v[116:117], v[104:105], v[112:113] op_sel:[1,1,0] op_sel_hi:[0,1,1]
	s_waitcnt lgkmcnt(0)
	v_pk_add_f32 v[104:105], v[108:109], v[104:105]
	v_pk_mul_f32 v[104:105], v[130:131], v[104:105]
	v_pk_mul_f32 v[108:109], v[116:117], v[104:105] op_sel:[1,1] op_sel_hi:[0,1] neg_lo:[1,0]
	v_pk_mul_f32 v[118:119], v[116:117], s[8:9] op_sel:[1,0]
	v_pk_fma_f32 v[108:109], v[116:117], v[104:105], v[108:109] op_sel_hi:[1,0,1]
	v_pk_fma_f32 v[116:117], v[116:117], s[30:31], v[118:119] op_sel_hi:[0,1,1]
	v_pk_mul_f32 v[120:121], v[116:117], v[106:107] op_sel_hi:[1,0] neg_hi:[1,0]
	v_mov_b32_e32 v106, v107
	v_pk_fma_f32 v[106:107], v[116:117], v[106:107], v[120:121] op_sel:[1,1,0] op_sel_hi:[0,1,1]
	v_pk_add_f32 v[106:107], v[110:111], v[106:107]
	ds_read2_b64 v[112:115], v136 offset0:6 offset1:7
	v_pk_mul_f32 v[4:5], v[4:5], v[106:107]
	v_add_co_u32_e32 v106, vcc, s5, v6
	s_nop 1
	v_addc_co_u32_e32 v107, vcc, 0, v7, vcc
	v_add_co_u32_e32 v110, vcc, s5, v132
	s_nop 1
	v_addc_co_u32_e32 v111, vcc, 0, v133, vcc
	v_add_co_u32_e32 v6, vcc, s27, v6
	s_nop 1
	v_addc_co_u32_e32 v7, vcc, 0, v7, vcc
	v_add_co_u32_e32 v120, vcc, s27, v132
	s_nop 1
	v_addc_co_u32_e32 v121, vcc, 0, v133, vcc
	global_load_ushort v233, v[106:107], off
	global_load_ushort v232, v[110:111], off
	global_load_ushort v231, v[6:7], off
	global_load_ushort v176, v[120:121], off
	v_pk_mul_f32 v[6:7], v[116:117], v[4:5] op_sel:[1,1] op_sel_hi:[0,1] neg_lo:[1,0]
	ds_write2_b64 v136, v[104:105], v[4:5] offset0:4 offset1:5
	v_pk_fma_f32 v[4:5], v[116:117], v[4:5], v[6:7] op_sel_hi:[1,0,1]
	v_add_u32_e32 v110, 0x8830, v136
	ds_write2_b64 v122, v[108:109], v[4:5] offset1:1
	ds_read2_b64 v[4:7], v110 offset1:1
	v_pk_mul_f32 v[104:105], v[116:117], s[8:9] op_sel:[1,0]
	v_mov_b32_e32 v111, v177
	v_pk_fma_f32 v[104:105], v[116:117], s[30:31], v[104:105] op_sel_hi:[0,1,1]
	s_waitcnt lgkmcnt(0)
	v_pk_mul_f32 v[108:109], v[104:105], v[4:5] op_sel_hi:[1,0] neg_hi:[1,0]
	v_pk_fma_f32 v[4:5], v[104:105], v[4:5], v[108:109] op_sel:[1,1,0] op_sel_hi:[0,1,1]
	v_pk_add_f32 v[4:5], v[112:113], v[4:5]
	v_pk_mul_f32 v[2:3], v[2:3], v[4:5]
	v_pk_mul_f32 v[4:5], v[104:105], v[2:3] op_sel:[1,1] op_sel_hi:[0,1] neg_lo:[1,0]
	v_pk_mul_f32 v[106:107], v[104:105], s[8:9] op_sel:[1,0]
	v_pk_fma_f32 v[4:5], v[104:105], v[2:3], v[4:5] op_sel_hi:[1,0,1]
	v_pk_fma_f32 v[104:105], v[104:105], s[30:31], v[106:107] op_sel_hi:[0,1,1]
	v_pk_mul_f32 v[108:109], v[104:105], v[6:7] op_sel_hi:[1,0] neg_hi:[1,0]
	v_mov_b32_e32 v6, v7
	v_pk_fma_f32 v[6:7], v[104:105], v[6:7], v[108:109] op_sel:[1,1,0] op_sel_hi:[0,1,1]
	v_pk_add_f32 v[6:7], v[114:115], v[6:7]
	v_pk_mul_f32 v[0:1], v[0:1], v[6:7]
	ds_write2_b64 v136, v[2:3], v[0:1] offset0:6 offset1:7
	v_pk_mul_f32 v[2:3], v[104:105], v[0:1] op_sel:[1,1] op_sel_hi:[0,1] neg_lo:[1,0]
	v_pk_fma_f32 v[0:1], v[104:105], v[0:1], v[2:3] op_sel_hi:[1,0,1]
	ds_write2_b64 v110, v[4:5], v[0:1] offset1:1
	v_and_b32_e32 v0, 0x1ff, v212
	v_lshl_add_u32 v0, v0, 3, 0
	v_add_u32_e32 v234, 0x11040, v0
	v_mov_b32_e32 v110, 1.0
	v_pk_mul_f32 v[2:3], v[208:209], v[208:209] op_sel:[1,1] op_sel_hi:[0,1] neg_lo:[1,0]
	s_waitcnt lgkmcnt(0)
	v_pk_fma_f32 v[2:3], v[208:209], v[208:209], v[2:3] op_sel_hi:[0,1,1]
	v_pk_mul_f32 v[104:105], v[2:3], v[2:3] op_sel:[1,1] op_sel_hi:[1,0] neg_lo:[0,1]
	v_pk_mul_f32 v[4:5], v[208:209], v[176:177] op_sel:[1,1] op_sel_hi:[0,1] neg_lo:[1,0]
	v_pk_fma_f32 v[104:105], v[2:3], v[2:3], v[104:105] op_sel_hi:[1,0,1]
	v_pk_fma_f32 v[114:115], v[208:209], v[110:111], v[4:5] op_sel_hi:[1,0,1]
	v_pk_mul_f32 v[0:1], v[176:177], v[2:3] op_sel:[1,1] op_sel_hi:[1,0] neg_lo:[0,1]
	v_pk_fma_f32 v[116:117], v[110:111], v[2:3], v[0:1] op_sel_hi:[0,1,1]
	v_pk_mul_f32 v[0:1], v[114:115], v[2:3] op_sel:[1,1] op_sel_hi:[1,0] neg_lo:[0,1]
	v_pk_mul_f32 v[108:109], v[104:105], v[104:105] op_sel:[1,1] op_sel_hi:[1,0] neg_lo:[0,1]
	v_pk_fma_f32 v[118:119], v[2:3], v[114:115], v[0:1] op_sel_hi:[1,0,1]
	v_pk_mul_f32 v[0:1], v[176:177], v[104:105] op_sel:[1,1] op_sel_hi:[1,0] neg_lo:[0,1]
	v_pk_fma_f32 v[120:121], v[110:111], v[104:105], v[0:1] op_sel_hi:[0,1,1]
	v_pk_mul_f32 v[0:1], v[114:115], v[104:105] op_sel:[1,1] op_sel_hi:[1,0] neg_lo:[0,1]
	s_barrier
	v_pk_fma_f32 v[122:123], v[114:115], v[104:105], v[0:1] op_sel_hi:[0,1,1]
	v_pk_mul_f32 v[0:1], v[116:117], v[104:105] op_sel:[1,1] op_sel_hi:[1,0] neg_lo:[0,1]
	v_pk_fma_f32 v[124:125], v[104:105], v[116:117], v[0:1] op_sel_hi:[1,0,1]
	v_pk_mul_f32 v[0:1], v[118:119], v[104:105] op_sel:[1,1] op_sel_hi:[1,0] neg_lo:[0,1]
	v_pk_fma_f32 v[126:127], v[104:105], v[118:119], v[0:1] op_sel_hi:[1,0,1]
	v_pk_fma_f32 v[0:1], v[104:105], v[104:105], v[108:109] op_sel_hi:[1,0,1]
	v_pk_mul_f32 v[2:3], v[176:177], v[0:1] op_sel:[1,1] op_sel_hi:[1,0] neg_lo:[0,1]
	v_pk_fma_f32 v[112:113], v[110:111], v[0:1], v[2:3] op_sel_hi:[0,1,1]
	v_pk_mul_f32 v[2:3], v[114:115], v[0:1] op_sel:[1,1] op_sel_hi:[1,0] neg_lo:[0,1]
	v_pk_fma_f32 v[108:109], v[114:115], v[0:1], v[2:3] op_sel_hi:[0,1,1]
	v_pk_mul_f32 v[2:3], v[116:117], v[0:1] op_sel:[1,1] op_sel_hi:[1,0] neg_lo:[0,1]
	v_pk_fma_f32 v[106:107], v[116:117], v[0:1], v[2:3] op_sel_hi:[0,1,1]
	v_pk_mul_f32 v[2:3], v[118:119], v[0:1] op_sel:[1,1] op_sel_hi:[1,0] neg_lo:[0,1]
	v_pk_fma_f32 v[104:105], v[118:119], v[0:1], v[2:3] op_sel_hi:[0,1,1]
	v_pk_mul_f32 v[2:3], v[120:121], v[0:1] op_sel:[1,1] op_sel_hi:[1,0] neg_lo:[0,1]
	v_pk_fma_f32 v[6:7], v[0:1], v[120:121], v[2:3] op_sel_hi:[1,0,1]
	v_pk_mul_f32 v[2:3], v[122:123], v[0:1] op_sel:[1,1] op_sel_hi:[1,0] neg_lo:[0,1]
	v_pk_fma_f32 v[4:5], v[0:1], v[122:123], v[2:3] op_sel_hi:[1,0,1]
	v_pk_mul_f32 v[2:3], v[124:125], v[0:1] op_sel:[1,1] op_sel_hi:[1,0] neg_lo:[0,1]
	v_pk_mul_f32 v[128:129], v[126:127], v[0:1] op_sel:[1,1] op_sel_hi:[1,0] neg_lo:[0,1]
	v_pk_fma_f32 v[2:3], v[0:1], v[124:125], v[2:3] op_sel_hi:[1,0,1]
	v_pk_fma_f32 v[0:1], v[0:1], v[126:127], v[128:129] op_sel_hi:[1,0,1]
	v_mov_b32_e32 v128, v206
	s_nop 0
	v_lshlrev_b32_sdwa v129, v228, v128 dst_sel:DWORD dst_unused:UNUSED_PAD src0_sel:DWORD src1_sel:BYTE_0
	v_lshrrev_b32_e32 v128, 1, v206
	v_and_b32_e32 v128, 0x78, v128
	v_add3_u32 v164, v207, v129, v128
	ds_read_b64 v[128:129], v164
	ds_read_b64 v[130:131], v164 offset:2176
	ds_read_b64 v[132:133], v164 offset:4352
	ds_read_b64 v[134:135], v164 offset:6528
	ds_read_b64 v[136:137], v164 offset:8704
	ds_read_b64 v[138:139], v164 offset:10880
	ds_read_b64 v[140:141], v164 offset:13056
	ds_read_b64 v[142:143], v164 offset:15232
	ds_read_b64 v[144:145], v164 offset:17408
	ds_read_b64 v[146:147], v164 offset:19584
	ds_read_b64 v[148:149], v164 offset:21760
	ds_read_b64 v[150:151], v164 offset:23936
	ds_read_b64 v[152:153], v164 offset:26112
	ds_read_b64 v[154:155], v164 offset:28288
	ds_read_b64 v[156:157], v164 offset:30464
	ds_read_b64 v[158:159], v164 offset:32640
	s_waitcnt lgkmcnt(7)
	v_pk_add_f32 v[160:161], v[128:129], v[144:145]
	v_pk_add_f32 v[128:129], v[128:129], v[144:145] neg_lo:[0,1] neg_hi:[0,1]
	s_waitcnt lgkmcnt(3)
	v_pk_add_f32 v[144:145], v[136:137], v[152:153]
	v_pk_add_f32 v[136:137], v[136:137], v[152:153] neg_lo:[0,1] neg_hi:[0,1]
	v_pk_add_f32 v[162:163], v[128:129], v[136:137] op_sel:[0,1] op_sel_hi:[1,0] neg_hi:[0,1]
	v_pk_add_f32 v[128:129], v[128:129], v[136:137] op_sel:[0,1] op_sel_hi:[1,0] neg_lo:[0,1]
	v_pk_add_f32 v[152:153], v[130:131], v[146:147]
	v_pk_add_f32 v[130:131], v[130:131], v[146:147] neg_lo:[0,1] neg_hi:[0,1]
	s_waitcnt lgkmcnt(2)
	v_pk_add_f32 v[146:147], v[138:139], v[154:155]
	v_pk_add_f32 v[138:139], v[138:139], v[154:155] neg_lo:[0,1] neg_hi:[0,1]
	v_pk_add_f32 v[136:137], v[160:161], v[144:145]
	v_xor_b32_e32 v155, 0x80000000, v138
	v_mov_b32_e32 v154, v139
	v_pk_add_f32 v[138:139], v[152:153], v[146:147]
	v_pk_add_f32 v[146:147], v[152:153], v[146:147] neg_lo:[0,1] neg_hi:[0,1]
	v_pk_add_f32 v[152:153], v[132:133], v[148:149]
	v_pk_add_f32 v[132:133], v[132:133], v[148:149] neg_lo:[0,1] neg_hi:[0,1]
	s_waitcnt lgkmcnt(1)
	v_pk_add_f32 v[148:149], v[140:141], v[156:157]
	v_pk_add_f32 v[140:141], v[140:141], v[156:157] neg_lo:[0,1] neg_hi:[0,1]
	v_pk_add_f32 v[144:145], v[160:161], v[144:145] neg_lo:[0,1] neg_hi:[0,1]
	v_pk_add_f32 v[160:161], v[130:131], v[154:155]
	v_pk_add_f32 v[130:131], v[130:131], v[154:155] neg_lo:[0,1] neg_hi:[0,1]
	v_xor_b32_e32 v155, 0x80000000, v140
	v_mov_b32_e32 v154, v141
	v_pk_add_f32 v[140:141], v[152:153], v[148:149]
	v_pk_add_f32 v[148:149], v[152:153], v[148:149] neg_lo:[0,1] neg_hi:[0,1]
	v_pk_add_f32 v[152:153], v[134:135], v[150:151]
	v_pk_add_f32 v[134:135], v[134:135], v[150:151] neg_lo:[0,1] neg_hi:[0,1]
	s_waitcnt lgkmcnt(0)
	v_pk_add_f32 v[150:151], v[142:143], v[158:159]
	v_pk_add_f32 v[142:143], v[142:143], v[158:159] neg_lo:[0,1] neg_hi:[0,1]
	v_pk_add_f32 v[156:157], v[132:133], v[154:155]
	v_pk_add_f32 v[132:133], v[132:133], v[154:155] neg_lo:[0,1] neg_hi:[0,1]
	v_pk_add_f32 v[158:159], v[134:135], v[142:143] op_sel:[0,1] op_sel_hi:[1,0] neg_hi:[0,1]
	v_pk_add_f32 v[134:135], v[134:135], v[142:143] op_sel:[0,1] op_sel_hi:[1,0] neg_lo:[0,1]
	v_pk_mul_f32 v[154:155], v[146:147], s[12:13] op_sel:[1,0] op_sel_hi:[0,0] neg_lo:[1,0]
	v_pk_add_f32 v[142:143], v[152:153], v[150:151]
	v_pk_fma_f32 v[146:147], v[146:147], s[12:13], v[154:155] op_sel_hi:[1,0,1] neg_lo:[0,0,1] neg_hi:[0,0,1]
	v_pk_mul_f32 v[154:155], v[130:131], s[36:37] op_sel:[1,0] op_sel_hi:[0,0] neg_lo:[1,0]
	v_pk_add_f32 v[150:151], v[152:153], v[150:151] neg_lo:[0,1] neg_hi:[0,1]
	v_pk_fma_f32 v[130:131], v[130:131], s[22:23], v[154:155] op_sel_hi:[1,0,1] neg_lo:[0,0,1] neg_hi:[0,0,1]
	v_pk_mul_f32 v[154:155], v[156:157], s[12:13] op_sel:[1,0] op_sel_hi:[0,0] neg_lo:[1,0]
	v_pk_fma_f32 v[154:155], v[156:157], s[12:13], v[154:155] op_sel_hi:[1,0,1] neg_lo:[0,0,1] neg_hi:[0,0,1]
	v_pk_fma_f32 v[148:149], v[148:149], 0, v[148:149] op_sel:[0,0,1] op_sel_hi:[1,0,0] neg_hi:[0,0,1]
	v_pk_mul_f32 v[156:157], v[132:133], s[12:13] op_sel:[1,0] op_sel_hi:[0,0] neg_lo:[1,0]
	v_pk_fma_f32 v[132:133], v[132:133], s[18:19], v[156:157] op_sel_hi:[1,0,1] neg_lo:[0,0,1] neg_hi:[0,0,1]
	v_pk_mul_f32 v[156:157], v[158:159], s[36:37] op_sel:[1,0] op_sel_hi:[0,0] neg_lo:[1,0]
	v_pk_mul_f32 v[152:153], v[160:161], s[22:23] op_sel:[1,0] op_sel_hi:[0,0] neg_lo:[1,0]
	v_pk_fma_f32 v[156:157], v[158:159], s[22:23], v[156:157] op_sel_hi:[1,0,1] neg_lo:[0,0,1] neg_hi:[0,0,1]
	v_pk_mul_f32 v[158:159], v[150:151], s[12:13] op_sel:[1,0] op_sel_hi:[0,0] neg_lo:[1,0]
	v_pk_fma_f32 v[152:153], v[160:161], s[36:37], v[152:153] op_sel_hi:[1,0,1] neg_lo:[0,0,1] neg_hi:[0,0,1]
	v_pk_fma_f32 v[150:151], v[150:151], s[18:19], v[158:159] op_sel_hi:[1,0,1] neg_lo:[0,0,1] neg_hi:[0,0,1]
	v_xor_b32_e32 v158, 0x80000000, v135
	v_mov_b32_e32 v159, v134
	v_pk_mul_f32 v[134:135], v[134:135], s[36:37] op_sel_hi:[1,0]
	v_pk_fma_f32 v[134:135], v[158:159], s[22:23], v[134:135] op_sel_hi:[1,0,1] neg_lo:[0,0,1] neg_hi:[0,0,1]
	v_pk_add_f32 v[158:159], v[136:137], v[140:141]
	v_pk_add_f32 v[136:137], v[136:137], v[140:141] neg_lo:[0,1] neg_hi:[0,1]
	v_pk_add_f32 v[140:141], v[138:139], v[142:143]
	v_pk_add_f32 v[138:139], v[138:139], v[142:143] neg_lo:[0,1] neg_hi:[0,1]
	v_xor_b32_e32 v143, 0x80000000, v138
	v_mov_b32_e32 v142, v139
	v_pk_add_f32 v[138:139], v[158:159], v[140:141]
	v_pk_add_f32 v[140:141], v[158:159], v[140:141] neg_lo:[0,1] neg_hi:[0,1]
	v_pk_add_f32 v[158:159], v[152:153], v[156:157]
	v_pk_add_f32 v[152:153], v[152:153], v[156:157] neg_lo:[0,1] neg_hi:[0,1]
	v_pk_add_f32 v[160:161], v[136:137], v[142:143]
	v_pk_add_f32 v[136:137], v[136:137], v[142:143] neg_lo:[0,1] neg_hi:[0,1]
	v_pk_add_f32 v[142:143], v[162:163], v[154:155]
	v_pk_add_f32 v[154:155], v[162:163], v[154:155] neg_lo:[0,1] neg_hi:[0,1]
	v_pk_add_f32 v[162:163], v[154:155], v[152:153] op_sel:[0,1] op_sel_hi:[1,0] neg_hi:[0,1]
	v_pk_add_f32 v[154:155], v[154:155], v[152:153] op_sel:[0,1] op_sel_hi:[1,0] neg_lo:[0,1]
	v_pk_add_f32 v[156:157], v[144:145], v[148:149]
	v_pk_add_f32 v[144:145], v[144:145], v[148:149] neg_lo:[0,1] neg_hi:[0,1]
	v_pk_add_f32 v[148:149], v[146:147], v[150:151]
	v_pk_add_f32 v[146:147], v[146:147], v[150:151] neg_lo:[0,1] neg_hi:[0,1]
	v_pk_add_f32 v[152:153], v[142:143], v[158:159]
	v_pk_add_f32 v[142:143], v[142:143], v[158:159] neg_lo:[0,1] neg_hi:[0,1]
	v_pk_add_f32 v[158:159], v[144:145], v[146:147] op_sel:[0,1] op_sel_hi:[1,0] neg_hi:[0,1]
	v_pk_add_f32 v[144:145], v[144:145], v[146:147] op_sel:[0,1] op_sel_hi:[1,0] neg_lo:[0,1]
	v_pk_add_f32 v[150:151], v[128:129], v[132:133]
	v_pk_add_f32 v[128:129], v[128:129], v[132:133] neg_lo:[0,1] neg_hi:[0,1]
	v_pk_add_f32 v[132:133], v[130:131], v[134:135]
	v_pk_add_f32 v[130:131], v[130:131], v[134:135] neg_lo:[0,1] neg_hi:[0,1]
	v_pk_add_f32 v[146:147], v[156:157], v[148:149]
	v_pk_add_f32 v[148:149], v[156:157], v[148:149] neg_lo:[0,1] neg_hi:[0,1]
	v_pk_add_f32 v[156:157], v[128:129], v[130:131] op_sel:[0,1] op_sel_hi:[1,0] neg_hi:[0,1]
	v_pk_add_f32 v[128:129], v[128:129], v[130:131] op_sel:[0,1] op_sel_hi:[1,0] neg_lo:[0,1]
	v_xor_b32_e32 v134, 0x80000000, v111
	v_mov_b32_e32 v135, v110
	v_pk_mul_f32 v[134:135], v[134:135], v[138:139] op_sel:[0,1]
	v_pk_add_f32 v[130:131], v[150:151], v[132:133]
	v_pk_fma_f32 v[110:111], v[110:111], v[138:139], v[134:135] op_sel_hi:[1,0,1]
	ds_write_b64 v164, v[110:111]
	v_pk_mul_f32 v[110:111], v[114:115], v[152:153] op_sel:[1,1] op_sel_hi:[0,1] neg_lo:[1,0]
	v_pk_add_f32 v[132:133], v[150:151], v[132:133] neg_lo:[0,1] neg_hi:[0,1]
	v_pk_fma_f32 v[110:111], v[114:115], v[152:153], v[110:111] op_sel_hi:[1,0,1]
	ds_write_b64 v164, v[110:111] offset:2176
	v_pk_mul_f32 v[110:111], v[116:117], v[146:147] op_sel:[1,1] op_sel_hi:[0,1] neg_lo:[1,0]
	v_pk_fma_f32 v[110:111], v[116:117], v[146:147], v[110:111] op_sel_hi:[1,0,1]
	ds_write_b64 v164, v[110:111] offset:4352
	v_pk_mul_f32 v[110:111], v[118:119], v[130:131] op_sel:[1,1] op_sel_hi:[0,1] neg_lo:[1,0]
	v_pk_fma_f32 v[110:111], v[118:119], v[130:131], v[110:111] op_sel_hi:[1,0,1]
	ds_write_b64 v164, v[110:111] offset:6528
	v_pk_mul_f32 v[110:111], v[120:121], v[160:161] op_sel:[1,1] op_sel_hi:[0,1] neg_lo:[1,0]
	v_pk_fma_f32 v[110:111], v[120:121], v[160:161], v[110:111] op_sel_hi:[1,0,1]
	ds_write_b64 v164, v[110:111] offset:8704
	v_pk_mul_f32 v[110:111], v[122:123], v[162:163] op_sel:[1,1] op_sel_hi:[0,1] neg_lo:[1,0]
	v_pk_fma_f32 v[110:111], v[122:123], v[162:163], v[110:111] op_sel_hi:[1,0,1]
	ds_write_b64 v164, v[110:111] offset:10880
	v_pk_mul_f32 v[110:111], v[124:125], v[158:159] op_sel:[1,1] op_sel_hi:[0,1] neg_lo:[1,0]
	v_pk_fma_f32 v[110:111], v[124:125], v[158:159], v[110:111] op_sel_hi:[1,0,1]
	ds_write_b64 v164, v[110:111] offset:13056
	v_pk_mul_f32 v[110:111], v[126:127], v[156:157] op_sel:[1,1] op_sel_hi:[0,1] neg_lo:[1,0]
	v_pk_fma_f32 v[110:111], v[126:127], v[156:157], v[110:111] op_sel_hi:[1,0,1]
	ds_write_b64 v164, v[110:111] offset:15232
	v_pk_mul_f32 v[110:111], v[112:113], v[140:141] op_sel:[1,1] op_sel_hi:[0,1] neg_lo:[1,0]
	v_pk_fma_f32 v[110:111], v[112:113], v[140:141], v[110:111] op_sel_hi:[1,0,1]
	ds_write_b64 v164, v[110:111] offset:17408
	v_pk_mul_f32 v[110:111], v[108:109], v[142:143] op_sel:[1,1] op_sel_hi:[0,1] neg_lo:[1,0]
	v_pk_fma_f32 v[108:109], v[108:109], v[142:143], v[110:111] op_sel_hi:[1,0,1]
	ds_write_b64 v164, v[108:109] offset:19584
	v_pk_mul_f32 v[108:109], v[106:107], v[148:149] op_sel:[1,1] op_sel_hi:[0,1] neg_lo:[1,0]
	v_pk_fma_f32 v[106:107], v[106:107], v[148:149], v[108:109] op_sel_hi:[1,0,1]
	ds_write_b64 v164, v[106:107] offset:21760
	v_pk_mul_f32 v[106:107], v[104:105], v[132:133] op_sel:[1,1] op_sel_hi:[0,1] neg_lo:[1,0]
	v_pk_fma_f32 v[104:105], v[104:105], v[132:133], v[106:107] op_sel_hi:[1,0,1]
	ds_write_b64 v164, v[104:105] offset:23936
	v_pk_mul_f32 v[104:105], v[6:7], v[136:137] op_sel:[1,1] op_sel_hi:[0,1] neg_lo:[1,0]
	v_pk_fma_f32 v[6:7], v[6:7], v[136:137], v[104:105] op_sel_hi:[1,0,1]
	ds_write_b64 v164, v[6:7] offset:26112
	v_pk_mul_f32 v[6:7], v[4:5], v[154:155] op_sel:[1,1] op_sel_hi:[0,1] neg_lo:[1,0]
	v_pk_fma_f32 v[4:5], v[4:5], v[154:155], v[6:7] op_sel_hi:[1,0,1]
	ds_write_b64 v164, v[4:5] offset:28288
	v_pk_mul_f32 v[4:5], v[2:3], v[144:145] op_sel:[1,1] op_sel_hi:[0,1] neg_lo:[1,0]
	v_pk_fma_f32 v[2:3], v[2:3], v[144:145], v[4:5] op_sel_hi:[1,0,1]
	ds_write_b64 v164, v[2:3] offset:30464
	v_pk_mul_f32 v[2:3], v[0:1], v[128:129] op_sel:[1,1] op_sel_hi:[0,1] neg_lo:[1,0]
	v_pk_fma_f32 v[0:1], v[0:1], v[128:129], v[2:3] op_sel_hi:[1,0,1]
	ds_write_b64 v164, v[0:1] offset:32640
	v_mov_b32_e32 v116, 1.0
	v_pk_mul_f32 v[2:3], v[210:211], v[210:211] op_sel:[1,1] op_sel_hi:[0,1] neg_lo:[1,0]
	v_mov_b32_e32 v117, v177
	v_pk_fma_f32 v[2:3], v[210:211], v[210:211], v[2:3] op_sel_hi:[0,1,1]
	v_pk_mul_f32 v[104:105], v[2:3], v[2:3] op_sel:[1,1] op_sel_hi:[1,0] neg_lo:[0,1]
	v_pk_mul_f32 v[4:5], v[210:211], v[176:177] op_sel:[1,1] op_sel_hi:[0,1] neg_lo:[1,0]
	v_pk_fma_f32 v[104:105], v[2:3], v[2:3], v[104:105] op_sel_hi:[1,0,1]
	v_pk_fma_f32 v[126:127], v[210:211], v[116:117], v[4:5] op_sel_hi:[1,0,1]
	v_pk_mul_f32 v[0:1], v[176:177], v[2:3] op_sel:[1,1] op_sel_hi:[1,0] neg_lo:[0,1]
	v_pk_fma_f32 v[124:125], v[116:117], v[2:3], v[0:1] op_sel_hi:[0,1,1]
	v_pk_mul_f32 v[0:1], v[126:127], v[2:3] op_sel:[1,1] op_sel_hi:[1,0] neg_lo:[0,1]
	v_pk_mul_f32 v[108:109], v[104:105], v[104:105] op_sel:[1,1] op_sel_hi:[1,0] neg_lo:[0,1]
	v_pk_fma_f32 v[122:123], v[2:3], v[126:127], v[0:1] op_sel_hi:[1,0,1]
	v_pk_mul_f32 v[0:1], v[176:177], v[104:105] op_sel:[1,1] op_sel_hi:[1,0] neg_lo:[0,1]
	v_pk_fma_f32 v[120:121], v[116:117], v[104:105], v[0:1] op_sel_hi:[0,1,1]
	v_pk_mul_f32 v[0:1], v[126:127], v[104:105] op_sel:[1,1] op_sel_hi:[1,0] neg_lo:[0,1]
	s_waitcnt lgkmcnt(0)
	v_pk_fma_f32 v[118:119], v[126:127], v[104:105], v[0:1] op_sel_hi:[0,1,1]
	v_pk_mul_f32 v[0:1], v[124:125], v[104:105] op_sel:[1,1] op_sel_hi:[1,0] neg_lo:[0,1]
	s_barrier
	v_pk_fma_f32 v[114:115], v[104:105], v[124:125], v[0:1] op_sel_hi:[1,0,1]
	v_pk_mul_f32 v[0:1], v[122:123], v[104:105] op_sel:[1,1] op_sel_hi:[1,0] neg_lo:[0,1]
	v_pk_fma_f32 v[112:113], v[104:105], v[122:123], v[0:1] op_sel_hi:[1,0,1]
	v_pk_fma_f32 v[0:1], v[104:105], v[104:105], v[108:109] op_sel_hi:[1,0,1]
	v_pk_mul_f32 v[2:3], v[176:177], v[0:1] op_sel:[1,1] op_sel_hi:[1,0] neg_lo:[0,1]
	v_pk_fma_f32 v[110:111], v[116:117], v[0:1], v[2:3] op_sel_hi:[0,1,1]
	v_pk_mul_f32 v[2:3], v[126:127], v[0:1] op_sel:[1,1] op_sel_hi:[1,0] neg_lo:[0,1]
	v_pk_fma_f32 v[108:109], v[126:127], v[0:1], v[2:3] op_sel_hi:[0,1,1]
	v_pk_mul_f32 v[2:3], v[124:125], v[0:1] op_sel:[1,1] op_sel_hi:[1,0] neg_lo:[0,1]
	v_pk_fma_f32 v[106:107], v[124:125], v[0:1], v[2:3] op_sel_hi:[0,1,1]
	v_pk_mul_f32 v[2:3], v[122:123], v[0:1] op_sel:[1,1] op_sel_hi:[1,0] neg_lo:[0,1]
	v_pk_fma_f32 v[104:105], v[122:123], v[0:1], v[2:3] op_sel_hi:[0,1,1]
	v_pk_mul_f32 v[2:3], v[120:121], v[0:1] op_sel:[1,1] op_sel_hi:[1,0] neg_lo:[0,1]
	v_pk_fma_f32 v[6:7], v[0:1], v[120:121], v[2:3] op_sel_hi:[1,0,1]
	v_pk_mul_f32 v[2:3], v[118:119], v[0:1] op_sel:[1,1] op_sel_hi:[1,0] neg_lo:[0,1]
	v_pk_fma_f32 v[4:5], v[0:1], v[118:119], v[2:3] op_sel_hi:[1,0,1]
	v_pk_mul_f32 v[2:3], v[114:115], v[0:1] op_sel:[1,1] op_sel_hi:[1,0] neg_lo:[0,1]
	v_pk_mul_f32 v[128:129], v[112:113], v[0:1] op_sel:[1,1] op_sel_hi:[1,0] neg_lo:[0,1]
	v_pk_fma_f32 v[2:3], v[0:1], v[114:115], v[2:3] op_sel_hi:[1,0,1]
	v_pk_fma_f32 v[0:1], v[0:1], v[112:113], v[128:129] op_sel_hi:[1,0,1]
	s_nop 0
	v_bfe_u32 v129, v206, 4, 4
	v_and_b32_e32 v128, 15, v206
	v_mul_u32_u24_e32 v129, 0x880, v129
	v_lshlrev_b32_e32 v128, 3, v128
	v_add3_u32 v184, v207, v129, v128
	ds_read2_b64 v[128:131], v184 offset1:17
	ds_read2_b64 v[132:135], v184 offset0:34 offset1:51
	ds_read2_b64 v[136:139], v184 offset0:68 offset1:85
	ds_read2_b64 v[140:143], v184 offset0:102 offset1:119
	ds_read2_b64 v[144:147], v184 offset0:136 offset1:153
	ds_read2_b64 v[148:151], v184 offset0:170 offset1:187
	ds_read2_b64 v[152:155], v184 offset0:204 offset1:221
	ds_read2_b64 v[156:159], v184 offset0:238 offset1:255
	s_waitcnt lgkmcnt(3)
	v_pk_add_f32 v[160:161], v[128:129], v[144:145]
	v_pk_add_f32 v[128:129], v[128:129], v[144:145] neg_lo:[0,1] neg_hi:[0,1]
	s_waitcnt lgkmcnt(1)
	v_pk_add_f32 v[144:145], v[136:137], v[152:153]
	v_pk_add_f32 v[136:137], v[136:137], v[152:153] neg_lo:[0,1] neg_hi:[0,1]
	v_pk_add_f32 v[162:163], v[128:129], v[136:137] op_sel:[0,1] op_sel_hi:[1,0] neg_hi:[0,1]
	v_pk_add_f32 v[128:129], v[128:129], v[136:137] op_sel:[0,1] op_sel_hi:[1,0] neg_lo:[0,1]
	v_pk_add_f32 v[152:153], v[130:131], v[146:147]
	v_pk_add_f32 v[130:131], v[130:131], v[146:147] neg_lo:[0,1] neg_hi:[0,1]
	v_pk_add_f32 v[146:147], v[138:139], v[154:155]
	v_pk_add_f32 v[138:139], v[138:139], v[154:155] neg_lo:[0,1] neg_hi:[0,1]
	v_pk_add_f32 v[136:137], v[160:161], v[144:145]
	v_xor_b32_e32 v155, 0x80000000, v138
	v_mov_b32_e32 v154, v139
	v_pk_add_f32 v[138:139], v[152:153], v[146:147]
	v_pk_add_f32 v[146:147], v[152:153], v[146:147] neg_lo:[0,1] neg_hi:[0,1]
	v_pk_add_f32 v[152:153], v[132:133], v[148:149]
	v_pk_add_f32 v[132:133], v[132:133], v[148:149] neg_lo:[0,1] neg_hi:[0,1]
	s_waitcnt lgkmcnt(0)
	v_pk_add_f32 v[148:149], v[140:141], v[156:157]
	v_pk_add_f32 v[140:141], v[140:141], v[156:157] neg_lo:[0,1] neg_hi:[0,1]
	v_pk_add_f32 v[144:145], v[160:161], v[144:145] neg_lo:[0,1] neg_hi:[0,1]
	v_pk_add_f32 v[160:161], v[130:131], v[154:155]
	v_pk_add_f32 v[130:131], v[130:131], v[154:155] neg_lo:[0,1] neg_hi:[0,1]
	v_xor_b32_e32 v155, 0x80000000, v140
	v_mov_b32_e32 v154, v141
	v_pk_add_f32 v[140:141], v[152:153], v[148:149]
	v_pk_add_f32 v[148:149], v[152:153], v[148:149] neg_lo:[0,1] neg_hi:[0,1]
	v_pk_add_f32 v[152:153], v[134:135], v[150:151]
	v_pk_add_f32 v[134:135], v[134:135], v[150:151] neg_lo:[0,1] neg_hi:[0,1]
	v_pk_add_f32 v[150:151], v[142:143], v[158:159]
	v_pk_add_f32 v[142:143], v[142:143], v[158:159] neg_lo:[0,1] neg_hi:[0,1]
	v_pk_add_f32 v[156:157], v[132:133], v[154:155]
	v_pk_add_f32 v[132:133], v[132:133], v[154:155] neg_lo:[0,1] neg_hi:[0,1]
	v_pk_add_f32 v[158:159], v[134:135], v[142:143] op_sel:[0,1] op_sel_hi:[1,0] neg_hi:[0,1]
	v_pk_add_f32 v[134:135], v[134:135], v[142:143] op_sel:[0,1] op_sel_hi:[1,0] neg_lo:[0,1]
	v_pk_mul_f32 v[154:155], v[146:147], s[12:13] op_sel:[1,0] op_sel_hi:[0,0] neg_lo:[1,0]
	v_pk_add_f32 v[142:143], v[152:153], v[150:151]
	v_pk_fma_f32 v[146:147], v[146:147], s[12:13], v[154:155] op_sel_hi:[1,0,1] neg_lo:[0,0,1] neg_hi:[0,0,1]
	v_pk_mul_f32 v[154:155], v[130:131], s[36:37] op_sel:[1,0] op_sel_hi:[0,0] neg_lo:[1,0]
	v_pk_add_f32 v[150:151], v[152:153], v[150:151] neg_lo:[0,1] neg_hi:[0,1]
	v_pk_fma_f32 v[130:131], v[130:131], s[22:23], v[154:155] op_sel_hi:[1,0,1] neg_lo:[0,0,1] neg_hi:[0,0,1]
	v_pk_mul_f32 v[154:155], v[156:157], s[12:13] op_sel:[1,0] op_sel_hi:[0,0] neg_lo:[1,0]
	v_pk_fma_f32 v[154:155], v[156:157], s[12:13], v[154:155] op_sel_hi:[1,0,1] neg_lo:[0,0,1] neg_hi:[0,0,1]
	v_pk_fma_f32 v[148:149], v[148:149], 0, v[148:149] op_sel:[0,0,1] op_sel_hi:[1,0,0] neg_hi:[0,0,1]
	v_pk_mul_f32 v[156:157], v[132:133], s[12:13] op_sel:[1,0] op_sel_hi:[0,0] neg_lo:[1,0]
	v_pk_fma_f32 v[132:133], v[132:133], s[18:19], v[156:157] op_sel_hi:[1,0,1] neg_lo:[0,0,1] neg_hi:[0,0,1]
	v_pk_mul_f32 v[156:157], v[158:159], s[36:37] op_sel:[1,0] op_sel_hi:[0,0] neg_lo:[1,0]
	v_pk_mul_f32 v[152:153], v[160:161], s[22:23] op_sel:[1,0] op_sel_hi:[0,0] neg_lo:[1,0]
	v_pk_fma_f32 v[156:157], v[158:159], s[22:23], v[156:157] op_sel_hi:[1,0,1] neg_lo:[0,0,1] neg_hi:[0,0,1]
	v_pk_mul_f32 v[158:159], v[150:151], s[12:13] op_sel:[1,0] op_sel_hi:[0,0] neg_lo:[1,0]
	v_pk_fma_f32 v[152:153], v[160:161], s[36:37], v[152:153] op_sel_hi:[1,0,1] neg_lo:[0,0,1] neg_hi:[0,0,1]
	v_pk_fma_f32 v[150:151], v[150:151], s[18:19], v[158:159] op_sel_hi:[1,0,1] neg_lo:[0,0,1] neg_hi:[0,0,1]
	v_xor_b32_e32 v158, 0x80000000, v135
	v_mov_b32_e32 v159, v134
	v_pk_mul_f32 v[134:135], v[134:135], s[36:37] op_sel_hi:[1,0]
	v_pk_fma_f32 v[134:135], v[158:159], s[22:23], v[134:135] op_sel_hi:[1,0,1] neg_lo:[0,0,1] neg_hi:[0,0,1]
	v_pk_add_f32 v[158:159], v[136:137], v[140:141]
	v_pk_add_f32 v[136:137], v[136:137], v[140:141] neg_lo:[0,1] neg_hi:[0,1]
	v_pk_add_f32 v[140:141], v[138:139], v[142:143]
	v_pk_add_f32 v[138:139], v[138:139], v[142:143] neg_lo:[0,1] neg_hi:[0,1]
	v_pk_add_f32 v[164:165], v[158:159], v[140:141] neg_lo:[0,1] neg_hi:[0,1]
	v_pk_add_f32 v[160:161], v[136:137], v[138:139] op_sel:[0,1] op_sel_hi:[1,0] neg_hi:[0,1]
	v_pk_add_f32 v[166:167], v[136:137], v[138:139] op_sel:[0,1] op_sel_hi:[1,0] neg_lo:[0,1]
	v_pk_add_f32 v[142:143], v[152:153], v[156:157]
	v_pk_add_f32 v[152:153], v[152:153], v[156:157] neg_lo:[0,1] neg_hi:[0,1]
	v_pk_add_f32 v[138:139], v[158:159], v[140:141]
	v_pk_add_f32 v[136:137], v[162:163], v[154:155]
	v_pk_add_f32 v[140:141], v[162:163], v[154:155] neg_lo:[0,1] neg_hi:[0,1]
	v_xor_b32_e32 v155, 0x80000000, v152
	v_mov_b32_e32 v154, v153
	v_pk_add_f32 v[152:153], v[136:137], v[142:143]
	v_pk_add_f32 v[162:163], v[140:141], v[154:155]
	v_pk_add_f32 v[168:169], v[136:137], v[142:143] neg_lo:[0,1] neg_hi:[0,1]
	v_pk_add_f32 v[170:171], v[140:141], v[154:155] neg_lo:[0,1] neg_hi:[0,1]
	v_pk_add_f32 v[136:137], v[144:145], v[148:149]
	v_pk_add_f32 v[140:141], v[144:145], v[148:149] neg_lo:[0,1] neg_hi:[0,1]
	v_pk_add_f32 v[142:143], v[146:147], v[150:151]
	v_pk_add_f32 v[144:145], v[146:147], v[150:151] neg_lo:[0,1] neg_hi:[0,1]
	v_pk_add_f32 v[172:173], v[136:137], v[142:143] neg_lo:[0,1] neg_hi:[0,1]
	v_xor_b32_e32 v147, 0x80000000, v144
	v_mov_b32_e32 v146, v145
	v_pk_add_f32 v[144:145], v[136:137], v[142:143]
	v_pk_add_f32 v[136:137], v[128:129], v[132:133]
	v_pk_add_f32 v[128:129], v[128:129], v[132:133] neg_lo:[0,1] neg_hi:[0,1]
	v_pk_add_f32 v[132:133], v[130:131], v[134:135]
	v_pk_add_f32 v[130:131], v[130:131], v[134:135] neg_lo:[0,1] neg_hi:[0,1]
	v_xor_b32_e32 v142, 0x80000000, v117
	v_xor_b32_e32 v135, 0x80000000, v130
	v_mov_b32_e32 v134, v131
	v_mov_b32_e32 v143, v116
	v_pk_add_f32 v[148:149], v[140:141], v[146:147]
	v_pk_add_f32 v[174:175], v[140:141], v[146:147] neg_lo:[0,1] neg_hi:[0,1]
	v_pk_add_f32 v[130:131], v[136:137], v[132:133]
	v_pk_add_f32 v[146:147], v[128:129], v[134:135]
	v_pk_add_f32 v[198:199], v[136:137], v[132:133] neg_lo:[0,1] neg_hi:[0,1]
	v_pk_add_f32 v[200:201], v[128:129], v[134:135] neg_lo:[0,1] neg_hi:[0,1]
	v_pk_mul_f32 v[128:129], v[142:143], v[138:139] op_sel:[0,1]
	v_pk_mul_f32 v[132:133], v[126:127], v[152:153] op_sel:[1,1] op_sel_hi:[0,1] neg_lo:[1,0]
	v_pk_fma_f32 v[128:129], v[116:117], v[138:139], v[128:129] op_sel_hi:[1,0,1]
	v_pk_fma_f32 v[132:133], v[126:127], v[152:153], v[132:133] op_sel_hi:[1,0,1]
	ds_write2_b64 v184, v[128:129], v[132:133] offset1:17
	v_pk_mul_f32 v[128:129], v[124:125], v[144:145] op_sel:[1,1] op_sel_hi:[0,1] neg_lo:[1,0]
	v_pk_mul_f32 v[132:133], v[122:123], v[130:131] op_sel:[1,1] op_sel_hi:[0,1] neg_lo:[1,0]
	v_pk_fma_f32 v[128:129], v[124:125], v[144:145], v[128:129] op_sel_hi:[1,0,1]
	v_pk_fma_f32 v[130:131], v[122:123], v[130:131], v[132:133] op_sel_hi:[1,0,1]
	ds_write2_b64 v184, v[128:129], v[130:131] offset0:34 offset1:51
	v_pk_mul_f32 v[128:129], v[120:121], v[160:161] op_sel:[1,1] op_sel_hi:[0,1] neg_lo:[1,0]
	v_pk_mul_f32 v[130:131], v[118:119], v[162:163] op_sel:[1,1] op_sel_hi:[0,1] neg_lo:[1,0]
	v_pk_fma_f32 v[128:129], v[120:121], v[160:161], v[128:129] op_sel_hi:[1,0,1]
	v_pk_fma_f32 v[130:131], v[118:119], v[162:163], v[130:131] op_sel_hi:[1,0,1]
	ds_write2_b64 v184, v[128:129], v[130:131] offset0:68 offset1:85
	v_pk_mul_f32 v[128:129], v[114:115], v[148:149] op_sel:[1,1] op_sel_hi:[0,1] neg_lo:[1,0]
	v_pk_mul_f32 v[130:131], v[112:113], v[146:147] op_sel:[1,1] op_sel_hi:[0,1] neg_lo:[1,0]
	v_pk_fma_f32 v[128:129], v[114:115], v[148:149], v[128:129] op_sel_hi:[1,0,1]
	v_pk_fma_f32 v[130:131], v[112:113], v[146:147], v[130:131] op_sel_hi:[1,0,1]
	ds_write2_b64 v184, v[128:129], v[130:131] offset0:102 offset1:119
	v_pk_mul_f32 v[128:129], v[110:111], v[164:165] op_sel:[1,1] op_sel_hi:[0,1] neg_lo:[1,0]
	v_pk_mul_f32 v[130:131], v[108:109], v[168:169] op_sel:[1,1] op_sel_hi:[0,1] neg_lo:[1,0]
	v_pk_fma_f32 v[128:129], v[110:111], v[164:165], v[128:129] op_sel_hi:[1,0,1]
	v_pk_fma_f32 v[130:131], v[108:109], v[168:169], v[130:131] op_sel_hi:[1,0,1]
	ds_write2_b64 v184, v[128:129], v[130:131] offset0:136 offset1:153
	v_pk_mul_f32 v[128:129], v[106:107], v[172:173] op_sel:[1,1] op_sel_hi:[0,1] neg_lo:[1,0]
	v_pk_mul_f32 v[130:131], v[104:105], v[198:199] op_sel:[1,1] op_sel_hi:[0,1] neg_lo:[1,0]
	v_pk_fma_f32 v[128:129], v[106:107], v[172:173], v[128:129] op_sel_hi:[1,0,1]
	v_pk_fma_f32 v[130:131], v[104:105], v[198:199], v[130:131] op_sel_hi:[1,0,1]
	ds_write2_b64 v184, v[128:129], v[130:131] offset0:170 offset1:187
	v_pk_mul_f32 v[128:129], v[6:7], v[166:167] op_sel:[1,1] op_sel_hi:[0,1] neg_lo:[1,0]
	v_pk_mul_f32 v[144:145], v[4:5], v[170:171] op_sel:[1,1] op_sel_hi:[0,1] neg_lo:[1,0]
	v_pk_fma_f32 v[128:129], v[6:7], v[166:167], v[128:129] op_sel_hi:[1,0,1]
	v_pk_fma_f32 v[144:145], v[4:5], v[170:171], v[144:145] op_sel_hi:[1,0,1]
	ds_write2_b64 v184, v[128:129], v[144:145] offset0:204 offset1:221
	v_pk_mul_f32 v[144:145], v[2:3], v[174:175] op_sel:[1,1] op_sel_hi:[0,1] neg_lo:[1,0]
	v_pk_fma_f32 v[160:161], v[2:3], v[174:175], v[144:145] op_sel_hi:[1,0,1]
	v_pk_mul_f32 v[162:163], v[0:1], v[200:201] op_sel:[1,1] op_sel_hi:[0,1] neg_lo:[1,0]
	v_pk_fma_f32 v[162:163], v[0:1], v[200:201], v[162:163] op_sel_hi:[1,0,1]
	ds_write2_b64 v184, v[160:161], v[162:163] offset0:238 offset1:255
	s_waitcnt lgkmcnt(0)
	s_barrier
	s_nop 0
	v_and_b32_e32 v129, 0xff, v206
	v_mad_u32_u24 v129, v129, s19, v207
	ds_read2_b64 v[160:163], v129 offset1:1
	ds_read2_b64 v[164:167], v129 offset0:2 offset1:3
	ds_read2_b64 v[168:171], v129 offset0:4 offset1:5
	ds_read2_b64 v[172:175], v129 offset0:6 offset1:7
	ds_read2_b64 v[198:201], v129 offset0:8 offset1:9
	ds_read2_b64 v[202:205], v129 offset0:10 offset1:11
	ds_read2_b64 v[236:239], v129 offset0:12 offset1:13
	ds_read2_b64 v[240:243], v129 offset0:14 offset1:15
	s_waitcnt lgkmcnt(3)
	v_pk_add_f32 v[244:245], v[160:161], v[198:199]
	v_pk_add_f32 v[160:161], v[160:161], v[198:199] neg_lo:[0,1] neg_hi:[0,1]
	s_waitcnt lgkmcnt(1)
	v_pk_add_f32 v[198:199], v[168:169], v[236:237]
	v_pk_add_f32 v[168:169], v[168:169], v[236:237] neg_lo:[0,1] neg_hi:[0,1]
	v_pk_add_f32 v[246:247], v[160:161], v[168:169] op_sel:[0,1] op_sel_hi:[1,0] neg_hi:[0,1]
	v_pk_add_f32 v[160:161], v[160:161], v[168:169] op_sel:[0,1] op_sel_hi:[1,0] neg_lo:[0,1]
	v_pk_add_f32 v[236:237], v[162:163], v[200:201]
	v_pk_add_f32 v[162:163], v[162:163], v[200:201] neg_lo:[0,1] neg_hi:[0,1]
	v_pk_add_f32 v[200:201], v[170:171], v[238:239]
	v_pk_add_f32 v[170:171], v[170:171], v[238:239] neg_lo:[0,1] neg_hi:[0,1]
	v_pk_add_f32 v[168:169], v[244:245], v[198:199]
	v_xor_b32_e32 v239, 0x80000000, v170
	v_mov_b32_e32 v238, v171
	v_pk_add_f32 v[170:171], v[236:237], v[200:201]
	v_pk_add_f32 v[200:201], v[236:237], v[200:201] neg_lo:[0,1] neg_hi:[0,1]
	v_pk_add_f32 v[236:237], v[164:165], v[202:203]
	v_pk_add_f32 v[164:165], v[164:165], v[202:203] neg_lo:[0,1] neg_hi:[0,1]
	s_waitcnt lgkmcnt(0)
	v_pk_add_f32 v[202:203], v[172:173], v[240:241]
	v_pk_add_f32 v[172:173], v[172:173], v[240:241] neg_lo:[0,1] neg_hi:[0,1]
	v_pk_add_f32 v[198:199], v[244:245], v[198:199] neg_lo:[0,1] neg_hi:[0,1]
	v_pk_add_f32 v[244:245], v[162:163], v[238:239]
	v_pk_add_f32 v[162:163], v[162:163], v[238:239] neg_lo:[0,1] neg_hi:[0,1]
	v_xor_b32_e32 v239, 0x80000000, v172
	v_mov_b32_e32 v238, v173
	v_pk_add_f32 v[172:173], v[236:237], v[202:203]
	v_pk_add_f32 v[202:203], v[236:237], v[202:203] neg_lo:[0,1] neg_hi:[0,1]
	v_pk_add_f32 v[236:237], v[166:167], v[204:205]
	v_pk_add_f32 v[166:167], v[166:167], v[204:205] neg_lo:[0,1] neg_hi:[0,1]
	v_pk_add_f32 v[204:205], v[174:175], v[242:243]
	v_pk_add_f32 v[174:175], v[174:175], v[242:243] neg_lo:[0,1] neg_hi:[0,1]
	v_pk_add_f32 v[240:241], v[164:165], v[238:239]
	v_pk_add_f32 v[164:165], v[164:165], v[238:239] neg_lo:[0,1] neg_hi:[0,1]
	v_pk_add_f32 v[242:243], v[166:167], v[174:175] op_sel:[0,1] op_sel_hi:[1,0] neg_hi:[0,1]
	v_pk_add_f32 v[166:167], v[166:167], v[174:175] op_sel:[0,1] op_sel_hi:[1,0] neg_lo:[0,1]
	v_pk_mul_f32 v[238:239], v[200:201], s[12:13] op_sel:[1,0] op_sel_hi:[0,0] neg_lo:[1,0]
	v_pk_add_f32 v[174:175], v[236:237], v[204:205]
	v_pk_fma_f32 v[200:201], v[200:201], s[12:13], v[238:239] op_sel_hi:[1,0,1] neg_lo:[0,0,1] neg_hi:[0,0,1]
	v_pk_mul_f32 v[238:239], v[162:163], s[36:37] op_sel:[1,0] op_sel_hi:[0,0] neg_lo:[1,0]
	v_pk_add_f32 v[204:205], v[236:237], v[204:205] neg_lo:[0,1] neg_hi:[0,1]
	v_pk_fma_f32 v[162:163], v[162:163], s[22:23], v[238:239] op_sel_hi:[1,0,1] neg_lo:[0,0,1] neg_hi:[0,0,1]
	v_pk_mul_f32 v[238:239], v[240:241], s[12:13] op_sel:[1,0] op_sel_hi:[0,0] neg_lo:[1,0]
	v_pk_fma_f32 v[238:239], v[240:241], s[12:13], v[238:239] op_sel_hi:[1,0,1] neg_lo:[0,0,1] neg_hi:[0,0,1]
	v_pk_fma_f32 v[202:203], v[202:203], 0, v[202:203] op_sel:[0,0,1] op_sel_hi:[1,0,0] neg_hi:[0,0,1]
	v_pk_mul_f32 v[240:241], v[164:165], s[12:13] op_sel:[1,0] op_sel_hi:[0,0] neg_lo:[1,0]
	v_pk_fma_f32 v[164:165], v[164:165], s[18:19], v[240:241] op_sel_hi:[1,0,1] neg_lo:[0,0,1] neg_hi:[0,0,1]
	v_pk_mul_f32 v[240:241], v[242:243], s[36:37] op_sel:[1,0] op_sel_hi:[0,0] neg_lo:[1,0]
	v_pk_mul_f32 v[236:237], v[244:245], s[22:23] op_sel:[1,0] op_sel_hi:[0,0] neg_lo:[1,0]
	v_pk_fma_f32 v[240:241], v[242:243], s[22:23], v[240:241] op_sel_hi:[1,0,1] neg_lo:[0,0,1] neg_hi:[0,0,1]
	v_pk_mul_f32 v[242:243], v[204:205], s[12:13] op_sel:[1,0] op_sel_hi:[0,0] neg_lo:[1,0]
	v_pk_fma_f32 v[236:237], v[244:245], s[36:37], v[236:237] op_sel_hi:[1,0,1] neg_lo:[0,0,1] neg_hi:[0,0,1]
	v_pk_fma_f32 v[204:205], v[204:205], s[18:19], v[242:243] op_sel_hi:[1,0,1] neg_lo:[0,0,1] neg_hi:[0,0,1]
	v_xor_b32_e32 v242, 0x80000000, v167
	v_mov_b32_e32 v243, v166
	v_pk_mul_f32 v[166:167], v[166:167], s[36:37] op_sel_hi:[1,0]
	v_pk_fma_f32 v[166:167], v[242:243], s[22:23], v[166:167] op_sel_hi:[1,0,1] neg_lo:[0,0,1] neg_hi:[0,0,1]
	v_pk_add_f32 v[242:243], v[168:169], v[172:173]
	v_pk_add_f32 v[168:169], v[168:169], v[172:173] neg_lo:[0,1] neg_hi:[0,1]
	v_pk_add_f32 v[172:173], v[170:171], v[174:175]
	v_pk_add_f32 v[170:171], v[170:171], v[174:175] neg_lo:[0,1] neg_hi:[0,1]
	v_pk_add_f32 v[244:245], v[242:243], v[172:173]
	v_pk_add_f32 v[248:249], v[168:169], v[170:171] op_sel:[0,1] op_sel_hi:[1,0] neg_hi:[0,1]
	v_pk_add_f32 v[250:251], v[168:169], v[170:171] op_sel:[0,1] op_sel_hi:[1,0] neg_lo:[0,1]
	v_pk_add_f32 v[174:175], v[236:237], v[240:241] neg_lo:[0,1] neg_hi:[0,1]
	v_pk_add_f32 v[242:243], v[242:243], v[172:173] neg_lo:[0,1] neg_hi:[0,1]
	v_pk_add_f32 v[168:169], v[246:247], v[238:239]
	v_pk_add_f32 v[172:173], v[236:237], v[240:241]
	v_xor_b32_e32 v237, 0x80000000, v174
	v_mov_b32_e32 v236, v175
	v_pk_add_f32 v[174:175], v[200:201], v[204:205] neg_lo:[0,1] neg_hi:[0,1]
	v_pk_add_f32 v[170:171], v[246:247], v[238:239] neg_lo:[0,1] neg_hi:[0,1]
	v_pk_add_f32 v[238:239], v[168:169], v[172:173]
	v_pk_add_f32 v[246:247], v[168:169], v[172:173] neg_lo:[0,1] neg_hi:[0,1]
	v_pk_add_f32 v[172:173], v[200:201], v[204:205]
	v_xor_b32_e32 v201, 0x80000000, v174
	v_mov_b32_e32 v200, v175
	v_pk_add_f32 v[174:175], v[160:161], v[164:165]
	v_pk_add_f32 v[160:161], v[160:161], v[164:165] neg_lo:[0,1] neg_hi:[0,1]
	v_pk_add_f32 v[164:165], v[162:163], v[166:167]
	v_pk_add_f32 v[162:163], v[162:163], v[166:167] neg_lo:[0,1] neg_hi:[0,1]
	v_pk_add_f32 v[240:241], v[170:171], v[236:237]
	v_pk_add_f32 v[192:193], v[170:171], v[236:237] neg_lo:[0,1] neg_hi:[0,1]
	v_pk_add_f32 v[168:169], v[198:199], v[202:203]
	v_pk_add_f32 v[170:171], v[198:199], v[202:203] neg_lo:[0,1] neg_hi:[0,1]
	v_xor_b32_e32 v167, 0x80000000, v162
	v_mov_b32_e32 v166, v163
	v_pk_add_f32 v[194:195], v[168:169], v[172:173]
	v_pk_add_f32 v[184:185], v[170:171], v[200:201]
	v_pk_add_f32 v[198:199], v[168:169], v[172:173] neg_lo:[0,1] neg_hi:[0,1]
	v_pk_add_f32 v[172:173], v[170:171], v[200:201] neg_lo:[0,1] neg_hi:[0,1]
	v_pk_add_f32 v[170:171], v[174:175], v[164:165]
	v_pk_add_f32 v[168:169], v[160:161], v[162:163] op_sel:[0,1] op_sel_hi:[1,0] neg_hi:[0,1]
	v_pk_add_f32 v[162:163], v[174:175], v[164:165] neg_lo:[0,1] neg_hi:[0,1]
	v_pk_add_f32 v[160:161], v[160:161], v[166:167] neg_lo:[0,1] neg_hi:[0,1]
	ds_read2st64_b64 v[164:167], v234 offset1:8
	ds_read2st64_b64 v[200:203], v234 offset0:16 offset1:24
	s_waitcnt lgkmcnt(1)
	v_pk_mul_f32 v[174:175], v[164:165], v[244:245] op_sel:[1,1] op_sel_hi:[0,1] neg_lo:[1,0]
	v_pk_fma_f32 v[164:165], v[164:165], v[244:245], v[174:175] op_sel_hi:[1,0,1]
	v_pk_mul_f32 v[174:175], v[166:167], v[248:249] op_sel:[1,1] op_sel_hi:[0,1] neg_lo:[1,0]
	v_pk_fma_f32 v[166:167], v[166:167], v[248:249], v[174:175] op_sel_hi:[1,0,1]
	s_waitcnt lgkmcnt(0)
	v_pk_mul_f32 v[174:175], v[242:243], v[200:201] op_sel:[1,1] op_sel_hi:[1,0] neg_lo:[0,1]
	v_pk_fma_f32 v[174:175], v[200:201], v[242:243], v[174:175] op_sel_hi:[1,0,1]
	v_pk_mul_f32 v[200:201], v[202:203], v[250:251] op_sel:[1,1] op_sel_hi:[0,1] neg_lo:[1,0]
	v_pk_fma_f32 v[200:201], v[202:203], v[250:251], v[200:201] op_sel_hi:[1,0,1]
	ds_read2st64_b64 v[202:205], v234 offset0:32 offset1:40
	s_waitcnt lgkmcnt(0)
	v_pk_mul_f32 v[236:237], v[202:203], v[238:239] op_sel:[1,1] op_sel_hi:[0,1] neg_lo:[1,0]
	v_pk_fma_f32 v[202:203], v[202:203], v[238:239], v[236:237] op_sel_hi:[1,0,1]
	v_pk_mul_f32 v[236:237], v[204:205], v[240:241] op_sel:[1,1] op_sel_hi:[0,1] neg_lo:[1,0]
	v_pk_fma_f32 v[204:205], v[204:205], v[240:241], v[236:237] op_sel_hi:[1,0,1]
	ds_read2st64_b64 v[236:239], v234 offset0:48 offset1:56
	s_waitcnt lgkmcnt(0)
	v_pk_mul_f32 v[240:241], v[236:237], v[246:247] op_sel:[1,1] op_sel_hi:[0,1] neg_lo:[1,0]
	v_pk_fma_f32 v[240:241], v[236:237], v[246:247], v[240:241] op_sel_hi:[1,0,1]
	v_pk_mul_f32 v[236:237], v[238:239], v[192:193] op_sel:[1,1] op_sel_hi:[0,1] neg_lo:[1,0]
	v_pk_fma_f32 v[192:193], v[238:239], v[192:193], v[236:237] op_sel_hi:[1,0,1]
	ds_read2st64_b64 v[236:239], v234 offset0:64 offset1:72
	s_waitcnt lgkmcnt(0)
	v_pk_mul_f32 v[242:243], v[194:195], v[236:237] op_sel:[1,1] op_sel_hi:[1,0] neg_lo:[0,1]
	v_pk_fma_f32 v[194:195], v[236:237], v[194:195], v[242:243] op_sel_hi:[1,0,1]
	v_pk_mul_f32 v[236:237], v[184:185], v[238:239] op_sel:[1,1] op_sel_hi:[1,0] neg_lo:[0,1]
	v_pk_fma_f32 v[184:185], v[238:239], v[184:185], v[236:237] op_sel_hi:[1,0,1]
	ds_read2st64_b64 v[236:239], v234 offset0:80 offset1:88
	s_waitcnt lgkmcnt(0)
	v_pk_mul_f32 v[242:243], v[198:199], v[236:237] op_sel:[1,1] op_sel_hi:[1,0] neg_lo:[0,1]
	v_pk_fma_f32 v[198:199], v[198:199], v[236:237], v[242:243] op_sel_hi:[0,1,1]
	v_pk_mul_f32 v[236:237], v[172:173], v[238:239] op_sel:[1,1] op_sel_hi:[1,0] neg_lo:[0,1]
	v_pk_fma_f32 v[172:173], v[238:239], v[172:173], v[236:237] op_sel_hi:[1,0,1]
	ds_read2st64_b64 v[236:239], v234 offset0:96 offset1:104
	s_waitcnt lgkmcnt(0)
	v_pk_mul_f32 v[242:243], v[170:171], v[236:237] op_sel:[1,1] op_sel_hi:[1,0] neg_lo:[0,1]
	v_pk_fma_f32 v[236:237], v[170:171], v[236:237], v[242:243] op_sel_hi:[0,1,1]
	v_pk_mul_f32 v[170:171], v[168:169], v[238:239] op_sel:[1,1] op_sel_hi:[1,0] neg_lo:[0,1]
	v_pk_fma_f32 v[238:239], v[238:239], v[168:169], v[170:171] op_sel_hi:[1,0,1]
	ds_read2st64_b64 v[168:171], v234 offset0:112 offset1:120
	s_waitcnt lgkmcnt(0)
	v_pk_mul_f32 v[234:235], v[162:163], v[168:169] op_sel:[1,1] op_sel_hi:[1,0] neg_lo:[0,1]
	v_pk_fma_f32 v[162:163], v[162:163], v[168:169], v[234:235] op_sel_hi:[0,1,1]
	v_pk_mul_f32 v[168:169], v[160:161], v[170:171] op_sel:[1,1] op_sel_hi:[1,0] neg_lo:[0,1]
	v_pk_fma_f32 v[160:161], v[160:161], v[170:171], v[168:169] op_sel_hi:[0,1,1]
	v_pk_add_f32 v[170:171], v[166:167], v[200:201]
	v_pk_add_f32 v[166:167], v[166:167], v[200:201] neg_lo:[0,1] neg_hi:[0,1]
	v_pk_add_f32 v[168:169], v[164:165], v[174:175]
	v_pk_add_f32 v[164:165], v[164:165], v[174:175] neg_lo:[0,1] neg_hi:[0,1]
	v_xor_b32_e32 v174, 0x80000000, v167
	v_mov_b32_e32 v175, v166
	v_pk_add_f32 v[166:167], v[168:169], v[170:171]
	v_pk_add_f32 v[200:201], v[164:165], v[174:175]
	v_pk_add_f32 v[168:169], v[168:169], v[170:171] neg_lo:[0,1] neg_hi:[0,1]
	v_pk_add_f32 v[164:165], v[164:165], v[174:175] neg_lo:[0,1] neg_hi:[0,1]
	v_pk_add_f32 v[170:171], v[202:203], v[240:241]
	v_pk_add_f32 v[174:175], v[202:203], v[240:241] neg_lo:[0,1] neg_hi:[0,1]
	v_pk_add_f32 v[202:203], v[204:205], v[192:193]
	v_pk_add_f32 v[192:193], v[204:205], v[192:193] neg_lo:[0,1] neg_hi:[0,1]
	v_xor_b32_e32 v204, 0x80000000, v193
	v_mov_b32_e32 v205, v192
	v_pk_add_f32 v[192:193], v[170:171], v[202:203]
	v_pk_add_f32 v[170:171], v[170:171], v[202:203] neg_lo:[0,1] neg_hi:[0,1]
	v_pk_add_f32 v[202:203], v[194:195], v[198:199]
	v_pk_add_f32 v[194:195], v[194:195], v[198:199] neg_lo:[0,1] neg_hi:[0,1]
	v_pk_add_f32 v[198:199], v[184:185], v[172:173]
	v_pk_add_f32 v[172:173], v[184:185], v[172:173] neg_lo:[0,1] neg_hi:[0,1]
	v_pk_add_f32 v[234:235], v[174:175], v[204:205]
	v_xor_b32_e32 v184, 0x80000000, v173
	v_mov_b32_e32 v185, v172
	v_pk_add_f32 v[174:175], v[174:175], v[204:205] neg_lo:[0,1] neg_hi:[0,1]
	v_pk_add_f32 v[172:173], v[202:203], v[198:199]
	v_pk_add_f32 v[204:205], v[194:195], v[184:185]
	v_pk_add_f32 v[198:199], v[202:203], v[198:199] neg_lo:[0,1] neg_hi:[0,1]
	v_pk_add_f32 v[184:185], v[194:195], v[184:185] neg_lo:[0,1] neg_hi:[0,1]
	v_pk_add_f32 v[194:195], v[236:237], v[162:163]
	v_pk_add_f32 v[202:203], v[238:239], v[160:161]
	v_pk_add_f32 v[160:161], v[238:239], v[160:161] neg_lo:[0,1] neg_hi:[0,1]
	v_pk_add_f32 v[162:163], v[236:237], v[162:163] neg_lo:[0,1] neg_hi:[0,1]
	v_xor_b32_e32 v236, 0x80000000, v161
	v_mov_b32_e32 v237, v160
	v_pk_add_f32 v[160:161], v[194:195], v[202:203]
	v_pk_add_f32 v[194:195], v[194:195], v[202:203] neg_lo:[0,1] neg_hi:[0,1]
	v_pk_mul_f32 v[202:203], v[234:235], s[22:23] op_sel:[1,0] op_sel_hi:[0,0] neg_lo:[1,0]
	v_pk_add_f32 v[238:239], v[162:163], v[236:237]
	v_pk_fma_f32 v[202:203], v[234:235], s[36:37], v[202:203] op_sel_hi:[1,0,1]
	v_pk_mul_f32 v[234:235], v[170:171], s[12:13] op_sel:[1,0] op_sel_hi:[0,0] neg_lo:[1,0]
	v_pk_add_f32 v[162:163], v[162:163], v[236:237] neg_lo:[0,1] neg_hi:[0,1]
	v_pk_fma_f32 v[170:171], v[170:171], s[12:13], v[234:235] op_sel_hi:[1,0,1]
	v_pk_mul_f32 v[234:235], v[174:175], s[36:37] op_sel:[1,0] op_sel_hi:[0,0] neg_lo:[1,0]
	v_xor_b32_e32 v236, 0x80000000, v195
	v_pk_fma_f32 v[174:175], v[174:175], s[22:23], v[234:235] op_sel_hi:[1,0,1]
	v_pk_mul_f32 v[234:235], v[204:205], s[12:13] op_sel:[1,0] op_sel_hi:[0,0] neg_lo:[1,0]
	v_mov_b32_e32 v237, v194
	v_pk_fma_f32 v[204:205], v[204:205], s[12:13], v[234:235] op_sel_hi:[1,0,1]
	v_pk_mul_f32 v[194:195], v[194:195], s[12:13] op_sel_hi:[1,0]
	v_pk_fma_f32 v[198:199], v[198:199], 0, v[198:199] op_sel:[0,0,1] op_sel_hi:[1,0,0] neg_lo:[0,0,1]
	v_xor_b32_e32 v234, 0x80000000, v185
	v_mov_b32_e32 v235, v184
	v_pk_mul_f32 v[184:185], v[184:185], s[12:13] op_sel_hi:[1,0]
	v_pk_fma_f32 v[194:195], v[236:237], s[12:13], v[194:195] op_sel_hi:[1,0,1] neg_lo:[0,0,1] neg_hi:[0,0,1]
	v_pk_fma_f32 v[184:185], v[234:235], s[12:13], v[184:185] op_sel_hi:[1,0,1] neg_lo:[0,0,1] neg_hi:[0,0,1]
	v_pk_mul_f32 v[236:237], v[162:163], s[22:23] op_sel:[1,0] op_sel_hi:[0,0] neg_lo:[1,0]
	v_pk_mul_f32 v[234:235], v[238:239], s[36:37] op_sel:[1,0] op_sel_hi:[0,0] neg_lo:[1,0]
	v_pk_fma_f32 v[162:163], v[162:163], s[26:27], v[236:237] op_sel_hi:[1,0,1] neg_lo:[0,0,1] neg_hi:[0,0,1]
	v_pk_add_f32 v[236:237], v[166:167], v[172:173]
	v_pk_add_f32 v[166:167], v[166:167], v[172:173] neg_lo:[0,1] neg_hi:[0,1]
	v_pk_add_f32 v[172:173], v[192:193], v[160:161]
	v_pk_add_f32 v[160:161], v[192:193], v[160:161] neg_lo:[0,1] neg_hi:[0,1]
	v_pk_fma_f32 v[234:235], v[238:239], s[22:23], v[234:235] op_sel_hi:[1,0,1]
	v_pk_add_f32 v[238:239], v[166:167], v[160:161] op_sel:[0,1] op_sel_hi:[1,0] neg_lo:[0,1]
	v_pk_add_f32 v[166:167], v[166:167], v[160:161] op_sel:[0,1] op_sel_hi:[1,0] neg_hi:[0,1]
	v_pk_add_f32 v[192:193], v[200:201], v[204:205]
	v_pk_add_f32 v[200:201], v[200:201], v[204:205] neg_lo:[0,1] neg_hi:[0,1]
	v_pk_add_f32 v[204:205], v[202:203], v[234:235]
	v_pk_add_f32 v[202:203], v[202:203], v[234:235] neg_lo:[0,1] neg_hi:[0,1]
	v_pk_add_f32 v[160:161], v[236:237], v[172:173]
	v_xor_b32_e32 v234, 0x80000000, v203
	v_mov_b32_e32 v235, v202
	v_pk_add_f32 v[202:203], v[192:193], v[204:205]
	v_pk_add_f32 v[192:193], v[192:193], v[204:205] neg_lo:[0,1] neg_hi:[0,1]
	v_pk_add_f32 v[204:205], v[168:169], v[198:199]
	v_pk_add_f32 v[168:169], v[168:169], v[198:199] neg_lo:[0,1] neg_hi:[0,1]
	v_pk_add_f32 v[198:199], v[170:171], v[194:195]
	v_pk_add_f32 v[170:171], v[170:171], v[194:195] neg_lo:[0,1] neg_hi:[0,1]
	v_pk_add_f32 v[172:173], v[236:237], v[172:173] neg_lo:[0,1] neg_hi:[0,1]
	v_pk_add_f32 v[236:237], v[200:201], v[234:235]
	v_pk_add_f32 v[200:201], v[200:201], v[234:235] neg_lo:[0,1] neg_hi:[0,1]
	v_pk_add_f32 v[234:235], v[168:169], v[170:171] op_sel:[0,1] op_sel_hi:[1,0] neg_lo:[0,1]
	v_pk_add_f32 v[168:169], v[168:169], v[170:171] op_sel:[0,1] op_sel_hi:[1,0] neg_hi:[0,1]
	v_pk_add_f32 v[194:195], v[164:165], v[184:185]
	v_pk_add_f32 v[164:165], v[164:165], v[184:185] neg_lo:[0,1] neg_hi:[0,1]
	v_pk_add_f32 v[184:185], v[174:175], v[162:163]
	v_pk_add_f32 v[162:163], v[174:175], v[162:163] neg_lo:[0,1] neg_hi:[0,1]
	v_pk_add_f32 v[170:171], v[204:205], v[198:199]
	v_pk_add_f32 v[198:199], v[204:205], v[198:199] neg_lo:[0,1] neg_hi:[0,1]
	v_pk_add_f32 v[204:205], v[164:165], v[162:163] op_sel:[0,1] op_sel_hi:[1,0] neg_lo:[0,1]
	v_pk_add_f32 v[164:165], v[164:165], v[162:163] op_sel:[0,1] op_sel_hi:[1,0] neg_hi:[0,1]
	v_mov_b32_e32 v174, v116
	v_mov_b32_e32 v175, v142
	v_pk_mul_f32 v[142:143], v[174:175], v[160:161] op_sel_hi:[1,0]
	v_pk_add_f32 v[162:163], v[194:195], v[184:185]
	v_pk_fma_f32 v[116:117], v[116:117], v[160:161], v[142:143] op_sel:[1,1,0] op_sel_hi:[0,1,1]
	v_pk_mul_f32 v[142:143], v[126:127], v[202:203] op_sel_hi:[1,0] neg_hi:[1,0]
	v_pk_add_f32 v[184:185], v[194:195], v[184:185] neg_lo:[0,1] neg_hi:[0,1]
	v_pk_fma_f32 v[126:127], v[126:127], v[202:203], v[142:143] op_sel:[1,1,0] op_sel_hi:[0,1,1]
	ds_write2_b64 v129, v[116:117], v[126:127] offset1:1
	v_pk_mul_f32 v[116:117], v[124:125], v[170:171] op_sel_hi:[1,0] neg_hi:[1,0]
	v_pk_fma_f32 v[116:117], v[124:125], v[170:171], v[116:117] op_sel:[1,1,0] op_sel_hi:[0,1,1]
	v_pk_mul_f32 v[124:125], v[122:123], v[162:163] op_sel_hi:[1,0] neg_hi:[1,0]
	v_pk_fma_f32 v[122:123], v[122:123], v[162:163], v[124:125] op_sel:[1,1,0] op_sel_hi:[0,1,1]
	ds_write2_b64 v129, v[116:117], v[122:123] offset0:2 offset1:3
	v_pk_mul_f32 v[116:117], v[120:121], v[238:239] op_sel_hi:[1,0] neg_hi:[1,0]
	v_pk_fma_f32 v[116:117], v[120:121], v[238:239], v[116:117] op_sel:[1,1,0] op_sel_hi:[0,1,1]
	v_pk_mul_f32 v[120:121], v[118:119], v[236:237] op_sel_hi:[1,0] neg_hi:[1,0]
	v_pk_fma_f32 v[118:119], v[118:119], v[236:237], v[120:121] op_sel:[1,1,0] op_sel_hi:[0,1,1]
	ds_write2_b64 v129, v[116:117], v[118:119] offset0:4 offset1:5
	v_pk_mul_f32 v[116:117], v[114:115], v[234:235] op_sel_hi:[1,0] neg_hi:[1,0]
	v_pk_fma_f32 v[114:115], v[114:115], v[234:235], v[116:117] op_sel:[1,1,0] op_sel_hi:[0,1,1]
	v_pk_mul_f32 v[116:117], v[112:113], v[204:205] op_sel_hi:[1,0] neg_hi:[1,0]
	v_pk_fma_f32 v[112:113], v[112:113], v[204:205], v[116:117] op_sel:[1,1,0] op_sel_hi:[0,1,1]
	ds_write2_b64 v129, v[114:115], v[112:113] offset0:6 offset1:7
	v_pk_mul_f32 v[112:113], v[110:111], v[172:173] op_sel_hi:[1,0] neg_hi:[1,0]
	v_pk_fma_f32 v[110:111], v[110:111], v[172:173], v[112:113] op_sel:[1,1,0] op_sel_hi:[0,1,1]
	v_pk_mul_f32 v[112:113], v[108:109], v[192:193] op_sel_hi:[1,0] neg_hi:[1,0]
	v_pk_fma_f32 v[108:109], v[108:109], v[192:193], v[112:113] op_sel:[1,1,0] op_sel_hi:[0,1,1]
	ds_write2_b64 v129, v[110:111], v[108:109] offset0:8 offset1:9
	v_pk_mul_f32 v[108:109], v[106:107], v[198:199] op_sel_hi:[1,0] neg_hi:[1,0]
	v_pk_fma_f32 v[106:107], v[106:107], v[198:199], v[108:109] op_sel:[1,1,0] op_sel_hi:[0,1,1]
	v_pk_mul_f32 v[108:109], v[104:105], v[184:185] op_sel_hi:[1,0] neg_hi:[1,0]
	v_pk_fma_f32 v[104:105], v[104:105], v[184:185], v[108:109] op_sel:[1,1,0] op_sel_hi:[0,1,1]
	ds_write2_b64 v129, v[106:107], v[104:105] offset0:10 offset1:11
	v_pk_mul_f32 v[104:105], v[6:7], v[166:167] op_sel_hi:[1,0] neg_hi:[1,0]
	v_pk_fma_f32 v[6:7], v[6:7], v[166:167], v[104:105] op_sel:[1,1,0] op_sel_hi:[0,1,1]
	v_pk_mul_f32 v[104:105], v[4:5], v[200:201] op_sel_hi:[1,0] neg_hi:[1,0]
	v_pk_fma_f32 v[4:5], v[4:5], v[200:201], v[104:105] op_sel:[1,1,0] op_sel_hi:[0,1,1]
	ds_write2_b64 v129, v[6:7], v[4:5] offset0:12 offset1:13
	v_pk_mul_f32 v[4:5], v[2:3], v[168:169] op_sel_hi:[1,0] neg_hi:[1,0]
	v_pk_fma_f32 v[2:3], v[2:3], v[168:169], v[4:5] op_sel:[1,1,0] op_sel_hi:[0,1,1]
	v_pk_mul_f32 v[4:5], v[0:1], v[164:165] op_sel_hi:[1,0] neg_hi:[1,0]
	v_pk_fma_f32 v[0:1], v[0:1], v[164:165], v[4:5] op_sel:[1,1,0] op_sel_hi:[0,1,1]
	ds_write2_b64 v129, v[2:3], v[0:1] offset0:14 offset1:15
	v_mov_b32_e32 v0, v217
	v_mov_b32_e32 v1, v218
	v_mov_b32_e32 v114, v215
	v_xor_b32_e32 v4, 0x80000000, v1
	v_mov_b32_e32 v5, v0
	v_pk_mul_f32 v[2:3], v[4:5], v[218:219] op_sel_hi:[1,0]
	v_mov_b32_e32 v115, v216
	v_pk_fma_f32 v[2:3], v[216:217], v[0:1], v[2:3] op_sel:[1,0,0]
	v_pk_mul_f32 v[104:105], v[2:3], v[2:3] op_sel:[1,1] op_sel_hi:[1,0] neg_lo:[0,1]
	v_pk_mul_f32 v[4:5], v[4:5], v[216:217] op_sel_hi:[1,0]
	v_pk_fma_f32 v[104:105], v[2:3], v[2:3], v[104:105] op_sel_hi:[1,0,1]
	v_pk_fma_f32 v[126:127], v[0:1], v[214:215], v[4:5] op_sel:[0,1,0]
	v_pk_mul_f32 v[0:1], v[216:217], v[2:3] op_sel:[0,1] op_sel_hi:[0,0] neg_lo:[0,1]
	v_pk_fma_f32 v[124:125], v[214:215], v[2:3], v[0:1] op_sel:[1,0,0]
	v_pk_mul_f32 v[0:1], v[126:127], v[2:3] op_sel:[1,1] op_sel_hi:[1,0] neg_lo:[0,1]
	v_pk_mul_f32 v[108:109], v[104:105], v[104:105] op_sel:[1,1] op_sel_hi:[1,0] neg_lo:[0,1]
	v_pk_fma_f32 v[122:123], v[2:3], v[126:127], v[0:1] op_sel_hi:[1,0,1]
	v_pk_mul_f32 v[0:1], v[216:217], v[104:105] op_sel:[0,1] op_sel_hi:[0,0] neg_lo:[0,1]
	v_pk_fma_f32 v[120:121], v[214:215], v[104:105], v[0:1] op_sel:[1,0,0]
	v_pk_mul_f32 v[0:1], v[126:127], v[104:105] op_sel:[1,1] op_sel_hi:[1,0] neg_lo:[0,1]
	s_waitcnt lgkmcnt(0)
	v_pk_fma_f32 v[118:119], v[126:127], v[104:105], v[0:1] op_sel_hi:[0,1,1]
	v_pk_mul_f32 v[0:1], v[124:125], v[104:105] op_sel:[1,1] op_sel_hi:[1,0] neg_lo:[0,1]
	s_barrier
	v_pk_fma_f32 v[116:117], v[104:105], v[124:125], v[0:1] op_sel_hi:[1,0,1]
	v_pk_mul_f32 v[0:1], v[122:123], v[104:105] op_sel:[1,1] op_sel_hi:[1,0] neg_lo:[0,1]
	v_pk_fma_f32 v[110:111], v[104:105], v[122:123], v[0:1] op_sel_hi:[1,0,1]
	v_pk_fma_f32 v[0:1], v[104:105], v[104:105], v[108:109] op_sel_hi:[1,0,1]
	s_cmpk_lg_u32 s42, 0xc000
	v_pk_mul_f32 v[2:3], v[216:217], v[0:1] op_sel:[0,1] op_sel_hi:[0,0] neg_lo:[0,1]
	v_pk_fma_f32 v[112:113], v[214:215], v[0:1], v[2:3] op_sel:[1,0,0]
	v_pk_mul_f32 v[2:3], v[126:127], v[0:1] op_sel:[1,1] op_sel_hi:[1,0] neg_lo:[0,1]
	s_cselect_b32 s34, s47, 0
	v_pk_fma_f32 v[108:109], v[126:127], v[0:1], v[2:3] op_sel_hi:[0,1,1]
	v_pk_mul_f32 v[2:3], v[124:125], v[0:1] op_sel:[1,1] op_sel_hi:[1,0] neg_lo:[0,1]
	s_lshl_b64 s[2:3], s[34:35], 1
	v_pk_fma_f32 v[106:107], v[124:125], v[0:1], v[2:3] op_sel_hi:[0,1,1]
	v_pk_mul_f32 v[2:3], v[122:123], v[0:1] op_sel:[1,1] op_sel_hi:[1,0] neg_lo:[0,1]
	s_add_u32 s2, s40, s2
	v_pk_fma_f32 v[104:105], v[122:123], v[0:1], v[2:3] op_sel_hi:[0,1,1]
	v_pk_mul_f32 v[2:3], v[120:121], v[0:1] op_sel:[1,1] op_sel_hi:[1,0] neg_lo:[0,1]
	s_addc_u32 s3, s41, s3
	v_pk_fma_f32 v[6:7], v[0:1], v[120:121], v[2:3] op_sel_hi:[1,0,1]
	v_pk_mul_f32 v[2:3], v[118:119], v[0:1] op_sel:[1,1] op_sel_hi:[1,0] neg_lo:[0,1]
	s_add_u32 s6, s2, 0x2000
	v_pk_fma_f32 v[4:5], v[0:1], v[118:119], v[2:3] op_sel_hi:[1,0,1]
	v_pk_mul_f32 v[2:3], v[116:117], v[0:1] op_sel:[1,1] op_sel_hi:[1,0] neg_lo:[0,1]
	v_pk_mul_f32 v[128:129], v[110:111], v[0:1] op_sel:[1,1] op_sel_hi:[1,0] neg_lo:[0,1]
	v_pk_fma_f32 v[2:3], v[0:1], v[116:117], v[2:3] op_sel_hi:[1,0,1]
	v_pk_fma_f32 v[0:1], v[0:1], v[110:111], v[128:129] op_sel_hi:[1,0,1]
	s_addc_u32 s7, s3, 0
	v_bfe_u32 v129, v206, 4, 4
	v_and_b32_e32 v128, 15, v206
	v_mul_u32_u24_e32 v129, 0x880, v129
	v_lshlrev_b32_e32 v128, 3, v128
	v_add3_u32 v164, v207, v129, v128
	ds_read2_b64 v[128:131], v164 offset1:17
	ds_read2_b64 v[132:135], v164 offset0:34 offset1:51
	ds_read2_b64 v[136:139], v164 offset0:68 offset1:85
	ds_read2_b64 v[140:143], v164 offset0:102 offset1:119
	ds_read2_b64 v[144:147], v164 offset0:136 offset1:153
	ds_read2_b64 v[148:151], v164 offset0:170 offset1:187
	ds_read2_b64 v[152:155], v164 offset0:204 offset1:221
	ds_read2_b64 v[156:159], v164 offset0:238 offset1:255
	s_add_u32 s42, s42, 0x4000
	s_waitcnt lgkmcnt(3)
	v_pk_add_f32 v[160:161], v[128:129], v[144:145]
	v_pk_add_f32 v[128:129], v[128:129], v[144:145] neg_lo:[0,1] neg_hi:[0,1]
	s_waitcnt lgkmcnt(1)
	v_pk_add_f32 v[144:145], v[136:137], v[152:153]
	v_pk_add_f32 v[136:137], v[136:137], v[152:153] neg_lo:[0,1] neg_hi:[0,1]
	s_addc_u32 s43, s43, 0
	v_pk_add_f32 v[162:163], v[128:129], v[136:137] op_sel:[0,1] op_sel_hi:[1,0] neg_lo:[0,1]
	v_pk_add_f32 v[128:129], v[128:129], v[136:137] op_sel:[0,1] op_sel_hi:[1,0] neg_hi:[0,1]
	v_pk_add_f32 v[152:153], v[130:131], v[146:147]
	v_pk_add_f32 v[130:131], v[130:131], v[146:147] neg_lo:[0,1] neg_hi:[0,1]
	v_pk_add_f32 v[146:147], v[138:139], v[154:155]
	v_pk_add_f32 v[138:139], v[138:139], v[154:155] neg_lo:[0,1] neg_hi:[0,1]
	v_pk_add_f32 v[136:137], v[160:161], v[144:145]
	v_xor_b32_e32 v154, 0x80000000, v139
	v_mov_b32_e32 v155, v138
	v_pk_add_f32 v[138:139], v[152:153], v[146:147]
	v_pk_add_f32 v[146:147], v[152:153], v[146:147] neg_lo:[0,1] neg_hi:[0,1]
	v_pk_add_f32 v[152:153], v[132:133], v[148:149]
	v_pk_add_f32 v[132:133], v[132:133], v[148:149] neg_lo:[0,1] neg_hi:[0,1]
	s_waitcnt lgkmcnt(0)
	v_pk_add_f32 v[148:149], v[140:141], v[156:157]
	v_pk_add_f32 v[140:141], v[140:141], v[156:157] neg_lo:[0,1] neg_hi:[0,1]
	v_pk_add_f32 v[144:145], v[160:161], v[144:145] neg_lo:[0,1] neg_hi:[0,1]
	v_pk_add_f32 v[160:161], v[130:131], v[154:155]
	v_pk_add_f32 v[130:131], v[130:131], v[154:155] neg_lo:[0,1] neg_hi:[0,1]
	v_xor_b32_e32 v154, 0x80000000, v141
	v_mov_b32_e32 v155, v140
	v_pk_add_f32 v[140:141], v[152:153], v[148:149]
	v_pk_add_f32 v[148:149], v[152:153], v[148:149] neg_lo:[0,1] neg_hi:[0,1]
	v_pk_add_f32 v[152:153], v[134:135], v[150:151]
	v_pk_add_f32 v[134:135], v[134:135], v[150:151] neg_lo:[0,1] neg_hi:[0,1]
	v_pk_add_f32 v[150:151], v[142:143], v[158:159]
	v_pk_add_f32 v[142:143], v[142:143], v[158:159] neg_lo:[0,1] neg_hi:[0,1]
	v_pk_add_f32 v[156:157], v[132:133], v[154:155]
	v_pk_add_f32 v[132:133], v[132:133], v[154:155] neg_lo:[0,1] neg_hi:[0,1]
	v_pk_add_f32 v[158:159], v[134:135], v[142:143] op_sel:[0,1] op_sel_hi:[1,0] neg_lo:[0,1]
	v_pk_add_f32 v[134:135], v[134:135], v[142:143] op_sel:[0,1] op_sel_hi:[1,0] neg_hi:[0,1]
	v_pk_mul_f32 v[154:155], v[146:147], s[12:13] op_sel:[1,0] op_sel_hi:[0,0] neg_lo:[1,0]
	v_pk_add_f32 v[142:143], v[152:153], v[150:151]
	v_pk_fma_f32 v[146:147], v[146:147], s[12:13], v[154:155] op_sel_hi:[1,0,1]
	v_pk_mul_f32 v[154:155], v[130:131], s[36:37] op_sel:[1,0] op_sel_hi:[0,0] neg_lo:[1,0]
	v_pk_add_f32 v[150:151], v[152:153], v[150:151] neg_lo:[0,1] neg_hi:[0,1]
	v_pk_fma_f32 v[130:131], v[130:131], s[22:23], v[154:155] op_sel_hi:[1,0,1]
	v_pk_mul_f32 v[154:155], v[156:157], s[12:13] op_sel:[1,0] op_sel_hi:[0,0] neg_lo:[1,0]
	v_pk_fma_f32 v[154:155], v[156:157], s[12:13], v[154:155] op_sel_hi:[1,0,1]
	v_pk_fma_f32 v[148:149], v[148:149], 0, v[148:149] op_sel:[0,0,1] op_sel_hi:[1,0,0] neg_lo:[0,0,1]
	v_xor_b32_e32 v156, 0x80000000, v133
	v_mov_b32_e32 v157, v132
	v_pk_mul_f32 v[132:133], v[132:133], s[12:13] op_sel_hi:[1,0]
	v_pk_fma_f32 v[132:133], v[156:157], s[12:13], v[132:133] op_sel_hi:[1,0,1] neg_lo:[0,0,1] neg_hi:[0,0,1]
	v_pk_mul_f32 v[156:157], v[158:159], s[36:37] op_sel:[1,0] op_sel_hi:[0,0] neg_lo:[1,0]
	v_pk_mul_f32 v[152:153], v[160:161], s[22:23] op_sel:[1,0] op_sel_hi:[0,0] neg_lo:[1,0]
	v_pk_fma_f32 v[156:157], v[158:159], s[22:23], v[156:157] op_sel_hi:[1,0,1]
	v_xor_b32_e32 v158, 0x80000000, v151
	v_mov_b32_e32 v159, v150
	v_pk_mul_f32 v[150:151], v[150:151], s[12:13] op_sel_hi:[1,0]
	v_pk_fma_f32 v[152:153], v[160:161], s[36:37], v[152:153] op_sel_hi:[1,0,1]
	v_pk_fma_f32 v[150:151], v[158:159], s[12:13], v[150:151] op_sel_hi:[1,0,1] neg_lo:[0,0,1] neg_hi:[0,0,1]
	v_pk_mul_f32 v[158:159], v[134:135], s[22:23] op_sel:[1,0] op_sel_hi:[0,0] neg_lo:[1,0]
	s_addk_i32 s47, 0x2000
	v_pk_fma_f32 v[134:135], v[134:135], s[26:27], v[158:159] op_sel_hi:[1,0,1] neg_lo:[0,0,1] neg_hi:[0,0,1]
	v_pk_add_f32 v[158:159], v[136:137], v[140:141]
	v_pk_add_f32 v[136:137], v[136:137], v[140:141] neg_lo:[0,1] neg_hi:[0,1]
	v_pk_add_f32 v[140:141], v[138:139], v[142:143]
	v_pk_add_f32 v[138:139], v[138:139], v[142:143] neg_lo:[0,1] neg_hi:[0,1]
	s_cmp_eq_u32 s42, 0x10000
	v_xor_b32_e32 v142, 0x80000000, v139
	v_mov_b32_e32 v143, v138
	v_pk_add_f32 v[138:139], v[158:159], v[140:141]
	v_pk_add_f32 v[140:141], v[158:159], v[140:141] neg_lo:[0,1] neg_hi:[0,1]
	v_pk_add_f32 v[158:159], v[152:153], v[156:157]
	v_pk_add_f32 v[152:153], v[152:153], v[156:157] neg_lo:[0,1] neg_hi:[0,1]
	v_pk_add_f32 v[160:161], v[136:137], v[142:143]
	v_pk_add_f32 v[136:137], v[136:137], v[142:143] neg_lo:[0,1] neg_hi:[0,1]
	v_pk_add_f32 v[142:143], v[162:163], v[154:155]
	v_pk_add_f32 v[154:155], v[162:163], v[154:155] neg_lo:[0,1] neg_hi:[0,1]
	v_pk_add_f32 v[162:163], v[154:155], v[152:153] op_sel:[0,1] op_sel_hi:[1,0] neg_lo:[0,1]
	v_pk_add_f32 v[154:155], v[154:155], v[152:153] op_sel:[0,1] op_sel_hi:[1,0] neg_hi:[0,1]
	v_pk_add_f32 v[156:157], v[144:145], v[148:149]
	v_pk_add_f32 v[144:145], v[144:145], v[148:149] neg_lo:[0,1] neg_hi:[0,1]
	v_pk_add_f32 v[148:149], v[146:147], v[150:151]
	v_pk_add_f32 v[146:147], v[146:147], v[150:151] neg_lo:[0,1] neg_hi:[0,1]
	v_pk_add_f32 v[152:153], v[142:143], v[158:159]
	v_pk_add_f32 v[142:143], v[142:143], v[158:159] neg_lo:[0,1] neg_hi:[0,1]
	v_pk_add_f32 v[158:159], v[144:145], v[146:147] op_sel:[0,1] op_sel_hi:[1,0] neg_lo:[0,1]
	v_pk_add_f32 v[144:145], v[144:145], v[146:147] op_sel:[0,1] op_sel_hi:[1,0] neg_hi:[0,1]
	v_pk_add_f32 v[150:151], v[128:129], v[132:133]
	v_pk_add_f32 v[128:129], v[128:129], v[132:133] neg_lo:[0,1] neg_hi:[0,1]
	v_pk_add_f32 v[132:133], v[130:131], v[134:135]
	v_pk_add_f32 v[130:131], v[130:131], v[134:135] neg_lo:[0,1] neg_hi:[0,1]
	v_pk_add_f32 v[146:147], v[156:157], v[148:149]
	v_pk_add_f32 v[148:149], v[156:157], v[148:149] neg_lo:[0,1] neg_hi:[0,1]
	v_pk_add_f32 v[156:157], v[128:129], v[130:131] op_sel:[0,1] op_sel_hi:[1,0] neg_lo:[0,1]
	v_pk_add_f32 v[128:129], v[128:129], v[130:131] op_sel:[0,1] op_sel_hi:[1,0] neg_hi:[0,1]
	v_xor_b32_e32 v134, 0x80000000, v115
	v_mov_b32_e32 v135, v114
	v_pk_mul_f32 v[134:135], v[134:135], v[138:139] op_sel:[0,1]
	v_pk_add_f32 v[130:131], v[150:151], v[132:133]
	v_pk_fma_f32 v[114:115], v[114:115], v[138:139], v[134:135] op_sel_hi:[1,0,1]
	v_pk_mul_f32 v[134:135], v[126:127], v[152:153] op_sel:[1,1] op_sel_hi:[0,1] neg_lo:[1,0]
	v_pk_add_f32 v[132:133], v[150:151], v[132:133] neg_lo:[0,1] neg_hi:[0,1]
	v_pk_fma_f32 v[126:127], v[126:127], v[152:153], v[134:135] op_sel_hi:[1,0,1]
	ds_write2_b64 v164, v[114:115], v[126:127] offset1:17
	v_pk_mul_f32 v[114:115], v[124:125], v[146:147] op_sel:[1,1] op_sel_hi:[0,1] neg_lo:[1,0]
	v_pk_fma_f32 v[114:115], v[124:125], v[146:147], v[114:115] op_sel_hi:[1,0,1]
	v_pk_mul_f32 v[124:125], v[122:123], v[130:131] op_sel:[1,1] op_sel_hi:[0,1] neg_lo:[1,0]
	v_pk_fma_f32 v[122:123], v[122:123], v[130:131], v[124:125] op_sel_hi:[1,0,1]
	ds_write2_b64 v164, v[114:115], v[122:123] offset0:34 offset1:51
	v_pk_mul_f32 v[114:115], v[120:121], v[160:161] op_sel:[1,1] op_sel_hi:[0,1] neg_lo:[1,0]
	v_pk_fma_f32 v[114:115], v[120:121], v[160:161], v[114:115] op_sel_hi:[1,0,1]
	v_pk_mul_f32 v[120:121], v[118:119], v[162:163] op_sel:[1,1] op_sel_hi:[0,1] neg_lo:[1,0]
	v_pk_fma_f32 v[118:119], v[118:119], v[162:163], v[120:121] op_sel_hi:[1,0,1]
	ds_write2_b64 v164, v[114:115], v[118:119] offset0:68 offset1:85
	v_pk_mul_f32 v[114:115], v[116:117], v[158:159] op_sel:[1,1] op_sel_hi:[0,1] neg_lo:[1,0]
	v_pk_fma_f32 v[114:115], v[116:117], v[158:159], v[114:115] op_sel_hi:[1,0,1]
	v_pk_mul_f32 v[116:117], v[110:111], v[156:157] op_sel:[1,1] op_sel_hi:[0,1] neg_lo:[1,0]
	v_pk_fma_f32 v[110:111], v[110:111], v[156:157], v[116:117] op_sel_hi:[1,0,1]
	ds_write2_b64 v164, v[114:115], v[110:111] offset0:102 offset1:119
	v_pk_mul_f32 v[110:111], v[112:113], v[140:141] op_sel:[1,1] op_sel_hi:[0,1] neg_lo:[1,0]
	v_pk_fma_f32 v[110:111], v[112:113], v[140:141], v[110:111] op_sel_hi:[1,0,1]
	v_pk_mul_f32 v[112:113], v[108:109], v[142:143] op_sel:[1,1] op_sel_hi:[0,1] neg_lo:[1,0]
	v_pk_fma_f32 v[108:109], v[108:109], v[142:143], v[112:113] op_sel_hi:[1,0,1]
	ds_write2_b64 v164, v[110:111], v[108:109] offset0:136 offset1:153
	v_pk_mul_f32 v[108:109], v[106:107], v[148:149] op_sel:[1,1] op_sel_hi:[0,1] neg_lo:[1,0]
	v_pk_fma_f32 v[106:107], v[106:107], v[148:149], v[108:109] op_sel_hi:[1,0,1]
	v_pk_mul_f32 v[108:109], v[104:105], v[132:133] op_sel:[1,1] op_sel_hi:[0,1] neg_lo:[1,0]
	v_pk_fma_f32 v[104:105], v[104:105], v[132:133], v[108:109] op_sel_hi:[1,0,1]
	ds_write2_b64 v164, v[106:107], v[104:105] offset0:170 offset1:187
	v_pk_mul_f32 v[104:105], v[6:7], v[136:137] op_sel:[1,1] op_sel_hi:[0,1] neg_lo:[1,0]
	s_waitcnt vmcnt(5)
	v_and_b32_e32 v133, 0xffff0000, v13
	v_pk_fma_f32 v[6:7], v[6:7], v[136:137], v[104:105] op_sel_hi:[1,0,1]
	v_pk_mul_f32 v[104:105], v[4:5], v[154:155] op_sel:[1,1] op_sel_hi:[0,1] neg_lo:[1,0]
	v_lshlrev_b32_e32 v136, 16, v12
	v_pk_fma_f32 v[4:5], v[4:5], v[154:155], v[104:105] op_sel_hi:[1,0,1]
	ds_write2_b64 v164, v[6:7], v[4:5] offset0:204 offset1:221
	v_pk_mul_f32 v[4:5], v[2:3], v[144:145] op_sel:[1,1] op_sel_hi:[0,1] neg_lo:[1,0]
	v_and_b32_e32 v137, 0xffff0000, v12
	v_pk_fma_f32 v[2:3], v[2:3], v[144:145], v[4:5] op_sel_hi:[1,0,1]
	v_pk_mul_f32 v[4:5], v[0:1], v[128:129] op_sel:[1,1] op_sel_hi:[0,1] neg_lo:[1,0]
	v_pk_fma_f32 v[0:1], v[0:1], v[128:129], v[4:5] op_sel_hi:[1,0,1]
	ds_write2_b64 v164, v[2:3], v[0:1] offset0:238 offset1:255
	v_mov_b32_e32 v0, v206
	s_waitcnt lgkmcnt(0)
	s_barrier
	s_nop 0
	v_lshlrev_b32_sdwa v1, v228, v0 dst_sel:DWORD dst_unused:UNUSED_PAD src0_sel:DWORD src1_sel:BYTE_0
	v_lshrrev_b32_e32 v0, 1, v206
	v_and_b32_e32 v0, 0x78, v0
	v_add3_u32 v132, v207, v1, v0
	ds_read_b64 v[0:1], v132
	ds_read_b64 v[2:3], v132 offset:2176
	ds_read_b64 v[4:5], v132 offset:4352
	ds_read_b64 v[6:7], v132 offset:6528
	ds_read_b64 v[104:105], v132 offset:8704
	ds_read_b64 v[106:107], v132 offset:10880
	ds_read_b64 v[108:109], v132 offset:13056
	ds_read_b64 v[110:111], v132 offset:15232
	ds_read_b64 v[112:113], v132 offset:17408
	ds_read_b64 v[114:115], v132 offset:19584
	ds_read_b64 v[116:117], v132 offset:21760
	ds_read_b64 v[118:119], v132 offset:23936
	ds_read_b64 v[120:121], v132 offset:26112
	ds_read_b64 v[122:123], v132 offset:28288
	ds_read_b64 v[124:125], v132 offset:30464
	ds_read_b64 v[126:127], v132 offset:32640
	s_waitcnt lgkmcnt(7)
	v_pk_add_f32 v[128:129], v[0:1], v[112:113]
	v_pk_add_f32 v[0:1], v[0:1], v[112:113] neg_lo:[0,1] neg_hi:[0,1]
	s_waitcnt lgkmcnt(3)
	v_pk_add_f32 v[112:113], v[104:105], v[120:121]
	v_pk_add_f32 v[104:105], v[104:105], v[120:121] neg_lo:[0,1] neg_hi:[0,1]
	v_pk_add_f32 v[130:131], v[0:1], v[104:105] op_sel:[0,1] op_sel_hi:[1,0] neg_lo:[0,1]
	v_pk_add_f32 v[0:1], v[0:1], v[104:105] op_sel:[0,1] op_sel_hi:[1,0] neg_hi:[0,1]
	v_pk_add_f32 v[120:121], v[2:3], v[114:115]
	v_pk_add_f32 v[2:3], v[2:3], v[114:115] neg_lo:[0,1] neg_hi:[0,1]
	s_waitcnt lgkmcnt(2)
	v_pk_add_f32 v[114:115], v[106:107], v[122:123]
	v_pk_add_f32 v[106:107], v[106:107], v[122:123] neg_lo:[0,1] neg_hi:[0,1]
	v_pk_add_f32 v[104:105], v[128:129], v[112:113]
	v_xor_b32_e32 v122, 0x80000000, v107
	v_mov_b32_e32 v123, v106
	v_pk_add_f32 v[106:107], v[120:121], v[114:115]
	v_pk_add_f32 v[114:115], v[120:121], v[114:115] neg_lo:[0,1] neg_hi:[0,1]
	v_pk_add_f32 v[120:121], v[4:5], v[116:117]
	v_pk_add_f32 v[4:5], v[4:5], v[116:117] neg_lo:[0,1] neg_hi:[0,1]
	s_waitcnt lgkmcnt(1)
	v_pk_add_f32 v[116:117], v[108:109], v[124:125]
	v_pk_add_f32 v[108:109], v[108:109], v[124:125] neg_lo:[0,1] neg_hi:[0,1]
	v_pk_add_f32 v[112:113], v[128:129], v[112:113] neg_lo:[0,1] neg_hi:[0,1]
	v_pk_add_f32 v[128:129], v[2:3], v[122:123]
	v_pk_add_f32 v[2:3], v[2:3], v[122:123] neg_lo:[0,1] neg_hi:[0,1]
	v_xor_b32_e32 v122, 0x80000000, v109
	v_mov_b32_e32 v123, v108
	v_pk_add_f32 v[108:109], v[120:121], v[116:117]
	v_pk_add_f32 v[116:117], v[120:121], v[116:117] neg_lo:[0,1] neg_hi:[0,1]
	v_pk_add_f32 v[120:121], v[6:7], v[118:119]
	v_pk_add_f32 v[6:7], v[6:7], v[118:119] neg_lo:[0,1] neg_hi:[0,1]
	s_waitcnt lgkmcnt(0)
	v_pk_add_f32 v[118:119], v[110:111], v[126:127]
	v_pk_add_f32 v[110:111], v[110:111], v[126:127] neg_lo:[0,1] neg_hi:[0,1]
	v_pk_add_f32 v[124:125], v[4:5], v[122:123]
	v_pk_add_f32 v[4:5], v[4:5], v[122:123] neg_lo:[0,1] neg_hi:[0,1]
	v_pk_add_f32 v[126:127], v[6:7], v[110:111] op_sel:[0,1] op_sel_hi:[1,0] neg_lo:[0,1]
	v_pk_add_f32 v[6:7], v[6:7], v[110:111] op_sel:[0,1] op_sel_hi:[1,0] neg_hi:[0,1]
	v_pk_mul_f32 v[122:123], v[114:115], s[12:13] op_sel:[1,0] op_sel_hi:[0,0] neg_lo:[1,0]
	v_pk_add_f32 v[110:111], v[120:121], v[118:119]
	v_pk_fma_f32 v[114:115], v[114:115], s[12:13], v[122:123] op_sel_hi:[1,0,1]
	v_pk_mul_f32 v[122:123], v[2:3], s[36:37] op_sel:[1,0] op_sel_hi:[0,0] neg_lo:[1,0]
	v_pk_add_f32 v[118:119], v[120:121], v[118:119] neg_lo:[0,1] neg_hi:[0,1]
	v_pk_fma_f32 v[2:3], v[2:3], s[22:23], v[122:123] op_sel_hi:[1,0,1]
	v_pk_mul_f32 v[122:123], v[124:125], s[12:13] op_sel:[1,0] op_sel_hi:[0,0] neg_lo:[1,0]
	v_pk_fma_f32 v[122:123], v[124:125], s[12:13], v[122:123] op_sel_hi:[1,0,1]
	v_pk_fma_f32 v[116:117], v[116:117], 0, v[116:117] op_sel:[0,0,1] op_sel_hi:[1,0,0] neg_lo:[0,0,1]
	v_xor_b32_e32 v124, 0x80000000, v5
	v_mov_b32_e32 v125, v4
	v_pk_mul_f32 v[4:5], v[4:5], s[12:13] op_sel_hi:[1,0]
	v_pk_fma_f32 v[4:5], v[124:125], s[12:13], v[4:5] op_sel_hi:[1,0,1] neg_lo:[0,0,1] neg_hi:[0,0,1]
	v_pk_mul_f32 v[124:125], v[126:127], s[36:37] op_sel:[1,0] op_sel_hi:[0,0] neg_lo:[1,0]
	v_pk_mul_f32 v[120:121], v[128:129], s[22:23] op_sel:[1,0] op_sel_hi:[0,0] neg_lo:[1,0]
	v_pk_fma_f32 v[124:125], v[126:127], s[22:23], v[124:125] op_sel_hi:[1,0,1]
	v_xor_b32_e32 v126, 0x80000000, v119
	v_mov_b32_e32 v127, v118
	v_pk_mul_f32 v[118:119], v[118:119], s[12:13] op_sel_hi:[1,0]
	v_pk_fma_f32 v[120:121], v[128:129], s[36:37], v[120:121] op_sel_hi:[1,0,1]
	v_pk_fma_f32 v[118:119], v[126:127], s[12:13], v[118:119] op_sel_hi:[1,0,1] neg_lo:[0,0,1] neg_hi:[0,0,1]
	v_pk_mul_f32 v[126:127], v[6:7], s[22:23] op_sel:[1,0] op_sel_hi:[0,0] neg_lo:[1,0]
	v_pk_fma_f32 v[6:7], v[6:7], s[26:27], v[126:127] op_sel_hi:[1,0,1] neg_lo:[0,0,1] neg_hi:[0,0,1]
	v_pk_add_f32 v[126:127], v[104:105], v[108:109]
	v_pk_add_f32 v[104:105], v[104:105], v[108:109] neg_lo:[0,1] neg_hi:[0,1]
	v_pk_add_f32 v[108:109], v[106:107], v[110:111]
	v_pk_add_f32 v[106:107], v[106:107], v[110:111] neg_lo:[0,1] neg_hi:[0,1]
	v_xor_b32_e32 v110, 0x80000000, v107
	v_mov_b32_e32 v111, v106
	v_pk_add_f32 v[106:107], v[126:127], v[108:109]
	v_pk_add_f32 v[108:109], v[126:127], v[108:109] neg_lo:[0,1] neg_hi:[0,1]
	v_pk_add_f32 v[126:127], v[120:121], v[124:125]
	v_pk_add_f32 v[120:121], v[120:121], v[124:125] neg_lo:[0,1] neg_hi:[0,1]
	v_pk_add_f32 v[128:129], v[104:105], v[110:111]
	v_pk_add_f32 v[104:105], v[104:105], v[110:111] neg_lo:[0,1] neg_hi:[0,1]
	v_pk_add_f32 v[110:111], v[130:131], v[122:123]
	v_pk_add_f32 v[122:123], v[130:131], v[122:123] neg_lo:[0,1] neg_hi:[0,1]
	v_pk_add_f32 v[130:131], v[122:123], v[120:121] op_sel:[0,1] op_sel_hi:[1,0] neg_lo:[0,1]
	v_pk_add_f32 v[122:123], v[122:123], v[120:121] op_sel:[0,1] op_sel_hi:[1,0] neg_hi:[0,1]
	v_pk_add_f32 v[124:125], v[112:113], v[116:117]
	v_pk_add_f32 v[112:113], v[112:113], v[116:117] neg_lo:[0,1] neg_hi:[0,1]
	v_pk_add_f32 v[116:117], v[114:115], v[118:119]
	v_pk_add_f32 v[114:115], v[114:115], v[118:119] neg_lo:[0,1] neg_hi:[0,1]
	v_pk_add_f32 v[120:121], v[110:111], v[126:127]
	v_pk_add_f32 v[110:111], v[110:111], v[126:127] neg_lo:[0,1] neg_hi:[0,1]
	v_pk_add_f32 v[126:127], v[112:113], v[114:115] op_sel:[0,1] op_sel_hi:[1,0] neg_lo:[0,1]
	v_pk_add_f32 v[112:113], v[112:113], v[114:115] op_sel:[0,1] op_sel_hi:[1,0] neg_hi:[0,1]
	v_pk_add_f32 v[118:119], v[0:1], v[4:5]
	v_pk_add_f32 v[0:1], v[0:1], v[4:5] neg_lo:[0,1] neg_hi:[0,1]
	v_pk_add_f32 v[4:5], v[2:3], v[6:7]
	v_pk_add_f32 v[2:3], v[2:3], v[6:7] neg_lo:[0,1] neg_hi:[0,1]
	v_pk_add_f32 v[114:115], v[124:125], v[116:117]
	v_pk_add_f32 v[116:117], v[124:125], v[116:117] neg_lo:[0,1] neg_hi:[0,1]
	v_pk_add_f32 v[124:125], v[0:1], v[2:3] op_sel:[0,1] op_sel_hi:[1,0] neg_lo:[0,1]
	v_pk_add_f32 v[0:1], v[0:1], v[2:3] op_sel:[0,1] op_sel_hi:[1,0] neg_hi:[0,1]
	v_pk_add_f32 v[2:3], v[118:119], v[4:5]
	v_pk_add_f32 v[4:5], v[118:119], v[4:5] neg_lo:[0,1] neg_hi:[0,1]
	ds_write_b64 v132, v[106:107]
	ds_write_b64 v132, v[128:129] offset:8704
	ds_write_b64 v132, v[108:109] offset:17408
	ds_write_b64 v132, v[104:105] offset:26112
	ds_write_b64 v132, v[120:121] offset:2176
	ds_write_b64 v132, v[130:131] offset:10880
	ds_write_b64 v132, v[110:111] offset:19584
	ds_write_b64 v132, v[122:123] offset:28288
	ds_write_b64 v132, v[114:115] offset:4352
	ds_write_b64 v132, v[126:127] offset:13056
	ds_write_b64 v132, v[116:117] offset:21760
	ds_write_b64 v132, v[112:113] offset:30464
	ds_write_b64 v132, v[2:3] offset:6528
	ds_write_b64 v132, v[124:125] offset:15232
	ds_write_b64 v132, v[4:5] offset:23936
	ds_write_b64 v132, v[0:1] offset:32640
	s_waitcnt lgkmcnt(0)
	s_barrier
	v_mov_b32_e32 v115, v214
	v_and_b32_e32 v1, 0x1ff, v212
	v_lshlrev_b32_e32 v2, 3, v1
	v_bfe_u32 v0, v212, 1, 8
	v_add_u32_e32 v104, v2, v0
	v_cmp_eq_u32_e32 vcc, 0, v1
	s_waitcnt vmcnt(3)
	v_lshlrev_b32_e32 v0, 16, v233
	v_cmp_eq_u32_e64 s[0:1], s37, v1
	v_cndmask_b32_e64 v139, v0, 0, vcc
	s_waitcnt vmcnt(2)
	v_lshlrev_b32_e32 v0, 16, v232
	v_cndmask_b32_e64 v135, v0, 0, s[0:1]
	s_waitcnt vmcnt(1)
	v_lshlrev_b32_e32 v0, 16, v231
	v_cndmask_b32_e64 v121, v0, 0, vcc
	s_waitcnt vmcnt(0)
	v_lshlrev_b32_e32 v0, 16, v176
	v_cndmask_b32_e64 v107, v0, 0, s[0:1]
	v_add_u32_e32 v0, -1, v2
	v_cndmask_b32_e64 v176, v0, 0, vcc
	v_add_u32_e32 v0, 8, v2
	v_cndmask_b32_e64 v12, v0, v229, s[0:1]
	v_lshlrev_b64 v[110:111], 1, v[176:177]
	v_mov_b32_e32 v114, v213
	v_lshlrev_b32_e32 v116, 16, v8
	v_and_b32_e32 v117, 0xffff0000, v8
	v_lshlrev_b32_e32 v8, 4, v1
	v_lshl_add_u64 v[112:113], s[2:3], 0, v[110:111]
	v_lshlrev_b32_e32 v12, 1, v12
	v_lshl_add_u64 v[110:111], s[6:7], 0, v[110:111]
	v_lshl_add_u32 v104, v104, 3, 0
	global_load_dwordx4 v[4:7], v8, s[2:3]
	global_load_dwordx4 v[0:3], v8, s[6:7]
	global_load_ushort v143, v[112:113], off
	global_load_ushort v142, v12, s[2:3]
	global_load_ushort v141, v[110:111], off
	global_load_ushort v140, v12, s[6:7]
	v_add_u32_e32 v12, 0x8800, v104
	ds_read2_b64 v[110:113], v104 offset1:1
	ds_read2_b64 v[122:125], v12 offset1:1
	v_xor_b32_e32 v119, 0x80000000, v115
	v_mov_b32_e32 v118, v114
	v_mov_b32_e32 v132, v137
	s_waitcnt lgkmcnt(0)
	v_pk_mul_f32 v[118:119], v[118:119], v[122:123] op_sel_hi:[1,0]
	v_lshlrev_b32_e32 v131, 16, v15
	v_pk_fma_f32 v[118:119], v[114:115], v[122:123], v[118:119] op_sel:[1,1,0] op_sel_hi:[0,1,1]
	v_pk_add_f32 v[122:123], v[110:111], v[118:119]
	v_pk_mul_f32 v[110:111], v[214:215], s[8:9] op_sel_hi:[0,1]
	v_pk_fma_f32 v[110:111], v[212:213], s[30:31], v[110:111] op_sel:[1,0,0]
	v_pk_add_f32 v[114:115], v[110:111], 0 neg_lo:[1,1] neg_hi:[1,1]
	v_mov_b32_e32 v114, v110
	v_pk_mul_f32 v[114:115], v[114:115], v[124:125] op_sel_hi:[1,0]
	v_and_b32_e32 v15, 0xffff0000, v15
	v_pk_fma_f32 v[114:115], v[110:111], v[124:125], v[114:115] op_sel:[1,1,0] op_sel_hi:[0,1,1]
	v_pk_add_f32 v[124:125], v[112:113], v[114:115]
	v_pk_mul_f32 v[112:113], v[110:111], s[8:9] op_sel:[1,0]
	v_add_u32_e32 v12, 0x8810, v104
	v_pk_fma_f32 v[114:115], v[110:111], s[30:31], v[112:113] op_sel_hi:[0,1,1]
	ds_read2_b64 v[110:113], v104 offset0:2 offset1:3
	ds_read2_b64 v[126:129], v12 offset1:1
	v_pk_add_f32 v[118:119], v[114:115], 0 neg_lo:[1,1] neg_hi:[1,1]
	v_mov_b32_e32 v134, v131
	v_mov_b32_e32 v118, v114
	v_and_b32_e32 v109, 0xffff0000, v9
	s_waitcnt lgkmcnt(0)
	v_pk_mul_f32 v[118:119], v[118:119], v[126:127] op_sel_hi:[1,0]
	v_pk_fma_f32 v[118:119], v[114:115], v[126:127], v[118:119] op_sel:[1,1,0] op_sel_hi:[0,1,1]
	v_pk_add_f32 v[126:127], v[110:111], v[118:119]
	v_pk_mul_f32 v[110:111], v[114:115], s[8:9] op_sel:[1,0]
	v_lshlrev_b32_e32 v105, 16, v11
	v_pk_fma_f32 v[110:111], v[114:115], s[30:31], v[110:111] op_sel_hi:[0,1,1]
	v_pk_add_f32 v[114:115], v[110:111], 0 neg_lo:[1,1] neg_hi:[1,1]
	v_and_b32_e32 v11, 0xffff0000, v11
	v_mov_b32_e32 v114, v110
	v_pk_mul_f32 v[114:115], v[114:115], v[128:129] op_sel_hi:[1,0]
	s_brev_b32 s0, 48
	v_pk_fma_f32 v[114:115], v[110:111], v[128:129], v[114:115] op_sel:[1,1,0] op_sel_hi:[0,1,1]
	v_pk_add_f32 v[128:129], v[112:113], v[114:115]
	v_pk_mul_f32 v[112:113], v[110:111], s[8:9] op_sel:[1,0]
	v_add_u32_e32 v12, 0x8820, v104
	v_pk_fma_f32 v[114:115], v[110:111], s[30:31], v[112:113] op_sel_hi:[0,1,1]
	ds_read2_b64 v[110:113], v104 offset0:4 offset1:5
	ds_read2_b64 v[144:147], v12 offset1:1
	v_pk_add_f32 v[118:119], v[114:115], 0 neg_lo:[1,1] neg_hi:[1,1]
	s_waitcnt lgkmcnt(0)
	v_mov_b32_e32 v12, v147
	v_mov_b32_e32 v118, v114
	v_pk_mul_f32 v[118:119], v[118:119], v[144:145] op_sel_hi:[1,0]
	v_pk_fma_f32 v[118:119], v[114:115], v[144:145], v[118:119] op_sel:[1,1,0] op_sel_hi:[0,1,1]
	v_pk_add_f32 v[110:111], v[110:111], v[118:119]
	v_pk_mul_f32 v[118:119], v[114:115], s[8:9] op_sel:[1,0]
	v_pk_fma_f32 v[114:115], v[114:115], s[30:31], v[118:119] op_sel_hi:[0,1,1]
	v_pk_add_f32 v[118:119], v[114:115], 0 neg_lo:[1,1] neg_hi:[1,1]
	v_mov_b32_e32 v118, v114
	v_pk_mul_f32 v[118:119], v[118:119], v[146:147] op_sel_hi:[1,0]
	ds_read2_b64 v[144:147], v104 offset0:6 offset1:7
	v_pk_fma_f32 v[118:119], v[114:115], v[12:13], v[118:119] op_sel:[1,0,0] op_sel_hi:[0,0,1]
	v_add_u32_e32 v12, 0x8830, v104
	ds_read2_b64 v[148:151], v12 offset1:1
	v_pk_add_f32 v[112:113], v[112:113], v[118:119]
	v_pk_mul_f32 v[118:119], v[114:115], s[8:9] op_sel:[1,0]
	s_waitcnt lgkmcnt(0)
	v_pk_fma_f32 v[118:119], v[114:115], s[30:31], v[118:119] op_sel_hi:[0,1,1]
	v_pk_add_f32 v[114:115], v[118:119], 0 neg_lo:[1,1] neg_hi:[1,1]
	v_mov_b32_e32 v114, v118
	v_pk_mul_f32 v[114:115], v[114:115], v[148:149] op_sel_hi:[1,0]
	v_pk_fma_f32 v[114:115], v[118:119], v[148:149], v[114:115] op_sel:[1,1,0] op_sel_hi:[0,1,1]
	v_pk_add_f32 v[114:115], v[144:145], v[114:115]
	v_pk_mul_f32 v[144:145], v[118:119], s[8:9] op_sel:[1,0]
	v_pk_fma_f32 v[118:119], v[118:119], s[30:31], v[144:145] op_sel_hi:[0,1,1]
	v_pk_add_f32 v[144:145], v[118:119], 0 neg_lo:[1,1] neg_hi:[1,1]
	v_mov_b32_e32 v144, v118
	v_pk_mul_f32 v[144:145], v[150:151], v[144:145] op_sel_hi:[0,1]
	v_pk_fma_f32 v[118:119], v[118:119], v[150:151], v[144:145] op_sel:[1,1,0] op_sel_hi:[0,1,1]
	v_lshlrev_b32_e32 v144, 16, v13
	v_mov_b32_e32 v138, v144
	v_pk_mul_f32 v[138:139], v[30:31], v[138:139]
	v_mov_b32_e32 v12, v136
	v_mov_b32_e32 v13, v144
	v_pk_fma_f32 v[136:137], v[30:31], v[136:137], v[138:139] op_sel:[0,0,1] op_sel_hi:[1,1,0]
	v_pk_mul_f32 v[138:139], v[102:103], v[132:133]
	v_lshlrev_b32_e32 v145, 16, v14
	v_pk_fma_f32 v[136:137], v[34:35], v[132:133], v[136:137]
	v_pk_fma_f32 v[12:13], v[100:101], v[12:13], v[138:139]
	v_pk_add_f32 v[136:137], v[36:37], v[136:137]
	v_pk_fma_f32 v[12:13], v[34:35], v[144:145], v[12:13]
	v_mov_b32_e32 v138, v122
	v_mov_b32_e32 v139, v126
	v_pk_add_f32 v[12:13], v[36:37], v[12:13]
	v_pk_mul_f32 v[136:137], v[136:137], v[138:139]
	v_mov_b32_e32 v138, v124
	v_mov_b32_e32 v139, v128
	v_pk_mul_f32 v[12:13], v[12:13], v[138:139]
	v_and_b32_e32 v14, 0xffff0000, v14
	v_mov_b32_e32 v138, v145
	v_mov_b32_e32 v139, v131
	v_pk_mov_b32 v[132:133], v[132:133], v[14:15] op_sel:[1,0]
	v_pk_mul_f32 v[138:139], v[102:103], v[138:139]
	v_mov_b32_e32 v144, v15
	v_pk_fma_f32 v[132:133], v[100:101], v[132:133], v[138:139]
	v_mov_b32_e32 v130, v14
	v_pk_fma_f32 v[132:133], v[34:35], v[14:15], v[132:133]
	v_pk_mul_f32 v[14:15], v[30:31], v[144:145]
	v_pk_add_f32 v[118:119], v[146:147], v[118:119]
	v_pk_fma_f32 v[14:15], v[30:31], v[130:131], v[14:15] op_sel:[0,0,1] op_sel_hi:[1,1,0]
	v_pk_add_f32 v[132:133], v[36:37], v[132:133]
	v_pk_fma_f32 v[14:15], v[34:35], v[134:135], v[14:15]
	v_mov_b32_e32 v130, v110
	v_mov_b32_e32 v131, v114
	v_pk_add_f32 v[14:15], v[36:37], v[14:15]
	v_pk_mul_f32 v[130:131], v[132:133], v[130:131]
	v_mov_b32_e32 v132, v112
	v_mov_b32_e32 v133, v118
	v_pk_mul_f32 v[14:15], v[14:15], v[132:133]
	v_bfe_u32 v108, v13, 16, 1
	v_bfe_u32 v104, v15, 16, 1
	v_add3_u32 v15, v15, v104, s13
	v_add3_u32 v13, v13, v108, s13
	v_bfe_u32 v104, v130, 16, 1
	v_bfe_u32 v108, v136, 16, 1
	v_bfe_u32 v106, v14, 16, 1
	v_bfe_u32 v110, v12, 16, 1
	v_add3_u32 v104, v130, v104, s13
	v_add3_u32 v108, v136, v108, s13
	v_lshlrev_b32_e32 v130, 16, v9
	v_add3_u32 v14, v14, v106, s13
	v_add3_u32 v12, v12, v110, s13
	v_bfe_u32 v106, v131, 16, 1
	v_lshrrev_b32_e32 v108, 16, v108
	v_mov_b32_e32 v120, v130
	v_add3_u32 v106, v131, v106, s13
	v_and_or_b32 v12, v12, s33, v108
	v_lshlrev_b32_e32 v131, 16, v10
	v_mov_b32_e32 v108, v117
	v_pk_mul_f32 v[120:121], v[30:31], v[120:121]
	v_mov_b32_e32 v132, v116
	v_mov_b32_e32 v133, v130
	v_pk_fma_f32 v[116:117], v[30:31], v[116:117], v[120:121] op_sel:[0,0,1] op_sel_hi:[1,1,0]
	v_pk_mul_f32 v[120:121], v[102:103], v[108:109]
	v_mov_b32_e32 v126, v123
	v_and_b32_e32 v10, 0xffff0000, v10
	v_mov_b32_e32 v122, v131
	v_mov_b32_e32 v123, v105
	v_pk_fma_f32 v[116:117], v[34:35], v[108:109], v[116:117]
	v_pk_fma_f32 v[120:121], v[100:101], v[132:133], v[120:121]
	v_pk_mov_b32 v[108:109], v[108:109], v[10:11] op_sel:[1,0]
	v_pk_mul_f32 v[122:123], v[102:103], v[122:123]
	v_lshrrev_b32_e32 v104, 16, v104
	v_pk_fma_f32 v[120:121], v[34:35], v[130:131], v[120:121]
	v_pk_fma_f32 v[108:109], v[100:101], v[108:109], v[122:123]
	v_mov_b32_e32 v130, v11
	v_lshrrev_b32_e32 v106, 16, v106
	v_and_or_b32 v14, v14, s33, v104
	v_mov_b32_e32 v104, v10
	v_pk_fma_f32 v[108:109], v[34:35], v[10:11], v[108:109]
	v_pk_mul_f32 v[10:11], v[30:31], v[130:131]
	v_and_or_b32 v15, v15, s33, v106
	v_mov_b32_e32 v106, v105
	v_pk_fma_f32 v[10:11], v[30:31], v[104:105], v[10:11] op_sel:[0,0,1] op_sel_hi:[1,1,0]
	v_pk_add_f32 v[120:121], v[36:37], v[120:121]
	v_pk_fma_f32 v[10:11], v[34:35], v[106:107], v[10:11]
	v_mov_b32_e32 v128, v125
	v_pk_add_f32 v[10:11], v[36:37], v[10:11]
	v_mov_b32_e32 v118, v113
	v_pk_mul_f32 v[120:121], v[120:121], v[128:129]
	v_pk_add_f32 v[108:109], v[36:37], v[108:109]
	v_mov_b32_e32 v114, v111
	v_pk_mul_f32 v[10:11], v[10:11], v[118:119]
	v_pk_add_f32 v[116:117], v[36:37], v[116:117]
	v_pk_mul_f32 v[104:105], v[108:109], v[114:115]
	v_bfe_u32 v9, v11, 16, 1
	v_bfe_u32 v107, v121, 16, 1
	v_bfe_u32 v108, v120, 16, 1
	v_bfe_u32 v110, v137, 16, 1
	v_pk_mul_f32 v[116:117], v[116:117], v[126:127]
	v_add3_u32 v9, v11, v9, s13
	v_add3_u32 v11, v120, v108, s13
	v_add3_u32 v108, v121, v107, s13
	v_bfe_u32 v107, v105, 16, 1
	v_add3_u32 v110, v137, v110, s13
	v_bfe_u32 v106, v10, 16, 1
	v_bfe_u32 v109, v116, 16, 1
	v_add3_u32 v105, v105, v107, s13
	v_lshrrev_b32_e32 v110, 16, v110
	v_add3_u32 v10, v10, v106, s13
	v_bfe_u32 v106, v104, 16, 1
	v_add3_u32 v107, v116, v109, s13
	v_lshrrev_b32_e32 v105, 16, v105
	v_and_or_b32 v13, v13, s33, v110
	v_bfe_u32 v110, v117, 16, 1
	v_add3_u32 v104, v104, v106, s13
	v_lshrrev_b32_e32 v109, 16, v107
	v_and_or_b32 v107, v9, s33, v105
	v_mov_b32_e32 v9, v177
	v_add3_u32 v106, v117, v110, s13
	v_lshrrev_b32_e32 v104, 16, v104
	v_lshl_add_u64 v[8:9], s[44:45], 0, v[8:9]
	v_lshrrev_b32_e32 v110, 16, v106
	v_and_or_b32 v106, v10, s33, v104
	v_add_co_u32_e32 v10, vcc, s0, v8
	v_and_or_b32 v104, v11, s33, v109
	s_nop 0
	v_addc_co_u32_e32 v11, vcc, 0, v9, vcc
	v_add_co_u32_e32 v8, vcc, 0xc002000, v8
	v_and_or_b32 v105, v108, s33, v110
	s_nop 0
	v_addc_co_u32_e32 v9, vcc, 0, v9, vcc
	global_store_dwordx4 v[10:11], v[12:15], off sc1
	global_store_dwordx4 v[8:9], v[104:107], off sc1
	s_cbranch_scc0 .LBB0_209
	s_load_dword s0, s[74:75], 0x0
	s_waitcnt lgkmcnt(0)
	s_add_i32 s38, s0, s38
	s_cmpk_gt_i32 s38, 0x1ff
	s_cbranch_scc0 .LBB0_204

.LBB0_214:
	s_mov_b32 s0, s9
	s_add_i32 s9, s9, s3
	s_cmpk_gt_i32 s9, 0x7ff
	s_cselect_b64 s[40:41], -1, 0
	s_cmpk_lt_i32 s9, 0x800
	v_add_u32_e32 v69, s0, v34
	s_cselect_b32 s0, s9, s0
	v_add_u32_e32 v2, s0, v34
	v_and_b32_e32 v0, 31, v2
	v_lshlrev_b32_e32 v1, 1, v2
	s_movk_i32 s0, 0x1c0
	v_and_or_b32 v0, v1, s0, v0
	v_readlane_b32 s0, v254, 43
	v_lshlrev_b32_e32 v2, 4, v2
	v_lshlrev_b32_e32 v176, 16, v0
	v_readlane_b32 s1, v254, 44
	v_and_b32_e32 v2, 0xfffff000, v2
	v_ashrrev_i32_e32 v3, 31, v2
	v_lshl_add_u64 v[0:1], s[0:1], 0, v[176:177]
	v_lshlrev_b32_e32 v4, 1, v206
	v_lshl_add_u64 v[0:1], v[2:3], 1, v[0:1]
	s_mov_b64 s[0:1], 0x200000
	v_and_b32_e32 v176, 0x1fe, v4
	v_lshl_add_u64 v[2:3], v[0:1], 0, s[0:1]
	v_lshl_add_u64 v[4:5], v[0:1], 0, v[176:177]
	s_waitcnt vmcnt(0)
	v_lshlrev_b32_e32 v70, 16, v68
	v_lshlrev_b32_e32 v71, 16, v67
	v_lshlrev_b32_e32 v72, 16, v63
	v_lshlrev_b32_e32 v73, 16, v66
	v_lshlrev_b32_e32 v22, 16, v62
	v_lshlrev_b32_e32 v23, 16, v65
	v_lshlrev_b32_e32 v6, 16, v59
	v_lshlrev_b32_e32 v7, 16, v64
	v_lshlrev_b32_e32 v74, 16, v57
	v_lshlrev_b32_e32 v75, 16, v61
	v_lshlrev_b32_e32 v76, 16, v55
	v_lshlrev_b32_e32 v77, 16, v58
	v_lshlrev_b32_e32 v24, 16, v54
	v_lshlrev_b32_e32 v25, 16, v56
	v_lshlrev_b32_e32 v10, 16, v51
	v_lshlrev_b32_e32 v11, 16, v53
	v_lshl_add_u64 v[8:9], v[2:3], 0, v[176:177]
	global_load_ushort v68, v[4:5], off
	global_load_ushort v63, v[4:5], off offset:512
	global_load_ushort v62, v[4:5], off offset:1024
	global_load_ushort v59, v[4:5], off offset:1536
	global_load_ushort v57, v[4:5], off offset:2048
	global_load_ushort v55, v[4:5], off offset:2560
	global_load_ushort v54, v[4:5], off offset:3072
	global_load_ushort v51, v[4:5], off offset:3584
	global_load_ushort v67, v[8:9], off
	global_load_ushort v66, v[8:9], off offset:512
	global_load_ushort v65, v[8:9], off offset:1024
	global_load_ushort v64, v[8:9], off offset:1536
	global_load_ushort v61, v[8:9], off offset:2048
	global_load_ushort v58, v[8:9], off offset:2560
	global_load_ushort v56, v[8:9], off offset:3072
	global_load_ushort v53, v[8:9], off offset:3584
	v_or_b32_e32 v4, 0x1000, v176
	v_mov_b32_e32 v5, v177
	v_or_b32_e32 v12, 0x1200, v176
	v_mov_b32_e32 v13, v177
	v_or_b32_e32 v16, 0x1400, v176
	v_mov_b32_e32 v17, v177
	v_lshl_add_u64 v[8:9], v[0:1], 0, v[4:5]
	v_lshl_add_u64 v[4:5], v[2:3], 0, v[4:5]
	v_lshl_add_u64 v[14:15], v[0:1], 0, v[12:13]
	v_lshl_add_u64 v[12:13], v[2:3], 0, v[12:13]
	v_lshl_add_u64 v[26:27], v[0:1], 0, v[16:17]
	v_lshl_add_u64 v[16:17], v[2:3], 0, v[16:17]
	v_or_b32_e32 v28, 0x1600, v176
	v_mov_b32_e32 v29, v177
	v_lshlrev_b32_e32 v78, 16, v60
	v_lshlrev_b32_e32 v79, 16, v50
	v_lshlrev_b32_e32 v80, 16, v48
	v_lshlrev_b32_e32 v81, 16, v47
	v_lshlrev_b32_e32 v82, 16, v45
	v_lshlrev_b32_e32 v83, 16, v44
	v_lshlrev_b32_e32 v18, 16, v43
	v_lshlrev_b32_e32 v19, 16, v42
	v_lshl_add_u64 v[30:31], v[0:1], 0, v[28:29]
	v_lshl_add_u64 v[28:29], v[2:3], 0, v[28:29]
	global_load_ushort v60, v[8:9], off
	global_load_ushort v50, v[4:5], off
	global_load_ushort v48, v[14:15], off
	global_load_ushort v47, v[12:13], off
	global_load_ushort v45, v[26:27], off
	global_load_ushort v44, v[16:17], off
	global_load_ushort v43, v[30:31], off
	global_load_ushort v42, v[28:29], off
	v_or_b32_e32 v4, 0x1800, v176
	v_mov_b32_e32 v5, v177
	v_or_b32_e32 v12, 0x1a00, v176
	v_mov_b32_e32 v13, v177
	v_or_b32_e32 v16, 0x1c00, v176
	v_mov_b32_e32 v17, v177
	v_or_b32_e32 v176, 0x1e00, v176
	v_lshl_add_u64 v[8:9], v[0:1], 0, v[4:5]
	v_lshl_add_u64 v[14:15], v[0:1], 0, v[12:13]
	v_lshl_add_u64 v[26:27], v[0:1], 0, v[16:17]
	v_lshl_add_u64 v[0:1], v[0:1], 0, v[176:177]
	v_lshlrev_b32_e32 v84, 16, v46
	v_lshlrev_b32_e32 v85, 16, v41
	v_lshlrev_b32_e32 v86, 16, v40
	v_lshlrev_b32_e32 v87, 16, v39
	v_lshlrev_b32_e32 v88, 16, v38
	v_lshlrev_b32_e32 v89, 16, v37
	v_lshlrev_b32_e32 v20, 16, v36
	v_lshlrev_b32_e32 v21, 16, v35
	v_lshl_add_u64 v[4:5], v[2:3], 0, v[4:5]
	v_lshl_add_u64 v[12:13], v[2:3], 0, v[12:13]
	v_lshl_add_u64 v[16:17], v[2:3], 0, v[16:17]
	v_lshl_add_u64 v[2:3], v[2:3], 0, v[176:177]
	global_load_ushort v46, v[8:9], off
	global_load_ushort v41, v[4:5], off
	global_load_ushort v40, v[14:15], off
	global_load_ushort v39, v[12:13], off
	global_load_ushort v38, v[26:27], off
	global_load_ushort v37, v[16:17], off
	global_load_ushort v36, v[0:1], off
	global_load_ushort v35, v[2:3], off
	v_mov_b32_e32 v90, 1.0
	v_pk_mul_f32 v[2:3], v[208:209], v[208:209] op_sel:[1,1] op_sel_hi:[0,1] neg_lo:[1,0]
	v_mov_b32_e32 v91, v177
	v_pk_fma_f32 v[2:3], v[208:209], v[208:209], v[2:3] op_sel_hi:[0,1,1]
	v_pk_mul_f32 v[12:13], v[2:3], v[2:3] op_sel:[1,1] op_sel_hi:[1,0] neg_lo:[0,1]
	v_pk_mul_f32 v[4:5], v[208:209], v[176:177] op_sel:[1,1] op_sel_hi:[0,1] neg_lo:[1,0]
	v_pk_fma_f32 v[12:13], v[2:3], v[2:3], v[12:13] op_sel_hi:[1,0,1]
	v_pk_fma_f32 v[92:93], v[208:209], v[90:91], v[4:5] op_sel_hi:[1,0,1]
	v_pk_mul_f32 v[0:1], v[176:177], v[2:3] op_sel:[1,1] op_sel_hi:[1,0] neg_lo:[0,1]
	v_pk_fma_f32 v[94:95], v[90:91], v[2:3], v[0:1] op_sel_hi:[0,1,1]
	v_pk_mul_f32 v[0:1], v[92:93], v[2:3] op_sel:[1,1] op_sel_hi:[1,0] neg_lo:[0,1]
	v_pk_mul_f32 v[16:17], v[12:13], v[12:13] op_sel:[1,1] op_sel_hi:[1,0] neg_lo:[0,1]
	v_pk_fma_f32 v[96:97], v[2:3], v[92:93], v[0:1] op_sel_hi:[1,0,1]
	v_pk_mul_f32 v[0:1], v[176:177], v[12:13] op_sel:[1,1] op_sel_hi:[1,0] neg_lo:[0,1]
	v_pk_fma_f32 v[98:99], v[90:91], v[12:13], v[0:1] op_sel_hi:[0,1,1]
	v_pk_mul_f32 v[0:1], v[92:93], v[12:13] op_sel:[1,1] op_sel_hi:[1,0] neg_lo:[0,1]
	v_pk_fma_f32 v[32:33], v[92:93], v[12:13], v[0:1] op_sel_hi:[0,1,1]
	v_pk_mul_f32 v[0:1], v[94:95], v[12:13] op_sel:[1,1] op_sel_hi:[1,0] neg_lo:[0,1]
	v_pk_fma_f32 v[30:31], v[12:13], v[94:95], v[0:1] op_sel_hi:[1,0,1]
	v_pk_mul_f32 v[0:1], v[96:97], v[12:13] op_sel:[1,1] op_sel_hi:[1,0] neg_lo:[0,1]
	v_pk_fma_f32 v[26:27], v[12:13], v[96:97], v[0:1] op_sel_hi:[1,0,1]
	v_pk_fma_f32 v[0:1], v[12:13], v[12:13], v[16:17] op_sel_hi:[1,0,1]
	v_pk_mul_f32 v[2:3], v[176:177], v[0:1] op_sel:[1,1] op_sel_hi:[1,0] neg_lo:[0,1]
	v_pk_fma_f32 v[28:29], v[90:91], v[0:1], v[2:3] op_sel_hi:[0,1,1]
	v_pk_mul_f32 v[2:3], v[92:93], v[0:1] op_sel:[1,1] op_sel_hi:[1,0] neg_lo:[0,1]
	v_pk_fma_f32 v[16:17], v[92:93], v[0:1], v[2:3] op_sel_hi:[0,1,1]
	v_pk_mul_f32 v[2:3], v[94:95], v[0:1] op_sel:[1,1] op_sel_hi:[1,0] neg_lo:[0,1]
	v_pk_fma_f32 v[14:15], v[94:95], v[0:1], v[2:3] op_sel_hi:[0,1,1]
	v_pk_mul_f32 v[2:3], v[96:97], v[0:1] op_sel:[1,1] op_sel_hi:[1,0] neg_lo:[0,1]
	v_pk_fma_f32 v[12:13], v[96:97], v[0:1], v[2:3] op_sel_hi:[0,1,1]
	v_pk_mul_f32 v[2:3], v[98:99], v[0:1] op_sel:[1,1] op_sel_hi:[1,0] neg_lo:[0,1]
	v_pk_fma_f32 v[8:9], v[0:1], v[98:99], v[2:3] op_sel_hi:[1,0,1]
	v_pk_mul_f32 v[2:3], v[32:33], v[0:1] op_sel:[1,1] op_sel_hi:[1,0] neg_lo:[0,1]
	v_pk_fma_f32 v[4:5], v[0:1], v[32:33], v[2:3] op_sel_hi:[1,0,1]
	v_pk_mul_f32 v[2:3], v[30:31], v[0:1] op_sel:[1,1] op_sel_hi:[1,0] neg_lo:[0,1]
	v_pk_mul_f32 v[100:101], v[26:27], v[0:1] op_sel:[1,1] op_sel_hi:[1,0] neg_lo:[0,1]
	v_pk_fma_f32 v[2:3], v[0:1], v[30:31], v[2:3] op_sel_hi:[1,0,1]
	v_pk_fma_f32 v[0:1], v[0:1], v[26:27], v[100:101] op_sel_hi:[1,0,1]
	v_pk_add_f32 v[100:101], v[78:79], v[70:71]
	v_pk_add_f32 v[70:71], v[70:71], v[78:79] neg_lo:[0,1] neg_hi:[0,1]
	v_pk_add_f32 v[78:79], v[84:85], v[74:75]
	v_pk_add_f32 v[74:75], v[74:75], v[84:85] neg_lo:[0,1] neg_hi:[0,1]
	v_pk_add_f32 v[102:103], v[74:75], v[70:71] op_sel:[1,0] op_sel_hi:[0,1] neg_hi:[1,0]
	v_pk_add_f32 v[70:71], v[70:71], v[74:75] op_sel:[0,1] op_sel_hi:[1,0] neg_lo:[0,1]
	v_pk_add_f32 v[84:85], v[80:81], v[72:73]
	v_pk_add_f32 v[72:73], v[72:73], v[80:81] neg_lo:[0,1] neg_hi:[0,1]
	v_pk_add_f32 v[80:81], v[86:87], v[76:77]
	v_pk_add_f32 v[76:77], v[76:77], v[86:87] neg_lo:[0,1] neg_hi:[0,1]
	v_pk_add_f32 v[74:75], v[78:79], v[100:101]
	v_xor_b32_e32 v87, 0x80000000, v76
	v_mov_b32_e32 v86, v77
	v_pk_add_f32 v[76:77], v[80:81], v[84:85]
	v_pk_add_f32 v[80:81], v[84:85], v[80:81] neg_lo:[0,1] neg_hi:[0,1]
	v_pk_add_f32 v[84:85], v[82:83], v[22:23]
	v_pk_add_f32 v[22:23], v[22:23], v[82:83] neg_lo:[0,1] neg_hi:[0,1]
	v_pk_add_f32 v[82:83], v[88:89], v[24:25]
	v_pk_add_f32 v[24:25], v[24:25], v[88:89] neg_lo:[0,1] neg_hi:[0,1]
	v_pk_add_f32 v[78:79], v[100:101], v[78:79] neg_lo:[0,1] neg_hi:[0,1]
	v_pk_add_f32 v[100:101], v[86:87], v[72:73]
	v_pk_add_f32 v[72:73], v[72:73], v[86:87] neg_lo:[0,1] neg_hi:[0,1]
	v_xor_b32_e32 v87, 0x80000000, v24
	v_mov_b32_e32 v86, v25
	v_pk_add_f32 v[24:25], v[82:83], v[84:85]
	v_pk_add_f32 v[82:83], v[84:85], v[82:83] neg_lo:[0,1] neg_hi:[0,1]
	v_pk_add_f32 v[84:85], v[18:19], v[6:7]
	v_pk_add_f32 v[6:7], v[6:7], v[18:19] neg_lo:[0,1] neg_hi:[0,1]
	v_pk_add_f32 v[18:19], v[20:21], v[10:11]
	v_pk_add_f32 v[10:11], v[10:11], v[20:21] neg_lo:[0,1] neg_hi:[0,1]
	v_pk_add_f32 v[88:89], v[86:87], v[22:23]
	v_xor_b32_e32 v21, 0x80000000, v10
	v_mov_b32_e32 v20, v11
	v_pk_add_f32 v[10:11], v[18:19], v[84:85]
	v_pk_add_f32 v[18:19], v[84:85], v[18:19] neg_lo:[0,1] neg_hi:[0,1]
	v_pk_mul_f32 v[84:85], v[80:81], s[12:13] op_sel:[1,0] op_sel_hi:[0,0] neg_lo:[1,0]
	v_pk_add_f32 v[22:23], v[22:23], v[86:87] neg_lo:[0,1] neg_hi:[0,1]
	v_pk_fma_f32 v[80:81], v[80:81], s[12:13], v[84:85] op_sel_hi:[1,0,1] neg_lo:[0,0,1] neg_hi:[0,0,1]
	v_pk_mul_f32 v[84:85], v[72:73], s[36:37] op_sel:[1,0] op_sel_hi:[0,0] neg_lo:[1,0]
	v_pk_add_f32 v[86:87], v[20:21], v[6:7]
	v_pk_fma_f32 v[72:73], v[72:73], s[22:23], v[84:85] op_sel_hi:[1,0,1] neg_lo:[0,0,1] neg_hi:[0,0,1]
	v_pk_mul_f32 v[84:85], v[88:89], s[12:13] op_sel:[1,0] op_sel_hi:[0,0] neg_lo:[1,0]
	v_pk_add_f32 v[6:7], v[6:7], v[20:21] neg_lo:[0,1] neg_hi:[0,1]
	v_pk_fma_f32 v[84:85], v[88:89], s[12:13], v[84:85] op_sel_hi:[1,0,1] neg_lo:[0,0,1] neg_hi:[0,0,1]
	v_pk_fma_f32 v[82:83], v[82:83], 0, v[82:83] op_sel:[0,0,1] op_sel_hi:[1,0,0] neg_hi:[0,0,1]
	v_pk_mul_f32 v[88:89], v[22:23], s[12:13] op_sel:[1,0] op_sel_hi:[0,0] neg_lo:[1,0]
	v_pk_fma_f32 v[22:23], v[22:23], s[18:19], v[88:89] op_sel_hi:[1,0,1] neg_lo:[0,0,1] neg_hi:[0,0,1]
	v_pk_mul_f32 v[88:89], v[86:87], s[36:37] op_sel:[1,0] op_sel_hi:[0,0] neg_lo:[1,0]
	v_pk_fma_f32 v[86:87], v[86:87], s[22:23], v[88:89] op_sel_hi:[1,0,1] neg_lo:[0,0,1] neg_hi:[0,0,1]
	v_pk_mul_f32 v[88:89], v[18:19], s[12:13] op_sel:[1,0] op_sel_hi:[0,0] neg_lo:[1,0]
	v_pk_mul_f32 v[20:21], v[100:101], s[22:23] op_sel:[1,0] op_sel_hi:[0,0] neg_lo:[1,0]
	v_pk_fma_f32 v[18:19], v[18:19], s[18:19], v[88:89] op_sel_hi:[1,0,1] neg_lo:[0,0,1] neg_hi:[0,0,1]
	v_xor_b32_e32 v88, 0x80000000, v7
	v_mov_b32_e32 v89, v6
	v_pk_mul_f32 v[6:7], v[6:7], s[36:37] op_sel_hi:[1,0]
	v_pk_fma_f32 v[20:21], v[100:101], s[36:37], v[20:21] op_sel_hi:[1,0,1] neg_lo:[0,0,1] neg_hi:[0,0,1]
	v_pk_fma_f32 v[6:7], v[88:89], s[22:23], v[6:7] op_sel_hi:[1,0,1] neg_lo:[0,0,1] neg_hi:[0,0,1]
	v_pk_add_f32 v[88:89], v[24:25], v[74:75]
	v_pk_add_f32 v[24:25], v[74:75], v[24:25] neg_lo:[0,1] neg_hi:[0,1]
	v_pk_add_f32 v[74:75], v[10:11], v[76:77]
	v_pk_add_f32 v[10:11], v[76:77], v[10:11] neg_lo:[0,1] neg_hi:[0,1]
	v_xor_b32_e32 v77, 0x80000000, v10
	v_mov_b32_e32 v76, v11
	v_pk_add_f32 v[10:11], v[74:75], v[88:89]
	v_pk_add_f32 v[74:75], v[88:89], v[74:75] neg_lo:[0,1] neg_hi:[0,1]
	v_pk_add_f32 v[88:89], v[86:87], v[20:21]
	v_pk_add_f32 v[20:21], v[20:21], v[86:87] neg_lo:[0,1] neg_hi:[0,1]
	v_pk_add_f32 v[100:101], v[24:25], v[76:77]
	v_pk_add_f32 v[24:25], v[24:25], v[76:77] neg_lo:[0,1] neg_hi:[0,1]
	v_pk_add_f32 v[76:77], v[102:103], v[84:85]
	v_pk_add_f32 v[84:85], v[102:103], v[84:85] neg_lo:[0,1] neg_hi:[0,1]
	v_pk_add_f32 v[102:103], v[84:85], v[20:21] op_sel:[0,1] op_sel_hi:[1,0] neg_hi:[0,1]
	v_pk_add_f32 v[84:85], v[84:85], v[20:21] op_sel:[0,1] op_sel_hi:[1,0] neg_lo:[0,1]
	v_pk_add_f32 v[86:87], v[78:79], v[82:83]
	v_pk_add_f32 v[78:79], v[78:79], v[82:83] neg_lo:[0,1] neg_hi:[0,1]
	v_pk_add_f32 v[82:83], v[18:19], v[80:81]
	v_pk_add_f32 v[18:19], v[80:81], v[18:19] neg_lo:[0,1] neg_hi:[0,1]
	v_pk_add_f32 v[20:21], v[76:77], v[88:89]
	v_pk_add_f32 v[76:77], v[76:77], v[88:89] neg_lo:[0,1] neg_hi:[0,1]
	v_pk_add_f32 v[88:89], v[78:79], v[18:19] op_sel:[0,1] op_sel_hi:[1,0] neg_hi:[0,1]
	v_pk_add_f32 v[78:79], v[78:79], v[18:19] op_sel:[0,1] op_sel_hi:[1,0] neg_lo:[0,1]
	v_pk_add_f32 v[80:81], v[70:71], v[22:23]
	v_pk_add_f32 v[22:23], v[70:71], v[22:23] neg_lo:[0,1] neg_hi:[0,1]
	v_pk_add_f32 v[70:71], v[6:7], v[72:73]
	v_pk_add_f32 v[6:7], v[72:73], v[6:7] neg_lo:[0,1] neg_hi:[0,1]
	v_pk_add_f32 v[18:19], v[86:87], v[82:83]
	v_pk_add_f32 v[82:83], v[86:87], v[82:83] neg_lo:[0,1] neg_hi:[0,1]
	v_pk_add_f32 v[86:87], v[22:23], v[6:7] op_sel:[0,1] op_sel_hi:[1,0] neg_hi:[0,1]
	v_pk_add_f32 v[22:23], v[22:23], v[6:7] op_sel:[0,1] op_sel_hi:[1,0] neg_lo:[0,1]
	v_mov_b32_e32 v72, v206
	v_pk_add_f32 v[6:7], v[80:81], v[70:71]
	v_lshlrev_b32_sdwa v73, v228, v72 dst_sel:DWORD dst_unused:UNUSED_PAD src0_sel:DWORD src1_sel:BYTE_0
	v_lshrrev_b32_e32 v72, 1, v206
	v_and_b32_e32 v72, 0x78, v72
	v_pk_add_f32 v[70:71], v[80:81], v[70:71] neg_lo:[0,1] neg_hi:[0,1]
	v_add3_u32 v80, v207, v73, v72
	v_xor_b32_e32 v72, 0x80000000, v91
	v_mov_b32_e32 v73, v90
	v_pk_mul_f32 v[72:73], v[10:11], v[72:73] op_sel:[1,0]
	v_pk_fma_f32 v[10:11], v[10:11], v[90:91], v[72:73] op_sel_hi:[0,1,1]
	ds_write_b64 v80, v[10:11]
	v_pk_mul_f32 v[10:11], v[20:21], v[92:93] op_sel:[1,1] op_sel_hi:[1,0] neg_lo:[0,1]
	v_pk_fma_f32 v[10:11], v[20:21], v[92:93], v[10:11] op_sel_hi:[0,1,1]
	ds_write_b64 v80, v[10:11] offset:2176
	v_pk_mul_f32 v[10:11], v[18:19], v[94:95] op_sel:[1,1] op_sel_hi:[1,0] neg_lo:[0,1]
	v_pk_fma_f32 v[10:11], v[18:19], v[94:95], v[10:11] op_sel_hi:[0,1,1]
	ds_write_b64 v80, v[10:11] offset:4352
	v_pk_mul_f32 v[10:11], v[6:7], v[96:97] op_sel:[1,1] op_sel_hi:[1,0] neg_lo:[0,1]
	v_pk_fma_f32 v[6:7], v[6:7], v[96:97], v[10:11] op_sel_hi:[0,1,1]
	ds_write_b64 v80, v[6:7] offset:6528
	v_pk_mul_f32 v[6:7], v[100:101], v[98:99] op_sel:[1,1] op_sel_hi:[1,0] neg_lo:[0,1]
	v_pk_fma_f32 v[6:7], v[100:101], v[98:99], v[6:7] op_sel_hi:[0,1,1]
	ds_write_b64 v80, v[6:7] offset:8704
	v_pk_mul_f32 v[6:7], v[102:103], v[32:33] op_sel:[1,1] op_sel_hi:[1,0] neg_lo:[0,1]
	v_pk_fma_f32 v[6:7], v[102:103], v[32:33], v[6:7] op_sel_hi:[0,1,1]
	ds_write_b64 v80, v[6:7] offset:10880
	v_pk_mul_f32 v[6:7], v[88:89], v[30:31] op_sel:[1,1] op_sel_hi:[1,0] neg_lo:[0,1]
	v_pk_fma_f32 v[6:7], v[88:89], v[30:31], v[6:7] op_sel_hi:[0,1,1]
	ds_write_b64 v80, v[6:7] offset:13056
	v_pk_mul_f32 v[6:7], v[86:87], v[26:27] op_sel:[1,1] op_sel_hi:[1,0] neg_lo:[0,1]
	v_pk_fma_f32 v[6:7], v[86:87], v[26:27], v[6:7] op_sel_hi:[0,1,1]
	ds_write_b64 v80, v[6:7] offset:15232
	v_pk_mul_f32 v[6:7], v[74:75], v[28:29] op_sel:[1,1] op_sel_hi:[1,0] neg_lo:[0,1]
	v_pk_fma_f32 v[6:7], v[74:75], v[28:29], v[6:7] op_sel_hi:[0,1,1]
	ds_write_b64 v80, v[6:7] offset:17408
	v_pk_mul_f32 v[6:7], v[76:77], v[16:17] op_sel:[1,1] op_sel_hi:[1,0] neg_lo:[0,1]
	v_pk_fma_f32 v[6:7], v[76:77], v[16:17], v[6:7] op_sel_hi:[0,1,1]
	ds_write_b64 v80, v[6:7] offset:19584
	v_pk_mul_f32 v[6:7], v[82:83], v[14:15] op_sel:[1,1] op_sel_hi:[1,0] neg_lo:[0,1]
	v_pk_fma_f32 v[6:7], v[82:83], v[14:15], v[6:7] op_sel_hi:[0,1,1]
	ds_write_b64 v80, v[6:7] offset:21760
	v_pk_mul_f32 v[6:7], v[70:71], v[12:13] op_sel:[1,1] op_sel_hi:[1,0] neg_lo:[0,1]
	v_pk_fma_f32 v[6:7], v[70:71], v[12:13], v[6:7] op_sel_hi:[0,1,1]
	ds_write_b64 v80, v[6:7] offset:23936
	v_pk_mul_f32 v[6:7], v[24:25], v[8:9] op_sel:[1,1] op_sel_hi:[1,0] neg_lo:[0,1]
	v_pk_fma_f32 v[6:7], v[24:25], v[8:9], v[6:7] op_sel_hi:[0,1,1]
	ds_write_b64 v80, v[6:7] offset:26112
	v_pk_mul_f32 v[6:7], v[84:85], v[4:5] op_sel:[1,1] op_sel_hi:[1,0] neg_lo:[0,1]
	v_pk_fma_f32 v[4:5], v[84:85], v[4:5], v[6:7] op_sel_hi:[0,1,1]
	ds_write_b64 v80, v[4:5] offset:28288
	v_pk_mul_f32 v[4:5], v[78:79], v[2:3] op_sel:[1,1] op_sel_hi:[1,0] neg_lo:[0,1]
	v_pk_fma_f32 v[2:3], v[78:79], v[2:3], v[4:5] op_sel_hi:[0,1,1]
	ds_write_b64 v80, v[2:3] offset:30464
	v_pk_mul_f32 v[2:3], v[22:23], v[0:1] op_sel:[1,1] op_sel_hi:[1,0] neg_lo:[0,1]
	v_pk_fma_f32 v[0:1], v[22:23], v[0:1], v[2:3] op_sel_hi:[0,1,1]
	ds_write_b64 v80, v[0:1] offset:32640
	v_mov_b32_e32 v78, 1.0
	v_pk_mul_f32 v[2:3], v[210:211], v[210:211] op_sel:[1,1] op_sel_hi:[0,1] neg_lo:[1,0]
	v_mov_b32_e32 v79, v177
	v_pk_fma_f32 v[2:3], v[210:211], v[210:211], v[2:3] op_sel_hi:[0,1,1]
	v_pk_mul_f32 v[8:9], v[2:3], v[2:3] op_sel:[1,1] op_sel_hi:[1,0] neg_lo:[0,1]
	v_pk_mul_f32 v[4:5], v[210:211], v[176:177] op_sel:[1,1] op_sel_hi:[0,1] neg_lo:[1,0]
	v_pk_fma_f32 v[8:9], v[2:3], v[2:3], v[8:9] op_sel_hi:[1,0,1]
	v_pk_fma_f32 v[80:81], v[210:211], v[78:79], v[4:5] op_sel_hi:[1,0,1]
	v_pk_mul_f32 v[0:1], v[176:177], v[2:3] op_sel:[1,1] op_sel_hi:[1,0] neg_lo:[0,1]
	v_pk_fma_f32 v[82:83], v[78:79], v[2:3], v[0:1] op_sel_hi:[0,1,1]
	v_pk_mul_f32 v[0:1], v[80:81], v[2:3] op_sel:[1,1] op_sel_hi:[1,0] neg_lo:[0,1]
	v_pk_mul_f32 v[12:13], v[8:9], v[8:9] op_sel:[1,1] op_sel_hi:[1,0] neg_lo:[0,1]
	v_pk_fma_f32 v[84:85], v[2:3], v[80:81], v[0:1] op_sel_hi:[1,0,1]
	v_pk_mul_f32 v[0:1], v[176:177], v[8:9] op_sel:[1,1] op_sel_hi:[1,0] neg_lo:[0,1]
	v_pk_fma_f32 v[86:87], v[78:79], v[8:9], v[0:1] op_sel_hi:[0,1,1]
	v_pk_mul_f32 v[0:1], v[80:81], v[8:9] op_sel:[1,1] op_sel_hi:[1,0] neg_lo:[0,1]
	s_waitcnt lgkmcnt(0)
	v_pk_fma_f32 v[88:89], v[80:81], v[8:9], v[0:1] op_sel_hi:[0,1,1]
	v_pk_mul_f32 v[0:1], v[82:83], v[8:9] op_sel:[1,1] op_sel_hi:[1,0] neg_lo:[0,1]
	s_barrier
	v_pk_fma_f32 v[90:91], v[8:9], v[82:83], v[0:1] op_sel_hi:[1,0,1]
	v_pk_mul_f32 v[0:1], v[84:85], v[8:9] op_sel:[1,1] op_sel_hi:[1,0] neg_lo:[0,1]
	v_pk_fma_f32 v[92:93], v[8:9], v[84:85], v[0:1] op_sel_hi:[1,0,1]
	v_pk_fma_f32 v[0:1], v[8:9], v[8:9], v[12:13] op_sel_hi:[1,0,1]
	v_pk_mul_f32 v[2:3], v[176:177], v[0:1] op_sel:[1,1] op_sel_hi:[1,0] neg_lo:[0,1]
	v_pk_fma_f32 v[94:95], v[78:79], v[0:1], v[2:3] op_sel_hi:[0,1,1]
	v_pk_mul_f32 v[2:3], v[80:81], v[0:1] op_sel:[1,1] op_sel_hi:[1,0] neg_lo:[0,1]
	v_pk_fma_f32 v[96:97], v[80:81], v[0:1], v[2:3] op_sel_hi:[0,1,1]
	v_pk_mul_f32 v[2:3], v[82:83], v[0:1] op_sel:[1,1] op_sel_hi:[1,0] neg_lo:[0,1]
	v_pk_fma_f32 v[98:99], v[82:83], v[0:1], v[2:3] op_sel_hi:[0,1,1]
	v_pk_mul_f32 v[2:3], v[84:85], v[0:1] op_sel:[1,1] op_sel_hi:[1,0] neg_lo:[0,1]
	v_pk_fma_f32 v[8:9], v[84:85], v[0:1], v[2:3] op_sel_hi:[0,1,1]
	v_pk_mul_f32 v[2:3], v[86:87], v[0:1] op_sel:[1,1] op_sel_hi:[1,0] neg_lo:[0,1]
	v_pk_fma_f32 v[6:7], v[0:1], v[86:87], v[2:3] op_sel_hi:[1,0,1]
	v_pk_mul_f32 v[2:3], v[88:89], v[0:1] op_sel:[1,1] op_sel_hi:[1,0] neg_lo:[0,1]
	v_pk_fma_f32 v[4:5], v[0:1], v[88:89], v[2:3] op_sel_hi:[1,0,1]
	v_pk_mul_f32 v[2:3], v[90:91], v[0:1] op_sel:[1,1] op_sel_hi:[1,0] neg_lo:[0,1]
	v_pk_mul_f32 v[10:11], v[92:93], v[0:1] op_sel:[1,1] op_sel_hi:[1,0] neg_lo:[0,1]
	v_pk_fma_f32 v[2:3], v[0:1], v[90:91], v[2:3] op_sel_hi:[1,0,1]
	v_pk_fma_f32 v[0:1], v[0:1], v[92:93], v[10:11] op_sel_hi:[1,0,1]
	s_nop 0
	v_bfe_u32 v11, v206, 4, 4
	v_and_b32_e32 v10, 15, v206
	v_mul_u32_u24_e32 v11, 0x880, v11
	v_lshlrev_b32_e32 v10, 3, v10
	v_add3_u32 v104, v207, v11, v10
	ds_read2_b64 v[10:13], v104 offset1:17
	ds_read2_b64 v[14:17], v104 offset0:34 offset1:51
	ds_read2_b64 v[18:21], v104 offset0:68 offset1:85
	ds_read2_b64 v[22:25], v104 offset0:136 offset1:153
	ds_read2_b64 v[26:29], v104 offset0:102 offset1:119
	ds_read2_b64 v[30:33], v104 offset0:204 offset1:221
	ds_read2_b64 v[70:73], v104 offset0:170 offset1:187
	ds_read2_b64 v[74:77], v104 offset0:238 offset1:255
	s_waitcnt lgkmcnt(4)
	v_pk_add_f32 v[100:101], v[10:11], v[22:23]
	v_pk_add_f32 v[10:11], v[10:11], v[22:23] neg_lo:[0,1] neg_hi:[0,1]
	s_waitcnt lgkmcnt(2)
	v_pk_add_f32 v[22:23], v[18:19], v[30:31]
	v_pk_add_f32 v[18:19], v[18:19], v[30:31] neg_lo:[0,1] neg_hi:[0,1]
	v_pk_add_f32 v[102:103], v[10:11], v[18:19] op_sel:[0,1] op_sel_hi:[1,0] neg_hi:[0,1]
	v_pk_add_f32 v[10:11], v[10:11], v[18:19] op_sel:[0,1] op_sel_hi:[1,0] neg_lo:[0,1]
	v_pk_add_f32 v[30:31], v[12:13], v[24:25]
	v_pk_add_f32 v[12:13], v[12:13], v[24:25] neg_lo:[0,1] neg_hi:[0,1]
	v_pk_add_f32 v[24:25], v[20:21], v[32:33]
	v_pk_add_f32 v[20:21], v[20:21], v[32:33] neg_lo:[0,1] neg_hi:[0,1]
	v_pk_add_f32 v[18:19], v[100:101], v[22:23]
	v_pk_add_f32 v[22:23], v[100:101], v[22:23] neg_lo:[0,1] neg_hi:[0,1]
	v_pk_add_f32 v[100:101], v[12:13], v[20:21] op_sel:[0,1] op_sel_hi:[1,0] neg_hi:[0,1]
	v_pk_add_f32 v[12:13], v[12:13], v[20:21] op_sel:[0,1] op_sel_hi:[1,0] neg_lo:[0,1]
	s_waitcnt lgkmcnt(0)
	v_pk_add_f32 v[32:33], v[26:27], v[74:75]
	v_pk_add_f32 v[26:27], v[26:27], v[74:75] neg_lo:[0,1] neg_hi:[0,1]
	v_pk_add_f32 v[20:21], v[30:31], v[24:25]
	v_pk_add_f32 v[24:25], v[30:31], v[24:25] neg_lo:[0,1] neg_hi:[0,1]
	v_pk_add_f32 v[30:31], v[14:15], v[70:71]
	v_pk_add_f32 v[14:15], v[14:15], v[70:71] neg_lo:[0,1] neg_hi:[0,1]
	v_pk_add_f32 v[74:75], v[14:15], v[26:27] op_sel:[0,1] op_sel_hi:[1,0] neg_hi:[0,1]
	v_pk_add_f32 v[14:15], v[14:15], v[26:27] op_sel:[0,1] op_sel_hi:[1,0] neg_lo:[0,1]
	v_pk_add_f32 v[70:71], v[28:29], v[76:77]
	v_pk_add_f32 v[28:29], v[28:29], v[76:77] neg_lo:[0,1] neg_hi:[0,1]
	v_pk_add_f32 v[26:27], v[30:31], v[32:33]
	v_pk_add_f32 v[30:31], v[30:31], v[32:33] neg_lo:[0,1] neg_hi:[0,1]
	v_pk_add_f32 v[32:33], v[16:17], v[72:73]
	v_pk_add_f32 v[16:17], v[16:17], v[72:73] neg_lo:[0,1] neg_hi:[0,1]
	v_pk_add_f32 v[76:77], v[16:17], v[28:29] op_sel:[0,1] op_sel_hi:[1,0] neg_hi:[0,1]
	v_pk_add_f32 v[16:17], v[16:17], v[28:29] op_sel:[0,1] op_sel_hi:[1,0] neg_lo:[0,1]
	v_pk_mul_f32 v[72:73], v[24:25], s[12:13] op_sel:[1,0] op_sel_hi:[0,0] neg_lo:[1,0]
	v_pk_add_f32 v[28:29], v[32:33], v[70:71]
	v_pk_fma_f32 v[24:25], v[24:25], s[12:13], v[72:73] op_sel_hi:[1,0,1] neg_lo:[0,0,1] neg_hi:[0,0,1]
	v_pk_mul_f32 v[72:73], v[12:13], s[36:37] op_sel:[1,0] op_sel_hi:[0,0] neg_lo:[1,0]
	v_pk_add_f32 v[32:33], v[32:33], v[70:71] neg_lo:[0,1] neg_hi:[0,1]
	v_pk_fma_f32 v[12:13], v[12:13], s[22:23], v[72:73] op_sel_hi:[1,0,1] neg_lo:[0,0,1] neg_hi:[0,0,1]
	v_pk_mul_f32 v[72:73], v[74:75], s[12:13] op_sel:[1,0] op_sel_hi:[0,0] neg_lo:[1,0]
	v_pk_fma_f32 v[72:73], v[74:75], s[12:13], v[72:73] op_sel_hi:[1,0,1] neg_lo:[0,0,1] neg_hi:[0,0,1]
	v_pk_fma_f32 v[30:31], v[30:31], 0, v[30:31] op_sel:[0,0,1] op_sel_hi:[1,0,0] neg_hi:[0,0,1]
	v_pk_mul_f32 v[74:75], v[14:15], s[12:13] op_sel:[1,0] op_sel_hi:[0,0] neg_lo:[1,0]
	v_pk_fma_f32 v[14:15], v[14:15], s[18:19], v[74:75] op_sel_hi:[1,0,1] neg_lo:[0,0,1] neg_hi:[0,0,1]
	v_pk_mul_f32 v[74:75], v[76:77], s[36:37] op_sel:[1,0] op_sel_hi:[0,0] neg_lo:[1,0]
	v_pk_mul_f32 v[70:71], v[100:101], s[22:23] op_sel:[1,0] op_sel_hi:[0,0] neg_lo:[1,0]
	v_pk_fma_f32 v[74:75], v[76:77], s[22:23], v[74:75] op_sel_hi:[1,0,1] neg_lo:[0,0,1] neg_hi:[0,0,1]
	v_pk_mul_f32 v[76:77], v[32:33], s[12:13] op_sel:[1,0] op_sel_hi:[0,0] neg_lo:[1,0]
	v_pk_fma_f32 v[70:71], v[100:101], s[36:37], v[70:71] op_sel_hi:[1,0,1] neg_lo:[0,0,1] neg_hi:[0,0,1]
	v_pk_fma_f32 v[32:33], v[32:33], s[18:19], v[76:77] op_sel_hi:[1,0,1] neg_lo:[0,0,1] neg_hi:[0,0,1]
	v_xor_b32_e32 v76, 0x80000000, v17
	v_mov_b32_e32 v77, v16
	v_pk_mul_f32 v[16:17], v[16:17], s[36:37] op_sel_hi:[1,0]
	v_pk_fma_f32 v[16:17], v[76:77], s[22:23], v[16:17] op_sel_hi:[1,0,1] neg_lo:[0,0,1] neg_hi:[0,0,1]
	v_pk_add_f32 v[76:77], v[18:19], v[26:27]
	v_pk_add_f32 v[18:19], v[18:19], v[26:27] neg_lo:[0,1] neg_hi:[0,1]
	v_pk_add_f32 v[26:27], v[20:21], v[28:29]
	v_pk_add_f32 v[20:21], v[20:21], v[28:29] neg_lo:[0,1] neg_hi:[0,1]
	v_xor_b32_e32 v29, 0x80000000, v20
	v_mov_b32_e32 v28, v21
	v_pk_add_f32 v[20:21], v[76:77], v[26:27]
	v_pk_add_f32 v[26:27], v[76:77], v[26:27] neg_lo:[0,1] neg_hi:[0,1]
	v_pk_add_f32 v[76:77], v[70:71], v[74:75]
	v_pk_add_f32 v[70:71], v[70:71], v[74:75] neg_lo:[0,1] neg_hi:[0,1]
	v_pk_add_f32 v[100:101], v[18:19], v[28:29]
	v_pk_add_f32 v[18:19], v[18:19], v[28:29] neg_lo:[0,1] neg_hi:[0,1]
	v_pk_add_f32 v[28:29], v[102:103], v[72:73]
	v_pk_add_f32 v[72:73], v[102:103], v[72:73] neg_lo:[0,1] neg_hi:[0,1]
	v_pk_add_f32 v[102:103], v[72:73], v[70:71] op_sel:[0,1] op_sel_hi:[1,0] neg_hi:[0,1]
	v_pk_add_f32 v[72:73], v[72:73], v[70:71] op_sel:[0,1] op_sel_hi:[1,0] neg_lo:[0,1]
	v_pk_add_f32 v[74:75], v[22:23], v[30:31]
	v_pk_add_f32 v[22:23], v[22:23], v[30:31] neg_lo:[0,1] neg_hi:[0,1]
	v_pk_add_f32 v[30:31], v[24:25], v[32:33]
	v_pk_add_f32 v[24:25], v[24:25], v[32:33] neg_lo:[0,1] neg_hi:[0,1]
	v_pk_add_f32 v[70:71], v[28:29], v[76:77]
	v_pk_add_f32 v[28:29], v[28:29], v[76:77] neg_lo:[0,1] neg_hi:[0,1]
	v_pk_add_f32 v[76:77], v[22:23], v[24:25] op_sel:[0,1] op_sel_hi:[1,0] neg_hi:[0,1]
	v_pk_add_f32 v[22:23], v[22:23], v[24:25] op_sel:[0,1] op_sel_hi:[1,0] neg_lo:[0,1]
	v_pk_add_f32 v[32:33], v[10:11], v[14:15]
	v_pk_add_f32 v[10:11], v[10:11], v[14:15] neg_lo:[0,1] neg_hi:[0,1]
	v_pk_add_f32 v[14:15], v[12:13], v[16:17]
	v_pk_add_f32 v[12:13], v[12:13], v[16:17] neg_lo:[0,1] neg_hi:[0,1]
	v_pk_add_f32 v[24:25], v[74:75], v[30:31]
	v_pk_add_f32 v[30:31], v[74:75], v[30:31] neg_lo:[0,1] neg_hi:[0,1]
	v_pk_add_f32 v[74:75], v[10:11], v[12:13] op_sel:[0,1] op_sel_hi:[1,0] neg_hi:[0,1]
	v_pk_add_f32 v[10:11], v[10:11], v[12:13] op_sel:[0,1] op_sel_hi:[1,0] neg_lo:[0,1]
	v_xor_b32_e32 v16, 0x80000000, v79
	v_mov_b32_e32 v17, v78
	v_pk_mul_f32 v[16:17], v[16:17], v[20:21] op_sel:[0,1]
	v_pk_add_f32 v[12:13], v[32:33], v[14:15]
	v_pk_fma_f32 v[16:17], v[78:79], v[20:21], v[16:17] op_sel_hi:[1,0,1]
	v_pk_mul_f32 v[20:21], v[80:81], v[70:71] op_sel:[1,1] op_sel_hi:[0,1] neg_lo:[1,0]
	v_pk_add_f32 v[14:15], v[32:33], v[14:15] neg_lo:[0,1] neg_hi:[0,1]
	v_pk_fma_f32 v[20:21], v[80:81], v[70:71], v[20:21] op_sel_hi:[1,0,1]
	ds_write2_b64 v104, v[16:17], v[20:21] offset1:17
	v_pk_mul_f32 v[16:17], v[82:83], v[24:25] op_sel:[1,1] op_sel_hi:[0,1] neg_lo:[1,0]
	v_pk_mul_f32 v[20:21], v[84:85], v[12:13] op_sel:[1,1] op_sel_hi:[0,1] neg_lo:[1,0]
	v_pk_fma_f32 v[16:17], v[82:83], v[24:25], v[16:17] op_sel_hi:[1,0,1]
	v_pk_fma_f32 v[12:13], v[84:85], v[12:13], v[20:21] op_sel_hi:[1,0,1]
	ds_write2_b64 v104, v[16:17], v[12:13] offset0:34 offset1:51
	v_pk_mul_f32 v[12:13], v[86:87], v[100:101] op_sel:[1,1] op_sel_hi:[0,1] neg_lo:[1,0]
	v_pk_mul_f32 v[16:17], v[88:89], v[102:103] op_sel:[1,1] op_sel_hi:[0,1] neg_lo:[1,0]
	v_pk_fma_f32 v[12:13], v[86:87], v[100:101], v[12:13] op_sel_hi:[1,0,1]
	v_pk_fma_f32 v[16:17], v[88:89], v[102:103], v[16:17] op_sel_hi:[1,0,1]
	ds_write2_b64 v104, v[12:13], v[16:17] offset0:68 offset1:85
	v_pk_mul_f32 v[12:13], v[90:91], v[76:77] op_sel:[1,1] op_sel_hi:[0,1] neg_lo:[1,0]
	v_pk_mul_f32 v[16:17], v[92:93], v[74:75] op_sel:[1,1] op_sel_hi:[0,1] neg_lo:[1,0]
	v_pk_fma_f32 v[12:13], v[90:91], v[76:77], v[12:13] op_sel_hi:[1,0,1]
	v_pk_fma_f32 v[16:17], v[92:93], v[74:75], v[16:17] op_sel_hi:[1,0,1]
	ds_write2_b64 v104, v[12:13], v[16:17] offset0:102 offset1:119
	v_pk_mul_f32 v[12:13], v[94:95], v[26:27] op_sel:[1,1] op_sel_hi:[0,1] neg_lo:[1,0]
	v_pk_mul_f32 v[16:17], v[96:97], v[28:29] op_sel:[1,1] op_sel_hi:[0,1] neg_lo:[1,0]
	v_pk_fma_f32 v[12:13], v[94:95], v[26:27], v[12:13] op_sel_hi:[1,0,1]
	v_pk_fma_f32 v[16:17], v[96:97], v[28:29], v[16:17] op_sel_hi:[1,0,1]
	ds_write2_b64 v104, v[12:13], v[16:17] offset0:136 offset1:153
	v_pk_mul_f32 v[12:13], v[98:99], v[30:31] op_sel:[1,1] op_sel_hi:[0,1] neg_lo:[1,0]
	v_pk_mul_f32 v[16:17], v[8:9], v[14:15] op_sel:[1,1] op_sel_hi:[0,1] neg_lo:[1,0]
	v_pk_fma_f32 v[12:13], v[98:99], v[30:31], v[12:13] op_sel_hi:[1,0,1]
	v_pk_fma_f32 v[8:9], v[8:9], v[14:15], v[16:17] op_sel_hi:[1,0,1]
	ds_write2_b64 v104, v[12:13], v[8:9] offset0:170 offset1:187
	v_pk_mul_f32 v[8:9], v[6:7], v[18:19] op_sel:[1,1] op_sel_hi:[0,1] neg_lo:[1,0]
	v_pk_fma_f32 v[6:7], v[6:7], v[18:19], v[8:9] op_sel_hi:[1,0,1]
	v_pk_mul_f32 v[8:9], v[4:5], v[72:73] op_sel:[1,1] op_sel_hi:[0,1] neg_lo:[1,0]
	v_pk_fma_f32 v[4:5], v[4:5], v[72:73], v[8:9] op_sel_hi:[1,0,1]
	ds_write2_b64 v104, v[6:7], v[4:5] offset0:204 offset1:221
	v_pk_mul_f32 v[4:5], v[2:3], v[22:23] op_sel:[1,1] op_sel_hi:[0,1] neg_lo:[1,0]
	v_pk_fma_f32 v[2:3], v[2:3], v[22:23], v[4:5] op_sel_hi:[1,0,1]
	v_pk_mul_f32 v[4:5], v[0:1], v[10:11] op_sel:[1,1] op_sel_hi:[0,1] neg_lo:[1,0]
	v_pk_fma_f32 v[0:1], v[0:1], v[10:11], v[4:5] op_sel_hi:[1,0,1]
	ds_write2_b64 v104, v[2:3], v[0:1] offset0:238 offset1:255
	s_waitcnt lgkmcnt(0)
	s_barrier
	s_nop 0
	v_and_b32_e32 v0, 0xff, v206
	v_mad_u32_u24 v28, v0, s19, v207
	ds_read2_b64 v[0:3], v28 offset1:1
	ds_read2_b64 v[4:7], v28 offset0:2 offset1:3
	ds_read2_b64 v[8:11], v28 offset0:8 offset1:9
	ds_read2_b64 v[12:15], v28 offset0:4 offset1:5
	ds_read2_b64 v[16:19], v28 offset0:6 offset1:7
	ds_read2_b64 v[20:23], v28 offset0:12 offset1:13
	ds_read2_b64 v[24:27], v28 offset0:10 offset1:11
	ds_read2_b64 v[28:31], v28 offset0:14 offset1:15
	s_waitcnt lgkmcnt(5)
	v_pk_add_f32 v[32:33], v[0:1], v[8:9]
	v_pk_add_f32 v[0:1], v[0:1], v[8:9] neg_lo:[0,1] neg_hi:[0,1]
	s_waitcnt lgkmcnt(2)
	v_pk_add_f32 v[8:9], v[12:13], v[20:21]
	v_pk_add_f32 v[12:13], v[12:13], v[20:21] neg_lo:[0,1] neg_hi:[0,1]
	s_waitcnt lgkmcnt(0)
	v_pk_add_f32 v[70:71], v[0:1], v[12:13] op_sel:[0,1] op_sel_hi:[1,0] neg_hi:[0,1]
	v_pk_add_f32 v[0:1], v[0:1], v[12:13] op_sel:[0,1] op_sel_hi:[1,0] neg_lo:[0,1]
	v_pk_add_f32 v[20:21], v[2:3], v[10:11]
	v_pk_add_f32 v[2:3], v[2:3], v[10:11] neg_lo:[0,1] neg_hi:[0,1]
	v_pk_add_f32 v[10:11], v[14:15], v[22:23]
	v_pk_add_f32 v[14:15], v[14:15], v[22:23] neg_lo:[0,1] neg_hi:[0,1]
	v_pk_add_f32 v[12:13], v[32:33], v[8:9]
	v_pk_add_f32 v[8:9], v[32:33], v[8:9] neg_lo:[0,1] neg_hi:[0,1]
	v_pk_add_f32 v[32:33], v[2:3], v[14:15] op_sel:[0,1] op_sel_hi:[1,0] neg_hi:[0,1]
	v_pk_add_f32 v[2:3], v[2:3], v[14:15] op_sel:[0,1] op_sel_hi:[1,0] neg_lo:[0,1]
	v_pk_add_f32 v[22:23], v[16:17], v[28:29]
	v_pk_add_f32 v[16:17], v[16:17], v[28:29] neg_lo:[0,1] neg_hi:[0,1]
	v_pk_add_f32 v[14:15], v[20:21], v[10:11]
	v_pk_add_f32 v[10:11], v[20:21], v[10:11] neg_lo:[0,1] neg_hi:[0,1]
	v_pk_add_f32 v[20:21], v[4:5], v[24:25]
	v_pk_add_f32 v[4:5], v[4:5], v[24:25] neg_lo:[0,1] neg_hi:[0,1]
	v_pk_add_f32 v[28:29], v[4:5], v[16:17] op_sel:[0,1] op_sel_hi:[1,0] neg_hi:[0,1]
	v_pk_add_f32 v[4:5], v[4:5], v[16:17] op_sel:[0,1] op_sel_hi:[1,0] neg_lo:[0,1]
	v_pk_add_f32 v[24:25], v[18:19], v[30:31]
	v_pk_add_f32 v[18:19], v[18:19], v[30:31] neg_lo:[0,1] neg_hi:[0,1]
	v_pk_add_f32 v[16:17], v[20:21], v[22:23]
	v_pk_add_f32 v[20:21], v[20:21], v[22:23] neg_lo:[0,1] neg_hi:[0,1]
	v_pk_add_f32 v[22:23], v[6:7], v[26:27]
	v_pk_add_f32 v[6:7], v[6:7], v[26:27] neg_lo:[0,1] neg_hi:[0,1]
	v_pk_add_f32 v[30:31], v[6:7], v[18:19] op_sel:[0,1] op_sel_hi:[1,0] neg_hi:[0,1]
	v_pk_add_f32 v[6:7], v[6:7], v[18:19] op_sel:[0,1] op_sel_hi:[1,0] neg_lo:[0,1]
	v_pk_mul_f32 v[26:27], v[10:11], s[12:13] op_sel:[1,0] op_sel_hi:[0,0] neg_lo:[1,0]
	v_pk_add_f32 v[18:19], v[22:23], v[24:25]
	v_pk_fma_f32 v[10:11], v[10:11], s[12:13], v[26:27] op_sel_hi:[1,0,1] neg_lo:[0,0,1] neg_hi:[0,0,1]
	v_pk_mul_f32 v[26:27], v[2:3], s[36:37] op_sel:[1,0] op_sel_hi:[0,0] neg_lo:[1,0]
	v_pk_add_f32 v[22:23], v[22:23], v[24:25] neg_lo:[0,1] neg_hi:[0,1]
	v_pk_fma_f32 v[2:3], v[2:3], s[22:23], v[26:27] op_sel_hi:[1,0,1] neg_lo:[0,0,1] neg_hi:[0,0,1]
	v_pk_mul_f32 v[26:27], v[28:29], s[12:13] op_sel:[1,0] op_sel_hi:[0,0] neg_lo:[1,0]
	v_pk_fma_f32 v[26:27], v[28:29], s[12:13], v[26:27] op_sel_hi:[1,0,1] neg_lo:[0,0,1] neg_hi:[0,0,1]
	v_pk_fma_f32 v[20:21], v[20:21], 0, v[20:21] op_sel:[0,0,1] op_sel_hi:[1,0,0] neg_hi:[0,0,1]
	v_pk_mul_f32 v[28:29], v[4:5], s[12:13] op_sel:[1,0] op_sel_hi:[0,0] neg_lo:[1,0]
	v_pk_fma_f32 v[4:5], v[4:5], s[18:19], v[28:29] op_sel_hi:[1,0,1] neg_lo:[0,0,1] neg_hi:[0,0,1]
	v_pk_mul_f32 v[28:29], v[30:31], s[36:37] op_sel:[1,0] op_sel_hi:[0,0] neg_lo:[1,0]
	v_pk_mul_f32 v[24:25], v[32:33], s[22:23] op_sel:[1,0] op_sel_hi:[0,0] neg_lo:[1,0]
	v_pk_fma_f32 v[28:29], v[30:31], s[22:23], v[28:29] op_sel_hi:[1,0,1] neg_lo:[0,0,1] neg_hi:[0,0,1]
	v_pk_mul_f32 v[30:31], v[22:23], s[12:13] op_sel:[1,0] op_sel_hi:[0,0] neg_lo:[1,0]
	v_pk_fma_f32 v[24:25], v[32:33], s[36:37], v[24:25] op_sel_hi:[1,0,1] neg_lo:[0,0,1] neg_hi:[0,0,1]
	v_pk_fma_f32 v[22:23], v[22:23], s[18:19], v[30:31] op_sel_hi:[1,0,1] neg_lo:[0,0,1] neg_hi:[0,0,1]
	v_xor_b32_e32 v30, 0x80000000, v7
	v_mov_b32_e32 v31, v6
	v_pk_mul_f32 v[6:7], v[6:7], s[36:37] op_sel_hi:[1,0]
	s_barrier
	v_pk_fma_f32 v[6:7], v[30:31], s[22:23], v[6:7] op_sel_hi:[1,0,1] neg_lo:[0,0,1] neg_hi:[0,0,1]
	v_pk_add_f32 v[30:31], v[12:13], v[16:17]
	v_pk_add_f32 v[12:13], v[12:13], v[16:17] neg_lo:[0,1] neg_hi:[0,1]
	v_pk_add_f32 v[16:17], v[14:15], v[18:19]
	v_pk_add_f32 v[14:15], v[14:15], v[18:19] neg_lo:[0,1] neg_hi:[0,1]
	v_xor_b32_e32 v19, 0x80000000, v14
	v_mov_b32_e32 v18, v15
	v_pk_add_f32 v[14:15], v[30:31], v[16:17]
	v_pk_add_f32 v[16:17], v[30:31], v[16:17] neg_lo:[0,1] neg_hi:[0,1]
	v_pk_add_f32 v[30:31], v[24:25], v[28:29]
	v_pk_add_f32 v[24:25], v[24:25], v[28:29] neg_lo:[0,1] neg_hi:[0,1]
	v_pk_add_f32 v[32:33], v[12:13], v[18:19]
	v_pk_add_f32 v[12:13], v[12:13], v[18:19] neg_lo:[0,1] neg_hi:[0,1]
	v_pk_add_f32 v[18:19], v[70:71], v[26:27]
	v_pk_add_f32 v[26:27], v[70:71], v[26:27] neg_lo:[0,1] neg_hi:[0,1]
	v_pk_add_f32 v[70:71], v[26:27], v[24:25] op_sel:[0,1] op_sel_hi:[1,0] neg_hi:[0,1]
	v_pk_add_f32 v[26:27], v[26:27], v[24:25] op_sel:[0,1] op_sel_hi:[1,0] neg_lo:[0,1]
	v_pk_add_f32 v[28:29], v[8:9], v[20:21]
	v_pk_add_f32 v[8:9], v[8:9], v[20:21] neg_lo:[0,1] neg_hi:[0,1]
	v_pk_add_f32 v[20:21], v[10:11], v[22:23]
	v_pk_add_f32 v[10:11], v[10:11], v[22:23] neg_lo:[0,1] neg_hi:[0,1]
	v_pk_add_f32 v[24:25], v[18:19], v[30:31]
	v_pk_add_f32 v[18:19], v[18:19], v[30:31] neg_lo:[0,1] neg_hi:[0,1]
	v_pk_add_f32 v[30:31], v[8:9], v[10:11] op_sel:[0,1] op_sel_hi:[1,0] neg_hi:[0,1]
	v_pk_add_f32 v[8:9], v[8:9], v[10:11] op_sel:[0,1] op_sel_hi:[1,0] neg_lo:[0,1]
	v_pk_add_f32 v[22:23], v[0:1], v[4:5]
	v_pk_add_f32 v[0:1], v[0:1], v[4:5] neg_lo:[0,1] neg_hi:[0,1]
	v_pk_add_f32 v[4:5], v[2:3], v[6:7]
	v_pk_add_f32 v[2:3], v[2:3], v[6:7] neg_lo:[0,1] neg_hi:[0,1]
	v_pk_add_f32 v[10:11], v[28:29], v[20:21]
	v_pk_add_f32 v[20:21], v[28:29], v[20:21] neg_lo:[0,1] neg_hi:[0,1]
	v_pk_add_f32 v[28:29], v[0:1], v[2:3] op_sel:[0,1] op_sel_hi:[1,0] neg_hi:[0,1]
	v_pk_add_f32 v[0:1], v[0:1], v[2:3] op_sel:[0,1] op_sel_hi:[1,0] neg_lo:[0,1]
	v_pk_add_f32 v[2:3], v[22:23], v[4:5]
	v_and_b32_e32 v7, 15, v206
	v_lshrrev_b32_e32 v6, 1, v206
	v_and_b32_e32 v6, 0x78, v6
	v_mul_u32_u24_e32 v7, 0x88, v7
	v_pk_add_f32 v[4:5], v[22:23], v[4:5] neg_lo:[0,1] neg_hi:[0,1]
	v_add3_u32 v6, v207, v6, v7
	ds_write_b64 v6, v[14:15]
	ds_write_b64 v6, v[32:33] offset:8704
	ds_write_b64 v6, v[16:17] offset:17408
	ds_write_b64 v6, v[12:13] offset:26112
	ds_write_b64 v6, v[24:25] offset:2176
	ds_write_b64 v6, v[70:71] offset:10880
	ds_write_b64 v6, v[18:19] offset:19584
	ds_write_b64 v6, v[26:27] offset:28288
	ds_write_b64 v6, v[10:11] offset:4352
	ds_write_b64 v6, v[30:31] offset:13056
	ds_write_b64 v6, v[20:21] offset:21760
	ds_write_b64 v6, v[8:9] offset:30464
	ds_write_b64 v6, v[2:3] offset:6528
	ds_write_b64 v6, v[28:29] offset:15232
	ds_write_b64 v6, v[4:5] offset:23936
	ds_write_b64 v6, v[0:1] offset:32640
	s_waitcnt lgkmcnt(0)
	s_barrier
	v_and_b32_e32 v12, 31, v69
	v_and_b32_e32 v4, 0xff, v206
	v_sub_u32_e32 v6, 0x100, v4
	v_lshrrev_b32_e32 v5, 1, v206
	v_lshlrev_b32_e32 v7, 3, v4
	v_and_b32_e32 v5, 0x78, v5
	v_lshrrev_b32_e32 v6, 1, v6
	v_add3_u32 v5, v207, v7, v5
	v_sub_u32_e32 v7, v207, v7
	v_and_b32_e32 v6, 0xf8, v6
	v_add_u32_e32 v14, v7, v6
	ds_read_b64 v[10:11], v5
	ds_read_b64 v[6:7], v14 offset:34688
	v_and_b32_e32 v13, 0x1c0, v52
	v_or_b32_sdwa v176, v13, v12 dst_sel:WORD_1 dst_unused:UNUSED_PAD src0_sel:DWORD src1_sel:DWORD
	v_and_b32_e32 v2, 0xfffff000, v49
	v_lshl_add_u64 v[0:1], s[48:49], 0, v[176:177]
	v_ashrrev_i32_e32 v3, 31, v2
	v_cmp_eq_u32_e64 s[38:39], 0, v4
	v_lshl_add_u64 v[0:1], v[2:3], 1, v[0:1]
	v_cmp_eq_u32_e64 s[0:1], 0, v12
	v_cmp_ne_u32_e32 vcc, 0, v12
	s_waitcnt lgkmcnt(0)
	v_cndmask_b32_e64 v9, v7, v11, s[38:39]
	v_cndmask_b32_e64 v8, v6, v10, s[38:39]
	v_lshlrev_b32_e32 v6, 1, v4
	s_and_saveexec_b64 s[20:21], vcc
	s_xor_b64 s[28:29], exec, s[20:21]
	s_cbranch_execz .LBB0_216
	v_bfe_u32 v7, v10, 16, 1
	v_add3_u32 v9, v10, v7, s13
	v_mov_b32_e32 v7, v177
	v_lshl_add_u64 v[10:11], v[0:1], 0, v[6:7]
	global_store_short_d16_hi v[10:11], v9, off sc1
